# token mixer: scalarized q-prep, dead q loads removed, stage-1 bpermute->DPP, SGU bias-in-acc + folded gelu constants
# speedup vs baseline: 1.0398x; 1.0004x over previous
; #define LAS __attribute__((address_space(3)))
; __device__ __forceinline__ void p2_block(LAS unsigned char* lds, const bf16_t* __restrict__ PROJ, bf16_t* __restrict__ ATT, bf16_t* __restrict__ SGU, const float* __restrict__ qn, const float* __restrict__ kn, ...
;     ...
;     const int b = item >> 6, n = (item >> 2) & 15, kvh = item & 3;
;     const int lane = tid & 63, w = __builtin_amdgcn_readfirstlane(tid >> 6), fr = lane & 15, fq = lane >> 4;
;     LAS unsigned char* KS = lds; LAS unsigned char* VT = lds + KS_BYTES;
;     const int g = w >> 1, rbase = (w & 1) * 64, hq = kvh * 4 + g;
;     const int kk = tid >> 1, h = tid & 1, s = n * 128 - 128 + kk, sc = s < 0 ? 0 : s;
;     const bf16_t* rowp = PROJ + (size_t)(b * pg8::SEQ + sc) * pg8::IN_W;
;     const bf16_t* kp = rowp + pg8::C_K + kvh * 64 + 16 * h;
;     const u32x4 ka = *(const u32x4*)kp, kb = *(const u32x4*)(kp + 8), kc = *(const u32x4*)(kp + 32), kd = *(const u32x4*)(kp + 40);
;     const bf16_t* vp = rowp + pg8::C_V + kvh * 64 + 32 * h;
;     u32x4 vv[4];
; #pragma unroll
;     for (int c4 = 0; c4 < 4; ++c4) vv[c4] = *(const u32x4*)(vp + 8 * c4);
;     const int sp_ = tid >> 2, q4 = tid & 3;
;     u32x4 sv[2][4];
;     const bf16_t* svsrc = PROJ + ((size_t)b * pg8::SEQ + n * 128 + sp_) * pg8::IN_W + pg8::C_VS + (2 * kvh) * 128 + 32 * q4;
; #pragma unroll
;     for (int c4 = 0; c4 < 4; ++c4) sv[0][c4] = *(const u32x4*)(svsrc + 8 * c4);
;     u32x4 qa[4], qb[4];
; #pragma unroll
;     for (int c = 0; c < 2; ++c) { const bf16_t* qp = PROJ + ((size_t)b * pg8::SEQ + n * 128 + rbase + 16 * c + fr) * pg8::IN_W + hq * 64 + 8 * fq; qa[c] = *(const u32x4*)qp; qb[c] = *(const u32x4*)(qp + 32); }
.LBB0_330:
	s_bfe_u32 s27, s2, 0x40002
	v_mov_b32_e32 v160, v204
	s_lshl_b32 s17, s27, 7
	s_add_i32 s4, s17, 0xffffff80
	v_ashrrev_i32_e32 v167, 1, v160
	v_add_u32_e32 v22, s4, v167
	s_ashr_i32 s6, s2, 6
	v_max_i32_e32 v66, 0, v22
	s_and_b32 s73, s2, 3
	v_lshl_add_u32 v0, s6, 11, v66
	s_waitcnt lgkmcnt(0)
	v_mov_b64_e32 v[2:3], s[10:11]
	v_and_b32_e32 v166, 1, v160
	v_mad_i64_i32 v[4:5], s[24:25], v0, s83, v[2:3]
	s_lshl_b32 s4, s73, 7
	v_lshl_add_u64 v[4:5], v[4:5], 0, s[4:5]
	v_lshlrev_b32_e32 v0, 5, v166
	v_lshl_add_u64 v[6:7], v[4:5], 0, v[0:1]
	global_load_dwordx4 v[50:53], v[6:7], off offset:2048
	global_load_dwordx4 v[58:61], v[6:7], off offset:2064
	global_load_dwordx4 v[54:57], v[6:7], off offset:2112
	global_load_dwordx4 v[62:65], v[6:7], off offset:2128
	v_readfirstlane_b32 s16, v160
	s_ashr_i32 s77, s16, 7
	s_lshl_b32 s7, s73, 2
	s_add_i32 s42, s77, s7
	s_ashr_i32 s7, s6, 31
	v_lshlrev_b32_e32 v74, 6, v166
	v_mov_b32_e32 v75, v1
	v_ashrrev_i32_e32 v136, 2, v160
	s_lshl_b64 s[48:49], s[6:7], 11
	v_lshl_add_u64 v[4:5], v[4:5], 0, v[74:75]
	s_or_b32 s24, s48, s17
	s_mov_b32 s25, s49
	v_ashrrev_i32_e32 v137, 31, v136
	s_waitcnt lgkmcnt(0)
	global_load_dwordx4 v[18:21], v[4:5], off offset:2560
	global_load_dwordx4 v[14:17], v[4:5], off offset:2576
	global_load_dwordx4 v[10:13], v[4:5], off offset:2592
	global_load_dwordx4 v[6:9], v[4:5], off offset:2608
	v_lshl_add_u64 v[4:5], s[24:25], 0, v[136:137]
	v_mad_u64_u32 v[2:3], s[6:7], v4, s83, v[2:3]
	v_lshlrev_b32_e32 v4, 5, v160
	v_mad_i32_i24 v3, v5, s83, v3
	s_lshl_b32 s4, s73, 9
	v_and_b32_e32 v165, 0x60, v4
	v_lshl_add_u64 v[2:3], v[2:3], 0, s[4:5]
	v_lshlrev_b32_e32 v4, 1, v165
	v_mov_b32_e32 v5, v1
	v_lshl_add_u64 v[2:3], v[2:3], 0, v[4:5]
	s_mov_b64 s[6:7], 0x1400
	v_lshl_add_u64 v[138:139], v[2:3], 0, s[6:7]
	s_lshl_b32 s6, s42, 6
	s_ashr_i32 s7, s6, 31
	s_and_b32 s26, s16, 64
	s_lshl_b64 s[6:7], s[6:7], 1
	v_bfe_u32 v162, v160, 4, 2
	s_add_u32 s28, s10, s6
	s_movk_i32 s4, 0x1000
	v_and_b32_e32 v137, 15, v160
	s_addc_u32 s29, s11, s7
	v_lshlrev_b32_e32 v132, 4, v162
	v_mov_b32_e32 v133, v1
	v_and_b32_e32 v68, 64, v211
	v_add_co_u32_e32 v2, vcc, s4, v2
	v_or_b32_e32 v161, s26, v137
	v_lshl_add_u64 v[134:135], s[28:29], 0, v[132:133]
	v_xor_b32_e32 v67, 1, v211
	v_add_u32_e32 v133, 64, v68
	v_addc_co_u32_e32 v3, vcc, 0, v3, vcc
	v_or_b32_e32 v163, s24, v161
	v_cmp_lt_i32_e64 s[40:41], v67, v133
	v_cmp_gt_i32_e32 vcc, 0, v22
	v_mad_u64_u32 v[22:23], s[28:29], v163, s83, v[134:135]
	v_cndmask_b32_e64 v67, v211, v67, s[40:41]
	v_mad_i32_i24 v23, s49, v212, v23
	v_lshlrev_b32_e32 v164, 2, v67
	v_lshlrev_b32_e32 v66, 5, v66
	v_mov_b32_e32 v67, v1
	v_readlane_b32 s44, v250, 36
	v_readlane_b32 s46, v250, 38
	global_load_dwordx4 v[46:49], v[2:3], off offset:1024
	global_load_dwordx4 v[34:37], v[138:139], off offset:48
	global_load_dwordx4 v[38:41], v[138:139], off offset:32
	global_load_dwordx4 v[42:45], v[138:139], off offset:16
	s_nop 0
	v_or_b32_e32 v22, 16, v163
	v_lshlrev_b64 v[66:67], 2, v[66:67]
	v_readlane_b32 s45, v250, 37
	v_readlane_b32 s47, v250, 39
	v_mad_u64_u32 v[26:27], s[28:29], v22, s83, v[134:135]
	v_lshl_add_u64 v[68:69], s[44:45], 0, v[66:67]
	v_lshl_add_u64 v[66:67], s[46:47], 0, v[66:67]
	v_mad_i32_i24 v27, s49, v212, v27
	v_lshl_add_u64 v[86:87], v[68:69], 0, v[74:75]
	v_lshl_add_u64 v[126:127], v[66:67], 0, v[74:75]
	s_nop 0
	s_nop 0
	global_load_dwordx4 v[66:69], v74, s[0:1] offset:48
	global_load_dwordx4 v[78:81], v74, s[0:1] offset:32
	global_load_dwordx4 v[94:97], v74, s[0:1] offset:16
	global_load_dwordx4 v[106:109], v74, s[0:1]
	global_load_dwordx4 v[70:73], v74, s[0:1] offset:176
	global_load_dwordx4 v[82:85], v74, s[0:1] offset:160
	global_load_dwordx4 v[98:101], v74, s[0:1] offset:144
	global_load_dwordx4 v[110:113], v74, s[0:1] offset:128
	s_nop 0
	global_load_dwordx4 v[74:77], v[86:87], off offset:48
	global_load_dwordx4 v[90:93], v[86:87], off offset:32
	global_load_dwordx4 v[102:105], v[86:87], off offset:16
	global_load_dwordx4 v[114:117], v[86:87], off
	s_nop 0
	global_load_dwordx4 v[86:89], v[126:127], off offset:48
	global_load_dwordx4 v[118:121], v[126:127], off offset:32
	global_load_dwordx4 v[122:125], v[126:127], off offset:16
	s_nop 0
	global_load_dwordx4 v[126:129], v[126:127], off
	v_cndmask_b32_e64 v180, 1.0, 0, vcc
	s_lshl_b32 s4, s73, 10
	s_waitcnt vmcnt(0)
; __device__ __forceinline__ void unpack8(const u32x4 w, float* f) { f[0] = bf_lo(w.x); f[1] = bf_hi(w.x); f[2] = bf_lo(w.y); f[3] = bf_hi(w.y); f[4] = bf_lo(w.z); f[5] = bf_hi(w.z); f[6] = bf_lo(w.w); f[7] = bf_hi(w.w); }
; __device__ __forceinline__ void p2_block(LAS unsigned char* lds, const bf16_t* __restrict__ PROJ, bf16_t* __restrict__ ATT, bf16_t* __restrict__ SGU, const float* __restrict__ qn, const float* __restrict__ kn, ...
;     ...
;         float x1[16], x2[16]; unpack8(ka, x1); unpack8(kb, x1 + 8); unpack8(kc, x2); unpack8(kd, x2 + 8);
;         float ss = 0.f;
; #pragma unroll
;         for (int j = 0; j < 16; ++j) ss += x1[j] * x1[j] + x2[j] * x2[j];
;         ss += __shfl_xor(ss, 1);
;         const float rinv = rsqrtf(ss * (1.0f / 64.0f) + pg8::EPS) * valid;
;         const float* cp = COS + sc * 32 + 16 * h; const float* sp = SIN + sc * 32 + 16 * h;
;         float o1[16], o2[16];
; #pragma unroll
;         for (int j = 0; j < 16; ++j) { const float a1 = x1[j] * rinv * kn[16 * h + j], a2 = x2[j] * rinv * kn[32 + 16 * h + j], c = cp[j], sn = sp[j]; o1[j] = a1 * c - a2 * sn; o2[j] = a2 * c + a1 * sn; }
	v_lshlrev_b32_e32 v226, 16, v51
	v_lshlrev_b32_e32 v142, 16, v61
	v_and_b32_e32 v140, 0xffff0000, v61
	v_lshlrev_b32_e32 v143, 16, v65
	v_and_b32_e32 v141, 0xffff0000, v65
	v_mov_b32_e32 v150, v141
	v_mov_b32_e32 v151, v143
	v_mov_b32_e32 v148, v140
	v_mov_b32_e32 v149, v142
	v_pk_mul_f32 v[150:151], v[150:151], v[150:151]
	v_and_b32_e32 v61, 0xffff0000, v64
	v_pk_fma_f32 v[182:183], v[148:149], v[148:149], v[150:151]
	v_lshlrev_b32_e32 v149, 16, v64
	v_lshlrev_b32_e32 v148, 16, v60
	v_and_b32_e32 v60, 0xffff0000, v60
	v_mov_b32_e32 v154, v61
	v_mov_b32_e32 v155, v149
	v_mov_b32_e32 v64, v60
	v_mov_b32_e32 v65, v148
	v_pk_mul_f32 v[154:155], v[154:155], v[154:155]
	v_and_b32_e32 v201, 0xffff0000, v57
	v_pk_fma_f32 v[184:185], v[64:65], v[64:65], v[154:155]
	v_lshlrev_b32_e32 v155, 16, v63
	v_and_b32_e32 v65, 0xffff0000, v63
	v_lshlrev_b32_e32 v154, 16, v59
	v_and_b32_e32 v64, 0xffff0000, v59
	v_mov_b32_e32 v188, v65
	v_mov_b32_e32 v189, v155
	v_mov_b32_e32 v186, v64
	v_mov_b32_e32 v187, v154
	v_pk_mul_f32 v[188:189], v[188:189], v[188:189]
	v_and_b32_e32 v59, 0xffff0000, v62
	v_pk_fma_f32 v[186:187], v[186:187], v[186:187], v[188:189]
	v_lshlrev_b32_e32 v189, 16, v62
	v_lshlrev_b32_e32 v188, 16, v58
	v_and_b32_e32 v58, 0xffff0000, v58
	v_mov_b32_e32 v194, v59
	v_mov_b32_e32 v195, v189
	v_mov_b32_e32 v62, v58
	v_mov_b32_e32 v63, v188
	v_pk_mul_f32 v[194:195], v[194:195], v[194:195]
	v_and_b32_e32 v234, 0xffff0000, v51
	v_pk_fma_f32 v[62:63], v[62:63], v[62:63], v[194:195]
	v_lshlrev_b32_e32 v195, 16, v57
	v_lshlrev_b32_e32 v239, 16, v54
	v_lshlrev_b32_e32 v238, 16, v50
	v_and_b32_e32 v51, 0xffff0000, v54
	v_and_b32_e32 v50, 0xffff0000, v50
	v_lshlrev_b32_e32 v194, 16, v53
	v_and_b32_e32 v200, 0xffff0000, v53
	v_mov_b32_e32 v218, v201
	v_mov_b32_e32 v219, v195
	v_lshlrev_b32_e32 v227, 16, v55
	v_and_b32_e32 v235, 0xffff0000, v55
	v_pk_mul_f32 v[240:241], v[238:239], v[238:239]
	v_pk_mul_f32 v[54:55], v[50:51], v[50:51]
	v_mov_b32_e32 v202, v200
	v_mov_b32_e32 v203, v194
	v_pk_mul_f32 v[218:219], v[218:219], v[218:219]
	v_pk_mul_f32 v[228:229], v[226:227], v[226:227]
	v_add_f32_e32 v54, v54, v55
	v_add_f32_e32 v55, v240, v241
	v_pk_fma_f32 v[202:203], v[202:203], v[202:203], v[218:219]
	v_lshlrev_b32_e32 v219, 16, v56
	v_lshlrev_b32_e32 v218, 16, v52
	v_pk_mul_f32 v[236:237], v[234:235], v[234:235]
	v_add_f32_e32 v54, v55, v54
	v_add_f32_e32 v55, v228, v229
	v_mov_b32_e32 v150, v66
	v_pk_mul_f32 v[220:221], v[218:219], v[218:219]
	v_and_b32_e32 v53, 0xffff0000, v56
	v_and_b32_e32 v52, 0xffff0000, v52
	v_add_f32_e32 v66, v236, v237
	v_add_f32_e32 v54, v55, v54
	v_pk_mul_f32 v[56:57], v[52:53], v[52:53]
	v_add_f32_e32 v54, v66, v54
	v_add_f32_e32 v55, v220, v221
	v_add_f32_e32 v54, v55, v54
	v_add_f32_e32 v55, v56, v57
	v_add_f32_e32 v54, v55, v54
	v_add_f32_e32 v54, v203, v54
	v_add_f32_e32 v54, v202, v54
	v_add_f32_e32 v54, v63, v54
	v_add_f32_e32 v54, v62, v54
	v_add_f32_e32 v54, v187, v54
	v_add_f32_e32 v54, v186, v54
	v_add_f32_e32 v54, v185, v54
	v_add_f32_e32 v54, v184, v54
	v_add_f32_e32 v54, v183, v54
	v_add_f32_e32 v54, v182, v54
	s_nop 1
	v_mov_b32_dpp v55, v54 quad_perm:[1,0,3,2] row_mask:0xf bank_mask:0xf
	v_mov_b32_e32 v242, v106
	v_mov_b32_e32 v243, v110
	v_mov_b32_e32 v244, v114
	v_mov_b32_e32 v245, v126
	s_waitcnt lgkmcnt(0)
	v_add_f32_e32 v54, v54, v55
	v_fmamk_f32 v54, v54, 0x3c800000, v209
	v_cmp_gt_f32_e64 s[40:41], s82, v54
	v_mul_f32_e32 v55, 0x4b800000, v54
	v_mov_b32_e32 v110, v107
	v_cndmask_b32_e64 v54, v54, v55, s[40:41]
	v_rsq_f32_e32 v54, v54
	v_mov_b32_e32 v230, v108
	v_mov_b32_e32 v231, v112
	v_mov_b32_e32 v232, v116
	v_mul_f32_e32 v55, 0x45800000, v54
	v_cndmask_b32_e64 v54, v54, v55, s[40:41]
	v_mul_f32_e32 v54, v180, v54
	v_pk_mul_f32 v[56:57], v[54:55], v[238:239] op_sel_hi:[0,1]
	v_pk_mul_f32 v[56:57], v[242:243], v[56:57]
	v_mov_b32_e32 v233, v128
	v_pk_mul_f32 v[62:63], v[244:245], v[56:57]
	v_mov_b32_e32 v144, v68
	v_sub_f32_e32 v55, v62, v63
	v_mov_b32_e32 v62, v126
	v_mov_b32_e32 v63, v114
	v_pk_mul_f32 v[50:51], v[54:55], v[50:51] op_sel_hi:[0,1]
	v_pk_mul_f32 v[56:57], v[62:63], v[56:57]
	v_pk_mul_f32 v[50:51], v[110:111], v[50:51]
	v_mov_b32_e32 v126, v115
	v_mov_b32_e32 v114, v127
	v_add_f32_e32 v62, v57, v56
	v_pk_mul_f32 v[56:57], v[126:127], v[50:51]
	v_pk_mul_f32 v[50:51], v[114:115], v[50:51]
	v_sub_f32_e32 v63, v56, v57
	v_add_f32_e32 v66, v51, v50
	v_pk_mul_f32 v[50:51], v[54:55], v[226:227] op_sel_hi:[0,1]
	v_pk_mul_f32 v[50:51], v[230:231], v[50:51]
	v_mov_b32_e32 v190, v78
	v_pk_mul_f32 v[56:57], v[232:233], v[50:51]
	v_mov_b32_e32 v112, v109
	v_sub_f32_e32 v68, v56, v57
	v_mov_b32_e32 v56, v128
	v_mov_b32_e32 v57, v116
	v_pk_mul_f32 v[50:51], v[56:57], v[50:51]
	v_mov_b32_e32 v128, v117
	v_add_f32_e32 v78, v51, v50
	v_pk_mul_f32 v[50:51], v[54:55], v[234:235] op_sel_hi:[0,1]
	v_pk_mul_f32 v[50:51], v[112:113], v[50:51]
	v_mov_b32_e32 v116, v129
	v_pk_mul_f32 v[56:57], v[128:129], v[50:51]
	v_pk_mul_f32 v[50:51], v[116:117], v[50:51]
	v_mov_b32_e32 v222, v94
	v_mov_b32_e32 v223, v98
	v_add_f32_e32 v94, v51, v50
	v_pk_mul_f32 v[50:51], v[54:55], v[218:219] op_sel_hi:[0,1]
	v_mov_b32_e32 v224, v102
	v_mov_b32_e32 v225, v122
	v_pk_mul_f32 v[50:51], v[50:51], v[222:223]
	v_mov_b32_e32 v156, v80
	v_sub_f32_e32 v80, v56, v57
	v_pk_mul_f32 v[56:57], v[50:51], v[224:225]
	v_mov_b32_e32 v196, v96
	v_sub_f32_e32 v96, v56, v57
	v_mov_b32_e32 v56, v122
	v_mov_b32_e32 v57, v102
	v_pk_mul_f32 v[50:51], v[50:51], v[56:57]
	v_mov_b32_e32 v98, v95
	v_add_f32_e32 v106, v51, v50
	v_pk_mul_f32 v[50:51], v[54:55], v[52:53] op_sel_hi:[0,1]
	v_pk_mul_f32 v[50:51], v[50:51], v[98:99]
	v_mov_b32_e32 v122, v103
; __device__ __forceinline__ unsigned cvt_pk_bf16(float lo, float hi) { unsigned r; asm volatile("v_cvt_pk_bf16_f32 %0, %1, %2" : "=v"(r) : "v"(lo), "v"(hi)); return r; }
; #define LAS __attribute__((address_space(3)))
; __device__ __forceinline__ void p2_block(LAS unsigned char* lds, const bf16_t* __restrict__ PROJ, bf16_t* __restrict__ ATT, bf16_t* __restrict__ SGU, const float* __restrict__ qn, const float* __restrict__ kn, ...
;     ...
;         for (int j = 0; j < 16; ++j) { const float a1 = x1[j] * rinv * kn[16 * h + j], a2 = x2[j] * rinv * kn[32 + 16 * h + j], c = cp[j], sn = sp[j]; o1[j] = a1 * c - a2 * sn; o2[j] = a2 * c + a1 * sn; }
;         LAS unsigned char* kdst = KS + kk * KS_STRIDE + 32 * h;
;         u32x4 w0, w1;
;         w0.x = cvt_pk_bf16(o1[0], o1[1]); w0.y = cvt_pk_bf16(o1[2], o1[3]); w0.z = cvt_pk_bf16(o1[4], o1[5]); w0.w = cvt_pk_bf16(o1[6], o1[7]);
;         w1.x = cvt_pk_bf16(o1[8], o1[9]); w1.y = cvt_pk_bf16(o1[10], o1[11]); w1.z = cvt_pk_bf16(o1[12], o1[13]); w1.w = cvt_pk_bf16(o1[14], o1[15]);
;         *(LAS u32x4*)kdst = w0; *(LAS u32x4*)(kdst + 16) = w1;
;         w0.x = cvt_pk_bf16(o2[0], o2[1]); w0.y = cvt_pk_bf16(o2[2], o2[3]); w0.z = cvt_pk_bf16(o2[4], o2[5]); w0.w = cvt_pk_bf16(o2[6], o2[7]);
;         w1.x = cvt_pk_bf16(o2[8], o2[9]); w1.y = cvt_pk_bf16(o2[10], o2[11]); w1.z = cvt_pk_bf16(o2[12], o2[13]); w1.w = cvt_pk_bf16(o2[14], o2[15]);
;         *(LAS u32x4*)(kdst + 64) = w0; *(LAS u32x4*)(kdst + 80) = w1;
;     ...
;         const float* gp = lng + gg * 128 + 32 * q4; const float* bp = lnb + gg * 128 + 32 * q4;
	v_mov_b32_e32 v102, v123
	v_pk_mul_f32 v[52:53], v[50:51], v[122:123]
	v_pk_mul_f32 v[50:51], v[50:51], v[102:103]
	v_mov_b32_e32 v197, v100
	v_add_f32_e32 v95, v51, v50
	v_pk_mul_f32 v[50:51], v[54:55], v[194:195] op_sel_hi:[0,1]
	v_mov_b32_e32 v198, v104
	v_mov_b32_e32 v199, v124
	v_pk_mul_f32 v[50:51], v[50:51], v[196:197]
	v_sub_f32_e32 v56, v52, v53
	v_pk_mul_f32 v[52:53], v[50:51], v[198:199]
	v_mov_b32_e32 v100, v97
	v_sub_f32_e32 v57, v52, v53
	v_mov_b32_e32 v52, v124
	v_mov_b32_e32 v53, v104
	v_pk_mul_f32 v[50:51], v[50:51], v[52:53]
	v_mov_b32_e32 v124, v105
	v_add_f32_e32 v98, v51, v50
	v_pk_mul_f32 v[50:51], v[54:55], v[200:201] op_sel_hi:[0,1]
	v_pk_mul_f32 v[50:51], v[50:51], v[100:101]
	v_mov_b32_e32 v104, v125
	v_pk_mul_f32 v[52:53], v[50:51], v[124:125]
	v_pk_mul_f32 v[50:51], v[50:51], v[104:105]
	v_mov_b32_e32 v191, v82
	v_add_f32_e32 v99, v51, v50
	v_pk_mul_f32 v[50:51], v[54:55], v[188:189] op_sel_hi:[0,1]
	v_mov_b32_e32 v192, v90
	v_mov_b32_e32 v193, v118
	v_pk_mul_f32 v[50:51], v[50:51], v[190:191]
	v_sub_f32_e32 v97, v52, v53
	v_pk_mul_f32 v[52:53], v[50:51], v[192:193]
	v_mov_b32_e32 v82, v79
	v_sub_f32_e32 v100, v52, v53
	v_mov_b32_e32 v52, v118
	v_mov_b32_e32 v53, v90
	v_pk_mul_f32 v[50:51], v[50:51], v[52:53]
	v_mov_b32_e32 v118, v91
	v_add_f32_e32 v101, v51, v50
	v_pk_mul_f32 v[50:51], v[54:55], v[58:59] op_sel_hi:[0,1]
	v_pk_mul_f32 v[50:51], v[50:51], v[82:83]
	v_mov_b32_e32 v90, v119
	v_pk_mul_f32 v[52:53], v[50:51], v[118:119]
	v_pk_mul_f32 v[50:51], v[50:51], v[90:91]
	v_mov_b32_e32 v157, v84
	v_add_f32_e32 v59, v51, v50
	v_pk_mul_f32 v[50:51], v[54:55], v[154:155] op_sel_hi:[0,1]
	v_mov_b32_e32 v158, v92
	v_mov_b32_e32 v159, v120
	v_pk_mul_f32 v[50:51], v[50:51], v[156:157]
	v_sub_f32_e32 v58, v52, v53
	v_pk_mul_f32 v[52:53], v[50:51], v[158:159]
	v_mov_b32_e32 v84, v81
	v_sub_f32_e32 v79, v52, v53
	v_mov_b32_e32 v52, v120
	v_mov_b32_e32 v53, v92
	v_pk_mul_f32 v[50:51], v[50:51], v[52:53]
	v_mov_b32_e32 v120, v93
	v_add_f32_e32 v82, v51, v50
	v_pk_mul_f32 v[50:51], v[54:55], v[64:65] op_sel_hi:[0,1]
	v_pk_mul_f32 v[50:51], v[50:51], v[84:85]
	v_mov_b32_e32 v92, v121
	v_pk_mul_f32 v[52:53], v[50:51], v[120:121]
	v_pk_mul_f32 v[50:51], v[50:51], v[92:93]
	v_mov_b32_e32 v151, v70
	v_add_f32_e32 v65, v51, v50
	v_pk_mul_f32 v[50:51], v[54:55], v[148:149] op_sel_hi:[0,1]
	v_mov_b32_e32 v152, v74
	v_mov_b32_e32 v153, v86
	v_pk_mul_f32 v[50:51], v[50:51], v[150:151]
	v_sub_f32_e32 v64, v52, v53
	v_pk_mul_f32 v[52:53], v[50:51], v[152:153]
	v_mov_b32_e32 v70, v67
	v_sub_f32_e32 v81, v52, v53
	v_mov_b32_e32 v52, v86
	v_mov_b32_e32 v53, v74
	v_pk_mul_f32 v[50:51], v[50:51], v[52:53]
	v_mov_b32_e32 v86, v75
	v_add_f32_e32 v83, v51, v50
	v_pk_mul_f32 v[50:51], v[54:55], v[60:61] op_sel_hi:[0,1]
	v_pk_mul_f32 v[50:51], v[50:51], v[70:71]
	v_mov_b32_e32 v74, v87
	v_pk_mul_f32 v[52:53], v[50:51], v[86:87]
	v_pk_mul_f32 v[50:51], v[50:51], v[74:75]
	v_mov_b32_e32 v145, v72
	v_add_f32_e32 v61, v51, v50
	v_pk_mul_f32 v[50:51], v[54:55], v[142:143] op_sel_hi:[0,1]
	v_mov_b32_e32 v146, v76
	v_mov_b32_e32 v147, v88
	v_pk_mul_f32 v[50:51], v[50:51], v[144:145]
	v_sub_f32_e32 v60, v52, v53
	v_pk_mul_f32 v[52:53], v[50:51], v[146:147]
	v_mov_b32_e32 v72, v69
	v_lshl_add_u32 v182, v165, 2, s4
	global_load_dwordx4 v[144:147], v182, s[36:37] offset:0
	global_load_dwordx4 v[148:151], v182, s[36:37] offset:16
	global_load_dwordx4 v[152:155], v182, s[36:37] offset:32
	global_load_dwordx4 v[156:159], v182, s[36:37] offset:48
	global_load_dwordx4 v[184:187], v182, s[36:37] offset:64
	global_load_dwordx4 v[188:191], v182, s[36:37] offset:80
	global_load_dwordx4 v[192:195], v182, s[36:37] offset:96
	global_load_dwordx4 v[196:199], v182, s[36:37] offset:112
	global_load_dwordx4 v[218:221], v182, s[18:19] offset:0
	global_load_dwordx4 v[222:225], v182, s[18:19] offset:16
	global_load_dwordx4 v[226:229], v182, s[18:19] offset:32
	global_load_dwordx4 v[230:233], v182, s[18:19] offset:48
	global_load_dwordx4 v[234:237], v182, s[18:19] offset:64
	global_load_dwordx4 v[238:241], v182, s[18:19] offset:80
	global_load_dwordx4 v[242:245], v182, s[18:19] offset:96
	global_load_dwordx4 v[200:203], v182, s[18:19] offset:112
	v_sub_f32_e32 v67, v52, v53
	v_mov_b32_e32 v52, v88
	v_mov_b32_e32 v53, v76
	v_pk_mul_f32 v[50:51], v[50:51], v[52:53]
	v_mov_b32_e32 v88, v77
	v_add_f32_e32 v70, v51, v50
	v_pk_mul_f32 v[50:51], v[54:55], v[140:141] op_sel_hi:[0,1]
	v_pk_mul_f32 v[50:51], v[50:51], v[72:73]
	v_mov_b32_e32 v76, v89
	v_pk_mul_f32 v[52:53], v[50:51], v[88:89]
	v_pk_mul_f32 v[50:51], v[50:51], v[76:77]
	v_sub_f32_e32 v69, v52, v53
	v_add_f32_e32 v71, v51, v50
	v_mul_lo_u32 v50, v167, s59
	v_add3_u32 v0, 0, v50, v0
	v_cvt_pk_bf16_f32 v50, v55, v63
	v_cvt_pk_bf16_f32 v51, v68, v80
	v_cvt_pk_bf16_f32 v52, v96, v56
	v_cvt_pk_bf16_f32 v53, v57, v97
	v_cvt_pk_bf16_f32 v54, v100, v58
	v_cvt_pk_bf16_f32 v55, v79, v64
	v_cvt_pk_bf16_f32 v56, v81, v60
	v_cvt_pk_bf16_f32 v57, v67, v69
	v_lshlrev_b32_e32 v73, 16, v46
	ds_write_b128 v0, v[50:53]
	ds_write_b128 v0, v[54:57] offset:16
	v_cvt_pk_bf16_f32 v50, v62, v66
	v_cvt_pk_bf16_f32 v51, v78, v94
	v_cvt_pk_bf16_f32 v52, v106, v95
	v_cvt_pk_bf16_f32 v53, v98, v99
	v_cvt_pk_bf16_f32 v54, v101, v59
	v_cvt_pk_bf16_f32 v55, v82, v65
	v_cvt_pk_bf16_f32 v56, v83, v61
	v_cvt_pk_bf16_f32 v57, v70, v71
	v_lshlrev_b32_e32 v70, 16, v48
	v_and_b32_e32 v69, 0xffff0000, v48
	v_lshlrev_b32_e32 v68, 16, v49
	v_and_b32_e32 v67, 0xffff0000, v49
	v_lshlrev_b32_e32 v66, 16, v42
	v_and_b32_e32 v65, 0xffff0000, v42
	v_lshlrev_b32_e32 v64, 16, v43
	v_and_b32_e32 v63, 0xffff0000, v43
	v_lshlrev_b32_e32 v62, 16, v44
; __device__ __forceinline__ float gelu_f(float x) { const float y2 = 1.5957691216057308f * x * (1.0f + 0.044715f * x * x); return x * sigmoid_f(y2); }
; __device__ __forceinline__ void unpack8(const u32x4 w, float* f) { f[0] = bf_lo(w.x); f[1] = bf_hi(w.x); f[2] = bf_lo(w.y); f[3] = bf_hi(w.y); f[4] = bf_lo(w.z); f[5] = bf_hi(w.z); f[6] = bf_lo(w.w); f[7] = bf_hi(w.w); }
; __device__ __forceinline__ float sigmoid_f(float v) { return __builtin_amdgcn_rcpf(1.0f + __expf(-v)); }
; __device__ __forceinline__ void p2_block(LAS unsigned char* lds, const bf16_t* __restrict__ PROJ, bf16_t* __restrict__ ATT, bf16_t* __restrict__ SGU, const float* __restrict__ qn, const float* __restrict__ kn, ...
;     ...
;         for (int c4 = 0; c4 < 4; ++c4) unpack8(sv[gi][c4], v + 8 * c4);
;         float sm = 0.f;
; #pragma unroll
;         for (int j = 0; j < 32; ++j) { v[j] = gelu_f(v[j]); sm += v[j]; }
	v_and_b32_e32 v61, 0xffff0000, v44
	v_lshlrev_b32_e32 v60, 16, v45
	v_and_b32_e32 v59, 0xffff0000, v45
	v_lshlrev_b32_e32 v49, 16, v40
	v_and_b32_e32 v48, 0xffff0000, v40
	v_lshlrev_b32_e32 v45, 16, v41
	v_and_b32_e32 v44, 0xffff0000, v41
	v_lshlrev_b32_e32 v43, 16, v34
	v_and_b32_e32 v42, 0xffff0000, v34
	v_lshlrev_b32_e32 v41, 16, v35
	v_and_b32_e32 v40, 0xffff0000, v35
	v_lshlrev_b32_e32 v35, 16, v37
	v_and_b32_e32 v34, 0xffff0000, v37
	v_mul_f32_e32 v37, 0x3d372713, v73
	ds_write_b128 v0, v[50:53] offset:64
	ds_write_b128 v0, v[54:57] offset:80
	v_lshlrev_b32_e32 v58, 16, v38
	v_and_b32_e32 v57, 0xffff0000, v38
	v_lshlrev_b32_e32 v56, 16, v39
	v_and_b32_e32 v55, 0xffff0000, v39
	v_lshlrev_b32_e32 v39, 16, v36
	v_and_b32_e32 v38, 0xffff0000, v36
	v_mul_f32_e32 v36, 0x3fcc422a, v73
	v_fma_f32 v37, v37, v73, 1.0
	v_mul_f32_e32 v36, v36, v37
	v_mul_f32_e32 v36, 0xbfb8aa3b, v36
	v_exp_f32_e32 v36, v36
	v_and_b32_e32 v74, 0xffff0000, v46
	v_mul_f32_e32 v37, 0x3d372713, v74
	v_fma_f32 v37, v37, v74, 1.0
	v_add_f32_e32 v36, 1.0, v36
	v_rcp_f32_e32 v75, v36
	v_mul_f32_e32 v36, 0x3fcc422a, v74
	v_mul_f32_e32 v36, v36, v37
	v_mul_f32_e32 v36, 0xbfb8aa3b, v36
	v_exp_f32_e32 v36, v36
	v_lshlrev_b32_e32 v72, 16, v47
	v_mul_f32_e32 v37, 0x3d372713, v72
	v_fma_f32 v37, v37, v72, 1.0
	v_add_f32_e32 v36, 1.0, v36
	v_rcp_f32_e32 v76, v36
	v_mul_f32_e32 v36, 0x3fcc422a, v72
	v_mul_f32_e32 v36, v36, v37
	v_mul_f32_e32 v36, 0xbfb8aa3b, v36
	v_exp_f32_e32 v36, v36
	v_and_b32_e32 v71, 0xffff0000, v47
	v_mul_f32_e32 v37, 0x3d372713, v71
	v_fma_f32 v37, v37, v71, 1.0
	v_add_f32_e32 v36, 1.0, v36
	v_rcp_f32_e32 v77, v36
	v_mul_f32_e32 v36, 0x3fcc422a, v71
	v_mul_f32_e32 v36, v36, v37
	v_mul_f32_e32 v36, 0xbfb8aa3b, v36
	v_exp_f32_e32 v36, v36
	v_mul_f32_e32 v37, 0x3d372713, v70
	v_fma_f32 v37, v37, v70, 1.0
	v_fma_f32 v46, v75, v73, 0
	v_add_f32_e32 v36, 1.0, v36
	v_rcp_f32_e32 v78, v36
	v_mul_f32_e32 v36, 0x3fcc422a, v70
	v_mul_f32_e32 v36, v36, v37
	v_mul_f32_e32 v36, 0xbfb8aa3b, v36
	v_exp_f32_e32 v36, v36
	v_mul_f32_e32 v37, 0x3d372713, v69
	v_fma_f32 v37, v37, v69, 1.0
	v_fmac_f32_e32 v46, v76, v74
	v_add_f32_e32 v36, 1.0, v36
	v_rcp_f32_e32 v79, v36
	v_mul_f32_e32 v36, 0x3fcc422a, v69
	v_mul_f32_e32 v36, v36, v37
	v_mul_f32_e32 v36, 0xbfb8aa3b, v36
	v_exp_f32_e32 v36, v36
	v_mul_f32_e32 v37, 0x3d372713, v68
	v_fma_f32 v37, v37, v68, 1.0
	v_fmac_f32_e32 v46, v77, v72
	v_add_f32_e32 v36, 1.0, v36
	v_rcp_f32_e32 v80, v36
	v_mul_f32_e32 v36, 0x3fcc422a, v68
	v_mul_f32_e32 v36, v36, v37
	v_mul_f32_e32 v36, 0xbfb8aa3b, v36
	v_exp_f32_e32 v36, v36
	v_mul_f32_e32 v37, 0x3d372713, v67
	v_fma_f32 v37, v37, v67, 1.0
	v_fmac_f32_e32 v46, v78, v71
	v_add_f32_e32 v36, 1.0, v36
	v_rcp_f32_e32 v81, v36
	v_mul_f32_e32 v36, 0x3fcc422a, v67
	v_mul_f32_e32 v36, v36, v37
	v_mul_f32_e32 v36, 0xbfb8aa3b, v36
	v_exp_f32_e32 v36, v36
	v_mul_f32_e32 v37, 0x3d372713, v66
	v_fma_f32 v37, v37, v66, 1.0
	v_fmac_f32_e32 v46, v79, v70
	v_add_f32_e32 v36, 1.0, v36
	v_rcp_f32_e32 v82, v36
	v_mul_f32_e32 v36, 0x3fcc422a, v66
	v_mul_f32_e32 v36, v36, v37
	v_mul_f32_e32 v36, 0xbfb8aa3b, v36
	v_exp_f32_e32 v36, v36
	v_mul_f32_e32 v37, 0x3d372713, v65
	v_fma_f32 v37, v37, v65, 1.0
	v_fmac_f32_e32 v46, v80, v69
	v_add_f32_e32 v36, 1.0, v36
	v_rcp_f32_e32 v84, v36
	v_mul_f32_e32 v36, 0x3fcc422a, v65
	v_mul_f32_e32 v36, v36, v37
	v_mul_f32_e32 v36, 0xbfb8aa3b, v36
	v_exp_f32_e32 v36, v36
	v_mul_f32_e32 v37, 0x3d372713, v64
	v_fma_f32 v37, v37, v64, 1.0
	v_fmac_f32_e32 v46, v81, v68
	v_add_f32_e32 v36, 1.0, v36
	v_rcp_f32_e32 v85, v36
	v_mul_f32_e32 v36, 0x3fcc422a, v64
	v_mul_f32_e32 v36, v36, v37
	v_mul_f32_e32 v36, 0xbfb8aa3b, v36
	v_exp_f32_e32 v36, v36
	v_mul_f32_e32 v37, 0x3d372713, v63
	v_fma_f32 v37, v37, v63, 1.0
	v_fmac_f32_e32 v46, v82, v67
	v_add_f32_e32 v36, 1.0, v36
	v_rcp_f32_e32 v86, v36
	v_mul_f32_e32 v36, 0x3fcc422a, v63
	v_mul_f32_e32 v36, v36, v37
	v_mul_f32_e32 v36, 0xbfb8aa3b, v36
	v_exp_f32_e32 v36, v36
	v_mul_f32_e32 v37, 0x3d372713, v62
	v_fma_f32 v37, v37, v62, 1.0
	v_fmac_f32_e32 v46, v84, v66
	v_add_f32_e32 v36, 1.0, v36
	v_rcp_f32_e32 v87, v36
	v_mul_f32_e32 v36, 0x3fcc422a, v62
	v_mul_f32_e32 v36, v36, v37
	v_mul_f32_e32 v36, 0xbfb8aa3b, v36
	v_exp_f32_e32 v36, v36
	v_mul_f32_e32 v37, 0x3d372713, v61
	v_fma_f32 v37, v37, v61, 1.0
	v_fmac_f32_e32 v46, v85, v65
	v_add_f32_e32 v36, 1.0, v36
	v_rcp_f32_e32 v88, v36
	v_mul_f32_e32 v36, 0x3fcc422a, v61
	v_mul_f32_e32 v36, v36, v37
	v_mul_f32_e32 v36, 0xbfb8aa3b, v36
	v_exp_f32_e32 v36, v36
	v_mul_f32_e32 v37, 0x3d372713, v60
	v_fma_f32 v37, v37, v60, 1.0
	v_fmac_f32_e32 v46, v86, v64
	v_add_f32_e32 v36, 1.0, v36
	v_rcp_f32_e32 v89, v36
	v_mul_f32_e32 v36, 0x3fcc422a, v60
	v_mul_f32_e32 v36, v36, v37
	v_mul_f32_e32 v36, 0xbfb8aa3b, v36
	v_exp_f32_e32 v36, v36
	v_mul_f32_e32 v37, 0x3d372713, v59
	v_fma_f32 v37, v37, v59, 1.0
	v_mul_f32_e32 v47, 0x3d372713, v42
	v_add_f32_e32 v36, 1.0, v36
	v_rcp_f32_e32 v90, v36
	v_mul_f32_e32 v36, 0x3fcc422a, v59
	v_mul_f32_e32 v36, v36, v37
	v_mul_f32_e32 v36, 0xbfb8aa3b, v36
	v_exp_f32_e32 v36, v36
	v_mul_f32_e32 v37, 0x3d372713, v58
	v_fma_f32 v37, v37, v58, 1.0
	v_fmac_f32_e32 v46, v87, v63
	v_add_f32_e32 v36, 1.0, v36
	v_rcp_f32_e32 v91, v36
	v_mul_f32_e32 v36, 0x3fcc422a, v58
	v_mul_f32_e32 v36, v36, v37
	v_mul_f32_e32 v36, 0xbfb8aa3b, v36
	v_exp_f32_e32 v36, v36
	v_mul_f32_e32 v37, 0x3d372713, v57
	v_fma_f32 v37, v37, v57, 1.0
	v_fma_f32 v47, v47, v42, 1.0
	v_add_f32_e32 v36, 1.0, v36
	v_rcp_f32_e32 v98, v36
	v_mul_f32_e32 v36, 0x3fcc422a, v57
	v_mul_f32_e32 v36, v36, v37
	v_mul_f32_e32 v36, 0xbfb8aa3b, v36
	v_exp_f32_e32 v36, v36
	v_mul_f32_e32 v37, 0x3d372713, v56
; __device__ __forceinline__ float gelu_f(float x) { const float y2 = 1.5957691216057308f * x * (1.0f + 0.044715f * x * x); return x * sigmoid_f(y2); }
; #define LAS __attribute__((address_space(3)))
; __device__ __forceinline__ void unpack8(const u32x4 w, float* f) { f[0] = bf_lo(w.x); f[1] = bf_hi(w.x); f[2] = bf_lo(w.y); f[3] = bf_hi(w.y); f[4] = bf_lo(w.z); f[5] = bf_hi(w.z); f[6] = bf_lo(w.w); f[7] = bf_hi(w.w); }
; __device__ __forceinline__ void p2_block(LAS unsigned char* lds, const bf16_t* __restrict__ PROJ, bf16_t* __restrict__ ATT, bf16_t* __restrict__ SGU, const float* __restrict__ qn, const float* __restrict__ kn, ...
;     ...
;         for (int c4 = 0; c4 < 4; ++c4) { u32x4 t = vv[c4]; if (s < 0) t = (u32x4){0u, 0u, 0u, 0u};
;             LAS unsigned char* vd = VT + (32 * h + 8 * c4) * VT_STRIDE + kk * 2;
;             *(LAS unsigned short*)(vd + 0 * VT_STRIDE) = (unsigned short)(t.x & 0xffffu); *(LAS unsigned short*)(vd + 1 * VT_STRIDE) = (unsigned short)(t.x >> 16);
;             *(LAS unsigned short*)(vd + 2 * VT_STRIDE) = (unsigned short)(t.y & 0xffffu); *(LAS unsigned short*)(vd + 3 * VT_STRIDE) = (unsigned short)(t.y >> 16);
;             *(LAS unsigned short*)(vd + 4 * VT_STRIDE) = (unsigned short)(t.z & 0xffffu); *(LAS unsigned short*)(vd + 5 * VT_STRIDE) = (unsigned short)(t.z >> 16);
;             *(LAS unsigned short*)(vd + 6 * VT_STRIDE) = (unsigned short)(t.w & 0xffffu); *(LAS unsigned short*)(vd + 7 * VT_STRIDE) = (unsigned short)(t.w >> 16); }
;     }
; #pragma unroll
;     for (int gi = 0; gi < 2; ++gi) {
;         const int gg = 2 * kvh + gi;
;         if (gi == 0) {
; #pragma unroll
;             for (int c4 = 0; c4 < 4; ++c4) sv[1][c4] = *(const u32x4*)(svsrc + 128 + 8 * c4); }
;         float v[32];
; #pragma unroll
;         for (int c4 = 0; c4 < 4; ++c4) unpack8(sv[gi][c4], v + 8 * c4);
;         float sm = 0.f;
; #pragma unroll
;         for (int j = 0; j < 32; ++j) { v[j] = gelu_f(v[j]); sm += v[j]; }
;         sm += __shfl_xor(sm, 1); sm += __shfl_xor(sm, 2);
	v_fma_f32 v37, v37, v56, 1.0
	v_fmac_f32_e32 v46, v88, v62
	v_add_f32_e32 v36, 1.0, v36
	v_rcp_f32_e32 v99, v36
	v_mul_f32_e32 v36, 0x3fcc422a, v56
	v_mul_f32_e32 v36, v36, v37
	v_mul_f32_e32 v36, 0xbfb8aa3b, v36
	v_exp_f32_e32 v36, v36
	v_mul_f32_e32 v37, 0x3d372713, v55
	v_fma_f32 v37, v37, v55, 1.0
	v_fmac_f32_e32 v46, v89, v61
	v_add_f32_e32 v36, 1.0, v36
	v_rcp_f32_e32 v100, v36
	v_mul_f32_e32 v36, 0x3fcc422a, v55
	v_mul_f32_e32 v36, v36, v37
	v_mul_f32_e32 v36, 0xbfb8aa3b, v36
	v_exp_f32_e32 v36, v36
	v_mul_f32_e32 v37, 0x3d372713, v49
	v_fma_f32 v37, v37, v49, 1.0
	v_fmac_f32_e32 v46, v90, v60
	v_add_f32_e32 v36, 1.0, v36
	v_rcp_f32_e32 v101, v36
	v_mul_f32_e32 v36, 0x3fcc422a, v49
	v_mul_f32_e32 v36, v36, v37
	v_mul_f32_e32 v36, 0xbfb8aa3b, v36
	v_exp_f32_e32 v36, v36
	v_mul_f32_e32 v37, 0x3d372713, v48
	v_fma_f32 v37, v37, v48, 1.0
	v_fmac_f32_e32 v46, v91, v59
	v_add_f32_e32 v36, 1.0, v36
	v_rcp_f32_e32 v102, v36
	v_mul_f32_e32 v36, 0x3fcc422a, v48
	v_mul_f32_e32 v36, v36, v37
	v_mul_f32_e32 v36, 0xbfb8aa3b, v36
	v_exp_f32_e32 v36, v36
	v_mul_f32_e32 v37, 0x3d372713, v45
	v_fma_f32 v37, v37, v45, 1.0
	v_fmac_f32_e32 v46, v98, v58
	v_add_f32_e32 v36, 1.0, v36
	v_rcp_f32_e32 v103, v36
	v_mul_f32_e32 v36, 0x3fcc422a, v45
	v_mul_f32_e32 v36, v36, v37
	v_mul_f32_e32 v36, 0xbfb8aa3b, v36
	v_exp_f32_e32 v36, v36
	v_mul_f32_e32 v37, 0x3d372713, v44
	v_fma_f32 v37, v37, v44, 1.0
	v_fmac_f32_e32 v46, v99, v57
	v_add_f32_e32 v36, 1.0, v36
	v_rcp_f32_e32 v104, v36
	v_mul_f32_e32 v36, 0x3fcc422a, v44
	v_mul_f32_e32 v36, v36, v37
	v_mul_f32_e32 v36, 0xbfb8aa3b, v36
	v_exp_f32_e32 v36, v36
	v_mul_f32_e32 v37, 0x3d372713, v43
	v_fma_f32 v37, v37, v43, 1.0
	v_fmac_f32_e32 v46, v100, v56
	v_add_f32_e32 v36, 1.0, v36
	v_rcp_f32_e32 v105, v36
	v_mul_f32_e32 v36, 0x3fcc422a, v43
	v_mul_f32_e32 v36, v36, v37
	v_mul_f32_e32 v36, 0xbfb8aa3b, v36
	v_exp_f32_e32 v36, v36
	v_fmac_f32_e32 v46, v101, v55
	v_fmac_f32_e32 v46, v102, v49
	v_fmac_f32_e32 v46, v103, v48
	v_add_f32_e32 v36, 1.0, v36
	v_rcp_f32_e32 v37, v36
	v_mul_f32_e32 v36, 0x3fcc422a, v42
	v_mul_f32_e32 v36, v36, v47
	v_mul_f32_e32 v36, 0xbfb8aa3b, v36
	v_exp_f32_e32 v36, v36
	v_fmac_f32_e32 v46, v104, v45
	v_fmac_f32_e32 v46, v105, v44
	v_mul_f32_e32 v47, 0x3d372713, v41
	v_add_f32_e32 v36, 1.0, v36
	v_rcp_f32_e32 v36, v36
	v_fma_f32 v47, v47, v41, 1.0
	v_mul_f32_e32 v94, 0x3d372713, v38
	v_fma_f32 v94, v94, v38, 1.0
	v_pk_mul_f32 v[92:93], v[36:37], v[42:43]
	v_mul_f32_e32 v96, 0x3d372713, v34
	v_add_f32_e32 v46, v93, v46
	v_add_f32_e32 v83, v92, v46
	v_mul_f32_e32 v46, 0x3fcc422a, v41
	v_mul_f32_e32 v46, v46, v47
	v_mul_f32_e32 v46, 0xbfb8aa3b, v46
	v_exp_f32_e32 v46, v46
	v_mul_f32_e32 v92, 0x3d372713, v40
	v_fma_f32 v92, v92, v40, 1.0
	v_fma_f32 v96, v96, v34, 1.0
	v_add_f32_e32 v46, 1.0, v46
	v_rcp_f32_e32 v47, v46
	v_mul_f32_e32 v46, 0x3fcc422a, v40
	v_mul_f32_e32 v46, v46, v92
	v_mul_f32_e32 v46, 0xbfb8aa3b, v46
	v_exp_f32_e32 v46, v46
	v_and_b32_e32 v0, -2, v160
	v_mul_u32_u24_e32 v50, 0x4200, v166
	v_cndmask_b32_e64 v18, v18, 0, vcc
	v_add_f32_e32 v46, 1.0, v46
	v_rcp_f32_e32 v46, v46
	v_add3_u32 v0, 0, v0, v50
	v_cndmask_b32_e64 v14, v14, 0, vcc
	v_cndmask_b32_e64 v10, v10, 0, vcc
	v_pk_mul_f32 v[92:93], v[46:47], v[40:41]
	v_cndmask_b32_e64 v6, v6, 0, vcc
	v_add_f32_e32 v83, v93, v83
	v_mul_f32_e32 v93, 0x3d372713, v39
	v_add_f32_e32 v83, v92, v83
	v_mul_f32_e32 v92, 0x3fcc422a, v39
	v_fma_f32 v93, v93, v39, 1.0
	v_mul_f32_e32 v92, v92, v93
	v_mul_f32_e32 v92, 0xbfb8aa3b, v92
	v_exp_f32_e32 v92, v92
	v_cndmask_b32_e64 v21, v21, 0, vcc
	v_cndmask_b32_e64 v20, v20, 0, vcc
	v_cndmask_b32_e64 v19, v19, 0, vcc
	v_add_f32_e32 v92, 1.0, v92
	v_rcp_f32_e32 v93, v92
	v_mul_f32_e32 v92, 0x3fcc422a, v38
	v_mul_f32_e32 v92, v92, v94
	v_mul_f32_e32 v92, 0xbfb8aa3b, v92
	v_exp_f32_e32 v92, v92
	ds_write_b16 v0, v18 offset:36864
	ds_write_b16_d16_hi v0, v18 offset:37392
	ds_write_b16 v0, v19 offset:37920
	ds_write_b16_d16_hi v0, v19 offset:38448
	ds_write_b16 v0, v20 offset:38976
	ds_write_b16_d16_hi v0, v20 offset:39504
	ds_write_b16 v0, v21 offset:40032
	ds_write_b16_d16_hi v0, v21 offset:40560
	v_cndmask_b32_e64 v17, v17, 0, vcc
	v_cndmask_b32_e64 v16, v16, 0, vcc
	v_add_f32_e32 v92, 1.0, v92
	v_rcp_f32_e32 v92, v92
	v_cndmask_b32_e64 v15, v15, 0, vcc
	ds_write_b16 v0, v14 offset:41088
	ds_write_b16_d16_hi v0, v14 offset:41616
	ds_write_b16 v0, v15 offset:42144
	ds_write_b16_d16_hi v0, v15 offset:42672
	ds_write_b16 v0, v16 offset:43200
	ds_write_b16_d16_hi v0, v16 offset:43728
	ds_write_b16 v0, v17 offset:44256
	ds_write_b16_d16_hi v0, v17 offset:44784
	v_cndmask_b32_e64 v13, v13, 0, vcc
	v_pk_mul_f32 v[94:95], v[92:93], v[38:39]
	v_cndmask_b32_e64 v12, v12, 0, vcc
	v_add_f32_e32 v83, v95, v83
	v_mul_f32_e32 v95, 0x3d372713, v35
	v_add_f32_e32 v83, v94, v83
	v_mul_f32_e32 v94, 0x3fcc422a, v35
	v_fma_f32 v95, v95, v35, 1.0
	v_mul_f32_e32 v94, v94, v95
	v_mul_f32_e32 v94, 0xbfb8aa3b, v94
	v_exp_f32_e32 v94, v94
	v_cndmask_b32_e64 v11, v11, 0, vcc
	ds_write_b16 v0, v10 offset:45312
	ds_write_b16_d16_hi v0, v10 offset:45840
	ds_write_b16 v0, v11 offset:46368
	ds_write_b16_d16_hi v0, v11 offset:46896
	ds_write_b16 v0, v12 offset:47424
	ds_write_b16_d16_hi v0, v12 offset:47952
	ds_write_b16 v0, v13 offset:48480
	ds_write_b16_d16_hi v0, v13 offset:49008
	v_cndmask_b32_e64 v9, v9, 0, vcc
	v_add_f32_e32 v94, 1.0, v94
	v_rcp_f32_e32 v95, v94
	v_mul_f32_e32 v94, 0x3fcc422a, v34
	v_mul_f32_e32 v94, v94, v96
	v_mul_f32_e32 v94, 0xbfb8aa3b, v94
	v_exp_f32_e32 v94, v94
	v_cndmask_b32_e64 v8, v8, 0, vcc
	v_cndmask_b32_e64 v7, v7, 0, vcc
	ds_write_b16 v0, v6 offset:49536
	ds_write_b16_d16_hi v0, v6 offset:50064
	ds_write_b16 v0, v7 offset:50592
	ds_write_b16_d16_hi v0, v7 offset:51120
	ds_write_b16 v0, v8 offset:51648
	ds_write_b16_d16_hi v0, v8 offset:52176
	ds_write_b16 v0, v9 offset:52704
	ds_write_b16_d16_hi v0, v9 offset:53232
	v_add_f32_e32 v94, 1.0, v94
	v_rcp_f32_e32 v94, v94
	v_xor_b32_e32 v0, 2, v211
	v_cmp_lt_i32_e32 vcc, v0, v133
	v_lshlrev_b32_e32 v6, 1, v136
	v_pk_mul_f32 v[96:97], v[94:95], v[34:35]
	v_cndmask_b32_e32 v0, v211, v0, vcc
	v_add_f32_e32 v83, v97, v83
	v_add_f32_e32 v83, v96, v83
	s_nop 1
	v_mov_b32_dpp v96, v83 quad_perm:[1,0,3,2] row_mask:0xf bank_mask:0xf
	v_lshlrev_b32_e32 v54, 2, v0
	v_lshlrev_b32_e32 v0, 2, v165
	v_lshl_add_u64 v[50:51], s[36:37], 0, v[0:1]
	v_lshl_add_u64 v[52:53], s[18:19], 0, v[0:1]
	s_waitcnt lgkmcnt(0)
; __device__ __forceinline__ unsigned cvt_pk_bf16(float lo, float hi) { unsigned r; asm volatile("v_cvt_pk_bf16_f32 %0, %1, %2" : "=v"(r) : "v"(lo), "v"(hi)); return r; }
; #define LAS __attribute__((address_space(3)))
; __device__ __forceinline__ void p2_block(LAS unsigned char* lds, const bf16_t* __restrict__ PROJ, bf16_t* __restrict__ ATT, bf16_t* __restrict__ SGU, const float* __restrict__ qn, const float* __restrict__ kn, ...
;     ...
;         sm += __shfl_xor(sm, 1); sm += __shfl_xor(sm, 2);
;         const float mu = sm * (1.0f / 128.0f); float q = 0.f;
; #pragma unroll
;         for (int j = 0; j < 32; ++j) { v[j] -= mu; q += v[j] * v[j]; }
;         q += __shfl_xor(q, 1); q += __shfl_xor(q, 2);
;         const float rstd = rsqrtf(q * (1.0f / 128.0f) + pg8::EPS);
;         const float* gp = lng + gg * 128 + 32 * q4; const float* bp = lnb + gg * 128 + 32 * q4;
;         LAS unsigned char* dst = lds + (gi ? VN_OFF1 : VN_OFF0) + (32 * q4) * VN_STRIDE + sp_ * 2;
; #pragma unroll
;         for (int j = 0; j < 32; j += 2) { const unsigned pk = cvt_pk_bf16(v[j] * rstd * gp[j] + bp[j], v[j + 1] * rstd * gp[j + 1] + bp[j + 1]);
;             *(LAS unsigned short*)(dst + j * VN_STRIDE) = (unsigned short)(pk & 0xffffu); *(LAS unsigned short*)(dst + (j + 1) * VN_STRIDE) = (unsigned short)(pk >> 16); }
	v_add_f32_e32 v83, v83, v96
	s_nop 1
	v_mov_b32_dpp v96, v83 quad_perm:[2,3,0,1] row_mask:0xf bank_mask:0xf
	v_mul_u32_u24_e32 v0, 0x110, v165
	v_add3_u32 v0, 0, v0, v6
	global_load_dwordx4 v[6:9], v[138:139], off offset:304
	global_load_dwordx4 v[10:13], v[138:139], off offset:288
	global_load_dwordx4 v[14:17], v[138:139], off offset:272
	global_load_dwordx4 v[18:21], v[138:139], off offset:256
	s_ashr_i32 s43, s42, 31
	s_waitcnt lgkmcnt(0)
	v_add_f32_e32 v83, v83, v96
	v_mul_f32_e32 v96, 0x3c000000, v83
	v_fma_f32 v83, v76, v74, -v96
	v_fma_f32 v97, v75, v73, -v96
	v_mul_f32_e32 v106, v83, v83
	v_fmac_f32_e32 v106, v97, v97
	v_fma_f32 v77, v77, v72, -v96
	v_fmac_f32_e32 v106, v77, v77
	v_fma_f32 v76, v78, v71, -v96
	v_fmac_f32_e32 v106, v76, v76
	v_fma_f32 v75, v79, v70, -v96
	v_fmac_f32_e32 v106, v75, v75
	v_fma_f32 v74, v80, v69, -v96
	v_fmac_f32_e32 v106, v74, v74
	v_fma_f32 v73, v81, v68, -v96
	v_fmac_f32_e32 v106, v73, v73
	v_fma_f32 v72, v82, v67, -v96
	v_fmac_f32_e32 v106, v72, v72
	v_fma_f32 v71, v84, v66, -v96
	v_fmac_f32_e32 v106, v71, v71
	v_fma_f32 v70, v85, v65, -v96
	v_fmac_f32_e32 v106, v70, v70
	v_fma_f32 v69, v86, v64, -v96
	v_fmac_f32_e32 v106, v69, v69
	v_fma_f32 v68, v87, v63, -v96
	v_fmac_f32_e32 v106, v68, v68
	v_fma_f32 v67, v88, v62, -v96
	v_fmac_f32_e32 v106, v67, v67
	v_fma_f32 v66, v89, v61, -v96
	v_fmac_f32_e32 v106, v66, v66
	v_fma_f32 v65, v90, v60, -v96
	v_fmac_f32_e32 v106, v65, v65
	v_fma_f32 v64, v91, v59, -v96
	v_fmac_f32_e32 v106, v64, v64
	v_fma_f32 v63, v98, v58, -v96
	v_fmac_f32_e32 v106, v63, v63
	v_fma_f32 v62, v99, v57, -v96
	v_fmac_f32_e32 v106, v62, v62
	v_fma_f32 v61, v100, v56, -v96
	v_fmac_f32_e32 v106, v61, v61
	v_fma_f32 v60, v101, v55, -v96
	v_fmac_f32_e32 v106, v60, v60
	v_fma_f32 v59, v102, v49, -v96
	v_fmac_f32_e32 v106, v59, v59
	v_fma_f32 v58, v103, v48, -v96
	v_fmac_f32_e32 v106, v58, v58
	v_fma_f32 v57, v104, v45, -v96
	v_fmac_f32_e32 v106, v57, v57
	v_fma_f32 v56, v105, v44, -v96
	v_pk_fma_f32 v[44:45], v[36:37], v[42:43], v[96:97] op_sel_hi:[1,1,0] neg_lo:[0,0,1] neg_hi:[0,0,1]
	v_fmac_f32_e32 v106, v56, v56
	v_pk_mul_f32 v[36:37], v[44:45], v[44:45]
	v_pk_fma_f32 v[42:43], v[46:47], v[40:41], v[96:97] op_sel_hi:[1,1,0] neg_lo:[0,0,1] neg_hi:[0,0,1]
	v_add_f32_e32 v37, v37, v106
	v_add_f32_e32 v48, v36, v37
	v_pk_mul_f32 v[36:37], v[42:43], v[42:43]
	v_pk_fma_f32 v[40:41], v[92:93], v[38:39], v[96:97] op_sel_hi:[1,1,0] neg_lo:[0,0,1] neg_hi:[0,0,1]
	v_add_f32_e32 v37, v37, v48
	v_add_f32_e32 v46, v36, v37
	v_pk_mul_f32 v[36:37], v[40:41], v[40:41]
	v_pk_fma_f32 v[38:39], v[94:95], v[34:35], v[96:97] op_sel_hi:[1,1,0] neg_lo:[0,0,1] neg_hi:[0,0,1]
	v_add_f32_e32 v37, v37, v46
	v_add_f32_e32 v36, v36, v37
	v_pk_mul_f32 v[34:35], v[38:39], v[38:39]
	v_lshlrev_b32_e32 v105, 16, v3
	v_add_f32_e32 v35, v35, v36
	v_add_f32_e32 v34, v34, v35
	s_nop 1
	v_mov_b32_dpp v35, v34 quad_perm:[1,0,3,2] row_mask:0xf bank_mask:0xf
	v_lshl_add_u64 v[36:37], v[52:53], 0, s[4:5]
	v_and_b32_e32 v109, 0xffff0000, v3
	v_lshlrev_b32_e32 v113, 16, v2
	v_lshlrev_b32_e32 v112, 16, v30
	s_waitcnt lgkmcnt(0)
	v_add_f32_e32 v34, v34, v35
	s_nop 1
	v_mov_b32_dpp v35, v34 quad_perm:[2,3,0,1] row_mask:0xf bank_mask:0xf
	v_and_b32_e32 v3, 0xffff0000, v2
	v_and_b32_e32 v2, 0xffff0000, v30
	v_and_b32_e32 v96, 0xffff0000, v33
	s_waitcnt vmcnt(1)
	v_lshlrev_b32_e32 v53, 16, v14
	s_waitcnt lgkmcnt(0)
	v_add_f32_e32 v34, v34, v35
	v_fmamk_f32 v34, v34, 0x3c000000, v209
	v_cmp_gt_f32_e32 vcc, s82, v34
	v_mul_f32_e32 v35, 0x4b800000, v34
	v_and_b32_e32 v52, 0xffff0000, v14
	v_cndmask_b32_e32 v34, v34, v35, vcc
	v_rsq_f32_e32 v34, v34
	v_and_b32_e32 v14, 0xffff0000, v6
	v_lshlrev_b32_e32 v104, 16, v31
	v_and_b32_e32 v108, 0xffff0000, v31
	v_mul_f32_e32 v35, 0x45800000, v34
	v_cndmask_b32_e32 v55, v34, v35, vcc
	v_lshl_add_u64 v[34:35], v[50:51], 0, s[4:5]
	v_mov_b64_e32 v[46:47], v[144:145]
	v_mov_b64_e32 v[48:49], v[218:219]
	v_mul_f32_e32 v51, v97, v55
	v_add_u32_e32 v50, 0x11800, v0
	v_mul_f32_e32 v45, v45, v55
	v_mul_f32_e32 v44, v44, v55
	v_mul_f32_e32 v43, v43, v55
	v_mul_f32_e32 v42, v42, v55
	v_mul_f32_e32 v41, v41, v55
	v_mul_f32_e32 v40, v40, v55
	v_mul_f32_e32 v39, v39, v55
	v_mul_f32_e32 v38, v38, v55
	v_mov_b32_e32 v116, v112
	v_mov_b32_e32 v117, v2
	v_and_b32_e32 v97, 0xffff0000, v5
	v_mov_b32_e32 v110, v108
	v_mov_b32_e32 v111, v104
	v_mov_b32_e32 v30, v113
	v_mov_b32_e32 v31, v3
	v_pk_mul_f32 v[116:117], v[116:117], v[116:117]
	v_lshlrev_b32_e32 v101, 16, v4
	v_lshlrev_b32_e32 v100, 16, v32
	v_pk_mul_f32 v[110:111], v[110:111], v[110:111]
	v_pk_fma_f32 v[30:31], v[30:31], v[30:31], v[116:117]
	v_lshlrev_b32_e32 v130, 3, v162
	v_mov_b32_e32 v131, v1
	s_mov_b32 s4, s5
	s_mov_b32 s52, 0xf149f2ca
	s_waitcnt vmcnt(0)
	v_fma_f32 v46, v46, v51, v48
	v_mul_f32_e32 v48, v83, v55
	v_fmac_f32_e32 v49, v47, v48
	v_add_u32_e32 v47, 0x11910, v0
	v_cvt_pk_bf16_f32 v46, v46, v49
	ds_write_b16 v50, v46
	ds_write_b16_d16_hi v47, v46
	v_mov_b64_e32 v[46:47], v[146:147]
	v_mov_b64_e32 v[48:49], v[220:221]
	v_mul_f32_e32 v50, v77, v55
	v_lshlrev_b32_e32 v51, 16, v15
	s_waitcnt vmcnt(0)
	v_fma_f32 v46, v46, v50, v48
	v_mul_f32_e32 v48, v76, v55
	v_fmac_f32_e32 v49, v47, v48
	v_add_u32_e32 v47, 0x11a20, v0
	v_cvt_pk_bf16_f32 v46, v46, v49
	ds_write_b16 v47, v46
	v_add_u32_e32 v47, 0x11b30, v0
	ds_write_b16_d16_hi v47, v46
	v_mov_b64_e32 v[46:47], v[148:149]
	v_mov_b64_e32 v[48:49], v[222:223]
	v_mul_f32_e32 v50, v75, v55
	s_waitcnt vmcnt(0)
	v_fma_f32 v46, v46, v50, v48
	v_mul_f32_e32 v48, v74, v55
	v_fmac_f32_e32 v49, v47, v48
	v_add_u32_e32 v47, 0x11c40, v0
	v_cvt_pk_bf16_f32 v46, v46, v49
	ds_write_b16 v47, v46
	v_add_u32_e32 v47, 0x11d50, v0
	ds_write_b16_d16_hi v47, v46
	v_mov_b64_e32 v[46:47], v[150:151]
	v_mov_b64_e32 v[48:49], v[224:225]
	v_mul_f32_e32 v50, v73, v55
	s_waitcnt vmcnt(0)
; __device__ __forceinline__ unsigned cvt_pk_bf16(float lo, float hi) { unsigned r; asm volatile("v_cvt_pk_bf16_f32 %0, %1, %2" : "=v"(r) : "v"(lo), "v"(hi)); return r; }
; #define LAS __attribute__((address_space(3)))
; __device__ __forceinline__ void p2_block(LAS unsigned char* lds, const bf16_t* __restrict__ PROJ, bf16_t* __restrict__ ATT, bf16_t* __restrict__ SGU, const float* __restrict__ qn, const float* __restrict__ kn, ...
;     ...
;         const float* gp = lng + gg * 128 + 32 * q4; const float* bp = lnb + gg * 128 + 32 * q4;
;         LAS unsigned char* dst = lds + (gi ? VN_OFF1 : VN_OFF0) + (32 * q4) * VN_STRIDE + sp_ * 2;
; #pragma unroll
;         for (int j = 0; j < 32; j += 2) { const unsigned pk = cvt_pk_bf16(v[j] * rstd * gp[j] + bp[j], v[j + 1] * rstd * gp[j + 1] + bp[j + 1]);
;             *(LAS unsigned short*)(dst + j * VN_STRIDE) = (unsigned short)(pk & 0xffffu); *(LAS unsigned short*)(dst + (j + 1) * VN_STRIDE) = (unsigned short)(pk >> 16); }
	v_fma_f32 v46, v46, v50, v48
	v_mul_f32_e32 v48, v72, v55
	v_fmac_f32_e32 v49, v47, v48
	v_add_u32_e32 v47, 0x11e60, v0
	v_cvt_pk_bf16_f32 v46, v46, v49
	ds_write_b16 v47, v46
	v_add_u32_e32 v47, 0x11f70, v0
	ds_write_b16_d16_hi v47, v46
	v_mov_b64_e32 v[46:47], v[152:153]
	v_mov_b64_e32 v[48:49], v[226:227]
	v_mul_f32_e32 v50, v71, v55
	s_waitcnt vmcnt(0)
	v_fma_f32 v46, v46, v50, v48
	v_mul_f32_e32 v48, v70, v55
	v_fmac_f32_e32 v49, v47, v48
	v_add_u32_e32 v47, 0x12080, v0
	v_cvt_pk_bf16_f32 v46, v46, v49
	ds_write_b16 v47, v46
	v_add_u32_e32 v47, 0x12190, v0
	ds_write_b16_d16_hi v47, v46
	v_mov_b64_e32 v[46:47], v[154:155]
	v_mov_b64_e32 v[48:49], v[228:229]
	v_mul_f32_e32 v50, v69, v55
	s_waitcnt vmcnt(0)
	v_fma_f32 v46, v46, v50, v48
	v_mul_f32_e32 v48, v68, v55
	v_fmac_f32_e32 v49, v47, v48
	v_add_u32_e32 v47, 0x122a0, v0
	v_cvt_pk_bf16_f32 v46, v46, v49
	ds_write_b16 v47, v46
	v_add_u32_e32 v47, 0x123b0, v0
	ds_write_b16_d16_hi v47, v46
	v_mov_b64_e32 v[46:47], v[156:157]
	v_mov_b64_e32 v[48:49], v[230:231]
	v_mul_f32_e32 v50, v67, v55
	s_waitcnt vmcnt(0)
	v_fma_f32 v46, v46, v50, v48
	v_mul_f32_e32 v48, v66, v55
	v_fmac_f32_e32 v49, v48, v47
	v_add_u32_e32 v47, 0x124c0, v0
	v_cvt_pk_bf16_f32 v46, v46, v49
	ds_write_b16 v47, v46
	v_add_u32_e32 v47, 0x125d0, v0
	ds_write_b16_d16_hi v47, v46
	v_mov_b64_e32 v[46:47], v[158:159]
	v_mov_b64_e32 v[48:49], v[232:233]
	v_mul_f32_e32 v50, v65, v55
	s_waitcnt vmcnt(0)
	v_fma_f32 v46, v50, v46, v48
	v_mul_f32_e32 v48, v64, v55
	v_fmac_f32_e32 v49, v48, v47
	v_add_u32_e32 v47, 0x126e0, v0
	v_cvt_pk_bf16_f32 v46, v46, v49
	ds_write_b16 v47, v46
	v_add_u32_e32 v47, 0x127f0, v0
	ds_write_b16_d16_hi v47, v46
	v_mov_b64_e32 v[46:47], v[184:185]
	v_mov_b64_e32 v[48:49], v[234:235]
	v_mul_f32_e32 v50, v63, v55
	s_waitcnt vmcnt(0)
	v_fma_f32 v46, v50, v46, v48
	v_mul_f32_e32 v48, v62, v55
	v_fmac_f32_e32 v49, v48, v47
	v_add_u32_e32 v47, 0x12900, v0
	v_cvt_pk_bf16_f32 v46, v46, v49
	ds_write_b16 v47, v46
	v_add_u32_e32 v47, 0x12a10, v0
	ds_write_b16_d16_hi v47, v46
	v_mov_b64_e32 v[46:47], v[186:187]
	v_mov_b64_e32 v[48:49], v[236:237]
	v_mul_f32_e32 v50, v61, v55
	v_lshlrev_b32_e32 v61, 16, v18
	v_and_b32_e32 v62, 0xffff0000, v18
	s_waitcnt vmcnt(0)
	v_fma_f32 v46, v50, v46, v48
	v_mul_f32_e32 v48, v60, v55
	v_fmac_f32_e32 v49, v48, v47
	v_add_u32_e32 v47, 0x12b20, v0
	v_cvt_pk_bf16_f32 v46, v46, v49
	ds_write_b16 v47, v46
	v_add_u32_e32 v47, 0x12c30, v0
	ds_write_b16_d16_hi v47, v46
	v_mov_b64_e32 v[46:47], v[188:189]
	v_mov_b64_e32 v[48:49], v[238:239]
	v_mul_f32_e32 v50, v59, v55
	v_lshlrev_b32_e32 v60, 16, v19
	v_and_b32_e32 v59, 0xffff0000, v19
	s_waitcnt vmcnt(0)
	v_fma_f32 v46, v50, v46, v48
	v_mul_f32_e32 v48, v58, v55
	v_fmac_f32_e32 v49, v48, v47
	v_add_u32_e32 v47, 0x12d40, v0
	v_cvt_pk_bf16_f32 v46, v46, v49
	ds_write_b16 v47, v46
	v_add_u32_e32 v47, 0x12e50, v0
	ds_write_b16_d16_hi v47, v46
	v_mov_b64_e32 v[46:47], v[190:191]
	v_mov_b64_e32 v[48:49], v[240:241]
	v_mul_f32_e32 v50, v57, v55
	v_lshlrev_b32_e32 v58, 16, v20
	v_and_b32_e32 v57, 0xffff0000, v20
	s_waitcnt vmcnt(0)
	v_fma_f32 v46, v50, v46, v48
	v_mul_f32_e32 v48, v56, v55
	v_fmac_f32_e32 v49, v48, v47
	v_add_u32_e32 v47, 0x12f60, v0
	v_cvt_pk_bf16_f32 v46, v46, v49
	ds_write_b16 v47, v46
	v_add_u32_e32 v47, 0x13070, v0
	ds_write_b16_d16_hi v47, v46
	v_mov_b64_e32 v[46:47], v[192:193]
	v_mov_b64_e32 v[48:49], v[242:243]
	v_and_b32_e32 v50, 0xffff0000, v15
	v_lshlrev_b32_e32 v15, 16, v6
	v_and_b32_e32 v6, 0xffff0000, v9
	v_lshlrev_b32_e32 v56, 16, v21
	v_and_b32_e32 v55, 0xffff0000, v21
	v_mul_f32_e32 v88, 0x3d372713, v6
	v_fma_f32 v88, v88, v6, 1.0
	s_waitcnt vmcnt(0)
	v_fma_f32 v45, v45, v46, v48
	v_fmac_f32_e32 v49, v44, v47
	v_cvt_pk_bf16_f32 v44, v45, v49
	v_add_u32_e32 v45, 0x13180, v0
	ds_write_b16 v45, v44
	v_add_u32_e32 v45, 0x13290, v0
	ds_write_b16_d16_hi v45, v44
	v_mov_b64_e32 v[44:45], v[194:195]
	v_mov_b64_e32 v[46:47], v[244:245]
	v_lshlrev_b32_e32 v49, 16, v16
	v_and_b32_e32 v48, 0xffff0000, v16
	s_waitcnt vmcnt(0)
	v_fma_f32 v43, v43, v44, v46
	v_fmac_f32_e32 v47, v42, v45
	v_cvt_pk_bf16_f32 v42, v43, v47
	v_add_u32_e32 v43, 0x133a0, v0
	ds_write_b16 v43, v42
	v_add_u32_e32 v43, 0x134b0, v0
	ds_write_b16_d16_hi v43, v42
	v_mov_b64_e32 v[42:43], v[196:197]
	v_mov_b64_e32 v[44:45], v[200:201]
	v_lshlrev_b32_e32 v47, 16, v17
	v_and_b32_e32 v46, 0xffff0000, v17
	v_mul_f32_e32 v17, 0x3d372713, v14
	v_fma_f32 v17, v17, v14, 1.0
	s_waitcnt vmcnt(0)
	v_fma_f32 v41, v41, v42, v44
	v_fmac_f32_e32 v45, v40, v43
	v_cvt_pk_bf16_f32 v40, v41, v45
	v_add_u32_e32 v41, 0x135c0, v0
	ds_write_b16 v41, v40
	v_add_u32_e32 v41, 0x136d0, v0
	ds_write_b16_d16_hi v41, v40
	v_mov_b64_e32 v[40:41], v[198:199]
	v_mov_b64_e32 v[42:43], v[202:203]
	v_lshlrev_b32_e32 v45, 16, v10
	v_and_b32_e32 v44, 0xffff0000, v10
	v_and_b32_e32 v10, 0xffff0000, v8
	s_waitcnt vmcnt(0)
; __device__ __forceinline__ unsigned cvt_pk_bf16(float lo, float hi) { unsigned r; asm volatile("v_cvt_pk_bf16_f32 %0, %1, %2" : "=v"(r) : "v"(lo), "v"(hi)); return r; }
; __device__ __forceinline__ float gelu_f(float x) { const float y2 = 1.5957691216057308f * x * (1.0f + 0.044715f * x * x); return x * sigmoid_f(y2); }
; #define LAS __attribute__((address_space(3)))
; __device__ __forceinline__ void unpack8(const u32x4 w, float* f) { f[0] = bf_lo(w.x); f[1] = bf_hi(w.x); f[2] = bf_lo(w.y); f[3] = bf_hi(w.y); f[4] = bf_lo(w.z); f[5] = bf_hi(w.z); f[6] = bf_lo(w.w); f[7] = bf_hi(w.w); }
; __device__ __forceinline__ void p2_block(LAS unsigned char* lds, const bf16_t* __restrict__ PROJ, bf16_t* __restrict__ ATT, bf16_t* __restrict__ SGU, const float* __restrict__ qn, const float* __restrict__ kn, ...
;     ...
;             for (int c4 = 0; c4 < 4; ++c4) sv[1][c4] = *(const u32x4*)(svsrc + 128 + 8 * c4); }
;         float v[32];
; #pragma unroll
;         for (int c4 = 0; c4 < 4; ++c4) unpack8(sv[gi][c4], v + 8 * c4);
;         float sm = 0.f;
; #pragma unroll
;         for (int j = 0; j < 32; ++j) { v[j] = gelu_f(v[j]); sm += v[j]; }
;         sm += __shfl_xor(sm, 1); sm += __shfl_xor(sm, 2);
;         const float mu = sm * (1.0f / 128.0f); float q = 0.f;
; #pragma unroll
;         for (int j = 0; j < 32; ++j) { v[j] -= mu; q += v[j] * v[j]; }
;         q += __shfl_xor(q, 1); q += __shfl_xor(q, 2);
;         const float rstd = rsqrtf(q * (1.0f / 128.0f) + pg8::EPS);
;         const float* gp = lng + gg * 128 + 32 * q4; const float* bp = lnb + gg * 128 + 32 * q4;
;         LAS unsigned char* dst = lds + (gi ? VN_OFF1 : VN_OFF0) + (32 * q4) * VN_STRIDE + sp_ * 2;
; #pragma unroll
;         for (int j = 0; j < 32; j += 2) { const unsigned pk = cvt_pk_bf16(v[j] * rstd * gp[j] + bp[j], v[j + 1] * rstd * gp[j + 1] + bp[j + 1]);
;             *(LAS unsigned short*)(dst + j * VN_STRIDE) = (unsigned short)(pk & 0xffffu); *(LAS unsigned short*)(dst + (j + 1) * VN_STRIDE) = (unsigned short)(pk >> 16); }
	global_load_dwordx4 v[144:147], v182, s[36:37] offset:512
	global_load_dwordx4 v[148:151], v182, s[36:37] offset:528
	global_load_dwordx4 v[152:155], v182, s[36:37] offset:544
	global_load_dwordx4 v[156:159], v182, s[36:37] offset:560
	global_load_dwordx4 v[184:187], v182, s[36:37] offset:576
	global_load_dwordx4 v[188:191], v182, s[36:37] offset:592
	global_load_dwordx4 v[192:195], v182, s[36:37] offset:608
	global_load_dwordx4 v[196:199], v182, s[36:37] offset:624
	global_load_dwordx4 v[218:221], v182, s[18:19] offset:512
	global_load_dwordx4 v[222:225], v182, s[18:19] offset:528
	global_load_dwordx4 v[226:229], v182, s[18:19] offset:544
	global_load_dwordx4 v[230:233], v182, s[18:19] offset:560
	global_load_dwordx4 v[234:237], v182, s[18:19] offset:576
	global_load_dwordx4 v[238:241], v182, s[18:19] offset:592
	global_load_dwordx4 v[242:245], v182, s[18:19] offset:608
	global_load_dwordx4 v[200:203], v182, s[18:19] offset:624
	v_fma_f32 v39, v39, v40, v42
	v_fmac_f32_e32 v43, v38, v41
	v_cvt_pk_bf16_f32 v38, v39, v43
	v_add_u32_e32 v39, 0x137e0, v0
	ds_write_b16 v39, v38
	v_add_u32_e32 v39, 0x138f0, v0
	ds_write_b16_d16_hi v39, v38
	v_lshlrev_b32_e32 v41, 16, v12
	v_and_b32_e32 v40, 0xffff0000, v12
	v_lshlrev_b32_e32 v39, 16, v13
	v_and_b32_e32 v38, 0xffff0000, v13
	v_lshlrev_b32_e32 v13, 16, v7
	v_and_b32_e32 v12, 0xffff0000, v7
	v_lshlrev_b32_e32 v7, 16, v9
	v_mul_f32_e32 v9, 0x3d372713, v61
	v_lshlrev_b32_e32 v43, 16, v11
	v_and_b32_e32 v42, 0xffff0000, v11
	v_lshlrev_b32_e32 v11, 16, v8
	v_mul_f32_e32 v8, 0x3fcc422a, v61
	v_fma_f32 v9, v9, v61, 1.0
	v_mul_f32_e32 v8, v8, v9
	v_mul_f32_e32 v8, 0xbfb8aa3b, v8
	v_exp_f32_e32 v8, v8
	v_mul_f32_e32 v9, 0x3d372713, v62
	v_fma_f32 v9, v9, v62, 1.0
	v_add_f32_e32 v8, 1.0, v8
	v_rcp_f32_e32 v63, v8
	v_mul_f32_e32 v8, 0x3fcc422a, v62
	v_mul_f32_e32 v8, v8, v9
	v_mul_f32_e32 v8, 0xbfb8aa3b, v8
	v_exp_f32_e32 v8, v8
	v_mul_f32_e32 v9, 0x3d372713, v60
	v_fma_f32 v9, v9, v60, 1.0
	v_fma_f32 v16, v63, v61, 0
	v_add_f32_e32 v8, 1.0, v8
	v_rcp_f32_e32 v64, v8
	v_mul_f32_e32 v8, 0x3fcc422a, v60
	v_mul_f32_e32 v8, v8, v9
	v_mul_f32_e32 v8, 0xbfb8aa3b, v8
	v_exp_f32_e32 v8, v8
	v_mul_f32_e32 v9, 0x3d372713, v59
	v_fma_f32 v9, v9, v59, 1.0
	v_fmac_f32_e32 v16, v64, v62
	v_add_f32_e32 v8, 1.0, v8
	v_rcp_f32_e32 v65, v8
	v_mul_f32_e32 v8, 0x3fcc422a, v59
	v_mul_f32_e32 v8, v8, v9
	v_mul_f32_e32 v8, 0xbfb8aa3b, v8
	v_exp_f32_e32 v8, v8
	v_mul_f32_e32 v9, 0x3d372713, v58
	v_fma_f32 v9, v9, v58, 1.0
	v_fmac_f32_e32 v16, v65, v60
	v_add_f32_e32 v8, 1.0, v8
	v_rcp_f32_e32 v66, v8
	v_mul_f32_e32 v8, 0x3fcc422a, v58
	v_mul_f32_e32 v8, v8, v9
	v_mul_f32_e32 v8, 0xbfb8aa3b, v8
	v_exp_f32_e32 v8, v8
	v_mul_f32_e32 v9, 0x3d372713, v57
	v_fma_f32 v9, v9, v57, 1.0
	v_fmac_f32_e32 v16, v66, v59
	v_add_f32_e32 v8, 1.0, v8
	v_rcp_f32_e32 v67, v8
	v_mul_f32_e32 v8, 0x3fcc422a, v57
	v_mul_f32_e32 v8, v8, v9
	v_mul_f32_e32 v8, 0xbfb8aa3b, v8
	v_exp_f32_e32 v8, v8
	v_mul_f32_e32 v9, 0x3d372713, v56
	v_fma_f32 v9, v9, v56, 1.0
	v_fmac_f32_e32 v16, v67, v58
	v_add_f32_e32 v8, 1.0, v8
	v_rcp_f32_e32 v68, v8
	v_mul_f32_e32 v8, 0x3fcc422a, v56
	v_mul_f32_e32 v8, v8, v9
	v_mul_f32_e32 v8, 0xbfb8aa3b, v8
	v_exp_f32_e32 v8, v8
	v_mul_f32_e32 v9, 0x3d372713, v55
	v_fma_f32 v9, v9, v55, 1.0
	v_fmac_f32_e32 v16, v68, v57
	v_add_f32_e32 v8, 1.0, v8
	v_rcp_f32_e32 v69, v8
	v_mul_f32_e32 v8, 0x3fcc422a, v55
	v_mul_f32_e32 v8, v8, v9
	v_mul_f32_e32 v8, 0xbfb8aa3b, v8
	v_exp_f32_e32 v8, v8
	v_mul_f32_e32 v9, 0x3d372713, v53
	v_fma_f32 v9, v9, v53, 1.0
	v_fmac_f32_e32 v16, v69, v56
	v_add_f32_e32 v8, 1.0, v8
	v_rcp_f32_e32 v70, v8
	v_mul_f32_e32 v8, 0x3fcc422a, v53
	v_mul_f32_e32 v8, v8, v9
	v_mul_f32_e32 v8, 0xbfb8aa3b, v8
	v_exp_f32_e32 v8, v8
	v_mul_f32_e32 v9, 0x3d372713, v52
	v_fma_f32 v9, v9, v52, 1.0
	v_fmac_f32_e32 v16, v70, v55
	v_add_f32_e32 v8, 1.0, v8
	v_rcp_f32_e32 v71, v8
	v_mul_f32_e32 v8, 0x3fcc422a, v52
	v_mul_f32_e32 v8, v8, v9
	v_mul_f32_e32 v8, 0xbfb8aa3b, v8
	v_exp_f32_e32 v8, v8
	v_mul_f32_e32 v9, 0x3d372713, v51
	v_fma_f32 v9, v9, v51, 1.0
	v_fmac_f32_e32 v16, v71, v53
	v_add_f32_e32 v8, 1.0, v8
	v_rcp_f32_e32 v72, v8
	v_mul_f32_e32 v8, 0x3fcc422a, v51
	v_mul_f32_e32 v8, v8, v9
	v_mul_f32_e32 v8, 0xbfb8aa3b, v8
	v_exp_f32_e32 v8, v8
	v_mul_f32_e32 v9, 0x3d372713, v50
	v_fma_f32 v9, v9, v50, 1.0
	v_fmac_f32_e32 v16, v72, v52
	v_add_f32_e32 v8, 1.0, v8
	v_rcp_f32_e32 v73, v8
	v_mul_f32_e32 v8, 0x3fcc422a, v50
	v_mul_f32_e32 v8, v8, v9
	v_mul_f32_e32 v8, 0xbfb8aa3b, v8
	v_exp_f32_e32 v8, v8
	v_mul_f32_e32 v9, 0x3d372713, v49
	v_fma_f32 v9, v9, v49, 1.0
	v_fmac_f32_e32 v16, v73, v51
	v_add_f32_e32 v8, 1.0, v8
	v_rcp_f32_e32 v74, v8
	v_mul_f32_e32 v8, 0x3fcc422a, v49
	v_mul_f32_e32 v8, v8, v9
	v_mul_f32_e32 v8, 0xbfb8aa3b, v8
	v_exp_f32_e32 v8, v8
	v_mul_f32_e32 v9, 0x3d372713, v48
	v_fma_f32 v9, v9, v48, 1.0
	v_fmac_f32_e32 v16, v74, v50
	v_add_f32_e32 v8, 1.0, v8
	v_rcp_f32_e32 v75, v8
	v_mul_f32_e32 v8, 0x3fcc422a, v48
	v_mul_f32_e32 v8, v8, v9
	v_mul_f32_e32 v8, 0xbfb8aa3b, v8
	v_exp_f32_e32 v8, v8
	v_mul_f32_e32 v9, 0x3d372713, v47
	v_fma_f32 v9, v9, v47, 1.0
	v_fmac_f32_e32 v16, v75, v49
	v_add_f32_e32 v8, 1.0, v8
	v_rcp_f32_e32 v76, v8
	v_mul_f32_e32 v8, 0x3fcc422a, v47
	v_mul_f32_e32 v8, v8, v9
	v_mul_f32_e32 v8, 0xbfb8aa3b, v8
	v_exp_f32_e32 v8, v8
	v_mul_f32_e32 v9, 0x3d372713, v46
	v_fma_f32 v9, v9, v46, 1.0
	v_fmac_f32_e32 v16, v76, v48
	v_add_f32_e32 v8, 1.0, v8
	v_rcp_f32_e32 v77, v8
	v_mul_f32_e32 v8, 0x3fcc422a, v46
	v_mul_f32_e32 v8, v8, v9
	v_mul_f32_e32 v8, 0xbfb8aa3b, v8
	v_exp_f32_e32 v8, v8
	v_mul_f32_e32 v9, 0x3d372713, v45
	v_fma_f32 v9, v9, v45, 1.0
	v_fmac_f32_e32 v16, v77, v47
	v_add_f32_e32 v8, 1.0, v8
; __device__ __forceinline__ float gelu_f(float x) { const float y2 = 1.5957691216057308f * x * (1.0f + 0.044715f * x * x); return x * sigmoid_f(y2); }
; __device__ __forceinline__ void p2_block(LAS unsigned char* lds, const bf16_t* __restrict__ PROJ, bf16_t* __restrict__ ATT, bf16_t* __restrict__ SGU, const float* __restrict__ qn, const float* __restrict__ kn, ...
;     ...
;         for (int j = 0; j < 32; ++j) { v[j] = gelu_f(v[j]); sm += v[j]; }
;         sm += __shfl_xor(sm, 1); sm += __shfl_xor(sm, 2);
	v_rcp_f32_e32 v78, v8
	v_mul_f32_e32 v8, 0x3fcc422a, v45
	v_mul_f32_e32 v8, v8, v9
	v_mul_f32_e32 v8, 0xbfb8aa3b, v8
	v_exp_f32_e32 v8, v8
	v_mul_f32_e32 v9, 0x3d372713, v44
	v_fma_f32 v9, v9, v44, 1.0
	v_fmac_f32_e32 v16, v78, v46
	v_add_f32_e32 v8, 1.0, v8
	v_rcp_f32_e32 v79, v8
	v_mul_f32_e32 v8, 0x3fcc422a, v44
	v_mul_f32_e32 v8, v8, v9
	v_mul_f32_e32 v8, 0xbfb8aa3b, v8
	v_exp_f32_e32 v8, v8
	v_mul_f32_e32 v9, 0x3d372713, v43
	v_fma_f32 v9, v9, v43, 1.0
	v_fmac_f32_e32 v16, v79, v45
	v_add_f32_e32 v8, 1.0, v8
	v_rcp_f32_e32 v80, v8
	v_mul_f32_e32 v8, 0x3fcc422a, v43
	v_mul_f32_e32 v8, v8, v9
	v_mul_f32_e32 v8, 0xbfb8aa3b, v8
	v_exp_f32_e32 v8, v8
	v_mul_f32_e32 v9, 0x3d372713, v42
	v_fma_f32 v9, v9, v42, 1.0
	v_fmac_f32_e32 v16, v80, v44
	v_add_f32_e32 v8, 1.0, v8
	v_rcp_f32_e32 v81, v8
	v_mul_f32_e32 v8, 0x3fcc422a, v42
	v_mul_f32_e32 v8, v8, v9
	v_mul_f32_e32 v8, 0xbfb8aa3b, v8
	v_exp_f32_e32 v8, v8
	v_mul_f32_e32 v9, 0x3d372713, v41
	v_fma_f32 v9, v9, v41, 1.0
	v_fmac_f32_e32 v16, v81, v43
	v_add_f32_e32 v8, 1.0, v8
	v_rcp_f32_e32 v82, v8
	v_mul_f32_e32 v8, 0x3fcc422a, v41
	v_mul_f32_e32 v8, v8, v9
	v_mul_f32_e32 v8, 0xbfb8aa3b, v8
	v_exp_f32_e32 v8, v8
	v_mul_f32_e32 v9, 0x3d372713, v40
	v_fma_f32 v9, v9, v40, 1.0
	v_fmac_f32_e32 v16, v82, v42
	v_add_f32_e32 v8, 1.0, v8
	v_rcp_f32_e32 v83, v8
	v_mul_f32_e32 v8, 0x3fcc422a, v40
	v_mul_f32_e32 v8, v8, v9
	v_mul_f32_e32 v8, 0xbfb8aa3b, v8
	v_exp_f32_e32 v8, v8
	v_mul_f32_e32 v9, 0x3d372713, v39
	v_fma_f32 v9, v9, v39, 1.0
	v_fmac_f32_e32 v16, v83, v41
	v_add_f32_e32 v8, 1.0, v8
	v_rcp_f32_e32 v84, v8
	v_mul_f32_e32 v8, 0x3fcc422a, v39
	v_mul_f32_e32 v8, v8, v9
	v_mul_f32_e32 v8, 0xbfb8aa3b, v8
	v_exp_f32_e32 v8, v8
	v_mul_f32_e32 v9, 0x3d372713, v38
	v_fma_f32 v9, v9, v38, 1.0
	v_fmac_f32_e32 v16, v84, v40
	v_add_f32_e32 v8, 1.0, v8
	v_rcp_f32_e32 v85, v8
	v_mul_f32_e32 v8, 0x3fcc422a, v38
	v_mul_f32_e32 v8, v8, v9
	v_mul_f32_e32 v8, 0xbfb8aa3b, v8
	v_exp_f32_e32 v8, v8
	v_mul_f32_e32 v9, 0x3d372713, v15
	v_fma_f32 v9, v9, v15, 1.0
	v_fmac_f32_e32 v16, v85, v39
	v_add_f32_e32 v8, 1.0, v8
	v_rcp_f32_e32 v86, v8
	v_mul_f32_e32 v8, 0x3fcc422a, v15
	v_mul_f32_e32 v8, v8, v9
	v_mul_f32_e32 v8, 0xbfb8aa3b, v8
	v_exp_f32_e32 v8, v8
	v_fmac_f32_e32 v16, v86, v38
	v_add_f32_e32 v8, 1.0, v8
	v_rcp_f32_e32 v9, v8
	v_mul_f32_e32 v8, 0x3fcc422a, v14
	v_mul_f32_e32 v8, v8, v17
	v_mul_f32_e32 v8, 0xbfb8aa3b, v8
	v_exp_f32_e32 v8, v8
	v_mul_f32_e32 v17, 0x3d372713, v13
	v_fma_f32 v17, v17, v13, 1.0
	v_add_f32_e32 v8, 1.0, v8
	v_rcp_f32_e32 v8, v8
	s_nop 0
	v_pk_mul_f32 v[18:19], v[8:9], v[14:15]
	s_nop 0
	v_add_f32_e32 v16, v19, v16
	v_add_f32_e32 v20, v18, v16
	v_mul_f32_e32 v16, 0x3fcc422a, v13
	v_mul_f32_e32 v16, v16, v17
	v_mul_f32_e32 v16, 0xbfb8aa3b, v16
	v_exp_f32_e32 v16, v16
	v_mul_f32_e32 v18, 0x3d372713, v12
	v_fma_f32 v18, v18, v12, 1.0
	v_add_f32_e32 v16, 1.0, v16
	v_rcp_f32_e32 v17, v16
	v_mul_f32_e32 v16, 0x3fcc422a, v12
	v_mul_f32_e32 v16, v16, v18
	v_mul_f32_e32 v16, 0xbfb8aa3b, v16
	v_exp_f32_e32 v16, v16
	s_nop 0
	v_add_f32_e32 v16, 1.0, v16
	v_rcp_f32_e32 v16, v16
	s_nop 0
	v_pk_mul_f32 v[18:19], v[16:17], v[12:13]
	s_nop 0
	v_add_f32_e32 v19, v19, v20
	v_add_f32_e32 v87, v18, v19
	v_mul_f32_e32 v19, 0x3d372713, v11
	v_mul_f32_e32 v18, 0x3fcc422a, v11
	v_fma_f32 v19, v19, v11, 1.0
	v_mul_f32_e32 v18, v18, v19
	v_mul_f32_e32 v18, 0xbfb8aa3b, v18
	v_exp_f32_e32 v18, v18
	v_mul_f32_e32 v20, 0x3d372713, v10
	v_fma_f32 v20, v20, v10, 1.0
	v_add_f32_e32 v18, 1.0, v18
	v_rcp_f32_e32 v19, v18
	v_mul_f32_e32 v18, 0x3fcc422a, v10
	v_mul_f32_e32 v18, v18, v20
	v_mul_f32_e32 v18, 0xbfb8aa3b, v18
	v_exp_f32_e32 v18, v18
	s_nop 0
	v_add_f32_e32 v18, 1.0, v18
	v_rcp_f32_e32 v18, v18
	s_nop 0
	v_pk_mul_f32 v[20:21], v[18:19], v[10:11]
	s_nop 0
	v_add_f32_e32 v21, v21, v87
	v_add_f32_e32 v87, v20, v21
	v_mul_f32_e32 v21, 0x3d372713, v7
	v_mul_f32_e32 v20, 0x3fcc422a, v7
	v_fma_f32 v21, v21, v7, 1.0
	v_mul_f32_e32 v20, v20, v21
	v_mul_f32_e32 v20, 0xbfb8aa3b, v20
	v_exp_f32_e32 v20, v20
	s_nop 0
	v_add_f32_e32 v20, 1.0, v20
	v_rcp_f32_e32 v21, v20
	v_mul_f32_e32 v20, 0x3fcc422a, v6
	v_mul_f32_e32 v20, v20, v88
	v_mul_f32_e32 v20, 0xbfb8aa3b, v20
	v_exp_f32_e32 v20, v20
	s_nop 0
	v_add_f32_e32 v20, 1.0, v20
	v_rcp_f32_e32 v20, v20
	s_nop 0
	v_pk_mul_f32 v[88:89], v[20:21], v[6:7]
	s_nop 0
	v_add_f32_e32 v87, v89, v87
	v_add_f32_e32 v87, v88, v87
	s_nop 1
	v_mov_b32_dpp v88, v87 quad_perm:[1,0,3,2] row_mask:0xf bank_mask:0xf
	s_waitcnt lgkmcnt(0)
	v_add_f32_e32 v87, v87, v88
	s_nop 1
	v_mov_b32_dpp v88, v87 quad_perm:[2,3,0,1] row_mask:0xf bank_mask:0xf
	s_waitcnt lgkmcnt(0)
; __device__ __forceinline__ unsigned cvt_pk_bf16(float lo, float hi) { unsigned r; asm volatile("v_cvt_pk_bf16_f32 %0, %1, %2" : "=v"(r) : "v"(lo), "v"(hi)); return r; }
; #define LAS __attribute__((address_space(3)))
; __device__ __forceinline__ void p2_block(LAS unsigned char* lds, const bf16_t* __restrict__ PROJ, bf16_t* __restrict__ ATT, bf16_t* __restrict__ SGU, const float* __restrict__ qn, const float* __restrict__ kn, ...
;     ...
;         const float mu = sm * (1.0f / 128.0f); float q = 0.f;
; #pragma unroll
;         for (int j = 0; j < 32; ++j) { v[j] -= mu; q += v[j] * v[j]; }
;         q += __shfl_xor(q, 1); q += __shfl_xor(q, 2);
;         const float rstd = rsqrtf(q * (1.0f / 128.0f) + pg8::EPS);
;         const float* gp = lng + gg * 128 + 32 * q4; const float* bp = lnb + gg * 128 + 32 * q4;
;         LAS unsigned char* dst = lds + (gi ? VN_OFF1 : VN_OFF0) + (32 * q4) * VN_STRIDE + sp_ * 2;
; #pragma unroll
;         for (int j = 0; j < 32; j += 2) { const unsigned pk = cvt_pk_bf16(v[j] * rstd * gp[j] + bp[j], v[j + 1] * rstd * gp[j + 1] + bp[j + 1]);
;             *(LAS unsigned short*)(dst + j * VN_STRIDE) = (unsigned short)(pk & 0xffffu); *(LAS unsigned short*)(dst + (j + 1) * VN_STRIDE) = (unsigned short)(pk >> 16); }
	v_add_f32_e32 v87, v87, v88
	v_mul_f32_e32 v88, 0x3c000000, v87
	v_fma_f32 v63, v63, v61, -v88
	v_fma_f32 v61, v64, v62, -v88
	v_mul_f32_e32 v62, v61, v61
	v_fmac_f32_e32 v62, v63, v63
	v_fma_f32 v60, v65, v60, -v88
	v_fmac_f32_e32 v62, v60, v60
	v_fma_f32 v59, v66, v59, -v88
	v_fmac_f32_e32 v62, v59, v59
	v_fma_f32 v58, v67, v58, -v88
	v_fmac_f32_e32 v62, v58, v58
	v_fma_f32 v57, v68, v57, -v88
	v_fmac_f32_e32 v62, v57, v57
	v_fma_f32 v56, v69, v56, -v88
	v_fmac_f32_e32 v62, v56, v56
	v_fma_f32 v55, v70, v55, -v88
	v_fmac_f32_e32 v62, v55, v55
	v_fma_f32 v53, v71, v53, -v88
	v_fmac_f32_e32 v62, v53, v53
	v_fma_f32 v52, v72, v52, -v88
	v_fmac_f32_e32 v62, v52, v52
	v_fma_f32 v51, v73, v51, -v88
	v_fmac_f32_e32 v62, v51, v51
	v_fma_f32 v50, v74, v50, -v88
	v_fmac_f32_e32 v62, v50, v50
	v_fma_f32 v49, v75, v49, -v88
	v_fmac_f32_e32 v62, v49, v49
	v_fma_f32 v48, v76, v48, -v88
	v_fmac_f32_e32 v62, v48, v48
	v_fma_f32 v47, v77, v47, -v88
	v_fmac_f32_e32 v62, v47, v47
	v_fma_f32 v46, v78, v46, -v88
	v_fmac_f32_e32 v62, v46, v46
	v_fma_f32 v45, v79, v45, -v88
	v_fmac_f32_e32 v62, v45, v45
	v_fma_f32 v44, v80, v44, -v88
	v_fmac_f32_e32 v62, v44, v44
	v_fma_f32 v43, v81, v43, -v88
	v_fmac_f32_e32 v62, v43, v43
	v_fma_f32 v42, v82, v42, -v88
	v_fmac_f32_e32 v62, v42, v42
	v_fma_f32 v41, v83, v41, -v88
	v_fmac_f32_e32 v62, v41, v41
	v_fma_f32 v40, v84, v40, -v88
	v_fmac_f32_e32 v62, v40, v40
	v_fma_f32 v39, v85, v39, -v88
	v_fmac_f32_e32 v62, v39, v39
	v_fma_f32 v38, v86, v38, -v88
	v_pk_fma_f32 v[14:15], v[8:9], v[14:15], v[88:89] op_sel_hi:[1,1,0] neg_lo:[0,0,1] neg_hi:[0,0,1]
	v_fmac_f32_e32 v62, v38, v38
	v_pk_mul_f32 v[8:9], v[14:15], v[14:15]
	v_pk_fma_f32 v[12:13], v[16:17], v[12:13], v[88:89] op_sel_hi:[1,1,0] neg_lo:[0,0,1] neg_hi:[0,0,1]
	v_add_f32_e32 v9, v9, v62
	v_add_f32_e32 v62, v8, v9
	v_pk_mul_f32 v[8:9], v[12:13], v[12:13]
	v_pk_fma_f32 v[6:7], v[20:21], v[6:7], v[88:89] op_sel_hi:[1,1,0] neg_lo:[0,0,1] neg_hi:[0,0,1]
	v_add_f32_e32 v9, v9, v62
	v_add_f32_e32 v16, v8, v9
	v_pk_fma_f32 v[8:9], v[18:19], v[10:11], v[88:89] op_sel_hi:[1,1,0] neg_lo:[0,0,1] neg_hi:[0,0,1]
	v_add_u32_e32 v19, 0x1a000, v0
	v_pk_mul_f32 v[10:11], v[8:9], v[8:9]
	v_lshlrev_b32_e32 v78, 16, v33
	v_add_f32_e32 v11, v11, v16
	v_add_f32_e32 v16, v10, v11
	v_pk_mul_f32 v[10:11], v[6:7], v[6:7]
	v_lshlrev_b32_e32 v79, 16, v5
	v_add_f32_e32 v11, v11, v16
	v_add_f32_e32 v10, v10, v11
	s_nop 1
	v_mov_b32_dpp v11, v10 quad_perm:[1,0,3,2] row_mask:0xf bank_mask:0xf
	v_and_b32_e32 v5, 0xffff0000, v4
	v_and_b32_e32 v4, 0xffff0000, v32
	v_mov_b32_e32 v32, v5
	v_mov_b32_e32 v33, v101
	s_waitcnt lgkmcnt(0)
	v_add_f32_e32 v10, v10, v11
	s_nop 1
	v_mov_b32_dpp v11, v10 quad_perm:[2,3,0,1] row_mask:0xf bank_mask:0xf
	v_mov_b32_e32 v54, v96
	v_add_u32_e32 v81, 0, v132
	v_lshlrev_b32_e32 v73, 2, v162
	v_sub_u32_e32 v74, v81, v130
	s_waitcnt lgkmcnt(0)
	v_add_f32_e32 v10, v10, v11
	v_fmamk_f32 v10, v10, 0x3c000000, v209
	v_cmp_gt_f32_e32 vcc, s82, v10
	v_mul_f32_e32 v11, 0x4b800000, v10
	v_or_b32_e32 v71, 2, v130
	v_cndmask_b32_e32 v10, v10, v11, vcc
	v_rsq_f32_e32 v10, v10
	v_or_b32_e32 v70, 3, v130
	v_or_b32_e32 v72, 4, v130
	v_mul_f32_e32 v11, 0x45800000, v10
	v_cndmask_b32_e32 v18, v10, v11, vcc
	s_waitcnt vmcnt(0)
	v_mov_b64_e32 v[10:11], v[144:145]
	v_mov_b64_e32 v[16:17], v[218:219]
	v_mul_f32_e32 v20, v63, v18
	v_mul_f32_e32 v15, v15, v18
	v_mul_f32_e32 v14, v14, v18
	v_mul_f32_e32 v13, v13, v18
	v_mul_f32_e32 v12, v12, v18
	v_mul_f32_e32 v9, v9, v18
	v_mul_f32_e32 v8, v8, v18
	v_mul_f32_e32 v7, v7, v18
	v_mul_f32_e32 v6, v6, v18
	s_waitcnt vmcnt(0)
	v_fma_f32 v10, v10, v20, v16
	v_mul_f32_e32 v16, v61, v18
	v_fmac_f32_e32 v17, v11, v16
	v_add_u32_e32 v11, 0x1a110, v0
	v_cvt_pk_bf16_f32 v10, v10, v17
	ds_write_b16 v19, v10
	ds_write_b16_d16_hi v11, v10
	v_mov_b64_e32 v[10:11], v[146:147]
	v_mov_b64_e32 v[16:17], v[220:221]
	v_mul_f32_e32 v19, v60, v18
	s_waitcnt vmcnt(0)
	v_fma_f32 v10, v10, v19, v16
	v_mul_f32_e32 v16, v59, v18
	v_fmac_f32_e32 v17, v11, v16
	v_add_u32_e32 v11, 0x1a220, v0
	v_cvt_pk_bf16_f32 v10, v10, v17
	ds_write_b16 v11, v10
	v_add_u32_e32 v11, 0x1a330, v0
	ds_write_b16_d16_hi v11, v10
	v_mov_b64_e32 v[10:11], v[148:149]
	v_mov_b64_e32 v[16:17], v[222:223]
	v_mul_f32_e32 v19, v58, v18
	s_waitcnt vmcnt(0)
	v_fma_f32 v10, v10, v19, v16
	v_mul_f32_e32 v16, v57, v18
	v_fmac_f32_e32 v17, v11, v16
	v_add_u32_e32 v11, 0x1a440, v0
	v_cvt_pk_bf16_f32 v10, v10, v17
	ds_write_b16 v11, v10
	v_add_u32_e32 v11, 0x1a550, v0
	ds_write_b16_d16_hi v11, v10
	v_mov_b64_e32 v[10:11], v[150:151]
	v_mov_b64_e32 v[16:17], v[224:225]
	v_mul_f32_e32 v19, v56, v18
	v_mov_b32_e32 v56, v109
	v_mov_b32_e32 v57, v105
	v_pk_fma_f32 v[110:111], v[56:57], v[56:57], v[110:111]
	s_waitcnt vmcnt(0)
	v_fma_f32 v10, v10, v19, v16
	v_mul_f32_e32 v16, v55, v18
	v_fmac_f32_e32 v17, v11, v16
	v_add_u32_e32 v11, 0x1a660, v0
	v_cvt_pk_bf16_f32 v10, v10, v17
	ds_write_b16 v11, v10
	v_add_u32_e32 v11, 0x1a770, v0
	ds_write_b16_d16_hi v11, v10
	v_mov_b64_e32 v[10:11], v[152:153]
	v_mov_b64_e32 v[16:17], v[226:227]
	v_mul_f32_e32 v19, v53, v18
	v_mov_b32_e32 v55, v78
	v_pk_mul_f32 v[54:55], v[54:55], v[54:55]
	s_waitcnt vmcnt(0)
	v_fma_f32 v10, v10, v19, v16
	v_mul_f32_e32 v16, v52, v18
	v_fmac_f32_e32 v17, v11, v16
	v_add_u32_e32 v11, 0x1a880, v0
	v_cvt_pk_bf16_f32 v10, v10, v17
	ds_write_b16 v11, v10
	v_add_u32_e32 v11, 0x1a990, v0
	ds_write_b16_d16_hi v11, v10
	v_mov_b64_e32 v[10:11], v[154:155]
	v_mov_b64_e32 v[16:17], v[228:229]
	v_mul_f32_e32 v19, v51, v18
	s_waitcnt vmcnt(0)
; __device__ __forceinline__ unsigned cvt_pk_bf16(float lo, float hi) { unsigned r; asm volatile("v_cvt_pk_bf16_f32 %0, %1, %2" : "=v"(r) : "v"(lo), "v"(hi)); return r; }
; #define LAS __attribute__((address_space(3)))
; __device__ __forceinline__ void unpack8(const u32x4 w, float* f) { f[0] = bf_lo(w.x); f[1] = bf_hi(w.x); f[2] = bf_lo(w.y); f[3] = bf_hi(w.y); f[4] = bf_lo(w.z); f[5] = bf_hi(w.z); f[6] = bf_lo(w.w); f[7] = bf_hi(w.w); }
; __device__ __forceinline__ void p2_block(LAS unsigned char* lds, const bf16_t* __restrict__ PROJ, bf16_t* __restrict__ ATT, bf16_t* __restrict__ SGU, const float* __restrict__ qn, const float* __restrict__ kn, ...
;     ...
;         for (int j = 0; j < 32; j += 2) { const unsigned pk = cvt_pk_bf16(v[j] * rstd * gp[j] + bp[j], v[j + 1] * rstd * gp[j + 1] + bp[j + 1]);
;             *(LAS unsigned short*)(dst + j * VN_STRIDE) = (unsigned short)(pk & 0xffffu); *(LAS unsigned short*)(dst + (j + 1) * VN_STRIDE) = (unsigned short)(pk >> 16); }
;     }
;     __syncthreads();
; #pragma unroll
;     for (int c = 2; c < 4; ++c) { const bf16_t* qp = PROJ + ((size_t)b * pg8::SEQ + n * 128 + rbase + 16 * c + fr) * pg8::IN_W + hq * 64 + 8 * fq; qa[c] = *(const u32x4*)qp; qb[c] = *(const u32x4*)(qp + 32); }
;     const float sink = sinks[hq];
;     constexpr float LOG2E = 1.4426950408889634f;
; #pragma unroll
;     for (int c = 0; c < 4; ++c) {
;         const int i0 = rbase + 16 * c, irow = i0 + fr, pos = n * 128 + irow; const size_t grow = (size_t)b * pg8::SEQ + pos;
;         bf16x8 qf0, qf1;
;         {
;             float x1[8], x2[8]; unpack8(qa[c], x1); unpack8(qb[c], x2);
;             float ss = 0.f;
; #pragma unroll
;             for (int j = 0; j < 8; ++j) ss += x1[j] * x1[j] + x2[j] * x2[j];
;             ss += __shfl_xor(ss, 16); ss += __shfl_xor(ss, 32);
;             const float rinv = rsqrtf(ss * (1.0f / 64.0f) + pg8::EPS) * 0.125f;
;             const float* cp = COS + pos * 32 + 8 * fq; const float* sp = SIN + pos * 32 + 8 * fq;
	v_fma_f32 v10, v10, v19, v16
	v_mul_f32_e32 v16, v50, v18
	v_fmac_f32_e32 v17, v11, v16
	v_add_u32_e32 v11, 0x1aaa0, v0
	v_cvt_pk_bf16_f32 v10, v10, v17
	ds_write_b16 v11, v10
	v_add_u32_e32 v11, 0x1abb0, v0
	ds_write_b16_d16_hi v11, v10
	v_mov_b64_e32 v[10:11], v[156:157]
	v_mov_b64_e32 v[16:17], v[230:231]
	v_mul_f32_e32 v19, v49, v18
	s_waitcnt vmcnt(0)
	v_fma_f32 v10, v10, v19, v16
	v_mul_f32_e32 v16, v48, v18
	v_fmac_f32_e32 v17, v16, v11
	v_add_u32_e32 v11, 0x1acc0, v0
	v_cvt_pk_bf16_f32 v10, v10, v17
	ds_write_b16 v11, v10
	v_add_u32_e32 v11, 0x1add0, v0
	ds_write_b16_d16_hi v11, v10
	v_mov_b64_e32 v[10:11], v[158:159]
	v_mov_b64_e32 v[16:17], v[232:233]
	v_mul_f32_e32 v19, v47, v18
	s_waitcnt vmcnt(0)
	v_fma_f32 v10, v19, v10, v16
	v_mul_f32_e32 v16, v46, v18
	v_fmac_f32_e32 v17, v16, v11
	v_add_u32_e32 v11, 0x1aee0, v0
	v_cvt_pk_bf16_f32 v10, v10, v17
	ds_write_b16 v11, v10
	v_add_u32_e32 v11, 0x1aff0, v0
	ds_write_b16_d16_hi v11, v10
	v_mov_b64_e32 v[10:11], v[184:185]
	v_mov_b64_e32 v[16:17], v[234:235]
	v_mul_f32_e32 v19, v45, v18
	s_waitcnt vmcnt(0)
	v_fma_f32 v10, v19, v10, v16
	v_mul_f32_e32 v16, v44, v18
	v_fmac_f32_e32 v17, v16, v11
	v_add_u32_e32 v11, 0x1b100, v0
	v_cvt_pk_bf16_f32 v10, v10, v17
	ds_write_b16 v11, v10
	v_add_u32_e32 v11, 0x1b210, v0
	ds_write_b16_d16_hi v11, v10
	v_mov_b64_e32 v[10:11], v[186:187]
	v_mov_b64_e32 v[16:17], v[236:237]
	v_mul_f32_e32 v19, v43, v18
	v_or_b32_e32 v44, s17, v161
	s_waitcnt vmcnt(0)
	v_fma_f32 v10, v19, v10, v16
	v_mul_f32_e32 v16, v42, v18
	v_fmac_f32_e32 v17, v16, v11
	v_add_u32_e32 v11, 0x1b320, v0
	v_cvt_pk_bf16_f32 v10, v10, v17
	ds_write_b16 v11, v10
	v_add_u32_e32 v11, 0x1b430, v0
	ds_write_b16_d16_hi v11, v10
	v_mov_b64_e32 v[10:11], v[188:189]
	v_mov_b64_e32 v[16:17], v[238:239]
	v_mul_f32_e32 v19, v41, v18
	s_waitcnt vmcnt(0)
	v_fma_f32 v10, v19, v10, v16
	v_mul_f32_e32 v16, v40, v18
	v_fmac_f32_e32 v17, v16, v11
	v_add_u32_e32 v11, 0x1b540, v0
	v_cvt_pk_bf16_f32 v10, v10, v17
	ds_write_b16 v11, v10
	v_add_u32_e32 v11, 0x1b650, v0
	ds_write_b16_d16_hi v11, v10
	v_mov_b64_e32 v[10:11], v[190:191]
	v_mov_b64_e32 v[16:17], v[240:241]
	v_mul_f32_e32 v19, v39, v18
	s_waitcnt vmcnt(0)
	v_fma_f32 v10, v19, v10, v16
	v_mul_f32_e32 v16, v38, v18
	v_fmac_f32_e32 v17, v16, v11
	v_add_u32_e32 v11, 0x1b760, v0
	v_cvt_pk_bf16_f32 v10, v10, v17
	ds_write_b16 v11, v10
	v_add_u32_e32 v11, 0x1b870, v0
	ds_write_b16_d16_hi v11, v10
	v_mov_b64_e32 v[10:11], v[192:193]
	v_mov_b64_e32 v[16:17], v[242:243]
	s_waitcnt vmcnt(0)
	v_fma_f32 v10, v15, v10, v16
	v_fmac_f32_e32 v17, v14, v11
	v_add_u32_e32 v11, 0x1b980, v0
	v_cvt_pk_bf16_f32 v10, v10, v17
	ds_write_b16 v11, v10
	v_add_u32_e32 v11, 0x1ba90, v0
	ds_write_b16_d16_hi v11, v10
	v_mov_b64_e32 v[10:11], v[194:195]
	v_mov_b64_e32 v[14:15], v[244:245]
	s_waitcnt vmcnt(0)
	v_fma_f32 v10, v13, v10, v14
	v_fmac_f32_e32 v15, v12, v11
	v_add_u32_e32 v11, 0x1bba0, v0
	v_cvt_pk_bf16_f32 v10, v10, v15
	ds_write_b16 v11, v10
	v_add_u32_e32 v11, 0x1bcb0, v0
	ds_write_b16_d16_hi v11, v10
	v_mov_b64_e32 v[10:11], v[196:197]
	v_mov_b64_e32 v[12:13], v[200:201]
	v_lshlrev_b32_e32 v14, 7, v44
	v_mov_b32_e32 v15, v1
	v_or_b32_e32 v44, s48, v44
	s_waitcnt vmcnt(0)
	v_fma_f32 v9, v9, v10, v12
	v_fmac_f32_e32 v13, v8, v11
	v_cvt_pk_bf16_f32 v8, v9, v13
	v_add_u32_e32 v9, 0x1bdc0, v0
	ds_write_b16 v9, v8
	v_add_u32_e32 v9, 0x1bed0, v0
	ds_write_b16_d16_hi v9, v8
	v_mov_b64_e32 v[8:9], v[198:199]
	v_mov_b64_e32 v[10:11], v[202:203]
	s_waitcnt vmcnt(0)
	v_fma_f32 v7, v7, v8, v10
	v_fmac_f32_e32 v11, v6, v9
	v_cvt_pk_bf16_f32 v6, v7, v11
	v_add_u32_e32 v7, 0x1bfe0, v0
	v_add_u32_e32 v0, 0x1c0f0, v0
	ds_write_b16_d16_hi v0, v6
	v_or_b32_e32 v0, 32, v163
	ds_write_b16 v7, v6
	v_mad_u64_u32 v[6:7], s[28:29], v0, s83, v[134:135]
	v_mad_i32_i24 v7, s49, v212, v7
	v_or_b32_e32 v0, 48, v163
	v_readfirstlane_b32 s16, v204
	v_and_b32_e32 v43, 15, v204
	v_bfe_u32 v44, v204, 4, 2
	s_and_b32 s24, s2, 3
	s_lshr_b32 s16, s16, 6
	s_bfe_u32 s27, s2, 0x40002
	s_lshr_b32 s17, s16, 1
	s_and_b32 s25, s16, 1
	s_lshl_b32 s25, s25, 6
	s_lshl_b32 s26, s24, 2
	s_add_i32 s26, s26, s17
	s_and_b32 s28, s2, -4
	s_lshl_b32 s28, s28, 5
	s_lshl_b32 s29, s27, 7
	s_add_i32 s28, s28, s25
	s_add_i32 s29, s29, s25
	s_lshl_b32 s4, s26, 7
	v_add_u32_e32 v166, s28, v43
	v_mul_u32_u24_e32 v46, 0x3c00, v166
	v_lshl_add_u32 v46, v44, 4, v46
	v_add_u32_e32 v46, s4, v46
	v_lshlrev_b32_e32 v48, 11, v166
	v_lshl_add_u32 v48, v44, 3, v48
	v_add_u32_e32 v48, s4, v48
	v_add_u32_e32 v166, s29, v43
	v_lshlrev_b32_e32 v47, 7, v166
	v_lshl_add_u32 v47, v44, 5, v47
	v_mul_u32_u24_e32 v45, 0x90, v43
	v_lshl_add_u32 v45, v44, 4, v45
	v_mul_u32_u24_e32 v166, 0x210, v43
	v_lshl_add_u32 v166, v44, 3, v166
	v_add_u32_e32 v194, 0x9000, v166
	v_add_u32_e32 v195, 0xb100, v166
	v_add_u32_e32 v196, 0xd200, v166
	v_add_u32_e32 v197, 0xf300, v166
	v_lshlrev_b32_e32 v166, 2, v44
	v_sub_u32_e32 v166, v43, v166
	v_cmp_gt_i32_e64 s[40:41], 0, v166
	v_cmp_gt_i32_e64 s[42:43], 1, v166
	v_cmp_gt_i32_e64 s[44:45], 2, v166
	v_cmp_gt_i32_e64 s[46:47], 3, v166
	v_mov_b32_e32 v49, 0xf149f2ca
	v_lshlrev_b32_e32 v167, 5, v44
	v_mov_b32_e32 v166, s26
	v_lshlrev_b32_e32 v166, 2, v166
	s_mov_b32 s4, s25
	s_mov_b32 vcc_lo, s63
	s_mov_b32 vcc_hi, s78
	s_cmp_lg_u32 s27, 0
	s_cselect_b64 s[28:29], -1, 0
	s_and_b64 s[48:49], s[40:41], s[28:29]
	s_and_b64 s[50:51], s[42:43], s[28:29]
	s_and_b64 s[52:53], s[44:45], s[28:29]
	s_and_b64 s[26:27], s[46:47], s[28:29]
	v_readlane_b32 s6, v250, 36
	v_readlane_b32 s7, v250, 37
	v_readlane_b32 s16, v250, 38
	v_readlane_b32 s17, v250, 39
	v_readlane_b32 s24, v248, 54
	v_readlane_b32 s25, v248, 55
	global_load_dwordx4 v[26:29], v167, s[38:39]
	global_load_dwordx4 v[30:33], v167, s[38:39] offset:16
	global_load_dwordx4 v[34:37], v167, s[38:39] offset:128
	global_load_dwordx4 v[38:41], v167, s[38:39] offset:144
	global_load_dword v42, v166, vcc
	s_nop 1
	global_load_dwordx4 v[2:5], v46, s[10:11]
	global_load_dwordx4 v[6:9], v46, s[10:11] offset:64
	global_load_dwordx4 v[10:13], v47, s[6:7]
	global_load_dwordx4 v[14:17], v47, s[6:7] offset:16
	global_load_dwordx4 v[18:21], v47, s[16:17]
	global_load_dwordx4 v[22:25], v47, s[16:17] offset:16
	v_add_u32_e32 v46, 0x3c000, v46
	v_add_u32_e32 v47, 0x800, v47
	global_load_dwordx4 v[218:221], v46, s[10:11]
	global_load_dwordx4 v[222:225], v46, s[10:11] offset:64
	global_load_dwordx4 v[226:229], v47, s[6:7]
	global_load_dwordx4 v[230:233], v47, s[6:7] offset:16
	global_load_dwordx4 v[234:237], v47, s[16:17]
	global_load_dwordx4 v[238:241], v47, s[16:17] offset:16
	v_add_u32_e32 v46, 0x3c000, v46
	v_add_u32_e32 v47, 0x800, v47
	s_waitcnt lgkmcnt(0)
	s_barrier
	s_cmp_eq_u32 s4, 0
	s_cbranch_scc1 .Latt_r0
; __device__ __forceinline__ unsigned cvt_pk_bf16(float lo, float hi) { unsigned r; asm volatile("v_cvt_pk_bf16_f32 %0, %1, %2" : "=v"(r) : "v"(lo), "v"(hi)); return r; }
; #define LAS __attribute__((address_space(3)))
; #define MFMA16(a, b, c) __builtin_amdgcn_mfma_f32_16x16x32_bf16((a), (b), (c), 0, 0, 0)
; __device__ __forceinline__ void p2_block(LAS unsigned char* lds, const bf16_t* __restrict__ PROJ, bf16_t* __restrict__ ATT, bf16_t* __restrict__ SGU, const float* __restrict__ qn, const float* __restrict__ kn, ...
;     ...
;         const int i0 = rbase + 16 * c, irow = i0 + fr, pos = n * 128 + irow; const size_t grow = (size_t)b * pg8::SEQ + pos;
;         bf16x8 qf0, qf1;
;         {
;             float x1[8], x2[8]; unpack8(qa[c], x1); unpack8(qb[c], x2);
;             float ss = 0.f;
; #pragma unroll
;             for (int j = 0; j < 8; ++j) ss += x1[j] * x1[j] + x2[j] * x2[j];
;             ss += __shfl_xor(ss, 16); ss += __shfl_xor(ss, 32);
;             const float rinv = rsqrtf(ss * (1.0f / 64.0f) + pg8::EPS) * 0.125f;
;             const float* cp = COS + pos * 32 + 8 * fq; const float* sp = SIN + pos * 32 + 8 * fq;
;             float o1[8], o2[8];
; #pragma unroll
;             for (int j = 0; j < 8; ++j) { const float a1 = x1[j] * rinv * qn[8 * fq + j], a2 = x2[j] * rinv * qn[32 + 8 * fq + j], cc = cp[j], sn = sp[j]; o1[j] = a1 * cc - a2 * sn; o2[j] = a2 * cc + a1 * sn; }
;             u32x4 w0, w1;
;             w0.x = cvt_pk_bf16(o1[0], o1[1]); w0.y = cvt_pk_bf16(o1[2], o1[3]); w0.z = cvt_pk_bf16(o1[4], o1[5]); w0.w = cvt_pk_bf16(o1[6], o1[7]);
;             w1.x = cvt_pk_bf16(o2[0], o2[1]); w1.y = cvt_pk_bf16(o2[2], o2[3]); w1.z = cvt_pk_bf16(o2[4], o2[5]); w1.w = cvt_pk_bf16(o2[6], o2[7]);
;             qf0 = __builtin_bit_cast(bf16x8, w0); qf1 = __builtin_bit_cast(bf16x8, w1);
;         }
;         const int t0 = (i0 >> 4) < 6 ? (i0 >> 4) : 6;
;         f32x4 sc_[10];
;         const LAS unsigned char* kbase = KS + (16 * t0 + fr) * KS_STRIDE + 16 * fq;
; #pragma unroll
;         for (int t = 0; t < 10; ++t) { const bf16x8 k0 = *(const LAS bf16x8*)(kbase + t * 16 * KS_STRIDE), k1 = *(const LAS bf16x8*)(kbase + t * 16 * KS_STRIDE + 64);
;             f32x4 z = (f32x4){0.f, 0.f, 0.f, 0.f}; z = MFMA16(k0, qf0, z); sc_[t] = MFMA16(k1, qf1, z); }
.Latt_r64:
	ds_read_b128 v[98:101], v45 offset:9216
	ds_read_b128 v[102:105], v45 offset:9280
	ds_read_b128 v[106:109], v45 offset:11520
	ds_read_b128 v[110:113], v45 offset:11584
	ds_read_b128 v[114:117], v45 offset:13824
	ds_read_b128 v[118:121], v45 offset:13888
	ds_read_b128 v[122:125], v45 offset:16128
	ds_read_b128 v[126:129], v45 offset:16192
	ds_read_b128 v[130:133], v45 offset:18432
	ds_read_b128 v[134:137], v45 offset:18496
	ds_read_b128 v[138:141], v45 offset:20736
	ds_read_b128 v[142:145], v45 offset:20800
	ds_read_b128 v[146:149], v45 offset:23040
	ds_read_b128 v[150:153], v45 offset:23104
	s_waitcnt vmcnt(6)
	v_lshlrev_b32_e32 v58, 16, v2
	v_and_b32_e32 v59, 0xffff0000, v2
	v_lshlrev_b32_e32 v66, 16, v6
	v_and_b32_e32 v67, 0xffff0000, v6
	v_lshlrev_b32_e32 v60, 16, v3
	v_and_b32_e32 v61, 0xffff0000, v3
	v_lshlrev_b32_e32 v68, 16, v7
	v_and_b32_e32 v69, 0xffff0000, v7
	v_lshlrev_b32_e32 v62, 16, v4
	v_and_b32_e32 v63, 0xffff0000, v4
	v_lshlrev_b32_e32 v70, 16, v8
	v_and_b32_e32 v71, 0xffff0000, v8
	v_lshlrev_b32_e32 v64, 16, v5
	v_and_b32_e32 v65, 0xffff0000, v5
	v_lshlrev_b32_e32 v72, 16, v9
	v_and_b32_e32 v73, 0xffff0000, v9
	v_mul_f32_e32 v74, v58, v58
	v_mul_f32_e32 v75, v59, v59
	v_fmac_f32_e32 v74, v60, v60
	v_fmac_f32_e32 v75, v61, v61
	v_fmac_f32_e32 v74, v62, v62
	v_fmac_f32_e32 v75, v63, v63
	v_fmac_f32_e32 v74, v64, v64
	v_fmac_f32_e32 v75, v65, v65
	v_fmac_f32_e32 v74, v66, v66
	v_fmac_f32_e32 v75, v67, v67
	v_fmac_f32_e32 v74, v68, v68
	v_fmac_f32_e32 v75, v69, v69
	v_fmac_f32_e32 v74, v70, v70
	v_fmac_f32_e32 v75, v71, v71
	v_fmac_f32_e32 v74, v72, v72
	v_fmac_f32_e32 v75, v73, v73
	v_add_f32_e32 v74, v74, v75
	v_mov_b32_e32 v166, v74
	s_nop 1
	v_permlane16_swap_b32_e32 v74, v166
	v_add_f32_e32 v74, v74, v166
	v_mov_b32_e32 v166, v74
	s_nop 1
	v_permlane32_swap_b32_e32 v74, v166
	v_add_f32_e32 v74, v74, v166
	v_fmamk_f32 v74, v74, 0x3c800000, v209
	v_rsq_f32_e32 v76, v74
	s_nop 0
	v_mul_f32_e32 v76, 0x3e000000, v76
	v_mul_f32_e32 v58, v58, v76
	v_mul_f32_e32 v66, v66, v76
	v_mul_f32_e32 v59, v59, v76
	v_mul_f32_e32 v67, v67, v76
	v_mul_f32_e32 v60, v60, v76
	v_mul_f32_e32 v68, v68, v76
	v_mul_f32_e32 v61, v61, v76
	v_mul_f32_e32 v69, v69, v76
	v_mul_f32_e32 v62, v62, v76
	v_mul_f32_e32 v70, v70, v76
	v_mul_f32_e32 v63, v63, v76
	v_mul_f32_e32 v71, v71, v76
	v_mul_f32_e32 v64, v64, v76
	v_mul_f32_e32 v72, v72, v76
	v_mul_f32_e32 v65, v65, v76
	v_mul_f32_e32 v73, v73, v76
	v_mul_f32_e32 v58, v58, v26
	v_mul_f32_e32 v66, v66, v34
	v_mul_f32_e32 v59, v59, v27
	v_mul_f32_e32 v67, v67, v35
	v_mul_f32_e32 v60, v60, v28
	v_mul_f32_e32 v68, v68, v36
	v_mul_f32_e32 v61, v61, v29
	v_mul_f32_e32 v69, v69, v37
	v_mul_f32_e32 v62, v62, v30
	v_mul_f32_e32 v70, v70, v38
	v_mul_f32_e32 v63, v63, v31
	v_mul_f32_e32 v71, v71, v39
	v_mul_f32_e32 v64, v64, v32
	v_mul_f32_e32 v72, v72, v40
	v_mul_f32_e32 v65, v65, v33
	v_mul_f32_e32 v73, v73, v41
	v_mul_f32_e32 v78, v66, v18
	v_mul_f32_e32 v86, v58, v18
	v_mul_f32_e32 v79, v67, v19
	v_mul_f32_e32 v87, v59, v19
	v_mul_f32_e32 v80, v68, v20
	v_mul_f32_e32 v88, v60, v20
	v_mul_f32_e32 v81, v69, v21
	v_mul_f32_e32 v89, v61, v21
	v_mul_f32_e32 v82, v70, v22
	v_mul_f32_e32 v90, v62, v22
	v_mul_f32_e32 v83, v71, v23
	v_mul_f32_e32 v91, v63, v23
	v_mul_f32_e32 v84, v72, v24
	v_mul_f32_e32 v92, v64, v24
	v_mul_f32_e32 v85, v73, v25
	v_mul_f32_e32 v93, v65, v25
	v_fma_f32 v78, v58, v10, -v78
	v_fmac_f32_e32 v86, v66, v10
	v_fma_f32 v79, v59, v11, -v79
	v_fmac_f32_e32 v87, v67, v11
	v_fma_f32 v80, v60, v12, -v80
	v_fmac_f32_e32 v88, v68, v12
	v_fma_f32 v81, v61, v13, -v81
	v_fmac_f32_e32 v89, v69, v13
	v_fma_f32 v82, v62, v14, -v82
	v_fmac_f32_e32 v90, v70, v14
	v_fma_f32 v83, v63, v15, -v83
	v_fmac_f32_e32 v91, v71, v15
	v_fma_f32 v84, v64, v16, -v84
	v_fmac_f32_e32 v92, v72, v16
	v_fma_f32 v85, v65, v17, -v85
	v_fmac_f32_e32 v93, v73, v17
	v_cvt_pk_bf16_f32 v50, v78, v79
	v_cvt_pk_bf16_f32 v54, v86, v87
	v_cvt_pk_bf16_f32 v51, v80, v81
	v_cvt_pk_bf16_f32 v55, v88, v89
	v_cvt_pk_bf16_f32 v52, v82, v83
	v_cvt_pk_bf16_f32 v56, v90, v91
	v_cvt_pk_bf16_f32 v53, v84, v85
	v_cvt_pk_bf16_f32 v57, v92, v93
	global_load_dwordx4 v[2:5], v46, s[10:11]
	global_load_dwordx4 v[6:9], v46, s[10:11] offset:64
	global_load_dwordx4 v[10:13], v47, s[6:7]
	global_load_dwordx4 v[14:17], v47, s[6:7] offset:16
	global_load_dwordx4 v[18:21], v47, s[16:17]
	global_load_dwordx4 v[22:25], v47, s[16:17] offset:16
	v_add_u32_e32 v46, 0x3c000, v46
	v_add_u32_e32 v47, 0x800, v47
	s_nop 1
	s_waitcnt lgkmcnt(13)
	v_mfma_f32_16x16x32_bf16 v[58:61], v[98:101], v[50:53], 0
	s_waitcnt lgkmcnt(12)
	v_mfma_f32_16x16x32_bf16 v[58:61], v[102:105], v[54:57], v[58:61]
	ds_read_b128 v[154:157], v45 offset:25344
	ds_read_b128 v[158:161], v45 offset:25408
	s_waitcnt lgkmcnt(13)
	v_mfma_f32_16x16x32_bf16 v[62:65], v[106:109], v[50:53], 0
	s_waitcnt lgkmcnt(12)
	v_mfma_f32_16x16x32_bf16 v[62:65], v[110:113], v[54:57], v[62:65]
	ds_read_b128 v[162:165], v45 offset:27648
	ds_read_b128 v[182:185], v45 offset:27712
	s_waitcnt lgkmcnt(13)
	v_mfma_f32_16x16x32_bf16 v[66:69], v[114:117], v[50:53], 0
	s_waitcnt lgkmcnt(12)
	v_mfma_f32_16x16x32_bf16 v[66:69], v[118:121], v[54:57], v[66:69]
	s_waitcnt lgkmcnt(11)
	v_mfma_f32_16x16x32_bf16 v[70:73], v[122:125], v[50:53], 0
	s_waitcnt lgkmcnt(10)
	v_mfma_f32_16x16x32_bf16 v[70:73], v[126:129], v[54:57], v[70:73]
	s_waitcnt lgkmcnt(9)
	v_mfma_f32_16x16x32_bf16 v[74:77], v[130:133], v[50:53], 0
	s_waitcnt lgkmcnt(8)
	v_mfma_f32_16x16x32_bf16 v[74:77], v[134:137], v[54:57], v[74:77]
	s_waitcnt lgkmcnt(7)
	v_mfma_f32_16x16x32_bf16 v[78:81], v[138:141], v[50:53], 0
	s_waitcnt lgkmcnt(6)
; #define LAS __attribute__((address_space(3)))
; #define MFMA16(a, b, c) __builtin_amdgcn_mfma_f32_16x16x32_bf16((a), (b), (c), 0, 0, 0)
; __device__ __forceinline__ void p2_block(LAS unsigned char* lds, const bf16_t* __restrict__ PROJ, bf16_t* __restrict__ ATT, bf16_t* __restrict__ SGU, const float* __restrict__ qn, const float* __restrict__ kn, ...
;     ...
;         for (int t = 0; t < 10; ++t) { const bf16x8 k0 = *(const LAS bf16x8*)(kbase + t * 16 * KS_STRIDE), k1 = *(const LAS bf16x8*)(kbase + t * 16 * KS_STRIDE + 64);
;             f32x4 z = (f32x4){0.f, 0.f, 0.f, 0.f}; z = MFMA16(k0, qf0, z); sc_[t] = MFMA16(k1, qf1, z); }
;         float mx = -1e30f;
; #pragma unroll
;         for (int t = 0; t < 10; ++t)
; #pragma unroll
;             for (int e = 0; e < 4; ++e) { const int kx = 16 * (t0 + t) + 4 * fq + e, d = kx - irow; const bool ok = (d >= 1) && (d <= 128) && (n > 0 || kx >= 128);
;                 const float v = ok ? sc_[t][e] : -1e30f; sc_[t][e] = v; mx = fmaxf(mx, v); }
;         mx = fmaxf(mx, __shfl_xor(mx, 16)); mx = fmaxf(mx, __shfl_xor(mx, 32)); mx = fmaxf(mx, sink);
;         float sum = 0.f;
; #pragma unroll
;         for (int t = 0; t < 10; ++t)
; #pragma unroll
;             for (int e = 0; e < 4; ++e) { const float p = __builtin_amdgcn_exp2f((sc_[t][e] - mx) * LOG2E); sc_[t][e] = p; sum += p; }
;         sum += __shfl_xor(sum, 16); sum += __shfl_xor(sum, 32);
;         const float inv = 1.0f / (sum + __builtin_amdgcn_exp2f((sink - mx) * LOG2E));
	v_mfma_f32_16x16x32_bf16 v[78:81], v[142:145], v[54:57], v[78:81]
	s_waitcnt lgkmcnt(5)
	v_mfma_f32_16x16x32_bf16 v[82:85], v[146:149], v[50:53], 0
	s_waitcnt lgkmcnt(4)
	v_mfma_f32_16x16x32_bf16 v[82:85], v[150:153], v[54:57], v[82:85]
	s_waitcnt lgkmcnt(3)
	v_mfma_f32_16x16x32_bf16 v[86:89], v[154:157], v[50:53], 0
	s_waitcnt lgkmcnt(2)
	v_mfma_f32_16x16x32_bf16 v[86:89], v[158:161], v[54:57], v[86:89]
	s_waitcnt lgkmcnt(1)
	v_mfma_f32_16x16x32_bf16 v[90:93], v[162:165], v[50:53], 0
	s_waitcnt lgkmcnt(0)
	v_mfma_f32_16x16x32_bf16 v[90:93], v[182:185], v[54:57], v[90:93]
	ds_read2_b64 v[98:101], v194 offset0:16 offset1:20
	ds_read2_b64 v[102:105], v195 offset0:16 offset1:20
	ds_read2_b64 v[106:109], v196 offset0:16 offset1:20
	ds_read2_b64 v[110:113], v197 offset0:16 offset1:20
	ds_read2_b64 v[114:117], v194 offset0:24 offset1:28
	ds_read2_b64 v[118:121], v195 offset0:24 offset1:28
	ds_read2_b64 v[122:125], v196 offset0:24 offset1:28
	ds_read2_b64 v[126:129], v197 offset0:24 offset1:28
	ds_read2_b64 v[130:133], v194 offset0:32 offset1:36
	ds_read2_b64 v[134:137], v195 offset0:32 offset1:36
	ds_read2_b64 v[138:141], v196 offset0:32 offset1:36
	ds_read2_b64 v[142:145], v197 offset0:32 offset1:36
	ds_read2_b64 v[146:149], v194 offset0:40 offset1:44
	ds_read2_b64 v[150:153], v195 offset0:40 offset1:44
	ds_read2_b64 v[154:157], v196 offset0:40 offset1:44
	s_nop 4
	v_cndmask_b32_e64 v58, v49, v58, s[48:49]
	v_cndmask_b32_e64 v59, v49, v59, s[50:51]
	v_cndmask_b32_e64 v60, v49, v60, s[52:53]
	v_cndmask_b32_e64 v61, v49, v61, s[26:27]
	v_cndmask_b32_e64 v62, v49, v62, s[28:29]
	v_cndmask_b32_e64 v63, v49, v63, s[28:29]
	v_cndmask_b32_e64 v64, v49, v64, s[28:29]
	v_cndmask_b32_e64 v65, v49, v65, s[28:29]
	v_cndmask_b32_e64 v66, v49, v66, s[28:29]
	v_cndmask_b32_e64 v67, v49, v67, s[28:29]
	v_cndmask_b32_e64 v68, v49, v68, s[28:29]
	v_cndmask_b32_e64 v69, v49, v69, s[28:29]
	v_cndmask_b32_e64 v70, v49, v70, s[28:29]
	v_cndmask_b32_e64 v71, v49, v71, s[28:29]
	v_cndmask_b32_e64 v72, v49, v72, s[28:29]
	v_cndmask_b32_e64 v73, v49, v73, s[28:29]
	v_cndmask_b32_e64 v90, v90, v49, s[40:41]
	v_cndmask_b32_e64 v91, v91, v49, s[42:43]
	v_cndmask_b32_e64 v92, v92, v49, s[44:45]
	v_cndmask_b32_e64 v93, v93, v49, s[46:47]
	v_max_f32_e32 v167, v58, v59
	v_max_f32_e32 v94, v60, v61
	v_max3_f32 v167, v167, v62, v63
	v_max3_f32 v94, v94, v64, v65
	v_max3_f32 v167, v167, v66, v67
	v_max3_f32 v94, v94, v68, v69
	v_max3_f32 v167, v167, v70, v71
	v_max3_f32 v94, v94, v72, v73
	v_max3_f32 v167, v167, v74, v75
	v_max3_f32 v94, v94, v76, v77
	v_max3_f32 v167, v167, v78, v79
	v_max3_f32 v94, v94, v80, v81
	v_max3_f32 v167, v167, v82, v83
	v_max3_f32 v94, v94, v84, v85
	v_max3_f32 v167, v167, v86, v87
	v_max3_f32 v94, v94, v88, v89
	v_max3_f32 v167, v167, v90, v91
	v_max3_f32 v94, v94, v92, v93
	v_max_f32_e32 v167, v167, v94
	v_mov_b32_e32 v166, v167
	s_nop 1
	v_permlane16_swap_b32_e32 v167, v166
	v_max_f32_e32 v167, v167, v166
	v_mov_b32_e32 v166, v167
	s_nop 1
	v_permlane32_swap_b32_e32 v167, v166
	v_max_f32_e32 v167, v167, v166
	v_max_f32_e32 v167, v167, v42
	v_mul_f32_e32 v94, 0xbfb8aa3b, v167
	v_fmamk_f32 v58, v58, 0x3fb8aa3b, v94
	v_fmamk_f32 v59, v59, 0x3fb8aa3b, v94
	v_fmamk_f32 v60, v60, 0x3fb8aa3b, v94
	v_fmamk_f32 v61, v61, 0x3fb8aa3b, v94
	v_fmamk_f32 v62, v62, 0x3fb8aa3b, v94
	v_fmamk_f32 v63, v63, 0x3fb8aa3b, v94
	v_fmamk_f32 v64, v64, 0x3fb8aa3b, v94
	v_fmamk_f32 v65, v65, 0x3fb8aa3b, v94
	v_fmamk_f32 v66, v66, 0x3fb8aa3b, v94
	v_fmamk_f32 v67, v67, 0x3fb8aa3b, v94
	v_fmamk_f32 v68, v68, 0x3fb8aa3b, v94
	v_fmamk_f32 v69, v69, 0x3fb8aa3b, v94
	v_fmamk_f32 v70, v70, 0x3fb8aa3b, v94
	v_fmamk_f32 v71, v71, 0x3fb8aa3b, v94
	v_fmamk_f32 v72, v72, 0x3fb8aa3b, v94
	v_fmamk_f32 v73, v73, 0x3fb8aa3b, v94
	v_fmamk_f32 v74, v74, 0x3fb8aa3b, v94
	v_fmamk_f32 v75, v75, 0x3fb8aa3b, v94
	v_fmamk_f32 v76, v76, 0x3fb8aa3b, v94
	v_fmamk_f32 v77, v77, 0x3fb8aa3b, v94
	v_fmamk_f32 v78, v78, 0x3fb8aa3b, v94
	v_fmamk_f32 v79, v79, 0x3fb8aa3b, v94
	v_fmamk_f32 v80, v80, 0x3fb8aa3b, v94
	v_fmamk_f32 v81, v81, 0x3fb8aa3b, v94
	v_fmamk_f32 v82, v82, 0x3fb8aa3b, v94
	v_fmamk_f32 v83, v83, 0x3fb8aa3b, v94
	v_fmamk_f32 v84, v84, 0x3fb8aa3b, v94
	v_fmamk_f32 v85, v85, 0x3fb8aa3b, v94
	v_fmamk_f32 v86, v86, 0x3fb8aa3b, v94
	v_fmamk_f32 v87, v87, 0x3fb8aa3b, v94
	v_fmamk_f32 v88, v88, 0x3fb8aa3b, v94
	v_fmamk_f32 v89, v89, 0x3fb8aa3b, v94
	v_fmamk_f32 v90, v90, 0x3fb8aa3b, v94
	v_fmamk_f32 v91, v91, 0x3fb8aa3b, v94
	v_fmamk_f32 v92, v92, 0x3fb8aa3b, v94
	v_fmamk_f32 v93, v93, 0x3fb8aa3b, v94
	v_exp_f32_e32 v58, v58
	v_exp_f32_e32 v59, v59
	v_exp_f32_e32 v60, v60
	v_exp_f32_e32 v61, v61
	v_exp_f32_e32 v62, v62
	v_exp_f32_e32 v63, v63
	v_exp_f32_e32 v64, v64
	v_exp_f32_e32 v65, v65
	v_exp_f32_e32 v66, v66
	v_exp_f32_e32 v67, v67
	v_exp_f32_e32 v68, v68
	v_exp_f32_e32 v69, v69
	v_exp_f32_e32 v70, v70
	v_exp_f32_e32 v71, v71
	v_exp_f32_e32 v72, v72
	v_exp_f32_e32 v73, v73
	v_exp_f32_e32 v74, v74
	v_exp_f32_e32 v75, v75
	v_exp_f32_e32 v76, v76
	v_exp_f32_e32 v77, v77
	v_exp_f32_e32 v78, v78
	v_exp_f32_e32 v79, v79
	v_exp_f32_e32 v80, v80
	v_exp_f32_e32 v81, v81
	v_exp_f32_e32 v82, v82
	v_exp_f32_e32 v83, v83
	v_exp_f32_e32 v84, v84
	v_exp_f32_e32 v85, v85
	v_exp_f32_e32 v86, v86
	v_exp_f32_e32 v87, v87
	v_exp_f32_e32 v88, v88
	v_exp_f32_e32 v89, v89
	v_exp_f32_e32 v90, v90
	v_exp_f32_e32 v91, v91
	v_exp_f32_e32 v92, v92
	v_exp_f32_e32 v93, v93
	v_fmamk_f32 v95, v42, 0x3fb8aa3b, v94
	v_exp_f32_e32 v95, v95
	v_add_f32_e32 v167, v58, v59
	v_add_f32_e32 v94, v60, v61
	v_add_f32_e32 v167, v167, v62
	v_add_f32_e32 v94, v94, v63
	v_add_f32_e32 v167, v167, v64
	v_add_f32_e32 v94, v94, v65
; __device__ __forceinline__ unsigned cvt_pk_bf16(float lo, float hi) { unsigned r; asm volatile("v_cvt_pk_bf16_f32 %0, %1, %2" : "=v"(r) : "v"(lo), "v"(hi)); return r; }
; #define LAS __attribute__((address_space(3)))
; #define MFMA16(a, b, c) __builtin_amdgcn_mfma_f32_16x16x32_bf16((a), (b), (c), 0, 0, 0)
; __device__ __forceinline__ void p2_block(LAS unsigned char* lds, const bf16_t* __restrict__ PROJ, bf16_t* __restrict__ ATT, bf16_t* __restrict__ SGU, const float* __restrict__ qn, const float* __restrict__ kn, ...
;     ...
;         float sum = 0.f;
; #pragma unroll
;         for (int t = 0; t < 10; ++t)
; #pragma unroll
;             for (int e = 0; e < 4; ++e) { const float p = __builtin_amdgcn_exp2f((sc_[t][e] - mx) * LOG2E); sc_[t][e] = p; sum += p; }
;         sum += __shfl_xor(sum, 16); sum += __shfl_xor(sum, 32);
;         const float inv = 1.0f / (sum + __builtin_amdgcn_exp2f((sink - mx) * LOG2E));
;         f32x4 o[4];
; #pragma unroll
;         for (int dt = 0; dt < 4; ++dt) o[dt] = (f32x4){0.f, 0.f, 0.f, 0.f};
; #pragma unroll
;         for (int j = 0; j < 5; ++j) {
;             u32x4 pw; pw.x = cvt_pk_bf16(sc_[2 * j][0], sc_[2 * j][1]); pw.y = cvt_pk_bf16(sc_[2 * j][2], sc_[2 * j][3]); pw.z = cvt_pk_bf16(sc_[2 * j + 1][0], sc_[2 * j + 1][1]); pw.w = cvt_pk_bf16(sc_[2 * j + 1][2], sc_[2 * j + 1][3]);
;             const bf16x8 pf = __builtin_bit_cast(bf16x8, pw);
; #pragma unroll
;             for (int dt = 0; dt < 4; ++dt) { const LAS unsigned char* vb = VT + (16 * dt + fr) * VT_STRIDE + (16 * (t0 + 2 * j) + 4 * fq) * 2;
;                 const u32x2 va = *(const LAS u32x2*)vb, vc = *(const LAS u32x2*)(vb + 32); u32x4 vw; vw.x = va.x; vw.y = va.y; vw.z = vc.x; vw.w = vc.y;
;                 o[dt] = MFMA16(__builtin_bit_cast(bf16x8, vw), pf, o[dt]); }
;         }
;         bf16_t* op = ATT + grow * 1024 + hq * 64 + 4 * fq;
; #pragma unroll
;         for (int dt = 0; dt < 4; ++dt) { u32x2 ow; ow.x = cvt_pk_bf16(o[dt][0] * inv, o[dt][1] * inv); ow.y = cvt_pk_bf16(o[dt][2] * inv, o[dt][3] * inv); *(u32x2*)(op + 16 * dt) = ow; }
	v_add_f32_e32 v167, v167, v66
	v_add_f32_e32 v94, v94, v67
	v_add_f32_e32 v167, v167, v68
	v_add_f32_e32 v94, v94, v69
	v_add_f32_e32 v167, v167, v70
	v_add_f32_e32 v94, v94, v71
	v_add_f32_e32 v167, v167, v72
	v_add_f32_e32 v94, v94, v73
	v_add_f32_e32 v167, v167, v74
	v_add_f32_e32 v94, v94, v75
	v_add_f32_e32 v167, v167, v76
	v_add_f32_e32 v94, v94, v77
	v_add_f32_e32 v167, v167, v78
	v_add_f32_e32 v94, v94, v79
	v_add_f32_e32 v167, v167, v80
	v_add_f32_e32 v94, v94, v81
	v_add_f32_e32 v167, v167, v82
	v_add_f32_e32 v94, v94, v83
	v_add_f32_e32 v167, v167, v84
	v_add_f32_e32 v94, v94, v85
	v_add_f32_e32 v167, v167, v86
	v_add_f32_e32 v94, v94, v87
	v_add_f32_e32 v167, v167, v88
	v_add_f32_e32 v94, v94, v89
	v_add_f32_e32 v167, v167, v90
	v_add_f32_e32 v94, v94, v91
	v_add_f32_e32 v167, v167, v92
	v_add_f32_e32 v94, v94, v93
	v_add_f32_e32 v167, v167, v94
	v_mov_b32_e32 v166, v167
	s_nop 1
	v_permlane16_swap_b32_e32 v167, v166
	v_add_f32_e32 v167, v167, v166
	v_mov_b32_e32 v166, v167
	s_nop 1
	v_permlane32_swap_b32_e32 v167, v166
	v_add_f32_e32 v167, v167, v166
	v_add_f32_e32 v167, v167, v95
	v_rcp_f32_e32 v167, v167
	v_mov_b32_e32 v94, 0
	v_mov_b32_e32 v95, 0
	v_mov_b32_e32 v96, 0
	v_mov_b32_e32 v97, 0
	v_cvt_pk_bf16_f32 v58, v58, v59
	v_cvt_pk_bf16_f32 v59, v60, v61
	v_cvt_pk_bf16_f32 v60, v62, v63
	v_cvt_pk_bf16_f32 v61, v64, v65
	v_cvt_pk_bf16_f32 v66, v66, v67
	v_cvt_pk_bf16_f32 v67, v68, v69
	v_cvt_pk_bf16_f32 v68, v70, v71
	v_cvt_pk_bf16_f32 v69, v72, v73
	v_cvt_pk_bf16_f32 v74, v74, v75
	v_cvt_pk_bf16_f32 v75, v76, v77
	v_cvt_pk_bf16_f32 v76, v78, v79
	v_cvt_pk_bf16_f32 v77, v80, v81
	v_cvt_pk_bf16_f32 v82, v82, v83
	v_cvt_pk_bf16_f32 v83, v84, v85
	v_cvt_pk_bf16_f32 v84, v86, v87
	v_cvt_pk_bf16_f32 v85, v88, v89
	v_cvt_pk_bf16_f32 v90, v90, v91
	v_cvt_pk_bf16_f32 v91, v92, v93
	v_cvt_pk_bf16_f32 v92, v94, v95
	v_cvt_pk_bf16_f32 v93, v96, v97
	s_nop 1
	s_waitcnt lgkmcnt(14)
	v_mfma_f32_16x16x32_bf16 v[62:65], v[98:101], v[58:61], 0
	ds_read2_b64 v[158:161], v197 offset0:40 offset1:44
	s_waitcnt lgkmcnt(14)
	v_mfma_f32_16x16x32_bf16 v[70:73], v[102:105], v[58:61], 0
	ds_read2_b64 v[162:165], v194 offset0:48 offset1:52
	s_waitcnt lgkmcnt(14)
	v_mfma_f32_16x16x32_bf16 v[78:81], v[106:109], v[58:61], 0
	ds_read2_b64 v[182:185], v195 offset0:48 offset1:52
	s_waitcnt lgkmcnt(14)
	v_mfma_f32_16x16x32_bf16 v[86:89], v[110:113], v[58:61], 0
	ds_read2_b64 v[186:189], v196 offset0:48 offset1:52
	s_waitcnt lgkmcnt(14)
	v_mfma_f32_16x16x32_bf16 v[62:65], v[114:117], v[66:69], v[62:65]
	ds_read2_b64 v[190:193], v197 offset0:48 offset1:52
	s_waitcnt lgkmcnt(14)
	v_mfma_f32_16x16x32_bf16 v[70:73], v[118:121], v[66:69], v[70:73]
	s_waitcnt lgkmcnt(13)
	v_mfma_f32_16x16x32_bf16 v[78:81], v[122:125], v[66:69], v[78:81]
	s_waitcnt lgkmcnt(12)
	v_mfma_f32_16x16x32_bf16 v[86:89], v[126:129], v[66:69], v[86:89]
	s_waitcnt lgkmcnt(11)
	v_mfma_f32_16x16x32_bf16 v[62:65], v[130:133], v[74:77], v[62:65]
	s_waitcnt lgkmcnt(10)
	v_mfma_f32_16x16x32_bf16 v[70:73], v[134:137], v[74:77], v[70:73]
	s_waitcnt lgkmcnt(9)
	v_mfma_f32_16x16x32_bf16 v[78:81], v[138:141], v[74:77], v[78:81]
	s_waitcnt lgkmcnt(8)
	v_mfma_f32_16x16x32_bf16 v[86:89], v[142:145], v[74:77], v[86:89]
	s_waitcnt lgkmcnt(7)
	v_mfma_f32_16x16x32_bf16 v[62:65], v[146:149], v[82:85], v[62:65]
	s_waitcnt lgkmcnt(6)
	v_mfma_f32_16x16x32_bf16 v[70:73], v[150:153], v[82:85], v[70:73]
	s_waitcnt lgkmcnt(5)
	v_mfma_f32_16x16x32_bf16 v[78:81], v[154:157], v[82:85], v[78:81]
	s_waitcnt lgkmcnt(4)
	v_mfma_f32_16x16x32_bf16 v[86:89], v[158:161], v[82:85], v[86:89]
	s_waitcnt lgkmcnt(3)
	v_mfma_f32_16x16x32_bf16 v[62:65], v[162:165], v[90:93], v[62:65]
	s_waitcnt lgkmcnt(2)
	v_mfma_f32_16x16x32_bf16 v[70:73], v[182:185], v[90:93], v[70:73]
	s_waitcnt lgkmcnt(1)
	v_mfma_f32_16x16x32_bf16 v[78:81], v[186:189], v[90:93], v[78:81]
	s_waitcnt lgkmcnt(0)
	v_mfma_f32_16x16x32_bf16 v[86:89], v[190:193], v[90:93], v[86:89]
	ds_read_b128 v[98:101], v45 offset:11520
	ds_read_b128 v[102:105], v45 offset:11584
	ds_read_b128 v[106:109], v45 offset:13824
	ds_read_b128 v[110:113], v45 offset:13888
	ds_read_b128 v[114:117], v45 offset:16128
	ds_read_b128 v[118:121], v45 offset:16192
	ds_read_b128 v[122:125], v45 offset:18432
	ds_read_b128 v[126:129], v45 offset:18496
	ds_read_b128 v[130:133], v45 offset:20736
	ds_read_b128 v[134:137], v45 offset:20800
	ds_read_b128 v[138:141], v45 offset:23040
	ds_read_b128 v[142:145], v45 offset:23104
	ds_read_b128 v[146:149], v45 offset:25344
	ds_read_b128 v[150:153], v45 offset:25408
	s_nop 7
	v_mul_f32_e32 v62, v62, v167
	v_mul_f32_e32 v63, v63, v167
	v_mul_f32_e32 v64, v64, v167
	v_mul_f32_e32 v65, v65, v167
	v_mul_f32_e32 v70, v70, v167
	v_mul_f32_e32 v71, v71, v167
	v_mul_f32_e32 v72, v72, v167
	v_mul_f32_e32 v73, v73, v167
	v_mul_f32_e32 v78, v78, v167
	v_mul_f32_e32 v79, v79, v167
	v_mul_f32_e32 v80, v80, v167
	v_mul_f32_e32 v81, v81, v167
	v_mul_f32_e32 v86, v86, v167
	v_mul_f32_e32 v87, v87, v167
	v_mul_f32_e32 v88, v88, v167
	v_mul_f32_e32 v89, v89, v167
	v_cvt_pk_bf16_f32 v62, v62, v63
	v_cvt_pk_bf16_f32 v63, v64, v65
	global_store_dwordx2 v48, v[62:63], s[24:25] offset:0
	v_cvt_pk_bf16_f32 v70, v70, v71
	v_cvt_pk_bf16_f32 v71, v72, v73
	global_store_dwordx2 v48, v[70:71], s[24:25] offset:32
	v_cvt_pk_bf16_f32 v78, v78, v79
	v_cvt_pk_bf16_f32 v79, v80, v81
	global_store_dwordx2 v48, v[78:79], s[24:25] offset:64
	v_cvt_pk_bf16_f32 v86, v86, v87
	v_cvt_pk_bf16_f32 v87, v88, v89
	global_store_dwordx2 v48, v[86:87], s[24:25] offset:96
	v_add_u32_e32 v48, 0x8000, v48
	s_waitcnt vmcnt(10)
; __device__ __forceinline__ unsigned cvt_pk_bf16(float lo, float hi) { unsigned r; asm volatile("v_cvt_pk_bf16_f32 %0, %1, %2" : "=v"(r) : "v"(lo), "v"(hi)); return r; }
; #define LAS __attribute__((address_space(3)))
; #define MFMA16(a, b, c) __builtin_amdgcn_mfma_f32_16x16x32_bf16((a), (b), (c), 0, 0, 0)
; __device__ __forceinline__ void p2_block(LAS unsigned char* lds, const bf16_t* __restrict__ PROJ, bf16_t* __restrict__ ATT, bf16_t* __restrict__ SGU, const float* __restrict__ qn, const float* __restrict__ kn, ...
;     ...
;         const int i0 = rbase + 16 * c, irow = i0 + fr, pos = n * 128 + irow; const size_t grow = (size_t)b * pg8::SEQ + pos;
;         bf16x8 qf0, qf1;
;         {
;             float x1[8], x2[8]; unpack8(qa[c], x1); unpack8(qb[c], x2);
;             float ss = 0.f;
; #pragma unroll
;             for (int j = 0; j < 8; ++j) ss += x1[j] * x1[j] + x2[j] * x2[j];
;             ss += __shfl_xor(ss, 16); ss += __shfl_xor(ss, 32);
;             const float rinv = rsqrtf(ss * (1.0f / 64.0f) + pg8::EPS) * 0.125f;
;             const float* cp = COS + pos * 32 + 8 * fq; const float* sp = SIN + pos * 32 + 8 * fq;
;             float o1[8], o2[8];
; #pragma unroll
;             for (int j = 0; j < 8; ++j) { const float a1 = x1[j] * rinv * qn[8 * fq + j], a2 = x2[j] * rinv * qn[32 + 8 * fq + j], cc = cp[j], sn = sp[j]; o1[j] = a1 * cc - a2 * sn; o2[j] = a2 * cc + a1 * sn; }
;             u32x4 w0, w1;
;             w0.x = cvt_pk_bf16(o1[0], o1[1]); w0.y = cvt_pk_bf16(o1[2], o1[3]); w0.z = cvt_pk_bf16(o1[4], o1[5]); w0.w = cvt_pk_bf16(o1[6], o1[7]);
;             w1.x = cvt_pk_bf16(o2[0], o2[1]); w1.y = cvt_pk_bf16(o2[2], o2[3]); w1.z = cvt_pk_bf16(o2[4], o2[5]); w1.w = cvt_pk_bf16(o2[6], o2[7]);
;             qf0 = __builtin_bit_cast(bf16x8, w0); qf1 = __builtin_bit_cast(bf16x8, w1);
;         }
;         const int t0 = (i0 >> 4) < 6 ? (i0 >> 4) : 6;
;         f32x4 sc_[10];
;         const LAS unsigned char* kbase = KS + (16 * t0 + fr) * KS_STRIDE + 16 * fq;
; #pragma unroll
;         for (int t = 0; t < 10; ++t) { const bf16x8 k0 = *(const LAS bf16x8*)(kbase + t * 16 * KS_STRIDE), k1 = *(const LAS bf16x8*)(kbase + t * 16 * KS_STRIDE + 64);
;             f32x4 z = (f32x4){0.f, 0.f, 0.f, 0.f}; z = MFMA16(k0, qf0, z); sc_[t] = MFMA16(k1, qf1, z); }
	v_lshlrev_b32_e32 v58, 16, v218
	v_and_b32_e32 v59, 0xffff0000, v218
	v_lshlrev_b32_e32 v66, 16, v222
	v_and_b32_e32 v67, 0xffff0000, v222
	v_lshlrev_b32_e32 v60, 16, v219
	v_and_b32_e32 v61, 0xffff0000, v219
	v_lshlrev_b32_e32 v68, 16, v223
	v_and_b32_e32 v69, 0xffff0000, v223
	v_lshlrev_b32_e32 v62, 16, v220
	v_and_b32_e32 v63, 0xffff0000, v220
	v_lshlrev_b32_e32 v70, 16, v224
	v_and_b32_e32 v71, 0xffff0000, v224
	v_lshlrev_b32_e32 v64, 16, v221
	v_and_b32_e32 v65, 0xffff0000, v221
	v_lshlrev_b32_e32 v72, 16, v225
	v_and_b32_e32 v73, 0xffff0000, v225
	v_mul_f32_e32 v74, v58, v58
	v_mul_f32_e32 v75, v59, v59
	v_fmac_f32_e32 v74, v60, v60
	v_fmac_f32_e32 v75, v61, v61
	v_fmac_f32_e32 v74, v62, v62
	v_fmac_f32_e32 v75, v63, v63
	v_fmac_f32_e32 v74, v64, v64
	v_fmac_f32_e32 v75, v65, v65
	v_fmac_f32_e32 v74, v66, v66
	v_fmac_f32_e32 v75, v67, v67
	v_fmac_f32_e32 v74, v68, v68
	v_fmac_f32_e32 v75, v69, v69
	v_fmac_f32_e32 v74, v70, v70
	v_fmac_f32_e32 v75, v71, v71
	v_fmac_f32_e32 v74, v72, v72
	v_fmac_f32_e32 v75, v73, v73
	v_add_f32_e32 v74, v74, v75
	v_mov_b32_e32 v166, v74
	s_nop 1
	v_permlane16_swap_b32_e32 v74, v166
	v_add_f32_e32 v74, v74, v166
	v_mov_b32_e32 v166, v74
	s_nop 1
	v_permlane32_swap_b32_e32 v74, v166
	v_add_f32_e32 v74, v74, v166
	v_fmamk_f32 v74, v74, 0x3c800000, v209
	v_rsq_f32_e32 v76, v74
	s_nop 0
	v_mul_f32_e32 v76, 0x3e000000, v76
	v_mul_f32_e32 v58, v58, v76
	v_mul_f32_e32 v66, v66, v76
	v_mul_f32_e32 v59, v59, v76
	v_mul_f32_e32 v67, v67, v76
	v_mul_f32_e32 v60, v60, v76
	v_mul_f32_e32 v68, v68, v76
	v_mul_f32_e32 v61, v61, v76
	v_mul_f32_e32 v69, v69, v76
	v_mul_f32_e32 v62, v62, v76
	v_mul_f32_e32 v70, v70, v76
	v_mul_f32_e32 v63, v63, v76
	v_mul_f32_e32 v71, v71, v76
	v_mul_f32_e32 v64, v64, v76
	v_mul_f32_e32 v72, v72, v76
	v_mul_f32_e32 v65, v65, v76
	v_mul_f32_e32 v73, v73, v76
	v_mul_f32_e32 v58, v58, v26
	v_mul_f32_e32 v66, v66, v34
	v_mul_f32_e32 v59, v59, v27
	v_mul_f32_e32 v67, v67, v35
	v_mul_f32_e32 v60, v60, v28
	v_mul_f32_e32 v68, v68, v36
	v_mul_f32_e32 v61, v61, v29
	v_mul_f32_e32 v69, v69, v37
	v_mul_f32_e32 v62, v62, v30
	v_mul_f32_e32 v70, v70, v38
	v_mul_f32_e32 v63, v63, v31
	v_mul_f32_e32 v71, v71, v39
	v_mul_f32_e32 v64, v64, v32
	v_mul_f32_e32 v72, v72, v40
	v_mul_f32_e32 v65, v65, v33
	v_mul_f32_e32 v73, v73, v41
	v_mul_f32_e32 v78, v66, v234
	v_mul_f32_e32 v86, v58, v234
	v_mul_f32_e32 v79, v67, v235
	v_mul_f32_e32 v87, v59, v235
	v_mul_f32_e32 v80, v68, v236
	v_mul_f32_e32 v88, v60, v236
	v_mul_f32_e32 v81, v69, v237
	v_mul_f32_e32 v89, v61, v237
	v_mul_f32_e32 v82, v70, v238
	v_mul_f32_e32 v90, v62, v238
	v_mul_f32_e32 v83, v71, v239
	v_mul_f32_e32 v91, v63, v239
	v_mul_f32_e32 v84, v72, v240
	v_mul_f32_e32 v92, v64, v240
	v_mul_f32_e32 v85, v73, v241
	v_mul_f32_e32 v93, v65, v241
	v_fma_f32 v78, v58, v226, -v78
	v_fmac_f32_e32 v86, v66, v226
	v_fma_f32 v79, v59, v227, -v79
	v_fmac_f32_e32 v87, v67, v227
	v_fma_f32 v80, v60, v228, -v80
	v_fmac_f32_e32 v88, v68, v228
	v_fma_f32 v81, v61, v229, -v81
	v_fmac_f32_e32 v89, v69, v229
	v_fma_f32 v82, v62, v230, -v82
	v_fmac_f32_e32 v90, v70, v230
	v_fma_f32 v83, v63, v231, -v83
	v_fmac_f32_e32 v91, v71, v231
	v_fma_f32 v84, v64, v232, -v84
	v_fmac_f32_e32 v92, v72, v232
	v_fma_f32 v85, v65, v233, -v85
	v_fmac_f32_e32 v93, v73, v233
	v_cvt_pk_bf16_f32 v50, v78, v79
	v_cvt_pk_bf16_f32 v54, v86, v87
	v_cvt_pk_bf16_f32 v51, v80, v81
	v_cvt_pk_bf16_f32 v55, v88, v89
	v_cvt_pk_bf16_f32 v52, v82, v83
	v_cvt_pk_bf16_f32 v56, v90, v91
	v_cvt_pk_bf16_f32 v53, v84, v85
	v_cvt_pk_bf16_f32 v57, v92, v93
	global_load_dwordx4 v[218:221], v46, s[10:11]
	global_load_dwordx4 v[222:225], v46, s[10:11] offset:64
	global_load_dwordx4 v[226:229], v47, s[6:7]
	global_load_dwordx4 v[230:233], v47, s[6:7] offset:16
	global_load_dwordx4 v[234:237], v47, s[16:17]
	global_load_dwordx4 v[238:241], v47, s[16:17] offset:16
	v_add_u32_e32 v46, 0x3c000, v46
	v_add_u32_e32 v47, 0x800, v47
	s_nop 1
	s_waitcnt lgkmcnt(13)
	v_mfma_f32_16x16x32_bf16 v[58:61], v[98:101], v[50:53], 0
	s_waitcnt lgkmcnt(12)
	v_mfma_f32_16x16x32_bf16 v[58:61], v[102:105], v[54:57], v[58:61]
	ds_read_b128 v[154:157], v45 offset:27648
	ds_read_b128 v[158:161], v45 offset:27712
	s_waitcnt lgkmcnt(13)
	v_mfma_f32_16x16x32_bf16 v[62:65], v[106:109], v[50:53], 0
	s_waitcnt lgkmcnt(12)
	v_mfma_f32_16x16x32_bf16 v[62:65], v[110:113], v[54:57], v[62:65]
	ds_read_b128 v[162:165], v45 offset:29952
	ds_read_b128 v[182:185], v45 offset:30016
	s_waitcnt lgkmcnt(13)
	v_mfma_f32_16x16x32_bf16 v[66:69], v[114:117], v[50:53], 0
	s_waitcnt lgkmcnt(12)
	v_mfma_f32_16x16x32_bf16 v[66:69], v[118:121], v[54:57], v[66:69]
	s_waitcnt lgkmcnt(11)
	v_mfma_f32_16x16x32_bf16 v[70:73], v[122:125], v[50:53], 0
	s_waitcnt lgkmcnt(10)
	v_mfma_f32_16x16x32_bf16 v[70:73], v[126:129], v[54:57], v[70:73]
	s_waitcnt lgkmcnt(9)
	v_mfma_f32_16x16x32_bf16 v[74:77], v[130:133], v[50:53], 0
	s_waitcnt lgkmcnt(8)
	v_mfma_f32_16x16x32_bf16 v[74:77], v[134:137], v[54:57], v[74:77]
	s_waitcnt lgkmcnt(7)
	v_mfma_f32_16x16x32_bf16 v[78:81], v[138:141], v[50:53], 0
	s_waitcnt lgkmcnt(6)
	v_mfma_f32_16x16x32_bf16 v[78:81], v[142:145], v[54:57], v[78:81]
	s_waitcnt lgkmcnt(5)
	v_mfma_f32_16x16x32_bf16 v[82:85], v[146:149], v[50:53], 0
	s_waitcnt lgkmcnt(4)
	v_mfma_f32_16x16x32_bf16 v[82:85], v[150:153], v[54:57], v[82:85]
	s_waitcnt lgkmcnt(3)
	v_mfma_f32_16x16x32_bf16 v[86:89], v[154:157], v[50:53], 0
	s_waitcnt lgkmcnt(2)
	v_mfma_f32_16x16x32_bf16 v[86:89], v[158:161], v[54:57], v[86:89]
	s_waitcnt lgkmcnt(1)
	v_mfma_f32_16x16x32_bf16 v[90:93], v[162:165], v[50:53], 0
	s_waitcnt lgkmcnt(0)
; __device__ __forceinline__ unsigned cvt_pk_bf16(float lo, float hi) { unsigned r; asm volatile("v_cvt_pk_bf16_f32 %0, %1, %2" : "=v"(r) : "v"(lo), "v"(hi)); return r; }
; __device__ __forceinline__ void p2_block(LAS unsigned char* lds, const bf16_t* __restrict__ PROJ, bf16_t* __restrict__ ATT, bf16_t* __restrict__ SGU, const float* __restrict__ qn, const float* __restrict__ kn, ...
;     ...
;         float mx = -1e30f;
; #pragma unroll
;         for (int t = 0; t < 10; ++t)
; #pragma unroll
;             for (int e = 0; e < 4; ++e) { const int kx = 16 * (t0 + t) + 4 * fq + e, d = kx - irow; const bool ok = (d >= 1) && (d <= 128) && (n > 0 || kx >= 128);
;                 const float v = ok ? sc_[t][e] : -1e30f; sc_[t][e] = v; mx = fmaxf(mx, v); }
;         mx = fmaxf(mx, __shfl_xor(mx, 16)); mx = fmaxf(mx, __shfl_xor(mx, 32)); mx = fmaxf(mx, sink);
;         float sum = 0.f;
; #pragma unroll
;         for (int t = 0; t < 10; ++t)
; #pragma unroll
;             for (int e = 0; e < 4; ++e) { const float p = __builtin_amdgcn_exp2f((sc_[t][e] - mx) * LOG2E); sc_[t][e] = p; sum += p; }
;         sum += __shfl_xor(sum, 16); sum += __shfl_xor(sum, 32);
;         const float inv = 1.0f / (sum + __builtin_amdgcn_exp2f((sink - mx) * LOG2E));
;         f32x4 o[4];
; #pragma unroll
;         for (int dt = 0; dt < 4; ++dt) o[dt] = (f32x4){0.f, 0.f, 0.f, 0.f};
; #pragma unroll
;         for (int j = 0; j < 5; ++j) {
;             u32x4 pw; pw.x = cvt_pk_bf16(sc_[2 * j][0], sc_[2 * j][1]); pw.y = cvt_pk_bf16(sc_[2 * j][2], sc_[2 * j][3]); pw.z = cvt_pk_bf16(sc_[2 * j + 1][0], sc_[2 * j + 1][1]); pw.w = cvt_pk_bf16(sc_[2 * j + 1][2], sc_[2 * j + 1][3]);
	v_mfma_f32_16x16x32_bf16 v[90:93], v[182:185], v[54:57], v[90:93]
	ds_read2_b64 v[98:101], v194 offset0:20 offset1:24
	ds_read2_b64 v[102:105], v195 offset0:20 offset1:24
	ds_read2_b64 v[106:109], v196 offset0:20 offset1:24
	ds_read2_b64 v[110:113], v197 offset0:20 offset1:24
	ds_read2_b64 v[114:117], v194 offset0:28 offset1:32
	ds_read2_b64 v[118:121], v195 offset0:28 offset1:32
	ds_read2_b64 v[122:125], v196 offset0:28 offset1:32
	ds_read2_b64 v[126:129], v197 offset0:28 offset1:32
	ds_read2_b64 v[130:133], v194 offset0:36 offset1:40
	ds_read2_b64 v[134:137], v195 offset0:36 offset1:40
	ds_read2_b64 v[138:141], v196 offset0:36 offset1:40
	ds_read2_b64 v[142:145], v197 offset0:36 offset1:40
	ds_read2_b64 v[146:149], v194 offset0:44 offset1:48
	ds_read2_b64 v[150:153], v195 offset0:44 offset1:48
	ds_read2_b64 v[154:157], v196 offset0:44 offset1:48
	s_nop 4
	v_cndmask_b32_e64 v58, v49, v58, s[48:49]
	v_cndmask_b32_e64 v59, v49, v59, s[50:51]
	v_cndmask_b32_e64 v60, v49, v60, s[52:53]
	v_cndmask_b32_e64 v61, v49, v61, s[26:27]
	v_cndmask_b32_e64 v62, v49, v62, s[28:29]
	v_cndmask_b32_e64 v63, v49, v63, s[28:29]
	v_cndmask_b32_e64 v64, v49, v64, s[28:29]
	v_cndmask_b32_e64 v65, v49, v65, s[28:29]
	v_cndmask_b32_e64 v66, v49, v66, s[28:29]
	v_cndmask_b32_e64 v67, v49, v67, s[28:29]
	v_cndmask_b32_e64 v68, v49, v68, s[28:29]
	v_cndmask_b32_e64 v69, v49, v69, s[28:29]
	v_cndmask_b32_e64 v90, v90, v49, s[40:41]
	v_cndmask_b32_e64 v91, v91, v49, s[42:43]
	v_cndmask_b32_e64 v92, v92, v49, s[44:45]
	v_cndmask_b32_e64 v93, v93, v49, s[46:47]
	v_max_f32_e32 v167, v58, v59
	v_max_f32_e32 v94, v60, v61
	v_max3_f32 v167, v167, v62, v63
	v_max3_f32 v94, v94, v64, v65
	v_max3_f32 v167, v167, v66, v67
	v_max3_f32 v94, v94, v68, v69
	v_max3_f32 v167, v167, v70, v71
	v_max3_f32 v94, v94, v72, v73
	v_max3_f32 v167, v167, v74, v75
	v_max3_f32 v94, v94, v76, v77
	v_max3_f32 v167, v167, v78, v79
	v_max3_f32 v94, v94, v80, v81
	v_max3_f32 v167, v167, v82, v83
	v_max3_f32 v94, v94, v84, v85
	v_max3_f32 v167, v167, v86, v87
	v_max3_f32 v94, v94, v88, v89
	v_max3_f32 v167, v167, v90, v91
	v_max3_f32 v94, v94, v92, v93
	v_max_f32_e32 v167, v167, v94
	v_mov_b32_e32 v166, v167
	s_nop 1
	v_permlane16_swap_b32_e32 v167, v166
	v_max_f32_e32 v167, v167, v166
	v_mov_b32_e32 v166, v167
	s_nop 1
	v_permlane32_swap_b32_e32 v167, v166
	v_max_f32_e32 v167, v167, v166
	v_max_f32_e32 v167, v167, v42
	v_mul_f32_e32 v94, 0xbfb8aa3b, v167
	v_fmamk_f32 v58, v58, 0x3fb8aa3b, v94
	v_fmamk_f32 v59, v59, 0x3fb8aa3b, v94
	v_fmamk_f32 v60, v60, 0x3fb8aa3b, v94
	v_fmamk_f32 v61, v61, 0x3fb8aa3b, v94
	v_fmamk_f32 v62, v62, 0x3fb8aa3b, v94
	v_fmamk_f32 v63, v63, 0x3fb8aa3b, v94
	v_fmamk_f32 v64, v64, 0x3fb8aa3b, v94
	v_fmamk_f32 v65, v65, 0x3fb8aa3b, v94
	v_fmamk_f32 v66, v66, 0x3fb8aa3b, v94
	v_fmamk_f32 v67, v67, 0x3fb8aa3b, v94
	v_fmamk_f32 v68, v68, 0x3fb8aa3b, v94
	v_fmamk_f32 v69, v69, 0x3fb8aa3b, v94
	v_fmamk_f32 v70, v70, 0x3fb8aa3b, v94
	v_fmamk_f32 v71, v71, 0x3fb8aa3b, v94
	v_fmamk_f32 v72, v72, 0x3fb8aa3b, v94
	v_fmamk_f32 v73, v73, 0x3fb8aa3b, v94
	v_fmamk_f32 v74, v74, 0x3fb8aa3b, v94
	v_fmamk_f32 v75, v75, 0x3fb8aa3b, v94
	v_fmamk_f32 v76, v76, 0x3fb8aa3b, v94
	v_fmamk_f32 v77, v77, 0x3fb8aa3b, v94
	v_fmamk_f32 v78, v78, 0x3fb8aa3b, v94
	v_fmamk_f32 v79, v79, 0x3fb8aa3b, v94
	v_fmamk_f32 v80, v80, 0x3fb8aa3b, v94
	v_fmamk_f32 v81, v81, 0x3fb8aa3b, v94
	v_fmamk_f32 v82, v82, 0x3fb8aa3b, v94
	v_fmamk_f32 v83, v83, 0x3fb8aa3b, v94
	v_fmamk_f32 v84, v84, 0x3fb8aa3b, v94
	v_fmamk_f32 v85, v85, 0x3fb8aa3b, v94
	v_fmamk_f32 v86, v86, 0x3fb8aa3b, v94
	v_fmamk_f32 v87, v87, 0x3fb8aa3b, v94
	v_fmamk_f32 v88, v88, 0x3fb8aa3b, v94
	v_fmamk_f32 v89, v89, 0x3fb8aa3b, v94
	v_fmamk_f32 v90, v90, 0x3fb8aa3b, v94
	v_fmamk_f32 v91, v91, 0x3fb8aa3b, v94
	v_fmamk_f32 v92, v92, 0x3fb8aa3b, v94
	v_fmamk_f32 v93, v93, 0x3fb8aa3b, v94
	v_exp_f32_e32 v58, v58
	v_exp_f32_e32 v59, v59
	v_exp_f32_e32 v60, v60
	v_exp_f32_e32 v61, v61
	v_exp_f32_e32 v62, v62
	v_exp_f32_e32 v63, v63
	v_exp_f32_e32 v64, v64
	v_exp_f32_e32 v65, v65
	v_exp_f32_e32 v66, v66
	v_exp_f32_e32 v67, v67
	v_exp_f32_e32 v68, v68
	v_exp_f32_e32 v69, v69
	v_exp_f32_e32 v70, v70
	v_exp_f32_e32 v71, v71
	v_exp_f32_e32 v72, v72
	v_exp_f32_e32 v73, v73
	v_exp_f32_e32 v74, v74
	v_exp_f32_e32 v75, v75
	v_exp_f32_e32 v76, v76
	v_exp_f32_e32 v77, v77
	v_exp_f32_e32 v78, v78
	v_exp_f32_e32 v79, v79
	v_exp_f32_e32 v80, v80
	v_exp_f32_e32 v81, v81
	v_exp_f32_e32 v82, v82
	v_exp_f32_e32 v83, v83
	v_exp_f32_e32 v84, v84
	v_exp_f32_e32 v85, v85
	v_exp_f32_e32 v86, v86
	v_exp_f32_e32 v87, v87
	v_exp_f32_e32 v88, v88
	v_exp_f32_e32 v89, v89
	v_exp_f32_e32 v90, v90
	v_exp_f32_e32 v91, v91
	v_exp_f32_e32 v92, v92
	v_exp_f32_e32 v93, v93
	v_fmamk_f32 v95, v42, 0x3fb8aa3b, v94
	v_exp_f32_e32 v95, v95
	v_add_f32_e32 v167, v58, v59
	v_add_f32_e32 v94, v60, v61
	v_add_f32_e32 v167, v167, v62
	v_add_f32_e32 v94, v94, v63
	v_add_f32_e32 v167, v167, v64
	v_add_f32_e32 v94, v94, v65
	v_add_f32_e32 v167, v167, v66
	v_add_f32_e32 v94, v94, v67
	v_add_f32_e32 v167, v167, v68
	v_add_f32_e32 v94, v94, v69
	v_add_f32_e32 v167, v167, v70
	v_add_f32_e32 v94, v94, v71
	v_add_f32_e32 v167, v167, v72
	v_add_f32_e32 v94, v94, v73
	v_add_f32_e32 v167, v167, v74
	v_add_f32_e32 v94, v94, v75
	v_add_f32_e32 v167, v167, v76
	v_add_f32_e32 v94, v94, v77
	v_add_f32_e32 v167, v167, v78
	v_add_f32_e32 v94, v94, v79
	v_add_f32_e32 v167, v167, v80
	v_add_f32_e32 v94, v94, v81
	v_add_f32_e32 v167, v167, v82
	v_add_f32_e32 v94, v94, v83
	v_add_f32_e32 v167, v167, v84
	v_add_f32_e32 v94, v94, v85
	v_add_f32_e32 v167, v167, v86
	v_add_f32_e32 v94, v94, v87
	v_add_f32_e32 v167, v167, v88
	v_add_f32_e32 v94, v94, v89
	v_add_f32_e32 v167, v167, v90
	v_add_f32_e32 v94, v94, v91
	v_add_f32_e32 v167, v167, v92
	v_add_f32_e32 v94, v94, v93
	v_add_f32_e32 v167, v167, v94
	v_mov_b32_e32 v166, v167
	s_nop 1
	v_permlane16_swap_b32_e32 v167, v166
	v_add_f32_e32 v167, v167, v166
	v_mov_b32_e32 v166, v167
	s_nop 1
	v_permlane32_swap_b32_e32 v167, v166
	v_add_f32_e32 v167, v167, v166
	v_add_f32_e32 v167, v167, v95
	v_rcp_f32_e32 v167, v167
	v_mov_b32_e32 v94, 0
	v_mov_b32_e32 v95, 0
	v_mov_b32_e32 v96, 0
	v_mov_b32_e32 v97, 0
	v_cvt_pk_bf16_f32 v58, v58, v59
	v_cvt_pk_bf16_f32 v59, v60, v61
	v_cvt_pk_bf16_f32 v60, v62, v63
	v_cvt_pk_bf16_f32 v61, v64, v65
	v_cvt_pk_bf16_f32 v66, v66, v67
	v_cvt_pk_bf16_f32 v67, v68, v69
	v_cvt_pk_bf16_f32 v68, v70, v71
	v_cvt_pk_bf16_f32 v69, v72, v73
	v_cvt_pk_bf16_f32 v74, v74, v75
	v_cvt_pk_bf16_f32 v75, v76, v77
	v_cvt_pk_bf16_f32 v76, v78, v79
	v_cvt_pk_bf16_f32 v77, v80, v81
	v_cvt_pk_bf16_f32 v82, v82, v83
	v_cvt_pk_bf16_f32 v83, v84, v85
	v_cvt_pk_bf16_f32 v84, v86, v87
	v_cvt_pk_bf16_f32 v85, v88, v89
	v_cvt_pk_bf16_f32 v90, v90, v91
	v_cvt_pk_bf16_f32 v91, v92, v93
	v_cvt_pk_bf16_f32 v92, v94, v95
	v_cvt_pk_bf16_f32 v93, v96, v97
	s_nop 1
	s_waitcnt lgkmcnt(14)
; #define LAS __attribute__((address_space(3)))
; __device__ __forceinline__ void p2_block(LAS unsigned char* lds, const bf16_t* __restrict__ PROJ, bf16_t* __restrict__ ATT, bf16_t* __restrict__ SGU, const float* __restrict__ qn, const float* __restrict__ kn, ...
;     ...
;         const int i0 = rbase + 16 * c, irow = i0 + fr, pos = n * 128 + irow; const size_t grow = (size_t)b * pg8::SEQ + pos;
;         bf16x8 qf0, qf1;
;         {
;             float x1[8], x2[8]; unpack8(qa[c], x1); unpack8(qb[c], x2);
;             float ss = 0.f;
; #pragma unroll
;             for (int j = 0; j < 8; ++j) ss += x1[j] * x1[j] + x2[j] * x2[j];
;             ss += __shfl_xor(ss, 16); ss += __shfl_xor(ss, 32);
;             const float rinv = rsqrtf(ss * (1.0f / 64.0f) + pg8::EPS) * 0.125f;
;             const float* cp = COS + pos * 32 + 8 * fq; const float* sp = SIN + pos * 32 + 8 * fq;
;             float o1[8], o2[8];
; #pragma unroll
;             for (int j = 0; j < 8; ++j) { const float a1 = x1[j] * rinv * qn[8 * fq + j], a2 = x2[j] * rinv * qn[32 + 8 * fq + j], cc = cp[j], sn = sp[j]; o1[j] = a1 * cc - a2 * sn; o2[j] = a2 * cc + a1 * sn; }
;             u32x4 w0, w1;
;             w0.x = cvt_pk_bf16(o1[0], o1[1]); w0.y = cvt_pk_bf16(o1[2], o1[3]); w0.z = cvt_pk_bf16(o1[4], o1[5]); w0.w = cvt_pk_bf16(o1[6], o1[7]);
;     ...
;         for (int j = 0; j < 5; ++j) {
;             u32x4 pw; pw.x = cvt_pk_bf16(sc_[2 * j][0], sc_[2 * j][1]); pw.y = cvt_pk_bf16(sc_[2 * j][2], sc_[2 * j][3]); pw.z = cvt_pk_bf16(sc_[2 * j + 1][0], sc_[2 * j + 1][1]); pw.w = cvt_pk_bf16(sc_[2 * j + 1][2], sc_[2 * j + 1][3]);
;             const bf16x8 pf = __builtin_bit_cast(bf16x8, pw);
; #pragma unroll
;             for (int dt = 0; dt < 4; ++dt) { const LAS unsigned char* vb = VT + (16 * dt + fr) * VT_STRIDE + (16 * (t0 + 2 * j) + 4 * fq) * 2;
;                 const u32x2 va = *(const LAS u32x2*)vb, vc = *(const LAS u32x2*)(vb + 32); u32x4 vw; vw.x = va.x; vw.y = va.y; vw.z = vc.x; vw.w = vc.y;
;                 o[dt] = MFMA16(__builtin_bit_cast(bf16x8, vw), pf, o[dt]); }
;         }
;         bf16_t* op = ATT + grow * 1024 + hq * 64 + 4 * fq;
; #pragma unroll
;         for (int dt = 0; dt < 4; ++dt) { u32x2 ow; ow.x = cvt_pk_bf16(o[dt][0] * inv, o[dt][1] * inv); ow.y = cvt_pk_bf16(o[dt][2] * inv, o[dt][3] * inv); *(u32x2*)(op + 16 * dt) = ow; }
	v_mfma_f32_16x16x32_bf16 v[62:65], v[98:101], v[58:61], 0
	ds_read2_b64 v[158:161], v197 offset0:44 offset1:48
	s_waitcnt lgkmcnt(14)
	v_mfma_f32_16x16x32_bf16 v[70:73], v[102:105], v[58:61], 0
	ds_read2_b64 v[162:165], v194 offset0:52 offset1:56
	s_waitcnt lgkmcnt(14)
	v_mfma_f32_16x16x32_bf16 v[78:81], v[106:109], v[58:61], 0
	ds_read2_b64 v[182:185], v195 offset0:52 offset1:56
	s_waitcnt lgkmcnt(14)
	v_mfma_f32_16x16x32_bf16 v[86:89], v[110:113], v[58:61], 0
	ds_read2_b64 v[186:189], v196 offset0:52 offset1:56
	s_waitcnt lgkmcnt(14)
	v_mfma_f32_16x16x32_bf16 v[62:65], v[114:117], v[66:69], v[62:65]
	ds_read2_b64 v[190:193], v197 offset0:52 offset1:56
	s_waitcnt lgkmcnt(14)
	v_mfma_f32_16x16x32_bf16 v[70:73], v[118:121], v[66:69], v[70:73]
	s_waitcnt lgkmcnt(13)
	v_mfma_f32_16x16x32_bf16 v[78:81], v[122:125], v[66:69], v[78:81]
	s_waitcnt lgkmcnt(12)
	v_mfma_f32_16x16x32_bf16 v[86:89], v[126:129], v[66:69], v[86:89]
	s_waitcnt lgkmcnt(11)
	v_mfma_f32_16x16x32_bf16 v[62:65], v[130:133], v[74:77], v[62:65]
	s_waitcnt lgkmcnt(10)
	v_mfma_f32_16x16x32_bf16 v[70:73], v[134:137], v[74:77], v[70:73]
	s_waitcnt lgkmcnt(9)
	v_mfma_f32_16x16x32_bf16 v[78:81], v[138:141], v[74:77], v[78:81]
	s_waitcnt lgkmcnt(8)
	v_mfma_f32_16x16x32_bf16 v[86:89], v[142:145], v[74:77], v[86:89]
	s_waitcnt lgkmcnt(7)
	v_mfma_f32_16x16x32_bf16 v[62:65], v[146:149], v[82:85], v[62:65]
	s_waitcnt lgkmcnt(6)
	v_mfma_f32_16x16x32_bf16 v[70:73], v[150:153], v[82:85], v[70:73]
	s_waitcnt lgkmcnt(5)
	v_mfma_f32_16x16x32_bf16 v[78:81], v[154:157], v[82:85], v[78:81]
	s_waitcnt lgkmcnt(4)
	v_mfma_f32_16x16x32_bf16 v[86:89], v[158:161], v[82:85], v[86:89]
	s_waitcnt lgkmcnt(3)
	v_mfma_f32_16x16x32_bf16 v[62:65], v[162:165], v[90:93], v[62:65]
	s_waitcnt lgkmcnt(2)
	v_mfma_f32_16x16x32_bf16 v[70:73], v[182:185], v[90:93], v[70:73]
	s_waitcnt lgkmcnt(1)
	v_mfma_f32_16x16x32_bf16 v[78:81], v[186:189], v[90:93], v[78:81]
	s_waitcnt lgkmcnt(0)
	v_mfma_f32_16x16x32_bf16 v[86:89], v[190:193], v[90:93], v[86:89]
	ds_read_b128 v[98:101], v45 offset:13824
	ds_read_b128 v[102:105], v45 offset:13888
	ds_read_b128 v[106:109], v45 offset:16128
	ds_read_b128 v[110:113], v45 offset:16192
	ds_read_b128 v[114:117], v45 offset:18432
	ds_read_b128 v[118:121], v45 offset:18496
	ds_read_b128 v[122:125], v45 offset:20736
	ds_read_b128 v[126:129], v45 offset:20800
	ds_read_b128 v[130:133], v45 offset:23040
	ds_read_b128 v[134:137], v45 offset:23104
	ds_read_b128 v[138:141], v45 offset:25344
	ds_read_b128 v[142:145], v45 offset:25408
	ds_read_b128 v[146:149], v45 offset:27648
	ds_read_b128 v[150:153], v45 offset:27712
	s_nop 7
	v_mul_f32_e32 v62, v62, v167
	v_mul_f32_e32 v63, v63, v167
	v_mul_f32_e32 v64, v64, v167
	v_mul_f32_e32 v65, v65, v167
	v_mul_f32_e32 v70, v70, v167
	v_mul_f32_e32 v71, v71, v167
	v_mul_f32_e32 v72, v72, v167
	v_mul_f32_e32 v73, v73, v167
	v_mul_f32_e32 v78, v78, v167
	v_mul_f32_e32 v79, v79, v167
	v_mul_f32_e32 v80, v80, v167
	v_mul_f32_e32 v81, v81, v167
	v_mul_f32_e32 v86, v86, v167
	v_mul_f32_e32 v87, v87, v167
	v_mul_f32_e32 v88, v88, v167
	v_mul_f32_e32 v89, v89, v167
	v_cvt_pk_bf16_f32 v62, v62, v63
	v_cvt_pk_bf16_f32 v63, v64, v65
	global_store_dwordx2 v48, v[62:63], s[24:25] offset:0
	v_cvt_pk_bf16_f32 v70, v70, v71
	v_cvt_pk_bf16_f32 v71, v72, v73
	global_store_dwordx2 v48, v[70:71], s[24:25] offset:32
	v_cvt_pk_bf16_f32 v78, v78, v79
	v_cvt_pk_bf16_f32 v79, v80, v81
	global_store_dwordx2 v48, v[78:79], s[24:25] offset:64
	v_cvt_pk_bf16_f32 v86, v86, v87
	v_cvt_pk_bf16_f32 v87, v88, v89
	global_store_dwordx2 v48, v[86:87], s[24:25] offset:96
	v_add_u32_e32 v48, 0x8000, v48
	s_waitcnt vmcnt(14)
	v_lshlrev_b32_e32 v58, 16, v2
	v_and_b32_e32 v59, 0xffff0000, v2
	v_lshlrev_b32_e32 v66, 16, v6
	v_and_b32_e32 v67, 0xffff0000, v6
	v_lshlrev_b32_e32 v60, 16, v3
	v_and_b32_e32 v61, 0xffff0000, v3
	v_lshlrev_b32_e32 v68, 16, v7
	v_and_b32_e32 v69, 0xffff0000, v7
	v_lshlrev_b32_e32 v62, 16, v4
	v_and_b32_e32 v63, 0xffff0000, v4
	v_lshlrev_b32_e32 v70, 16, v8
	v_and_b32_e32 v71, 0xffff0000, v8
	v_lshlrev_b32_e32 v64, 16, v5
	v_and_b32_e32 v65, 0xffff0000, v5
	v_lshlrev_b32_e32 v72, 16, v9
	v_and_b32_e32 v73, 0xffff0000, v9
	v_mul_f32_e32 v74, v58, v58
	v_mul_f32_e32 v75, v59, v59
	v_fmac_f32_e32 v74, v60, v60
	v_fmac_f32_e32 v75, v61, v61
	v_fmac_f32_e32 v74, v62, v62
	v_fmac_f32_e32 v75, v63, v63
	v_fmac_f32_e32 v74, v64, v64
	v_fmac_f32_e32 v75, v65, v65
	v_fmac_f32_e32 v74, v66, v66
	v_fmac_f32_e32 v75, v67, v67
	v_fmac_f32_e32 v74, v68, v68
	v_fmac_f32_e32 v75, v69, v69
	v_fmac_f32_e32 v74, v70, v70
	v_fmac_f32_e32 v75, v71, v71
	v_fmac_f32_e32 v74, v72, v72
	v_fmac_f32_e32 v75, v73, v73
	v_add_f32_e32 v74, v74, v75
	v_mov_b32_e32 v166, v74
	s_nop 1
	v_permlane16_swap_b32_e32 v74, v166
	v_add_f32_e32 v74, v74, v166
	v_mov_b32_e32 v166, v74
	s_nop 1
	v_permlane32_swap_b32_e32 v74, v166
	v_add_f32_e32 v74, v74, v166
	v_fmamk_f32 v74, v74, 0x3c800000, v209
	v_rsq_f32_e32 v76, v74
	s_nop 0
	v_mul_f32_e32 v76, 0x3e000000, v76
	v_mul_f32_e32 v58, v58, v76
	v_mul_f32_e32 v66, v66, v76
	v_mul_f32_e32 v59, v59, v76
	v_mul_f32_e32 v67, v67, v76
	v_mul_f32_e32 v60, v60, v76
	v_mul_f32_e32 v68, v68, v76
	v_mul_f32_e32 v61, v61, v76
	v_mul_f32_e32 v69, v69, v76
	v_mul_f32_e32 v62, v62, v76
	v_mul_f32_e32 v70, v70, v76
	v_mul_f32_e32 v63, v63, v76
	v_mul_f32_e32 v71, v71, v76
	v_mul_f32_e32 v64, v64, v76
	v_mul_f32_e32 v72, v72, v76
	v_mul_f32_e32 v65, v65, v76
	v_mul_f32_e32 v73, v73, v76
	v_mul_f32_e32 v58, v58, v26
	v_mul_f32_e32 v66, v66, v34
	v_mul_f32_e32 v59, v59, v27
	v_mul_f32_e32 v67, v67, v35
	v_mul_f32_e32 v60, v60, v28
	v_mul_f32_e32 v68, v68, v36
	v_mul_f32_e32 v61, v61, v29
; __device__ __forceinline__ unsigned cvt_pk_bf16(float lo, float hi) { unsigned r; asm volatile("v_cvt_pk_bf16_f32 %0, %1, %2" : "=v"(r) : "v"(lo), "v"(hi)); return r; }
; #define LAS __attribute__((address_space(3)))
; #define MFMA16(a, b, c) __builtin_amdgcn_mfma_f32_16x16x32_bf16((a), (b), (c), 0, 0, 0)
; __device__ __forceinline__ void p2_block(LAS unsigned char* lds, const bf16_t* __restrict__ PROJ, bf16_t* __restrict__ ATT, bf16_t* __restrict__ SGU, const float* __restrict__ qn, const float* __restrict__ kn, ...
;     ...
;             float o1[8], o2[8];
; #pragma unroll
;             for (int j = 0; j < 8; ++j) { const float a1 = x1[j] * rinv * qn[8 * fq + j], a2 = x2[j] * rinv * qn[32 + 8 * fq + j], cc = cp[j], sn = sp[j]; o1[j] = a1 * cc - a2 * sn; o2[j] = a2 * cc + a1 * sn; }
;             u32x4 w0, w1;
;             w0.x = cvt_pk_bf16(o1[0], o1[1]); w0.y = cvt_pk_bf16(o1[2], o1[3]); w0.z = cvt_pk_bf16(o1[4], o1[5]); w0.w = cvt_pk_bf16(o1[6], o1[7]);
;             w1.x = cvt_pk_bf16(o2[0], o2[1]); w1.y = cvt_pk_bf16(o2[2], o2[3]); w1.z = cvt_pk_bf16(o2[4], o2[5]); w1.w = cvt_pk_bf16(o2[6], o2[7]);
;             qf0 = __builtin_bit_cast(bf16x8, w0); qf1 = __builtin_bit_cast(bf16x8, w1);
;         }
;         const int t0 = (i0 >> 4) < 6 ? (i0 >> 4) : 6;
;         f32x4 sc_[10];
;         const LAS unsigned char* kbase = KS + (16 * t0 + fr) * KS_STRIDE + 16 * fq;
; #pragma unroll
;         for (int t = 0; t < 10; ++t) { const bf16x8 k0 = *(const LAS bf16x8*)(kbase + t * 16 * KS_STRIDE), k1 = *(const LAS bf16x8*)(kbase + t * 16 * KS_STRIDE + 64);
;             f32x4 z = (f32x4){0.f, 0.f, 0.f, 0.f}; z = MFMA16(k0, qf0, z); sc_[t] = MFMA16(k1, qf1, z); }
;         float mx = -1e30f;
; #pragma unroll
;         for (int t = 0; t < 10; ++t)
; #pragma unroll
;             for (int e = 0; e < 4; ++e) { const int kx = 16 * (t0 + t) + 4 * fq + e, d = kx - irow; const bool ok = (d >= 1) && (d <= 128) && (n > 0 || kx >= 128);
;                 const float v = ok ? sc_[t][e] : -1e30f; sc_[t][e] = v; mx = fmaxf(mx, v); }
;         mx = fmaxf(mx, __shfl_xor(mx, 16)); mx = fmaxf(mx, __shfl_xor(mx, 32)); mx = fmaxf(mx, sink);
	v_mul_f32_e32 v69, v69, v37
	v_mul_f32_e32 v62, v62, v30
	v_mul_f32_e32 v70, v70, v38
	v_mul_f32_e32 v63, v63, v31
	v_mul_f32_e32 v71, v71, v39
	v_mul_f32_e32 v64, v64, v32
	v_mul_f32_e32 v72, v72, v40
	v_mul_f32_e32 v65, v65, v33
	v_mul_f32_e32 v73, v73, v41
	v_mul_f32_e32 v78, v66, v18
	v_mul_f32_e32 v86, v58, v18
	v_mul_f32_e32 v79, v67, v19
	v_mul_f32_e32 v87, v59, v19
	v_mul_f32_e32 v80, v68, v20
	v_mul_f32_e32 v88, v60, v20
	v_mul_f32_e32 v81, v69, v21
	v_mul_f32_e32 v89, v61, v21
	v_mul_f32_e32 v82, v70, v22
	v_mul_f32_e32 v90, v62, v22
	v_mul_f32_e32 v83, v71, v23
	v_mul_f32_e32 v91, v63, v23
	v_mul_f32_e32 v84, v72, v24
	v_mul_f32_e32 v92, v64, v24
	v_mul_f32_e32 v85, v73, v25
	v_mul_f32_e32 v93, v65, v25
	v_fma_f32 v78, v58, v10, -v78
	v_fmac_f32_e32 v86, v66, v10
	v_fma_f32 v79, v59, v11, -v79
	v_fmac_f32_e32 v87, v67, v11
	v_fma_f32 v80, v60, v12, -v80
	v_fmac_f32_e32 v88, v68, v12
	v_fma_f32 v81, v61, v13, -v81
	v_fmac_f32_e32 v89, v69, v13
	v_fma_f32 v82, v62, v14, -v82
	v_fmac_f32_e32 v90, v70, v14
	v_fma_f32 v83, v63, v15, -v83
	v_fmac_f32_e32 v91, v71, v15
	v_fma_f32 v84, v64, v16, -v84
	v_fmac_f32_e32 v92, v72, v16
	v_fma_f32 v85, v65, v17, -v85
	v_fmac_f32_e32 v93, v73, v17
	v_cvt_pk_bf16_f32 v50, v78, v79
	v_cvt_pk_bf16_f32 v54, v86, v87
	v_cvt_pk_bf16_f32 v51, v80, v81
	v_cvt_pk_bf16_f32 v55, v88, v89
	v_cvt_pk_bf16_f32 v52, v82, v83
	v_cvt_pk_bf16_f32 v56, v90, v91
	v_cvt_pk_bf16_f32 v53, v84, v85
	v_cvt_pk_bf16_f32 v57, v92, v93
	s_nop 1
	s_waitcnt lgkmcnt(13)
	v_mfma_f32_16x16x32_bf16 v[58:61], v[98:101], v[50:53], 0
	s_waitcnt lgkmcnt(12)
	v_mfma_f32_16x16x32_bf16 v[58:61], v[102:105], v[54:57], v[58:61]
	ds_read_b128 v[154:157], v45 offset:29952
	ds_read_b128 v[158:161], v45 offset:30016
	s_waitcnt lgkmcnt(13)
	v_mfma_f32_16x16x32_bf16 v[62:65], v[106:109], v[50:53], 0
	s_waitcnt lgkmcnt(12)
	v_mfma_f32_16x16x32_bf16 v[62:65], v[110:113], v[54:57], v[62:65]
	ds_read_b128 v[162:165], v45 offset:32256
	ds_read_b128 v[182:185], v45 offset:32320
	s_waitcnt lgkmcnt(13)
	v_mfma_f32_16x16x32_bf16 v[66:69], v[114:117], v[50:53], 0
	s_waitcnt lgkmcnt(12)
	v_mfma_f32_16x16x32_bf16 v[66:69], v[118:121], v[54:57], v[66:69]
	s_waitcnt lgkmcnt(11)
	v_mfma_f32_16x16x32_bf16 v[70:73], v[122:125], v[50:53], 0
	s_waitcnt lgkmcnt(10)
	v_mfma_f32_16x16x32_bf16 v[70:73], v[126:129], v[54:57], v[70:73]
	s_waitcnt lgkmcnt(9)
	v_mfma_f32_16x16x32_bf16 v[74:77], v[130:133], v[50:53], 0
	s_waitcnt lgkmcnt(8)
	v_mfma_f32_16x16x32_bf16 v[74:77], v[134:137], v[54:57], v[74:77]
	s_waitcnt lgkmcnt(7)
	v_mfma_f32_16x16x32_bf16 v[78:81], v[138:141], v[50:53], 0
	s_waitcnt lgkmcnt(6)
	v_mfma_f32_16x16x32_bf16 v[78:81], v[142:145], v[54:57], v[78:81]
	s_waitcnt lgkmcnt(5)
	v_mfma_f32_16x16x32_bf16 v[82:85], v[146:149], v[50:53], 0
	s_waitcnt lgkmcnt(4)
	v_mfma_f32_16x16x32_bf16 v[82:85], v[150:153], v[54:57], v[82:85]
	s_waitcnt lgkmcnt(3)
	v_mfma_f32_16x16x32_bf16 v[86:89], v[154:157], v[50:53], 0
	s_waitcnt lgkmcnt(2)
	v_mfma_f32_16x16x32_bf16 v[86:89], v[158:161], v[54:57], v[86:89]
	s_waitcnt lgkmcnt(1)
	v_mfma_f32_16x16x32_bf16 v[90:93], v[162:165], v[50:53], 0
	s_waitcnt lgkmcnt(0)
	v_mfma_f32_16x16x32_bf16 v[90:93], v[182:185], v[54:57], v[90:93]
	ds_read2_b64 v[98:101], v194 offset0:24 offset1:28
	ds_read2_b64 v[102:105], v195 offset0:24 offset1:28
	ds_read2_b64 v[106:109], v196 offset0:24 offset1:28
	ds_read2_b64 v[110:113], v197 offset0:24 offset1:28
	ds_read2_b64 v[114:117], v194 offset0:32 offset1:36
	ds_read2_b64 v[118:121], v195 offset0:32 offset1:36
	ds_read2_b64 v[122:125], v196 offset0:32 offset1:36
	ds_read2_b64 v[126:129], v197 offset0:32 offset1:36
	ds_read2_b64 v[130:133], v194 offset0:40 offset1:44
	ds_read2_b64 v[134:137], v195 offset0:40 offset1:44
	ds_read2_b64 v[138:141], v196 offset0:40 offset1:44
	ds_read2_b64 v[142:145], v197 offset0:40 offset1:44
	ds_read2_b64 v[146:149], v194 offset0:48 offset1:52
	ds_read2_b64 v[150:153], v195 offset0:48 offset1:52
	ds_read2_b64 v[154:157], v196 offset0:48 offset1:52
	s_nop 4
	v_cndmask_b32_e64 v58, v49, v58, s[48:49]
	v_cndmask_b32_e64 v59, v49, v59, s[50:51]
	v_cndmask_b32_e64 v60, v49, v60, s[52:53]
	v_cndmask_b32_e64 v61, v49, v61, s[26:27]
	v_cndmask_b32_e64 v62, v49, v62, s[28:29]
	v_cndmask_b32_e64 v63, v49, v63, s[28:29]
	v_cndmask_b32_e64 v64, v49, v64, s[28:29]
	v_cndmask_b32_e64 v65, v49, v65, s[28:29]
	v_cndmask_b32_e64 v90, v90, v49, s[40:41]
	v_cndmask_b32_e64 v91, v91, v49, s[42:43]
	v_cndmask_b32_e64 v92, v92, v49, s[44:45]
	v_cndmask_b32_e64 v93, v93, v49, s[46:47]
	v_max_f32_e32 v167, v58, v59
	v_max_f32_e32 v94, v60, v61
	v_max3_f32 v167, v167, v62, v63
	v_max3_f32 v94, v94, v64, v65
	v_max3_f32 v167, v167, v66, v67
	v_max3_f32 v94, v94, v68, v69
	v_max3_f32 v167, v167, v70, v71
	v_max3_f32 v94, v94, v72, v73
	v_max3_f32 v167, v167, v74, v75
	v_max3_f32 v94, v94, v76, v77
	v_max3_f32 v167, v167, v78, v79
	v_max3_f32 v94, v94, v80, v81
	v_max3_f32 v167, v167, v82, v83
	v_max3_f32 v94, v94, v84, v85
	v_max3_f32 v167, v167, v86, v87
	v_max3_f32 v94, v94, v88, v89
	v_max3_f32 v167, v167, v90, v91
	v_max3_f32 v94, v94, v92, v93
	v_max_f32_e32 v167, v167, v94
	v_mov_b32_e32 v166, v167
	s_nop 1
	v_permlane16_swap_b32_e32 v167, v166
	v_max_f32_e32 v167, v167, v166
	v_mov_b32_e32 v166, v167
	s_nop 1
	v_permlane32_swap_b32_e32 v167, v166
	v_max_f32_e32 v167, v167, v166
	v_max_f32_e32 v167, v167, v42
	v_mul_f32_e32 v94, 0xbfb8aa3b, v167
	v_fmamk_f32 v58, v58, 0x3fb8aa3b, v94
	v_fmamk_f32 v59, v59, 0x3fb8aa3b, v94
	v_fmamk_f32 v60, v60, 0x3fb8aa3b, v94
	v_fmamk_f32 v61, v61, 0x3fb8aa3b, v94
	v_fmamk_f32 v62, v62, 0x3fb8aa3b, v94
	v_fmamk_f32 v63, v63, 0x3fb8aa3b, v94
; __device__ __forceinline__ unsigned cvt_pk_bf16(float lo, float hi) { unsigned r; asm volatile("v_cvt_pk_bf16_f32 %0, %1, %2" : "=v"(r) : "v"(lo), "v"(hi)); return r; }
; #define LAS __attribute__((address_space(3)))
; #define MFMA16(a, b, c) __builtin_amdgcn_mfma_f32_16x16x32_bf16((a), (b), (c), 0, 0, 0)
; __device__ __forceinline__ void p2_block(LAS unsigned char* lds, const bf16_t* __restrict__ PROJ, bf16_t* __restrict__ ATT, bf16_t* __restrict__ SGU, const float* __restrict__ qn, const float* __restrict__ kn, ...
;     ...
;         float sum = 0.f;
; #pragma unroll
;         for (int t = 0; t < 10; ++t)
; #pragma unroll
;             for (int e = 0; e < 4; ++e) { const float p = __builtin_amdgcn_exp2f((sc_[t][e] - mx) * LOG2E); sc_[t][e] = p; sum += p; }
;         sum += __shfl_xor(sum, 16); sum += __shfl_xor(sum, 32);
;         const float inv = 1.0f / (sum + __builtin_amdgcn_exp2f((sink - mx) * LOG2E));
;         f32x4 o[4];
; #pragma unroll
;         for (int dt = 0; dt < 4; ++dt) o[dt] = (f32x4){0.f, 0.f, 0.f, 0.f};
; #pragma unroll
;         for (int j = 0; j < 5; ++j) {
;             u32x4 pw; pw.x = cvt_pk_bf16(sc_[2 * j][0], sc_[2 * j][1]); pw.y = cvt_pk_bf16(sc_[2 * j][2], sc_[2 * j][3]); pw.z = cvt_pk_bf16(sc_[2 * j + 1][0], sc_[2 * j + 1][1]); pw.w = cvt_pk_bf16(sc_[2 * j + 1][2], sc_[2 * j + 1][3]);
;             const bf16x8 pf = __builtin_bit_cast(bf16x8, pw);
; #pragma unroll
;             for (int dt = 0; dt < 4; ++dt) { const LAS unsigned char* vb = VT + (16 * dt + fr) * VT_STRIDE + (16 * (t0 + 2 * j) + 4 * fq) * 2;
;                 const u32x2 va = *(const LAS u32x2*)vb, vc = *(const LAS u32x2*)(vb + 32); u32x4 vw; vw.x = va.x; vw.y = va.y; vw.z = vc.x; vw.w = vc.y;
;                 o[dt] = MFMA16(__builtin_bit_cast(bf16x8, vw), pf, o[dt]); }
	v_fmamk_f32 v64, v64, 0x3fb8aa3b, v94
	v_fmamk_f32 v65, v65, 0x3fb8aa3b, v94
	v_fmamk_f32 v66, v66, 0x3fb8aa3b, v94
	v_fmamk_f32 v67, v67, 0x3fb8aa3b, v94
	v_fmamk_f32 v68, v68, 0x3fb8aa3b, v94
	v_fmamk_f32 v69, v69, 0x3fb8aa3b, v94
	v_fmamk_f32 v70, v70, 0x3fb8aa3b, v94
	v_fmamk_f32 v71, v71, 0x3fb8aa3b, v94
	v_fmamk_f32 v72, v72, 0x3fb8aa3b, v94
	v_fmamk_f32 v73, v73, 0x3fb8aa3b, v94
	v_fmamk_f32 v74, v74, 0x3fb8aa3b, v94
	v_fmamk_f32 v75, v75, 0x3fb8aa3b, v94
	v_fmamk_f32 v76, v76, 0x3fb8aa3b, v94
	v_fmamk_f32 v77, v77, 0x3fb8aa3b, v94
	v_fmamk_f32 v78, v78, 0x3fb8aa3b, v94
	v_fmamk_f32 v79, v79, 0x3fb8aa3b, v94
	v_fmamk_f32 v80, v80, 0x3fb8aa3b, v94
	v_fmamk_f32 v81, v81, 0x3fb8aa3b, v94
	v_fmamk_f32 v82, v82, 0x3fb8aa3b, v94
	v_fmamk_f32 v83, v83, 0x3fb8aa3b, v94
	v_fmamk_f32 v84, v84, 0x3fb8aa3b, v94
	v_fmamk_f32 v85, v85, 0x3fb8aa3b, v94
	v_fmamk_f32 v86, v86, 0x3fb8aa3b, v94
	v_fmamk_f32 v87, v87, 0x3fb8aa3b, v94
	v_fmamk_f32 v88, v88, 0x3fb8aa3b, v94
	v_fmamk_f32 v89, v89, 0x3fb8aa3b, v94
	v_fmamk_f32 v90, v90, 0x3fb8aa3b, v94
	v_fmamk_f32 v91, v91, 0x3fb8aa3b, v94
	v_fmamk_f32 v92, v92, 0x3fb8aa3b, v94
	v_fmamk_f32 v93, v93, 0x3fb8aa3b, v94
	v_exp_f32_e32 v58, v58
	v_exp_f32_e32 v59, v59
	v_exp_f32_e32 v60, v60
	v_exp_f32_e32 v61, v61
	v_exp_f32_e32 v62, v62
	v_exp_f32_e32 v63, v63
	v_exp_f32_e32 v64, v64
	v_exp_f32_e32 v65, v65
	v_exp_f32_e32 v66, v66
	v_exp_f32_e32 v67, v67
	v_exp_f32_e32 v68, v68
	v_exp_f32_e32 v69, v69
	v_exp_f32_e32 v70, v70
	v_exp_f32_e32 v71, v71
	v_exp_f32_e32 v72, v72
	v_exp_f32_e32 v73, v73
	v_exp_f32_e32 v74, v74
	v_exp_f32_e32 v75, v75
	v_exp_f32_e32 v76, v76
	v_exp_f32_e32 v77, v77
	v_exp_f32_e32 v78, v78
	v_exp_f32_e32 v79, v79
	v_exp_f32_e32 v80, v80
	v_exp_f32_e32 v81, v81
	v_exp_f32_e32 v82, v82
	v_exp_f32_e32 v83, v83
	v_exp_f32_e32 v84, v84
	v_exp_f32_e32 v85, v85
	v_exp_f32_e32 v86, v86
	v_exp_f32_e32 v87, v87
	v_exp_f32_e32 v88, v88
	v_exp_f32_e32 v89, v89
	v_exp_f32_e32 v90, v90
	v_exp_f32_e32 v91, v91
	v_exp_f32_e32 v92, v92
	v_exp_f32_e32 v93, v93
	v_fmamk_f32 v95, v42, 0x3fb8aa3b, v94
	v_exp_f32_e32 v95, v95
	v_add_f32_e32 v167, v58, v59
	v_add_f32_e32 v94, v60, v61
	v_add_f32_e32 v167, v167, v62
	v_add_f32_e32 v94, v94, v63
	v_add_f32_e32 v167, v167, v64
	v_add_f32_e32 v94, v94, v65
	v_add_f32_e32 v167, v167, v66
	v_add_f32_e32 v94, v94, v67
	v_add_f32_e32 v167, v167, v68
	v_add_f32_e32 v94, v94, v69
	v_add_f32_e32 v167, v167, v70
	v_add_f32_e32 v94, v94, v71
	v_add_f32_e32 v167, v167, v72
	v_add_f32_e32 v94, v94, v73
	v_add_f32_e32 v167, v167, v74
	v_add_f32_e32 v94, v94, v75
	v_add_f32_e32 v167, v167, v76
	v_add_f32_e32 v94, v94, v77
	v_add_f32_e32 v167, v167, v78
	v_add_f32_e32 v94, v94, v79
	v_add_f32_e32 v167, v167, v80
	v_add_f32_e32 v94, v94, v81
	v_add_f32_e32 v167, v167, v82
	v_add_f32_e32 v94, v94, v83
	v_add_f32_e32 v167, v167, v84
	v_add_f32_e32 v94, v94, v85
	v_add_f32_e32 v167, v167, v86
	v_add_f32_e32 v94, v94, v87
	v_add_f32_e32 v167, v167, v88
	v_add_f32_e32 v94, v94, v89
	v_add_f32_e32 v167, v167, v90
	v_add_f32_e32 v94, v94, v91
	v_add_f32_e32 v167, v167, v92
	v_add_f32_e32 v94, v94, v93
	v_add_f32_e32 v167, v167, v94
	v_mov_b32_e32 v166, v167
	s_nop 1
	v_permlane16_swap_b32_e32 v167, v166
	v_add_f32_e32 v167, v167, v166
	v_mov_b32_e32 v166, v167
	s_nop 1
	v_permlane32_swap_b32_e32 v167, v166
	v_add_f32_e32 v167, v167, v166
	v_add_f32_e32 v167, v167, v95
	v_rcp_f32_e32 v167, v167
	v_mov_b32_e32 v94, 0
	v_mov_b32_e32 v95, 0
	v_mov_b32_e32 v96, 0
	v_mov_b32_e32 v97, 0
	v_cvt_pk_bf16_f32 v58, v58, v59
	v_cvt_pk_bf16_f32 v59, v60, v61
	v_cvt_pk_bf16_f32 v60, v62, v63
	v_cvt_pk_bf16_f32 v61, v64, v65
	v_cvt_pk_bf16_f32 v66, v66, v67
	v_cvt_pk_bf16_f32 v67, v68, v69
	v_cvt_pk_bf16_f32 v68, v70, v71
	v_cvt_pk_bf16_f32 v69, v72, v73
	v_cvt_pk_bf16_f32 v74, v74, v75
	v_cvt_pk_bf16_f32 v75, v76, v77
	v_cvt_pk_bf16_f32 v76, v78, v79
	v_cvt_pk_bf16_f32 v77, v80, v81
	v_cvt_pk_bf16_f32 v82, v82, v83
	v_cvt_pk_bf16_f32 v83, v84, v85
	v_cvt_pk_bf16_f32 v84, v86, v87
	v_cvt_pk_bf16_f32 v85, v88, v89
	v_cvt_pk_bf16_f32 v90, v90, v91
	v_cvt_pk_bf16_f32 v91, v92, v93
	v_cvt_pk_bf16_f32 v92, v94, v95
	v_cvt_pk_bf16_f32 v93, v96, v97
	s_nop 1
	s_waitcnt lgkmcnt(14)
	v_mfma_f32_16x16x32_bf16 v[62:65], v[98:101], v[58:61], 0
	ds_read2_b64 v[158:161], v197 offset0:48 offset1:52
	s_waitcnt lgkmcnt(14)
	v_mfma_f32_16x16x32_bf16 v[70:73], v[102:105], v[58:61], 0
	ds_read2_b64 v[162:165], v194 offset0:56 offset1:60
	s_waitcnt lgkmcnt(14)
	v_mfma_f32_16x16x32_bf16 v[78:81], v[106:109], v[58:61], 0
	ds_read2_b64 v[182:185], v195 offset0:56 offset1:60
	s_waitcnt lgkmcnt(14)
	v_mfma_f32_16x16x32_bf16 v[86:89], v[110:113], v[58:61], 0
	ds_read2_b64 v[186:189], v196 offset0:56 offset1:60
	s_waitcnt lgkmcnt(14)
	v_mfma_f32_16x16x32_bf16 v[62:65], v[114:117], v[66:69], v[62:65]
	ds_read2_b64 v[190:193], v197 offset0:56 offset1:60
	s_waitcnt lgkmcnt(14)
	v_mfma_f32_16x16x32_bf16 v[70:73], v[118:121], v[66:69], v[70:73]
	s_waitcnt lgkmcnt(13)
	v_mfma_f32_16x16x32_bf16 v[78:81], v[122:125], v[66:69], v[78:81]
	s_waitcnt lgkmcnt(12)
	v_mfma_f32_16x16x32_bf16 v[86:89], v[126:129], v[66:69], v[86:89]
	s_waitcnt lgkmcnt(11)
	v_mfma_f32_16x16x32_bf16 v[62:65], v[130:133], v[74:77], v[62:65]
	s_waitcnt lgkmcnt(10)
	v_mfma_f32_16x16x32_bf16 v[70:73], v[134:137], v[74:77], v[70:73]
	s_waitcnt lgkmcnt(9)
	v_mfma_f32_16x16x32_bf16 v[78:81], v[138:141], v[74:77], v[78:81]
	s_waitcnt lgkmcnt(8)
	v_mfma_f32_16x16x32_bf16 v[86:89], v[142:145], v[74:77], v[86:89]
	s_waitcnt lgkmcnt(7)
	v_mfma_f32_16x16x32_bf16 v[62:65], v[146:149], v[82:85], v[62:65]
	s_waitcnt lgkmcnt(6)
; __device__ __forceinline__ unsigned cvt_pk_bf16(float lo, float hi) { unsigned r; asm volatile("v_cvt_pk_bf16_f32 %0, %1, %2" : "=v"(r) : "v"(lo), "v"(hi)); return r; }
; #define LAS __attribute__((address_space(3)))
; __device__ __forceinline__ void p2_block(LAS unsigned char* lds, const bf16_t* __restrict__ PROJ, bf16_t* __restrict__ ATT, bf16_t* __restrict__ SGU, const float* __restrict__ qn, const float* __restrict__ kn, ...
;     ...
;         const int i0 = rbase + 16 * c, irow = i0 + fr, pos = n * 128 + irow; const size_t grow = (size_t)b * pg8::SEQ + pos;
;         bf16x8 qf0, qf1;
;         {
;             float x1[8], x2[8]; unpack8(qa[c], x1); unpack8(qb[c], x2);
;             float ss = 0.f;
; #pragma unroll
;             for (int j = 0; j < 8; ++j) ss += x1[j] * x1[j] + x2[j] * x2[j];
;             ss += __shfl_xor(ss, 16); ss += __shfl_xor(ss, 32);
;             const float rinv = rsqrtf(ss * (1.0f / 64.0f) + pg8::EPS) * 0.125f;
;             const float* cp = COS + pos * 32 + 8 * fq; const float* sp = SIN + pos * 32 + 8 * fq;
;             float o1[8], o2[8];
; #pragma unroll
;             for (int j = 0; j < 8; ++j) { const float a1 = x1[j] * rinv * qn[8 * fq + j], a2 = x2[j] * rinv * qn[32 + 8 * fq + j], cc = cp[j], sn = sp[j]; o1[j] = a1 * cc - a2 * sn; o2[j] = a2 * cc + a1 * sn; }
;             u32x4 w0, w1;
;             w0.x = cvt_pk_bf16(o1[0], o1[1]); w0.y = cvt_pk_bf16(o1[2], o1[3]); w0.z = cvt_pk_bf16(o1[4], o1[5]); w0.w = cvt_pk_bf16(o1[6], o1[7]);
;             w1.x = cvt_pk_bf16(o2[0], o2[1]); w1.y = cvt_pk_bf16(o2[2], o2[3]); w1.z = cvt_pk_bf16(o2[4], o2[5]); w1.w = cvt_pk_bf16(o2[6], o2[7]);
;             qf0 = __builtin_bit_cast(bf16x8, w0); qf1 = __builtin_bit_cast(bf16x8, w1);
;     ...
;             for (int dt = 0; dt < 4; ++dt) { const LAS unsigned char* vb = VT + (16 * dt + fr) * VT_STRIDE + (16 * (t0 + 2 * j) + 4 * fq) * 2;
;                 const u32x2 va = *(const LAS u32x2*)vb, vc = *(const LAS u32x2*)(vb + 32); u32x4 vw; vw.x = va.x; vw.y = va.y; vw.z = vc.x; vw.w = vc.y;
;                 o[dt] = MFMA16(__builtin_bit_cast(bf16x8, vw), pf, o[dt]); }
;         }
;         bf16_t* op = ATT + grow * 1024 + hq * 64 + 4 * fq;
; #pragma unroll
;         for (int dt = 0; dt < 4; ++dt) { u32x2 ow; ow.x = cvt_pk_bf16(o[dt][0] * inv, o[dt][1] * inv); ow.y = cvt_pk_bf16(o[dt][2] * inv, o[dt][3] * inv); *(u32x2*)(op + 16 * dt) = ow; }
	v_mfma_f32_16x16x32_bf16 v[70:73], v[150:153], v[82:85], v[70:73]
	s_waitcnt lgkmcnt(5)
	v_mfma_f32_16x16x32_bf16 v[78:81], v[154:157], v[82:85], v[78:81]
	s_waitcnt lgkmcnt(4)
	v_mfma_f32_16x16x32_bf16 v[86:89], v[158:161], v[82:85], v[86:89]
	s_waitcnt lgkmcnt(3)
	v_mfma_f32_16x16x32_bf16 v[62:65], v[162:165], v[90:93], v[62:65]
	s_waitcnt lgkmcnt(2)
	v_mfma_f32_16x16x32_bf16 v[70:73], v[182:185], v[90:93], v[70:73]
	s_waitcnt lgkmcnt(1)
	v_mfma_f32_16x16x32_bf16 v[78:81], v[186:189], v[90:93], v[78:81]
	s_waitcnt lgkmcnt(0)
	v_mfma_f32_16x16x32_bf16 v[86:89], v[190:193], v[90:93], v[86:89]
	ds_read_b128 v[106:109], v45 offset:16128
	ds_read_b128 v[110:113], v45 offset:16192
	ds_read_b128 v[114:117], v45 offset:18432
	ds_read_b128 v[118:121], v45 offset:18496
	ds_read_b128 v[122:125], v45 offset:20736
	ds_read_b128 v[126:129], v45 offset:20800
	ds_read_b128 v[130:133], v45 offset:23040
	ds_read_b128 v[134:137], v45 offset:23104
	ds_read_b128 v[138:141], v45 offset:25344
	ds_read_b128 v[142:145], v45 offset:25408
	ds_read_b128 v[146:149], v45 offset:27648
	ds_read_b128 v[150:153], v45 offset:27712
	ds_read_b128 v[154:157], v45 offset:29952
	ds_read_b128 v[158:161], v45 offset:30016
	s_nop 7
	v_mul_f32_e32 v62, v62, v167
	v_mul_f32_e32 v63, v63, v167
	v_mul_f32_e32 v64, v64, v167
	v_mul_f32_e32 v65, v65, v167
	v_mul_f32_e32 v70, v70, v167
	v_mul_f32_e32 v71, v71, v167
	v_mul_f32_e32 v72, v72, v167
	v_mul_f32_e32 v73, v73, v167
	v_mul_f32_e32 v78, v78, v167
	v_mul_f32_e32 v79, v79, v167
	v_mul_f32_e32 v80, v80, v167
	v_mul_f32_e32 v81, v81, v167
	v_mul_f32_e32 v86, v86, v167
	v_mul_f32_e32 v87, v87, v167
	v_mul_f32_e32 v88, v88, v167
	v_mul_f32_e32 v89, v89, v167
	v_cvt_pk_bf16_f32 v62, v62, v63
	v_cvt_pk_bf16_f32 v63, v64, v65
	global_store_dwordx2 v48, v[62:63], s[24:25] offset:0
	v_cvt_pk_bf16_f32 v70, v70, v71
	v_cvt_pk_bf16_f32 v71, v72, v73
	global_store_dwordx2 v48, v[70:71], s[24:25] offset:32
	v_cvt_pk_bf16_f32 v78, v78, v79
	v_cvt_pk_bf16_f32 v79, v80, v81
	global_store_dwordx2 v48, v[78:79], s[24:25] offset:64
	v_cvt_pk_bf16_f32 v86, v86, v87
	v_cvt_pk_bf16_f32 v87, v88, v89
	global_store_dwordx2 v48, v[86:87], s[24:25] offset:96
	v_add_u32_e32 v48, 0x8000, v48
	s_waitcnt vmcnt(8)
	v_lshlrev_b32_e32 v58, 16, v218
	v_and_b32_e32 v59, 0xffff0000, v218
	v_lshlrev_b32_e32 v66, 16, v222
	v_and_b32_e32 v67, 0xffff0000, v222
	v_lshlrev_b32_e32 v60, 16, v219
	v_and_b32_e32 v61, 0xffff0000, v219
	v_lshlrev_b32_e32 v68, 16, v223
	v_and_b32_e32 v69, 0xffff0000, v223
	v_lshlrev_b32_e32 v62, 16, v220
	v_and_b32_e32 v63, 0xffff0000, v220
	v_lshlrev_b32_e32 v70, 16, v224
	v_and_b32_e32 v71, 0xffff0000, v224
	v_lshlrev_b32_e32 v64, 16, v221
	v_and_b32_e32 v65, 0xffff0000, v221
	v_lshlrev_b32_e32 v72, 16, v225
	v_and_b32_e32 v73, 0xffff0000, v225
	v_mul_f32_e32 v74, v58, v58
	v_mul_f32_e32 v75, v59, v59
	v_fmac_f32_e32 v74, v60, v60
	v_fmac_f32_e32 v75, v61, v61
	v_fmac_f32_e32 v74, v62, v62
	v_fmac_f32_e32 v75, v63, v63
	v_fmac_f32_e32 v74, v64, v64
	v_fmac_f32_e32 v75, v65, v65
	v_fmac_f32_e32 v74, v66, v66
	v_fmac_f32_e32 v75, v67, v67
	v_fmac_f32_e32 v74, v68, v68
	v_fmac_f32_e32 v75, v69, v69
	v_fmac_f32_e32 v74, v70, v70
	v_fmac_f32_e32 v75, v71, v71
	v_fmac_f32_e32 v74, v72, v72
	v_fmac_f32_e32 v75, v73, v73
	v_add_f32_e32 v74, v74, v75
	v_mov_b32_e32 v166, v74
	s_nop 1
	v_permlane16_swap_b32_e32 v74, v166
	v_add_f32_e32 v74, v74, v166
	v_mov_b32_e32 v166, v74
	s_nop 1
	v_permlane32_swap_b32_e32 v74, v166
	v_add_f32_e32 v74, v74, v166
	v_fmamk_f32 v74, v74, 0x3c800000, v209
	v_rsq_f32_e32 v76, v74
	s_nop 0
	v_mul_f32_e32 v76, 0x3e000000, v76
	v_mul_f32_e32 v58, v58, v76
	v_mul_f32_e32 v66, v66, v76
	v_mul_f32_e32 v59, v59, v76
	v_mul_f32_e32 v67, v67, v76
	v_mul_f32_e32 v60, v60, v76
	v_mul_f32_e32 v68, v68, v76
	v_mul_f32_e32 v61, v61, v76
	v_mul_f32_e32 v69, v69, v76
	v_mul_f32_e32 v62, v62, v76
	v_mul_f32_e32 v70, v70, v76
	v_mul_f32_e32 v63, v63, v76
	v_mul_f32_e32 v71, v71, v76
	v_mul_f32_e32 v64, v64, v76
	v_mul_f32_e32 v72, v72, v76
	v_mul_f32_e32 v65, v65, v76
	v_mul_f32_e32 v73, v73, v76
	v_mul_f32_e32 v58, v58, v26
	v_mul_f32_e32 v66, v66, v34
	v_mul_f32_e32 v59, v59, v27
	v_mul_f32_e32 v67, v67, v35
	v_mul_f32_e32 v60, v60, v28
	v_mul_f32_e32 v68, v68, v36
	v_mul_f32_e32 v61, v61, v29
	v_mul_f32_e32 v69, v69, v37
	v_mul_f32_e32 v62, v62, v30
	v_mul_f32_e32 v70, v70, v38
	v_mul_f32_e32 v63, v63, v31
	v_mul_f32_e32 v71, v71, v39
	v_mul_f32_e32 v64, v64, v32
	v_mul_f32_e32 v72, v72, v40
	v_mul_f32_e32 v65, v65, v33
	v_mul_f32_e32 v73, v73, v41
	v_mul_f32_e32 v78, v66, v234
	v_mul_f32_e32 v86, v58, v234
	v_mul_f32_e32 v79, v67, v235
	v_mul_f32_e32 v87, v59, v235
	v_mul_f32_e32 v80, v68, v236
	v_mul_f32_e32 v88, v60, v236
	v_mul_f32_e32 v81, v69, v237
	v_mul_f32_e32 v89, v61, v237
	v_mul_f32_e32 v82, v70, v238
	v_mul_f32_e32 v90, v62, v238
	v_mul_f32_e32 v83, v71, v239
	v_mul_f32_e32 v91, v63, v239
	v_mul_f32_e32 v84, v72, v240
	v_mul_f32_e32 v92, v64, v240
	v_mul_f32_e32 v85, v73, v241
	v_mul_f32_e32 v93, v65, v241
	v_fma_f32 v78, v58, v226, -v78
	v_fmac_f32_e32 v86, v66, v226
	v_fma_f32 v79, v59, v227, -v79
	v_fmac_f32_e32 v87, v67, v227
	v_fma_f32 v80, v60, v228, -v80
	v_fmac_f32_e32 v88, v68, v228
	v_fma_f32 v81, v61, v229, -v81
	v_fmac_f32_e32 v89, v69, v229
	v_fma_f32 v82, v62, v230, -v82
	v_fmac_f32_e32 v90, v70, v230
	v_fma_f32 v83, v63, v231, -v83
	v_fmac_f32_e32 v91, v71, v231
	v_fma_f32 v84, v64, v232, -v84
	v_fmac_f32_e32 v92, v72, v232
	v_fma_f32 v85, v65, v233, -v85
	v_fmac_f32_e32 v93, v73, v233
	v_cvt_pk_bf16_f32 v50, v78, v79
	v_cvt_pk_bf16_f32 v54, v86, v87
	v_cvt_pk_bf16_f32 v51, v80, v81
	v_cvt_pk_bf16_f32 v55, v88, v89
; #define LAS __attribute__((address_space(3)))
; #define MFMA16(a, b, c) __builtin_amdgcn_mfma_f32_16x16x32_bf16((a), (b), (c), 0, 0, 0)
; __device__ __forceinline__ void p2_block(LAS unsigned char* lds, const bf16_t* __restrict__ PROJ, bf16_t* __restrict__ ATT, bf16_t* __restrict__ SGU, const float* __restrict__ qn, const float* __restrict__ kn, ...
;     ...
;         for (int t = 0; t < 10; ++t) { const bf16x8 k0 = *(const LAS bf16x8*)(kbase + t * 16 * KS_STRIDE), k1 = *(const LAS bf16x8*)(kbase + t * 16 * KS_STRIDE + 64);
;             f32x4 z = (f32x4){0.f, 0.f, 0.f, 0.f}; z = MFMA16(k0, qf0, z); sc_[t] = MFMA16(k1, qf1, z); }
;         float mx = -1e30f;
; #pragma unroll
;         for (int t = 0; t < 10; ++t)
; #pragma unroll
;             for (int e = 0; e < 4; ++e) { const int kx = 16 * (t0 + t) + 4 * fq + e, d = kx - irow; const bool ok = (d >= 1) && (d <= 128) && (n > 0 || kx >= 128);
;                 const float v = ok ? sc_[t][e] : -1e30f; sc_[t][e] = v; mx = fmaxf(mx, v); }
;         mx = fmaxf(mx, __shfl_xor(mx, 16)); mx = fmaxf(mx, __shfl_xor(mx, 32)); mx = fmaxf(mx, sink);
;     ...
;         const float bias = bsp[gg * 128 + irow];
;         const size_t grow = (size_t)b * pg8::SEQ + n * 128 + irow;
;         const bf16_t* up = PROJ + grow * pg8::IN_W + pg8::C_U + gg * 128 + 4 * fq; bf16_t* op = SGU + grow * 1024 + gg * 128 + 4 * fq;
; #pragma unroll
;         for (int dt = 0; dt < 8; ++dt) { const u32x2 uw = *(const u32x2*)(up + 16 * dt);
	v_cvt_pk_bf16_f32 v52, v82, v83
	v_cvt_pk_bf16_f32 v56, v90, v91
	v_cvt_pk_bf16_f32 v53, v84, v85
	v_cvt_pk_bf16_f32 v57, v92, v93
	v_lshrrev_b32_e32 v242, 2, v204
	v_and_b32_e32 v242, 0x70, v242
	v_and_b32_e32 v243, 15, v204
	v_or_b32_e32 v242, v242, v243
	v_lshrrev_b32_e32 v243, 1, v204
	v_and_b32_e32 v243, 24, v243
	v_and_b32_e64 v244, s2, 3
	v_lshlrev_b32_e32 v244, 9, v244
	v_and_b32_e64 v245, s2, -4
	v_lshl_add_u32 v245, v245, 5, v242
	v_mul_u32_u24_e32 v245, 0x3c00, v245
	v_add3_u32 v245, v245, v244, v243
	v_lshlrev_b32_e32 v244, 1, v244
	v_lshl_add_u32 v244, v242, 2, v244
	global_load_dword v198, v244, s[22:23]
	global_load_dword v199, v244, s[22:23] offset:512
	global_load_dwordx2 v[218:219], v245, s[10:11] offset:3072
	global_load_dwordx2 v[220:221], v245, s[10:11] offset:3104
	global_load_dwordx2 v[222:223], v245, s[10:11] offset:3136
	global_load_dwordx2 v[224:225], v245, s[10:11] offset:3168
	global_load_dwordx2 v[226:227], v245, s[10:11] offset:3200
	global_load_dwordx2 v[228:229], v245, s[10:11] offset:3232
	global_load_dwordx2 v[230:231], v245, s[10:11] offset:3264
	global_load_dwordx2 v[232:233], v245, s[10:11] offset:3296
	global_load_dwordx2 v[234:235], v245, s[10:11] offset:3328
	global_load_dwordx2 v[236:237], v245, s[10:11] offset:3360
	global_load_dwordx2 v[238:239], v245, s[10:11] offset:3392
	global_load_dwordx2 v[240:241], v245, s[10:11] offset:3424
	global_load_dwordx2 v[242:243], v245, s[10:11] offset:3456
	global_load_dwordx2 v[200:201], v245, s[10:11] offset:3520
	global_load_dwordx2 v[202:203], v245, s[10:11] offset:3552
	global_load_dwordx2 v[244:245], v245, s[10:11] offset:3488
	s_nop 1
	s_waitcnt lgkmcnt(13)
	v_mfma_f32_16x16x32_bf16 v[62:65], v[106:109], v[50:53], 0
	s_waitcnt lgkmcnt(12)
	v_mfma_f32_16x16x32_bf16 v[62:65], v[110:113], v[54:57], v[62:65]
	ds_read_b128 v[162:165], v45 offset:32256
	ds_read_b128 v[182:185], v45 offset:32320
	s_waitcnt lgkmcnt(13)
	v_mfma_f32_16x16x32_bf16 v[66:69], v[114:117], v[50:53], 0
	s_waitcnt lgkmcnt(12)
	v_mfma_f32_16x16x32_bf16 v[66:69], v[118:121], v[54:57], v[66:69]
	ds_read_b128 v[186:189], v45 offset:34560
	ds_read_b128 v[190:193], v45 offset:34624
	s_waitcnt lgkmcnt(13)
	v_mfma_f32_16x16x32_bf16 v[70:73], v[122:125], v[50:53], 0
	s_waitcnt lgkmcnt(12)
	v_mfma_f32_16x16x32_bf16 v[70:73], v[126:129], v[54:57], v[70:73]
	s_waitcnt lgkmcnt(11)
	v_mfma_f32_16x16x32_bf16 v[74:77], v[130:133], v[50:53], 0
	s_waitcnt lgkmcnt(10)
	v_mfma_f32_16x16x32_bf16 v[74:77], v[134:137], v[54:57], v[74:77]
	s_waitcnt lgkmcnt(9)
	v_mfma_f32_16x16x32_bf16 v[78:81], v[138:141], v[50:53], 0
	s_waitcnt lgkmcnt(8)
	v_mfma_f32_16x16x32_bf16 v[78:81], v[142:145], v[54:57], v[78:81]
	s_waitcnt lgkmcnt(7)
	v_mfma_f32_16x16x32_bf16 v[82:85], v[146:149], v[50:53], 0
	s_waitcnt lgkmcnt(6)
	v_mfma_f32_16x16x32_bf16 v[82:85], v[150:153], v[54:57], v[82:85]
	s_waitcnt lgkmcnt(5)
	v_mfma_f32_16x16x32_bf16 v[86:89], v[154:157], v[50:53], 0
	s_waitcnt lgkmcnt(4)
	v_mfma_f32_16x16x32_bf16 v[86:89], v[158:161], v[54:57], v[86:89]
	s_waitcnt lgkmcnt(3)
	v_mfma_f32_16x16x32_bf16 v[90:93], v[162:165], v[50:53], 0
	s_waitcnt lgkmcnt(2)
	v_mfma_f32_16x16x32_bf16 v[90:93], v[182:185], v[54:57], v[90:93]
	s_waitcnt lgkmcnt(1)
	v_mfma_f32_16x16x32_bf16 v[94:97], v[186:189], v[50:53], 0
	s_waitcnt lgkmcnt(0)
	v_mfma_f32_16x16x32_bf16 v[94:97], v[190:193], v[54:57], v[94:97]
	ds_read2_b64 v[98:101], v194 offset0:24 offset1:28
	ds_read2_b64 v[102:105], v195 offset0:24 offset1:28
	ds_read2_b64 v[106:109], v196 offset0:24 offset1:28
	ds_read2_b64 v[110:113], v197 offset0:24 offset1:28
	ds_read2_b64 v[114:117], v194 offset0:32 offset1:36
	ds_read2_b64 v[118:121], v195 offset0:32 offset1:36
	ds_read2_b64 v[122:125], v196 offset0:32 offset1:36
	ds_read2_b64 v[126:129], v197 offset0:32 offset1:36
	ds_read2_b64 v[130:133], v194 offset0:40 offset1:44
	ds_read2_b64 v[134:137], v195 offset0:40 offset1:44
	ds_read2_b64 v[138:141], v196 offset0:40 offset1:44
	ds_read2_b64 v[142:145], v197 offset0:40 offset1:44
	ds_read2_b64 v[146:149], v194 offset0:48 offset1:52
	ds_read2_b64 v[150:153], v195 offset0:48 offset1:52
	ds_read2_b64 v[154:157], v196 offset0:48 offset1:52
	s_nop 4
	v_cndmask_b32_e64 v62, v49, v62, s[48:49]
	v_cndmask_b32_e64 v63, v49, v63, s[50:51]
	v_cndmask_b32_e64 v64, v49, v64, s[52:53]
	v_cndmask_b32_e64 v65, v49, v65, s[26:27]
	v_cndmask_b32_e64 v94, v94, v49, s[40:41]
	v_cndmask_b32_e64 v95, v95, v49, s[42:43]
	v_cndmask_b32_e64 v96, v96, v49, s[44:45]
	v_cndmask_b32_e64 v97, v97, v49, s[46:47]
	v_max_f32_e32 v167, v62, v63
	v_max_f32_e32 v58, v64, v65
	v_max3_f32 v167, v167, v66, v67
	v_max3_f32 v58, v58, v68, v69
	v_max3_f32 v167, v167, v70, v71
	v_max3_f32 v58, v58, v72, v73
	v_max3_f32 v167, v167, v74, v75
	v_max3_f32 v58, v58, v76, v77
	v_max3_f32 v167, v167, v78, v79
	v_max3_f32 v58, v58, v80, v81
	v_max3_f32 v167, v167, v82, v83
	v_max3_f32 v58, v58, v84, v85
	v_max3_f32 v167, v167, v86, v87
	v_max3_f32 v58, v58, v88, v89
	v_max3_f32 v167, v167, v90, v91
	v_max3_f32 v58, v58, v92, v93
	v_max3_f32 v167, v167, v94, v95
	v_max3_f32 v58, v58, v96, v97
	v_max_f32_e32 v167, v167, v58
	v_mov_b32_e32 v166, v167
	s_nop 1
	v_permlane16_swap_b32_e32 v167, v166
	v_max_f32_e32 v167, v167, v166
	v_mov_b32_e32 v166, v167
	s_nop 1
	v_permlane32_swap_b32_e32 v167, v166
	v_max_f32_e32 v167, v167, v166
	v_max_f32_e32 v167, v167, v42
	v_mul_f32_e32 v58, 0xbfb8aa3b, v167
	v_fmamk_f32 v62, v62, 0x3fb8aa3b, v58
	v_fmamk_f32 v63, v63, 0x3fb8aa3b, v58
	v_fmamk_f32 v64, v64, 0x3fb8aa3b, v58
	v_fmamk_f32 v65, v65, 0x3fb8aa3b, v58
	v_fmamk_f32 v66, v66, 0x3fb8aa3b, v58
	v_fmamk_f32 v67, v67, 0x3fb8aa3b, v58
; __device__ __forceinline__ unsigned cvt_pk_bf16(float lo, float hi) { unsigned r; asm volatile("v_cvt_pk_bf16_f32 %0, %1, %2" : "=v"(r) : "v"(lo), "v"(hi)); return r; }
; #define LAS __attribute__((address_space(3)))
; #define MFMA16(a, b, c) __builtin_amdgcn_mfma_f32_16x16x32_bf16((a), (b), (c), 0, 0, 0)
; __device__ __forceinline__ void p2_block(LAS unsigned char* lds, const bf16_t* __restrict__ PROJ, bf16_t* __restrict__ ATT, bf16_t* __restrict__ SGU, const float* __restrict__ qn, const float* __restrict__ kn, ...
;     ...
;         float sum = 0.f;
; #pragma unroll
;         for (int t = 0; t < 10; ++t)
; #pragma unroll
;             for (int e = 0; e < 4; ++e) { const float p = __builtin_amdgcn_exp2f((sc_[t][e] - mx) * LOG2E); sc_[t][e] = p; sum += p; }
;         sum += __shfl_xor(sum, 16); sum += __shfl_xor(sum, 32);
;         const float inv = 1.0f / (sum + __builtin_amdgcn_exp2f((sink - mx) * LOG2E));
;         f32x4 o[4];
; #pragma unroll
;         for (int dt = 0; dt < 4; ++dt) o[dt] = (f32x4){0.f, 0.f, 0.f, 0.f};
; #pragma unroll
;         for (int j = 0; j < 5; ++j) {
;             u32x4 pw; pw.x = cvt_pk_bf16(sc_[2 * j][0], sc_[2 * j][1]); pw.y = cvt_pk_bf16(sc_[2 * j][2], sc_[2 * j][3]); pw.z = cvt_pk_bf16(sc_[2 * j + 1][0], sc_[2 * j + 1][1]); pw.w = cvt_pk_bf16(sc_[2 * j + 1][2], sc_[2 * j + 1][3]);
;             const bf16x8 pf = __builtin_bit_cast(bf16x8, pw);
; #pragma unroll
;             for (int dt = 0; dt < 4; ++dt) { const LAS unsigned char* vb = VT + (16 * dt + fr) * VT_STRIDE + (16 * (t0 + 2 * j) + 4 * fq) * 2;
;                 const u32x2 va = *(const LAS u32x2*)vb, vc = *(const LAS u32x2*)(vb + 32); u32x4 vw; vw.x = va.x; vw.y = va.y; vw.z = vc.x; vw.w = vc.y;
;                 o[dt] = MFMA16(__builtin_bit_cast(bf16x8, vw), pf, o[dt]); }
	v_fmamk_f32 v68, v68, 0x3fb8aa3b, v58
	v_fmamk_f32 v69, v69, 0x3fb8aa3b, v58
	v_fmamk_f32 v70, v70, 0x3fb8aa3b, v58
	v_fmamk_f32 v71, v71, 0x3fb8aa3b, v58
	v_fmamk_f32 v72, v72, 0x3fb8aa3b, v58
	v_fmamk_f32 v73, v73, 0x3fb8aa3b, v58
	v_fmamk_f32 v74, v74, 0x3fb8aa3b, v58
	v_fmamk_f32 v75, v75, 0x3fb8aa3b, v58
	v_fmamk_f32 v76, v76, 0x3fb8aa3b, v58
	v_fmamk_f32 v77, v77, 0x3fb8aa3b, v58
	v_fmamk_f32 v78, v78, 0x3fb8aa3b, v58
	v_fmamk_f32 v79, v79, 0x3fb8aa3b, v58
	v_fmamk_f32 v80, v80, 0x3fb8aa3b, v58
	v_fmamk_f32 v81, v81, 0x3fb8aa3b, v58
	v_fmamk_f32 v82, v82, 0x3fb8aa3b, v58
	v_fmamk_f32 v83, v83, 0x3fb8aa3b, v58
	v_fmamk_f32 v84, v84, 0x3fb8aa3b, v58
	v_fmamk_f32 v85, v85, 0x3fb8aa3b, v58
	v_fmamk_f32 v86, v86, 0x3fb8aa3b, v58
	v_fmamk_f32 v87, v87, 0x3fb8aa3b, v58
	v_fmamk_f32 v88, v88, 0x3fb8aa3b, v58
	v_fmamk_f32 v89, v89, 0x3fb8aa3b, v58
	v_fmamk_f32 v90, v90, 0x3fb8aa3b, v58
	v_fmamk_f32 v91, v91, 0x3fb8aa3b, v58
	v_fmamk_f32 v92, v92, 0x3fb8aa3b, v58
	v_fmamk_f32 v93, v93, 0x3fb8aa3b, v58
	v_fmamk_f32 v94, v94, 0x3fb8aa3b, v58
	v_fmamk_f32 v95, v95, 0x3fb8aa3b, v58
	v_fmamk_f32 v96, v96, 0x3fb8aa3b, v58
	v_fmamk_f32 v97, v97, 0x3fb8aa3b, v58
	v_exp_f32_e32 v62, v62
	v_exp_f32_e32 v63, v63
	v_exp_f32_e32 v64, v64
	v_exp_f32_e32 v65, v65
	v_exp_f32_e32 v66, v66
	v_exp_f32_e32 v67, v67
	v_exp_f32_e32 v68, v68
	v_exp_f32_e32 v69, v69
	v_exp_f32_e32 v70, v70
	v_exp_f32_e32 v71, v71
	v_exp_f32_e32 v72, v72
	v_exp_f32_e32 v73, v73
	v_exp_f32_e32 v74, v74
	v_exp_f32_e32 v75, v75
	v_exp_f32_e32 v76, v76
	v_exp_f32_e32 v77, v77
	v_exp_f32_e32 v78, v78
	v_exp_f32_e32 v79, v79
	v_exp_f32_e32 v80, v80
	v_exp_f32_e32 v81, v81
	v_exp_f32_e32 v82, v82
	v_exp_f32_e32 v83, v83
	v_exp_f32_e32 v84, v84
	v_exp_f32_e32 v85, v85
	v_exp_f32_e32 v86, v86
	v_exp_f32_e32 v87, v87
	v_exp_f32_e32 v88, v88
	v_exp_f32_e32 v89, v89
	v_exp_f32_e32 v90, v90
	v_exp_f32_e32 v91, v91
	v_exp_f32_e32 v92, v92
	v_exp_f32_e32 v93, v93
	v_exp_f32_e32 v94, v94
	v_exp_f32_e32 v95, v95
	v_exp_f32_e32 v96, v96
	v_exp_f32_e32 v97, v97
	v_fmamk_f32 v59, v42, 0x3fb8aa3b, v58
	v_exp_f32_e32 v59, v59
	v_add_f32_e32 v167, v62, v63
	v_add_f32_e32 v58, v64, v65
	v_add_f32_e32 v167, v167, v66
	v_add_f32_e32 v58, v58, v67
	v_add_f32_e32 v167, v167, v68
	v_add_f32_e32 v58, v58, v69
	v_add_f32_e32 v167, v167, v70
	v_add_f32_e32 v58, v58, v71
	v_add_f32_e32 v167, v167, v72
	v_add_f32_e32 v58, v58, v73
	v_add_f32_e32 v167, v167, v74
	v_add_f32_e32 v58, v58, v75
	v_add_f32_e32 v167, v167, v76
	v_add_f32_e32 v58, v58, v77
	v_add_f32_e32 v167, v167, v78
	v_add_f32_e32 v58, v58, v79
	v_add_f32_e32 v167, v167, v80
	v_add_f32_e32 v58, v58, v81
	v_add_f32_e32 v167, v167, v82
	v_add_f32_e32 v58, v58, v83
	v_add_f32_e32 v167, v167, v84
	v_add_f32_e32 v58, v58, v85
	v_add_f32_e32 v167, v167, v86
	v_add_f32_e32 v58, v58, v87
	v_add_f32_e32 v167, v167, v88
	v_add_f32_e32 v58, v58, v89
	v_add_f32_e32 v167, v167, v90
	v_add_f32_e32 v58, v58, v91
	v_add_f32_e32 v167, v167, v92
	v_add_f32_e32 v58, v58, v93
	v_add_f32_e32 v167, v167, v94
	v_add_f32_e32 v58, v58, v95
	v_add_f32_e32 v167, v167, v96
	v_add_f32_e32 v58, v58, v97
	v_add_f32_e32 v167, v167, v58
	v_mov_b32_e32 v166, v167
	s_nop 1
	v_permlane16_swap_b32_e32 v167, v166
	v_add_f32_e32 v167, v167, v166
	v_mov_b32_e32 v166, v167
	s_nop 1
	v_permlane32_swap_b32_e32 v167, v166
	v_add_f32_e32 v167, v167, v166
	v_add_f32_e32 v167, v167, v59
	v_rcp_f32_e32 v167, v167
	v_mov_b32_e32 v58, 0
	v_mov_b32_e32 v59, 0
	v_mov_b32_e32 v60, 0
	v_mov_b32_e32 v61, 0
	v_cvt_pk_bf16_f32 v58, v58, v59
	v_cvt_pk_bf16_f32 v59, v60, v61
	v_cvt_pk_bf16_f32 v60, v62, v63
	v_cvt_pk_bf16_f32 v61, v64, v65
	v_cvt_pk_bf16_f32 v66, v66, v67
	v_cvt_pk_bf16_f32 v67, v68, v69
	v_cvt_pk_bf16_f32 v68, v70, v71
	v_cvt_pk_bf16_f32 v69, v72, v73
	v_cvt_pk_bf16_f32 v74, v74, v75
	v_cvt_pk_bf16_f32 v75, v76, v77
	v_cvt_pk_bf16_f32 v76, v78, v79
	v_cvt_pk_bf16_f32 v77, v80, v81
	v_cvt_pk_bf16_f32 v82, v82, v83
	v_cvt_pk_bf16_f32 v83, v84, v85
	v_cvt_pk_bf16_f32 v84, v86, v87
	v_cvt_pk_bf16_f32 v85, v88, v89
	v_cvt_pk_bf16_f32 v90, v90, v91
	v_cvt_pk_bf16_f32 v91, v92, v93
	v_cvt_pk_bf16_f32 v92, v94, v95
	v_cvt_pk_bf16_f32 v93, v96, v97
	s_nop 1
	s_waitcnt lgkmcnt(14)
	v_mfma_f32_16x16x32_bf16 v[62:65], v[98:101], v[58:61], 0
	ds_read2_b64 v[158:161], v197 offset0:48 offset1:52
	s_waitcnt lgkmcnt(14)
	v_mfma_f32_16x16x32_bf16 v[70:73], v[102:105], v[58:61], 0
	ds_read2_b64 v[162:165], v194 offset0:56 offset1:60
	s_waitcnt lgkmcnt(14)
	v_mfma_f32_16x16x32_bf16 v[78:81], v[106:109], v[58:61], 0
	ds_read2_b64 v[182:185], v195 offset0:56 offset1:60
	s_waitcnt lgkmcnt(14)
	v_mfma_f32_16x16x32_bf16 v[86:89], v[110:113], v[58:61], 0
	ds_read2_b64 v[186:189], v196 offset0:56 offset1:60
	s_waitcnt lgkmcnt(14)
	v_mfma_f32_16x16x32_bf16 v[62:65], v[114:117], v[66:69], v[62:65]
	ds_read2_b64 v[190:193], v197 offset0:56 offset1:60
	s_waitcnt lgkmcnt(14)
	v_mfma_f32_16x16x32_bf16 v[70:73], v[118:121], v[66:69], v[70:73]
	s_waitcnt lgkmcnt(13)
	v_mfma_f32_16x16x32_bf16 v[78:81], v[122:125], v[66:69], v[78:81]
	s_waitcnt lgkmcnt(12)
	v_mfma_f32_16x16x32_bf16 v[86:89], v[126:129], v[66:69], v[86:89]
	s_waitcnt lgkmcnt(11)
	v_mfma_f32_16x16x32_bf16 v[62:65], v[130:133], v[74:77], v[62:65]
	s_waitcnt lgkmcnt(10)
	v_mfma_f32_16x16x32_bf16 v[70:73], v[134:137], v[74:77], v[70:73]
	s_waitcnt lgkmcnt(9)
	v_mfma_f32_16x16x32_bf16 v[78:81], v[138:141], v[74:77], v[78:81]
	s_waitcnt lgkmcnt(8)
	v_mfma_f32_16x16x32_bf16 v[86:89], v[142:145], v[74:77], v[86:89]
	s_waitcnt lgkmcnt(7)
	v_mfma_f32_16x16x32_bf16 v[62:65], v[146:149], v[82:85], v[62:65]
	s_waitcnt lgkmcnt(6)
; __device__ __forceinline__ unsigned cvt_pk_bf16(float lo, float hi) { unsigned r; asm volatile("v_cvt_pk_bf16_f32 %0, %1, %2" : "=v"(r) : "v"(lo), "v"(hi)); return r; }
; #define LAS __attribute__((address_space(3)))
; __device__ __forceinline__ void p2_block(LAS unsigned char* lds, const bf16_t* __restrict__ PROJ, bf16_t* __restrict__ ATT, bf16_t* __restrict__ SGU, const float* __restrict__ qn, const float* __restrict__ kn, ...
;     ...
;         const int i0 = rbase + 16 * c, irow = i0 + fr, pos = n * 128 + irow; const size_t grow = (size_t)b * pg8::SEQ + pos;
;         bf16x8 qf0, qf1;
;         {
;             float x1[8], x2[8]; unpack8(qa[c], x1); unpack8(qb[c], x2);
;             float ss = 0.f;
; #pragma unroll
;             for (int j = 0; j < 8; ++j) ss += x1[j] * x1[j] + x2[j] * x2[j];
;             ss += __shfl_xor(ss, 16); ss += __shfl_xor(ss, 32);
;             const float rinv = rsqrtf(ss * (1.0f / 64.0f) + pg8::EPS) * 0.125f;
;             const float* cp = COS + pos * 32 + 8 * fq; const float* sp = SIN + pos * 32 + 8 * fq;
;             float o1[8], o2[8];
; #pragma unroll
;             for (int j = 0; j < 8; ++j) { const float a1 = x1[j] * rinv * qn[8 * fq + j], a2 = x2[j] * rinv * qn[32 + 8 * fq + j], cc = cp[j], sn = sp[j]; o1[j] = a1 * cc - a2 * sn; o2[j] = a2 * cc + a1 * sn; }
;             u32x4 w0, w1;
;             w0.x = cvt_pk_bf16(o1[0], o1[1]); w0.y = cvt_pk_bf16(o1[2], o1[3]); w0.z = cvt_pk_bf16(o1[4], o1[5]); w0.w = cvt_pk_bf16(o1[6], o1[7]);
;             w1.x = cvt_pk_bf16(o2[0], o2[1]); w1.y = cvt_pk_bf16(o2[2], o2[3]); w1.z = cvt_pk_bf16(o2[4], o2[5]); w1.w = cvt_pk_bf16(o2[6], o2[7]);
;             qf0 = __builtin_bit_cast(bf16x8, w0); qf1 = __builtin_bit_cast(bf16x8, w1);
;     ...
;             for (int dt = 0; dt < 4; ++dt) { const LAS unsigned char* vb = VT + (16 * dt + fr) * VT_STRIDE + (16 * (t0 + 2 * j) + 4 * fq) * 2;
;                 const u32x2 va = *(const LAS u32x2*)vb, vc = *(const LAS u32x2*)(vb + 32); u32x4 vw; vw.x = va.x; vw.y = va.y; vw.z = vc.x; vw.w = vc.y;
;                 o[dt] = MFMA16(__builtin_bit_cast(bf16x8, vw), pf, o[dt]); }
;         }
;         bf16_t* op = ATT + grow * 1024 + hq * 64 + 4 * fq;
; #pragma unroll
;         for (int dt = 0; dt < 4; ++dt) { u32x2 ow; ow.x = cvt_pk_bf16(o[dt][0] * inv, o[dt][1] * inv); ow.y = cvt_pk_bf16(o[dt][2] * inv, o[dt][3] * inv); *(u32x2*)(op + 16 * dt) = ow; }
	v_mfma_f32_16x16x32_bf16 v[70:73], v[150:153], v[82:85], v[70:73]
	s_waitcnt lgkmcnt(5)
	v_mfma_f32_16x16x32_bf16 v[78:81], v[154:157], v[82:85], v[78:81]
	s_waitcnt lgkmcnt(4)
	v_mfma_f32_16x16x32_bf16 v[86:89], v[158:161], v[82:85], v[86:89]
	s_waitcnt lgkmcnt(3)
	v_mfma_f32_16x16x32_bf16 v[62:65], v[162:165], v[90:93], v[62:65]
	s_waitcnt lgkmcnt(2)
	v_mfma_f32_16x16x32_bf16 v[70:73], v[182:185], v[90:93], v[70:73]
	s_waitcnt lgkmcnt(1)
	v_mfma_f32_16x16x32_bf16 v[78:81], v[186:189], v[90:93], v[78:81]
	s_waitcnt lgkmcnt(0)
	v_mfma_f32_16x16x32_bf16 v[86:89], v[190:193], v[90:93], v[86:89]
	s_nop 7
	v_mul_f32_e32 v62, v62, v167
	v_mul_f32_e32 v63, v63, v167
	v_mul_f32_e32 v64, v64, v167
	v_mul_f32_e32 v65, v65, v167
	v_mul_f32_e32 v70, v70, v167
	v_mul_f32_e32 v71, v71, v167
	v_mul_f32_e32 v72, v72, v167
	v_mul_f32_e32 v73, v73, v167
	v_mul_f32_e32 v78, v78, v167
	v_mul_f32_e32 v79, v79, v167
	v_mul_f32_e32 v80, v80, v167
	v_mul_f32_e32 v81, v81, v167
	v_mul_f32_e32 v86, v86, v167
	v_mul_f32_e32 v87, v87, v167
	v_mul_f32_e32 v88, v88, v167
	v_mul_f32_e32 v89, v89, v167
	v_cvt_pk_bf16_f32 v62, v62, v63
	v_cvt_pk_bf16_f32 v63, v64, v65
	global_store_dwordx2 v48, v[62:63], s[24:25] offset:0
	v_cvt_pk_bf16_f32 v70, v70, v71
	v_cvt_pk_bf16_f32 v71, v72, v73
	global_store_dwordx2 v48, v[70:71], s[24:25] offset:32
	v_cvt_pk_bf16_f32 v78, v78, v79
	v_cvt_pk_bf16_f32 v79, v80, v81
	global_store_dwordx2 v48, v[78:79], s[24:25] offset:64
	v_cvt_pk_bf16_f32 v86, v86, v87
	v_cvt_pk_bf16_f32 v87, v88, v89
	global_store_dwordx2 v48, v[86:87], s[24:25] offset:96
	v_add_u32_e32 v48, 0x8000, v48
	s_branch .Latt_done
.Latt_r0:
	ds_read_b128 v[98:101], v45 offset:0
	ds_read_b128 v[102:105], v45 offset:64
	ds_read_b128 v[106:109], v45 offset:2304
	ds_read_b128 v[110:113], v45 offset:2368
	ds_read_b128 v[114:117], v45 offset:4608
	ds_read_b128 v[118:121], v45 offset:4672
	ds_read_b128 v[122:125], v45 offset:6912
	ds_read_b128 v[126:129], v45 offset:6976
	ds_read_b128 v[130:133], v45 offset:9216
	ds_read_b128 v[134:137], v45 offset:9280
	ds_read_b128 v[138:141], v45 offset:11520
	ds_read_b128 v[142:145], v45 offset:11584
	ds_read_b128 v[146:149], v45 offset:13824
	ds_read_b128 v[150:153], v45 offset:13888
	s_waitcnt vmcnt(6)
	v_lshlrev_b32_e32 v58, 16, v2
	v_and_b32_e32 v59, 0xffff0000, v2
	v_lshlrev_b32_e32 v66, 16, v6
	v_and_b32_e32 v67, 0xffff0000, v6
	v_lshlrev_b32_e32 v60, 16, v3
	v_and_b32_e32 v61, 0xffff0000, v3
	v_lshlrev_b32_e32 v68, 16, v7
	v_and_b32_e32 v69, 0xffff0000, v7
	v_lshlrev_b32_e32 v62, 16, v4
	v_and_b32_e32 v63, 0xffff0000, v4
	v_lshlrev_b32_e32 v70, 16, v8
	v_and_b32_e32 v71, 0xffff0000, v8
	v_lshlrev_b32_e32 v64, 16, v5
	v_and_b32_e32 v65, 0xffff0000, v5
	v_lshlrev_b32_e32 v72, 16, v9
	v_and_b32_e32 v73, 0xffff0000, v9
	v_mul_f32_e32 v74, v58, v58
	v_mul_f32_e32 v75, v59, v59
	v_fmac_f32_e32 v74, v60, v60
	v_fmac_f32_e32 v75, v61, v61
	v_fmac_f32_e32 v74, v62, v62
	v_fmac_f32_e32 v75, v63, v63
	v_fmac_f32_e32 v74, v64, v64
	v_fmac_f32_e32 v75, v65, v65
	v_fmac_f32_e32 v74, v66, v66
	v_fmac_f32_e32 v75, v67, v67
	v_fmac_f32_e32 v74, v68, v68
	v_fmac_f32_e32 v75, v69, v69
	v_fmac_f32_e32 v74, v70, v70
	v_fmac_f32_e32 v75, v71, v71
	v_fmac_f32_e32 v74, v72, v72
	v_fmac_f32_e32 v75, v73, v73
	v_add_f32_e32 v74, v74, v75
	v_mov_b32_e32 v166, v74
	s_nop 1
	v_permlane16_swap_b32_e32 v74, v166
	v_add_f32_e32 v74, v74, v166
	v_mov_b32_e32 v166, v74
	s_nop 1
	v_permlane32_swap_b32_e32 v74, v166
	v_add_f32_e32 v74, v74, v166
	v_fmamk_f32 v74, v74, 0x3c800000, v209
	v_rsq_f32_e32 v76, v74
	s_nop 0
	v_mul_f32_e32 v76, 0x3e000000, v76
	v_mul_f32_e32 v58, v58, v76
	v_mul_f32_e32 v66, v66, v76
	v_mul_f32_e32 v59, v59, v76
	v_mul_f32_e32 v67, v67, v76
	v_mul_f32_e32 v60, v60, v76
	v_mul_f32_e32 v68, v68, v76
	v_mul_f32_e32 v61, v61, v76
	v_mul_f32_e32 v69, v69, v76
	v_mul_f32_e32 v62, v62, v76
	v_mul_f32_e32 v70, v70, v76
	v_mul_f32_e32 v63, v63, v76
	v_mul_f32_e32 v71, v71, v76
	v_mul_f32_e32 v64, v64, v76
	v_mul_f32_e32 v72, v72, v76
	v_mul_f32_e32 v65, v65, v76
	v_mul_f32_e32 v73, v73, v76
	v_mul_f32_e32 v58, v58, v26
	v_mul_f32_e32 v66, v66, v34
	v_mul_f32_e32 v59, v59, v27
	v_mul_f32_e32 v67, v67, v35
	v_mul_f32_e32 v60, v60, v28
	v_mul_f32_e32 v68, v68, v36
	v_mul_f32_e32 v61, v61, v29
	v_mul_f32_e32 v69, v69, v37
	v_mul_f32_e32 v62, v62, v30
	v_mul_f32_e32 v70, v70, v38
	v_mul_f32_e32 v63, v63, v31
	v_mul_f32_e32 v71, v71, v39
	v_mul_f32_e32 v64, v64, v32
	v_mul_f32_e32 v72, v72, v40
	v_mul_f32_e32 v65, v65, v33
	v_mul_f32_e32 v73, v73, v41
	v_mul_f32_e32 v78, v66, v18
	v_mul_f32_e32 v86, v58, v18
	v_mul_f32_e32 v79, v67, v19
	v_mul_f32_e32 v87, v59, v19
	v_mul_f32_e32 v80, v68, v20
	v_mul_f32_e32 v88, v60, v20
	v_mul_f32_e32 v81, v69, v21
	v_mul_f32_e32 v89, v61, v21
	v_mul_f32_e32 v82, v70, v22
	v_mul_f32_e32 v90, v62, v22
	v_mul_f32_e32 v83, v71, v23
	v_mul_f32_e32 v91, v63, v23
	v_mul_f32_e32 v84, v72, v24
	v_mul_f32_e32 v92, v64, v24
	v_mul_f32_e32 v85, v73, v25
	v_mul_f32_e32 v93, v65, v25
	v_fma_f32 v78, v58, v10, -v78
	v_fmac_f32_e32 v86, v66, v10
	v_fma_f32 v79, v59, v11, -v79
	v_fmac_f32_e32 v87, v67, v11
	v_fma_f32 v80, v60, v12, -v80
	v_fmac_f32_e32 v88, v68, v12
	v_fma_f32 v81, v61, v13, -v81
	v_fmac_f32_e32 v89, v69, v13
	v_fma_f32 v82, v62, v14, -v82
	v_fmac_f32_e32 v90, v70, v14
	v_fma_f32 v83, v63, v15, -v83
	v_fmac_f32_e32 v91, v71, v15
	v_fma_f32 v84, v64, v16, -v84
	v_fmac_f32_e32 v92, v72, v16
	v_fma_f32 v85, v65, v17, -v85
	v_fmac_f32_e32 v93, v73, v17
	v_cvt_pk_bf16_f32 v50, v78, v79
	v_cvt_pk_bf16_f32 v54, v86, v87
	v_cvt_pk_bf16_f32 v51, v80, v81
	v_cvt_pk_bf16_f32 v55, v88, v89
	v_cvt_pk_bf16_f32 v52, v82, v83
	v_cvt_pk_bf16_f32 v56, v90, v91
	v_cvt_pk_bf16_f32 v53, v84, v85
	v_cvt_pk_bf16_f32 v57, v92, v93
	global_load_dwordx4 v[2:5], v46, s[10:11]
	global_load_dwordx4 v[6:9], v46, s[10:11] offset:64
	global_load_dwordx4 v[10:13], v47, s[6:7]
	global_load_dwordx4 v[14:17], v47, s[6:7] offset:16
	global_load_dwordx4 v[18:21], v47, s[16:17]
	global_load_dwordx4 v[22:25], v47, s[16:17] offset:16
	v_add_u32_e32 v46, 0x3c000, v46
	v_add_u32_e32 v47, 0x800, v47
	s_nop 1
	s_waitcnt lgkmcnt(13)
; #define LAS __attribute__((address_space(3)))
; #define MFMA16(a, b, c) __builtin_amdgcn_mfma_f32_16x16x32_bf16((a), (b), (c), 0, 0, 0)
; __device__ __forceinline__ void p2_block(LAS unsigned char* lds, const bf16_t* __restrict__ PROJ, bf16_t* __restrict__ ATT, bf16_t* __restrict__ SGU, const float* __restrict__ qn, const float* __restrict__ kn, ...
;     ...
;         const int t0 = (i0 >> 4) < 6 ? (i0 >> 4) : 6;
;         f32x4 sc_[10];
;         const LAS unsigned char* kbase = KS + (16 * t0 + fr) * KS_STRIDE + 16 * fq;
; #pragma unroll
;         for (int t = 0; t < 10; ++t) { const bf16x8 k0 = *(const LAS bf16x8*)(kbase + t * 16 * KS_STRIDE), k1 = *(const LAS bf16x8*)(kbase + t * 16 * KS_STRIDE + 64);
;             f32x4 z = (f32x4){0.f, 0.f, 0.f, 0.f}; z = MFMA16(k0, qf0, z); sc_[t] = MFMA16(k1, qf1, z); }
;         float mx = -1e30f;
; #pragma unroll
;         for (int t = 0; t < 10; ++t)
; #pragma unroll
;             for (int e = 0; e < 4; ++e) { const int kx = 16 * (t0 + t) + 4 * fq + e, d = kx - irow; const bool ok = (d >= 1) && (d <= 128) && (n > 0 || kx >= 128);
;                 const float v = ok ? sc_[t][e] : -1e30f; sc_[t][e] = v; mx = fmaxf(mx, v); }
;         mx = fmaxf(mx, __shfl_xor(mx, 16)); mx = fmaxf(mx, __shfl_xor(mx, 32)); mx = fmaxf(mx, sink);
;         float sum = 0.f;
; #pragma unroll
;         for (int t = 0; t < 10; ++t)
; #pragma unroll
;             for (int e = 0; e < 4; ++e) { const float p = __builtin_amdgcn_exp2f((sc_[t][e] - mx) * LOG2E); sc_[t][e] = p; sum += p; }
	v_mfma_f32_16x16x32_bf16 v[58:61], v[98:101], v[50:53], 0
	s_waitcnt lgkmcnt(12)
	v_mfma_f32_16x16x32_bf16 v[58:61], v[102:105], v[54:57], v[58:61]
	ds_read_b128 v[154:157], v45 offset:16128
	ds_read_b128 v[158:161], v45 offset:16192
	s_waitcnt lgkmcnt(13)
	v_mfma_f32_16x16x32_bf16 v[62:65], v[106:109], v[50:53], 0
	s_waitcnt lgkmcnt(12)
	v_mfma_f32_16x16x32_bf16 v[62:65], v[110:113], v[54:57], v[62:65]
	ds_read_b128 v[162:165], v45 offset:18432
	ds_read_b128 v[182:185], v45 offset:18496
	s_waitcnt lgkmcnt(13)
	v_mfma_f32_16x16x32_bf16 v[66:69], v[114:117], v[50:53], 0
	s_waitcnt lgkmcnt(12)
	v_mfma_f32_16x16x32_bf16 v[66:69], v[118:121], v[54:57], v[66:69]
	s_waitcnt lgkmcnt(11)
	v_mfma_f32_16x16x32_bf16 v[70:73], v[122:125], v[50:53], 0
	s_waitcnt lgkmcnt(10)
	v_mfma_f32_16x16x32_bf16 v[70:73], v[126:129], v[54:57], v[70:73]
	s_waitcnt lgkmcnt(9)
	v_mfma_f32_16x16x32_bf16 v[74:77], v[130:133], v[50:53], 0
	s_waitcnt lgkmcnt(8)
	v_mfma_f32_16x16x32_bf16 v[74:77], v[134:137], v[54:57], v[74:77]
	s_waitcnt lgkmcnt(7)
	v_mfma_f32_16x16x32_bf16 v[78:81], v[138:141], v[50:53], 0
	s_waitcnt lgkmcnt(6)
	v_mfma_f32_16x16x32_bf16 v[78:81], v[142:145], v[54:57], v[78:81]
	s_waitcnt lgkmcnt(5)
	v_mfma_f32_16x16x32_bf16 v[82:85], v[146:149], v[50:53], 0
	s_waitcnt lgkmcnt(4)
	v_mfma_f32_16x16x32_bf16 v[82:85], v[150:153], v[54:57], v[82:85]
	s_waitcnt lgkmcnt(3)
	v_mfma_f32_16x16x32_bf16 v[86:89], v[154:157], v[50:53], 0
	s_waitcnt lgkmcnt(2)
	v_mfma_f32_16x16x32_bf16 v[86:89], v[158:161], v[54:57], v[86:89]
	s_waitcnt lgkmcnt(1)
	v_mfma_f32_16x16x32_bf16 v[90:93], v[162:165], v[50:53], 0
	s_waitcnt lgkmcnt(0)
	v_mfma_f32_16x16x32_bf16 v[90:93], v[182:185], v[54:57], v[90:93]
	ds_read2_b64 v[98:101], v194 offset0:0 offset1:4
	ds_read2_b64 v[102:105], v195 offset0:0 offset1:4
	ds_read2_b64 v[106:109], v196 offset0:0 offset1:4
	ds_read2_b64 v[110:113], v197 offset0:0 offset1:4
	ds_read2_b64 v[114:117], v194 offset0:8 offset1:12
	ds_read2_b64 v[118:121], v195 offset0:8 offset1:12
	ds_read2_b64 v[122:125], v196 offset0:8 offset1:12
	ds_read2_b64 v[126:129], v197 offset0:8 offset1:12
	ds_read2_b64 v[130:133], v194 offset0:16 offset1:20
	ds_read2_b64 v[134:137], v195 offset0:16 offset1:20
	ds_read2_b64 v[138:141], v196 offset0:16 offset1:20
	ds_read2_b64 v[142:145], v197 offset0:16 offset1:20
	ds_read2_b64 v[146:149], v194 offset0:24 offset1:28
	ds_read2_b64 v[150:153], v195 offset0:24 offset1:28
	ds_read2_b64 v[154:157], v196 offset0:24 offset1:28
	s_nop 4
	v_cndmask_b32_e64 v58, v49, v58, s[48:49]
	v_cndmask_b32_e64 v59, v49, v59, s[50:51]
	v_cndmask_b32_e64 v60, v49, v60, s[52:53]
	v_cndmask_b32_e64 v61, v49, v61, s[26:27]
	v_cndmask_b32_e64 v62, v49, v62, s[28:29]
	v_cndmask_b32_e64 v63, v49, v63, s[28:29]
	v_cndmask_b32_e64 v64, v49, v64, s[28:29]
	v_cndmask_b32_e64 v65, v49, v65, s[28:29]
	v_cndmask_b32_e64 v66, v49, v66, s[28:29]
	v_cndmask_b32_e64 v67, v49, v67, s[28:29]
	v_cndmask_b32_e64 v68, v49, v68, s[28:29]
	v_cndmask_b32_e64 v69, v49, v69, s[28:29]
	v_cndmask_b32_e64 v70, v49, v70, s[28:29]
	v_cndmask_b32_e64 v71, v49, v71, s[28:29]
	v_cndmask_b32_e64 v72, v49, v72, s[28:29]
	v_cndmask_b32_e64 v73, v49, v73, s[28:29]
	v_cndmask_b32_e64 v74, v49, v74, s[28:29]
	v_cndmask_b32_e64 v75, v49, v75, s[28:29]
	v_cndmask_b32_e64 v76, v49, v76, s[28:29]
	v_cndmask_b32_e64 v77, v49, v77, s[28:29]
	v_cndmask_b32_e64 v78, v49, v78, s[28:29]
	v_cndmask_b32_e64 v79, v49, v79, s[28:29]
	v_cndmask_b32_e64 v80, v49, v80, s[28:29]
	v_cndmask_b32_e64 v81, v49, v81, s[28:29]
	v_cndmask_b32_e64 v82, v49, v82, s[28:29]
	v_cndmask_b32_e64 v83, v49, v83, s[28:29]
	v_cndmask_b32_e64 v84, v49, v84, s[28:29]
	v_cndmask_b32_e64 v85, v49, v85, s[28:29]
	v_cndmask_b32_e64 v86, v49, v86, s[28:29]
	v_cndmask_b32_e64 v87, v49, v87, s[28:29]
	v_cndmask_b32_e64 v88, v49, v88, s[28:29]
	v_cndmask_b32_e64 v89, v49, v89, s[28:29]
	v_cndmask_b32_e64 v90, v90, v49, s[40:41]
	v_cndmask_b32_e64 v91, v91, v49, s[42:43]
	v_cndmask_b32_e64 v92, v92, v49, s[44:45]
	v_cndmask_b32_e64 v93, v93, v49, s[46:47]
	v_max_f32_e32 v167, v58, v59
	v_max_f32_e32 v94, v60, v61
	v_max3_f32 v167, v167, v62, v63
	v_max3_f32 v94, v94, v64, v65
	v_max3_f32 v167, v167, v66, v67
	v_max3_f32 v94, v94, v68, v69
	v_max3_f32 v167, v167, v70, v71
	v_max3_f32 v94, v94, v72, v73
	v_max3_f32 v167, v167, v74, v75
	v_max3_f32 v94, v94, v76, v77
	v_max3_f32 v167, v167, v78, v79
	v_max3_f32 v94, v94, v80, v81
	v_max3_f32 v167, v167, v82, v83
	v_max3_f32 v94, v94, v84, v85
	v_max3_f32 v167, v167, v86, v87
	v_max3_f32 v94, v94, v88, v89
	v_max3_f32 v167, v167, v90, v91
	v_max3_f32 v94, v94, v92, v93
	v_max_f32_e32 v167, v167, v94
	v_mov_b32_e32 v166, v167
	s_nop 1
	v_permlane16_swap_b32_e32 v167, v166
	v_max_f32_e32 v167, v167, v166
	v_mov_b32_e32 v166, v167
	s_nop 1
	v_permlane32_swap_b32_e32 v167, v166
	v_max_f32_e32 v167, v167, v166
	v_max_f32_e32 v167, v167, v42
	v_mul_f32_e32 v94, 0xbfb8aa3b, v167
	v_fmamk_f32 v58, v58, 0x3fb8aa3b, v94
	v_fmamk_f32 v59, v59, 0x3fb8aa3b, v94
	v_fmamk_f32 v60, v60, 0x3fb8aa3b, v94
	v_fmamk_f32 v61, v61, 0x3fb8aa3b, v94
	v_fmamk_f32 v62, v62, 0x3fb8aa3b, v94
	v_fmamk_f32 v63, v63, 0x3fb8aa3b, v94
	v_fmamk_f32 v64, v64, 0x3fb8aa3b, v94
	v_fmamk_f32 v65, v65, 0x3fb8aa3b, v94
	v_fmamk_f32 v66, v66, 0x3fb8aa3b, v94
	v_fmamk_f32 v67, v67, 0x3fb8aa3b, v94
	v_fmamk_f32 v68, v68, 0x3fb8aa3b, v94
	v_fmamk_f32 v69, v69, 0x3fb8aa3b, v94
	v_fmamk_f32 v70, v70, 0x3fb8aa3b, v94
	v_fmamk_f32 v71, v71, 0x3fb8aa3b, v94
	v_fmamk_f32 v72, v72, 0x3fb8aa3b, v94
	v_fmamk_f32 v73, v73, 0x3fb8aa3b, v94
	v_fmamk_f32 v74, v74, 0x3fb8aa3b, v94
	v_fmamk_f32 v75, v75, 0x3fb8aa3b, v94
	v_fmamk_f32 v76, v76, 0x3fb8aa3b, v94
; __device__ __forceinline__ unsigned cvt_pk_bf16(float lo, float hi) { unsigned r; asm volatile("v_cvt_pk_bf16_f32 %0, %1, %2" : "=v"(r) : "v"(lo), "v"(hi)); return r; }
; #define LAS __attribute__((address_space(3)))
; #define MFMA16(a, b, c) __builtin_amdgcn_mfma_f32_16x16x32_bf16((a), (b), (c), 0, 0, 0)
; __device__ __forceinline__ void p2_block(LAS unsigned char* lds, const bf16_t* __restrict__ PROJ, bf16_t* __restrict__ ATT, bf16_t* __restrict__ SGU, const float* __restrict__ qn, const float* __restrict__ kn, ...
;     ...
;         float sum = 0.f;
; #pragma unroll
;         for (int t = 0; t < 10; ++t)
; #pragma unroll
;             for (int e = 0; e < 4; ++e) { const float p = __builtin_amdgcn_exp2f((sc_[t][e] - mx) * LOG2E); sc_[t][e] = p; sum += p; }
;         sum += __shfl_xor(sum, 16); sum += __shfl_xor(sum, 32);
;         const float inv = 1.0f / (sum + __builtin_amdgcn_exp2f((sink - mx) * LOG2E));
;         f32x4 o[4];
; #pragma unroll
;         for (int dt = 0; dt < 4; ++dt) o[dt] = (f32x4){0.f, 0.f, 0.f, 0.f};
; #pragma unroll
;         for (int j = 0; j < 5; ++j) {
;             u32x4 pw; pw.x = cvt_pk_bf16(sc_[2 * j][0], sc_[2 * j][1]); pw.y = cvt_pk_bf16(sc_[2 * j][2], sc_[2 * j][3]); pw.z = cvt_pk_bf16(sc_[2 * j + 1][0], sc_[2 * j + 1][1]); pw.w = cvt_pk_bf16(sc_[2 * j + 1][2], sc_[2 * j + 1][3]);
;             const bf16x8 pf = __builtin_bit_cast(bf16x8, pw);
; #pragma unroll
;             for (int dt = 0; dt < 4; ++dt) { const LAS unsigned char* vb = VT + (16 * dt + fr) * VT_STRIDE + (16 * (t0 + 2 * j) + 4 * fq) * 2;
;                 const u32x2 va = *(const LAS u32x2*)vb, vc = *(const LAS u32x2*)(vb + 32); u32x4 vw; vw.x = va.x; vw.y = va.y; vw.z = vc.x; vw.w = vc.y;
;                 o[dt] = MFMA16(__builtin_bit_cast(bf16x8, vw), pf, o[dt]); }
	v_fmamk_f32 v77, v77, 0x3fb8aa3b, v94
	v_fmamk_f32 v78, v78, 0x3fb8aa3b, v94
	v_fmamk_f32 v79, v79, 0x3fb8aa3b, v94
	v_fmamk_f32 v80, v80, 0x3fb8aa3b, v94
	v_fmamk_f32 v81, v81, 0x3fb8aa3b, v94
	v_fmamk_f32 v82, v82, 0x3fb8aa3b, v94
	v_fmamk_f32 v83, v83, 0x3fb8aa3b, v94
	v_fmamk_f32 v84, v84, 0x3fb8aa3b, v94
	v_fmamk_f32 v85, v85, 0x3fb8aa3b, v94
	v_fmamk_f32 v86, v86, 0x3fb8aa3b, v94
	v_fmamk_f32 v87, v87, 0x3fb8aa3b, v94
	v_fmamk_f32 v88, v88, 0x3fb8aa3b, v94
	v_fmamk_f32 v89, v89, 0x3fb8aa3b, v94
	v_fmamk_f32 v90, v90, 0x3fb8aa3b, v94
	v_fmamk_f32 v91, v91, 0x3fb8aa3b, v94
	v_fmamk_f32 v92, v92, 0x3fb8aa3b, v94
	v_fmamk_f32 v93, v93, 0x3fb8aa3b, v94
	v_exp_f32_e32 v58, v58
	v_exp_f32_e32 v59, v59
	v_exp_f32_e32 v60, v60
	v_exp_f32_e32 v61, v61
	v_exp_f32_e32 v62, v62
	v_exp_f32_e32 v63, v63
	v_exp_f32_e32 v64, v64
	v_exp_f32_e32 v65, v65
	v_exp_f32_e32 v66, v66
	v_exp_f32_e32 v67, v67
	v_exp_f32_e32 v68, v68
	v_exp_f32_e32 v69, v69
	v_exp_f32_e32 v70, v70
	v_exp_f32_e32 v71, v71
	v_exp_f32_e32 v72, v72
	v_exp_f32_e32 v73, v73
	v_exp_f32_e32 v74, v74
	v_exp_f32_e32 v75, v75
	v_exp_f32_e32 v76, v76
	v_exp_f32_e32 v77, v77
	v_exp_f32_e32 v78, v78
	v_exp_f32_e32 v79, v79
	v_exp_f32_e32 v80, v80
	v_exp_f32_e32 v81, v81
	v_exp_f32_e32 v82, v82
	v_exp_f32_e32 v83, v83
	v_exp_f32_e32 v84, v84
	v_exp_f32_e32 v85, v85
	v_exp_f32_e32 v86, v86
	v_exp_f32_e32 v87, v87
	v_exp_f32_e32 v88, v88
	v_exp_f32_e32 v89, v89
	v_exp_f32_e32 v90, v90
	v_exp_f32_e32 v91, v91
	v_exp_f32_e32 v92, v92
	v_exp_f32_e32 v93, v93
	v_fmamk_f32 v95, v42, 0x3fb8aa3b, v94
	v_exp_f32_e32 v95, v95
	v_add_f32_e32 v167, v58, v59
	v_add_f32_e32 v94, v60, v61
	v_add_f32_e32 v167, v167, v62
	v_add_f32_e32 v94, v94, v63
	v_add_f32_e32 v167, v167, v64
	v_add_f32_e32 v94, v94, v65
	v_add_f32_e32 v167, v167, v66
	v_add_f32_e32 v94, v94, v67
	v_add_f32_e32 v167, v167, v68
	v_add_f32_e32 v94, v94, v69
	v_add_f32_e32 v167, v167, v70
	v_add_f32_e32 v94, v94, v71
	v_add_f32_e32 v167, v167, v72
	v_add_f32_e32 v94, v94, v73
	v_add_f32_e32 v167, v167, v74
	v_add_f32_e32 v94, v94, v75
	v_add_f32_e32 v167, v167, v76
	v_add_f32_e32 v94, v94, v77
	v_add_f32_e32 v167, v167, v78
	v_add_f32_e32 v94, v94, v79
	v_add_f32_e32 v167, v167, v80
	v_add_f32_e32 v94, v94, v81
	v_add_f32_e32 v167, v167, v82
	v_add_f32_e32 v94, v94, v83
	v_add_f32_e32 v167, v167, v84
	v_add_f32_e32 v94, v94, v85
	v_add_f32_e32 v167, v167, v86
	v_add_f32_e32 v94, v94, v87
	v_add_f32_e32 v167, v167, v88
	v_add_f32_e32 v94, v94, v89
	v_add_f32_e32 v167, v167, v90
	v_add_f32_e32 v94, v94, v91
	v_add_f32_e32 v167, v167, v92
	v_add_f32_e32 v94, v94, v93
	v_add_f32_e32 v167, v167, v94
	v_mov_b32_e32 v166, v167
	s_nop 1
	v_permlane16_swap_b32_e32 v167, v166
	v_add_f32_e32 v167, v167, v166
	v_mov_b32_e32 v166, v167
	s_nop 1
	v_permlane32_swap_b32_e32 v167, v166
	v_add_f32_e32 v167, v167, v166
	v_add_f32_e32 v167, v167, v95
	v_rcp_f32_e32 v167, v167
	v_mov_b32_e32 v94, 0
	v_mov_b32_e32 v95, 0
	v_mov_b32_e32 v96, 0
	v_mov_b32_e32 v97, 0
	v_cvt_pk_bf16_f32 v58, v58, v59
	v_cvt_pk_bf16_f32 v59, v60, v61
	v_cvt_pk_bf16_f32 v60, v62, v63
	v_cvt_pk_bf16_f32 v61, v64, v65
	v_cvt_pk_bf16_f32 v66, v66, v67
	v_cvt_pk_bf16_f32 v67, v68, v69
	v_cvt_pk_bf16_f32 v68, v70, v71
	v_cvt_pk_bf16_f32 v69, v72, v73
	v_cvt_pk_bf16_f32 v74, v74, v75
	v_cvt_pk_bf16_f32 v75, v76, v77
	v_cvt_pk_bf16_f32 v76, v78, v79
	v_cvt_pk_bf16_f32 v77, v80, v81
	v_cvt_pk_bf16_f32 v82, v82, v83
	v_cvt_pk_bf16_f32 v83, v84, v85
	v_cvt_pk_bf16_f32 v84, v86, v87
	v_cvt_pk_bf16_f32 v85, v88, v89
	v_cvt_pk_bf16_f32 v90, v90, v91
	v_cvt_pk_bf16_f32 v91, v92, v93
	v_cvt_pk_bf16_f32 v92, v94, v95
	v_cvt_pk_bf16_f32 v93, v96, v97
	s_nop 1
	s_waitcnt lgkmcnt(14)
	v_mfma_f32_16x16x32_bf16 v[62:65], v[98:101], v[58:61], 0
	ds_read2_b64 v[158:161], v197 offset0:24 offset1:28
	s_waitcnt lgkmcnt(14)
	v_mfma_f32_16x16x32_bf16 v[70:73], v[102:105], v[58:61], 0
	ds_read2_b64 v[162:165], v194 offset0:32 offset1:36
	s_waitcnt lgkmcnt(14)
	v_mfma_f32_16x16x32_bf16 v[78:81], v[106:109], v[58:61], 0
	ds_read2_b64 v[182:185], v195 offset0:32 offset1:36
	s_waitcnt lgkmcnt(14)
	v_mfma_f32_16x16x32_bf16 v[86:89], v[110:113], v[58:61], 0
	ds_read2_b64 v[186:189], v196 offset0:32 offset1:36
	s_waitcnt lgkmcnt(14)
	v_mfma_f32_16x16x32_bf16 v[62:65], v[114:117], v[66:69], v[62:65]
	ds_read2_b64 v[190:193], v197 offset0:32 offset1:36
	s_waitcnt lgkmcnt(14)
	v_mfma_f32_16x16x32_bf16 v[70:73], v[118:121], v[66:69], v[70:73]
	s_waitcnt lgkmcnt(13)
	v_mfma_f32_16x16x32_bf16 v[78:81], v[122:125], v[66:69], v[78:81]
	s_waitcnt lgkmcnt(12)
	v_mfma_f32_16x16x32_bf16 v[86:89], v[126:129], v[66:69], v[86:89]
	s_waitcnt lgkmcnt(11)
	v_mfma_f32_16x16x32_bf16 v[62:65], v[130:133], v[74:77], v[62:65]
	s_waitcnt lgkmcnt(10)
	v_mfma_f32_16x16x32_bf16 v[70:73], v[134:137], v[74:77], v[70:73]
	s_waitcnt lgkmcnt(9)
	v_mfma_f32_16x16x32_bf16 v[78:81], v[138:141], v[74:77], v[78:81]
	s_waitcnt lgkmcnt(8)
	v_mfma_f32_16x16x32_bf16 v[86:89], v[142:145], v[74:77], v[86:89]
	s_waitcnt lgkmcnt(7)
	v_mfma_f32_16x16x32_bf16 v[62:65], v[146:149], v[82:85], v[62:65]
	s_waitcnt lgkmcnt(6)
	v_mfma_f32_16x16x32_bf16 v[70:73], v[150:153], v[82:85], v[70:73]
	s_waitcnt lgkmcnt(5)
	v_mfma_f32_16x16x32_bf16 v[78:81], v[154:157], v[82:85], v[78:81]
	s_waitcnt lgkmcnt(4)
	v_mfma_f32_16x16x32_bf16 v[86:89], v[158:161], v[82:85], v[86:89]
	s_waitcnt lgkmcnt(3)
	v_mfma_f32_16x16x32_bf16 v[62:65], v[162:165], v[90:93], v[62:65]
	s_waitcnt lgkmcnt(2)
	v_mfma_f32_16x16x32_bf16 v[70:73], v[182:185], v[90:93], v[70:73]
	s_waitcnt lgkmcnt(1)
	v_mfma_f32_16x16x32_bf16 v[78:81], v[186:189], v[90:93], v[78:81]
	s_waitcnt lgkmcnt(0)
; __device__ __forceinline__ unsigned cvt_pk_bf16(float lo, float hi) { unsigned r; asm volatile("v_cvt_pk_bf16_f32 %0, %1, %2" : "=v"(r) : "v"(lo), "v"(hi)); return r; }
; #define LAS __attribute__((address_space(3)))
; __device__ __forceinline__ void p2_block(LAS unsigned char* lds, const bf16_t* __restrict__ PROJ, bf16_t* __restrict__ ATT, bf16_t* __restrict__ SGU, const float* __restrict__ qn, const float* __restrict__ kn, ...
;     ...
;         const int i0 = rbase + 16 * c, irow = i0 + fr, pos = n * 128 + irow; const size_t grow = (size_t)b * pg8::SEQ + pos;
;         bf16x8 qf0, qf1;
;         {
;             float x1[8], x2[8]; unpack8(qa[c], x1); unpack8(qb[c], x2);
;             float ss = 0.f;
; #pragma unroll
;             for (int j = 0; j < 8; ++j) ss += x1[j] * x1[j] + x2[j] * x2[j];
;             ss += __shfl_xor(ss, 16); ss += __shfl_xor(ss, 32);
;             const float rinv = rsqrtf(ss * (1.0f / 64.0f) + pg8::EPS) * 0.125f;
;             const float* cp = COS + pos * 32 + 8 * fq; const float* sp = SIN + pos * 32 + 8 * fq;
;             float o1[8], o2[8];
; #pragma unroll
;             for (int j = 0; j < 8; ++j) { const float a1 = x1[j] * rinv * qn[8 * fq + j], a2 = x2[j] * rinv * qn[32 + 8 * fq + j], cc = cp[j], sn = sp[j]; o1[j] = a1 * cc - a2 * sn; o2[j] = a2 * cc + a1 * sn; }
;             u32x4 w0, w1;
;             w0.x = cvt_pk_bf16(o1[0], o1[1]); w0.y = cvt_pk_bf16(o1[2], o1[3]); w0.z = cvt_pk_bf16(o1[4], o1[5]); w0.w = cvt_pk_bf16(o1[6], o1[7]);
;             w1.x = cvt_pk_bf16(o2[0], o2[1]); w1.y = cvt_pk_bf16(o2[2], o2[3]); w1.z = cvt_pk_bf16(o2[4], o2[5]); w1.w = cvt_pk_bf16(o2[6], o2[7]);
;             qf0 = __builtin_bit_cast(bf16x8, w0); qf1 = __builtin_bit_cast(bf16x8, w1);
;     ...
;             for (int dt = 0; dt < 4; ++dt) { const LAS unsigned char* vb = VT + (16 * dt + fr) * VT_STRIDE + (16 * (t0 + 2 * j) + 4 * fq) * 2;
;                 const u32x2 va = *(const LAS u32x2*)vb, vc = *(const LAS u32x2*)(vb + 32); u32x4 vw; vw.x = va.x; vw.y = va.y; vw.z = vc.x; vw.w = vc.y;
;                 o[dt] = MFMA16(__builtin_bit_cast(bf16x8, vw), pf, o[dt]); }
;         }
;         bf16_t* op = ATT + grow * 1024 + hq * 64 + 4 * fq;
; #pragma unroll
;         for (int dt = 0; dt < 4; ++dt) { u32x2 ow; ow.x = cvt_pk_bf16(o[dt][0] * inv, o[dt][1] * inv); ow.y = cvt_pk_bf16(o[dt][2] * inv, o[dt][3] * inv); *(u32x2*)(op + 16 * dt) = ow; }
	v_mfma_f32_16x16x32_bf16 v[86:89], v[190:193], v[90:93], v[86:89]
	ds_read_b128 v[98:101], v45 offset:2304
	ds_read_b128 v[102:105], v45 offset:2368
	ds_read_b128 v[106:109], v45 offset:4608
	ds_read_b128 v[110:113], v45 offset:4672
	ds_read_b128 v[114:117], v45 offset:6912
	ds_read_b128 v[118:121], v45 offset:6976
	ds_read_b128 v[122:125], v45 offset:9216
	ds_read_b128 v[126:129], v45 offset:9280
	ds_read_b128 v[130:133], v45 offset:11520
	ds_read_b128 v[134:137], v45 offset:11584
	ds_read_b128 v[138:141], v45 offset:13824
	ds_read_b128 v[142:145], v45 offset:13888
	ds_read_b128 v[146:149], v45 offset:16128
	ds_read_b128 v[150:153], v45 offset:16192
	s_nop 7
	v_mul_f32_e32 v62, v62, v167
	v_mul_f32_e32 v63, v63, v167
	v_mul_f32_e32 v64, v64, v167
	v_mul_f32_e32 v65, v65, v167
	v_mul_f32_e32 v70, v70, v167
	v_mul_f32_e32 v71, v71, v167
	v_mul_f32_e32 v72, v72, v167
	v_mul_f32_e32 v73, v73, v167
	v_mul_f32_e32 v78, v78, v167
	v_mul_f32_e32 v79, v79, v167
	v_mul_f32_e32 v80, v80, v167
	v_mul_f32_e32 v81, v81, v167
	v_mul_f32_e32 v86, v86, v167
	v_mul_f32_e32 v87, v87, v167
	v_mul_f32_e32 v88, v88, v167
	v_mul_f32_e32 v89, v89, v167
	v_cvt_pk_bf16_f32 v62, v62, v63
	v_cvt_pk_bf16_f32 v63, v64, v65
	global_store_dwordx2 v48, v[62:63], s[24:25] offset:0
	v_cvt_pk_bf16_f32 v70, v70, v71
	v_cvt_pk_bf16_f32 v71, v72, v73
	global_store_dwordx2 v48, v[70:71], s[24:25] offset:32
	v_cvt_pk_bf16_f32 v78, v78, v79
	v_cvt_pk_bf16_f32 v79, v80, v81
	global_store_dwordx2 v48, v[78:79], s[24:25] offset:64
	v_cvt_pk_bf16_f32 v86, v86, v87
	v_cvt_pk_bf16_f32 v87, v88, v89
	global_store_dwordx2 v48, v[86:87], s[24:25] offset:96
	v_add_u32_e32 v48, 0x8000, v48
	s_waitcnt vmcnt(10)
	v_lshlrev_b32_e32 v58, 16, v218
	v_and_b32_e32 v59, 0xffff0000, v218
	v_lshlrev_b32_e32 v66, 16, v222
	v_and_b32_e32 v67, 0xffff0000, v222
	v_lshlrev_b32_e32 v60, 16, v219
	v_and_b32_e32 v61, 0xffff0000, v219
	v_lshlrev_b32_e32 v68, 16, v223
	v_and_b32_e32 v69, 0xffff0000, v223
	v_lshlrev_b32_e32 v62, 16, v220
	v_and_b32_e32 v63, 0xffff0000, v220
	v_lshlrev_b32_e32 v70, 16, v224
	v_and_b32_e32 v71, 0xffff0000, v224
	v_lshlrev_b32_e32 v64, 16, v221
	v_and_b32_e32 v65, 0xffff0000, v221
	v_lshlrev_b32_e32 v72, 16, v225
	v_and_b32_e32 v73, 0xffff0000, v225
	v_mul_f32_e32 v74, v58, v58
	v_mul_f32_e32 v75, v59, v59
	v_fmac_f32_e32 v74, v60, v60
	v_fmac_f32_e32 v75, v61, v61
	v_fmac_f32_e32 v74, v62, v62
	v_fmac_f32_e32 v75, v63, v63
	v_fmac_f32_e32 v74, v64, v64
	v_fmac_f32_e32 v75, v65, v65
	v_fmac_f32_e32 v74, v66, v66
	v_fmac_f32_e32 v75, v67, v67
	v_fmac_f32_e32 v74, v68, v68
	v_fmac_f32_e32 v75, v69, v69
	v_fmac_f32_e32 v74, v70, v70
	v_fmac_f32_e32 v75, v71, v71
	v_fmac_f32_e32 v74, v72, v72
	v_fmac_f32_e32 v75, v73, v73
	v_add_f32_e32 v74, v74, v75
	v_mov_b32_e32 v166, v74
	s_nop 1
	v_permlane16_swap_b32_e32 v74, v166
	v_add_f32_e32 v74, v74, v166
	v_mov_b32_e32 v166, v74
	s_nop 1
	v_permlane32_swap_b32_e32 v74, v166
	v_add_f32_e32 v74, v74, v166
	v_fmamk_f32 v74, v74, 0x3c800000, v209
	v_rsq_f32_e32 v76, v74
	s_nop 0
	v_mul_f32_e32 v76, 0x3e000000, v76
	v_mul_f32_e32 v58, v58, v76
	v_mul_f32_e32 v66, v66, v76
	v_mul_f32_e32 v59, v59, v76
	v_mul_f32_e32 v67, v67, v76
	v_mul_f32_e32 v60, v60, v76
	v_mul_f32_e32 v68, v68, v76
	v_mul_f32_e32 v61, v61, v76
	v_mul_f32_e32 v69, v69, v76
	v_mul_f32_e32 v62, v62, v76
	v_mul_f32_e32 v70, v70, v76
	v_mul_f32_e32 v63, v63, v76
	v_mul_f32_e32 v71, v71, v76
	v_mul_f32_e32 v64, v64, v76
	v_mul_f32_e32 v72, v72, v76
	v_mul_f32_e32 v65, v65, v76
	v_mul_f32_e32 v73, v73, v76
	v_mul_f32_e32 v58, v58, v26
	v_mul_f32_e32 v66, v66, v34
	v_mul_f32_e32 v59, v59, v27
	v_mul_f32_e32 v67, v67, v35
	v_mul_f32_e32 v60, v60, v28
	v_mul_f32_e32 v68, v68, v36
	v_mul_f32_e32 v61, v61, v29
	v_mul_f32_e32 v69, v69, v37
	v_mul_f32_e32 v62, v62, v30
	v_mul_f32_e32 v70, v70, v38
	v_mul_f32_e32 v63, v63, v31
	v_mul_f32_e32 v71, v71, v39
	v_mul_f32_e32 v64, v64, v32
	v_mul_f32_e32 v72, v72, v40
	v_mul_f32_e32 v65, v65, v33
	v_mul_f32_e32 v73, v73, v41
	v_mul_f32_e32 v78, v66, v234
	v_mul_f32_e32 v86, v58, v234
	v_mul_f32_e32 v79, v67, v235
	v_mul_f32_e32 v87, v59, v235
	v_mul_f32_e32 v80, v68, v236
	v_mul_f32_e32 v88, v60, v236
	v_mul_f32_e32 v81, v69, v237
	v_mul_f32_e32 v89, v61, v237
	v_mul_f32_e32 v82, v70, v238
	v_mul_f32_e32 v90, v62, v238
	v_mul_f32_e32 v83, v71, v239
	v_mul_f32_e32 v91, v63, v239
	v_mul_f32_e32 v84, v72, v240
	v_mul_f32_e32 v92, v64, v240
	v_mul_f32_e32 v85, v73, v241
	v_mul_f32_e32 v93, v65, v241
	v_fma_f32 v78, v58, v226, -v78
	v_fmac_f32_e32 v86, v66, v226
	v_fma_f32 v79, v59, v227, -v79
	v_fmac_f32_e32 v87, v67, v227
	v_fma_f32 v80, v60, v228, -v80
	v_fmac_f32_e32 v88, v68, v228
	v_fma_f32 v81, v61, v229, -v81
	v_fmac_f32_e32 v89, v69, v229
	v_fma_f32 v82, v62, v230, -v82
	v_fmac_f32_e32 v90, v70, v230
	v_fma_f32 v83, v63, v231, -v83
	v_fmac_f32_e32 v91, v71, v231
	v_fma_f32 v84, v64, v232, -v84
	v_fmac_f32_e32 v92, v72, v232
	v_fma_f32 v85, v65, v233, -v85
	v_fmac_f32_e32 v93, v73, v233
	v_cvt_pk_bf16_f32 v50, v78, v79
	v_cvt_pk_bf16_f32 v54, v86, v87
	v_cvt_pk_bf16_f32 v51, v80, v81
	v_cvt_pk_bf16_f32 v55, v88, v89
	v_cvt_pk_bf16_f32 v52, v82, v83
	v_cvt_pk_bf16_f32 v56, v90, v91
	v_cvt_pk_bf16_f32 v53, v84, v85
	v_cvt_pk_bf16_f32 v57, v92, v93
	global_load_dwordx4 v[218:221], v46, s[10:11]
	global_load_dwordx4 v[222:225], v46, s[10:11] offset:64
	global_load_dwordx4 v[226:229], v47, s[6:7]
	global_load_dwordx4 v[230:233], v47, s[6:7] offset:16
	global_load_dwordx4 v[234:237], v47, s[16:17]
	global_load_dwordx4 v[238:241], v47, s[16:17] offset:16
	v_add_u32_e32 v46, 0x3c000, v46
	v_add_u32_e32 v47, 0x800, v47
	s_nop 1
	s_waitcnt lgkmcnt(13)
; #define LAS __attribute__((address_space(3)))
; #define MFMA16(a, b, c) __builtin_amdgcn_mfma_f32_16x16x32_bf16((a), (b), (c), 0, 0, 0)
; __device__ __forceinline__ void p2_block(LAS unsigned char* lds, const bf16_t* __restrict__ PROJ, bf16_t* __restrict__ ATT, bf16_t* __restrict__ SGU, const float* __restrict__ qn, const float* __restrict__ kn, ...
;     ...
;         for (int t = 0; t < 10; ++t) { const bf16x8 k0 = *(const LAS bf16x8*)(kbase + t * 16 * KS_STRIDE), k1 = *(const LAS bf16x8*)(kbase + t * 16 * KS_STRIDE + 64);
;             f32x4 z = (f32x4){0.f, 0.f, 0.f, 0.f}; z = MFMA16(k0, qf0, z); sc_[t] = MFMA16(k1, qf1, z); }
;         float mx = -1e30f;
; #pragma unroll
;         for (int t = 0; t < 10; ++t)
; #pragma unroll
;             for (int e = 0; e < 4; ++e) { const int kx = 16 * (t0 + t) + 4 * fq + e, d = kx - irow; const bool ok = (d >= 1) && (d <= 128) && (n > 0 || kx >= 128);
;                 const float v = ok ? sc_[t][e] : -1e30f; sc_[t][e] = v; mx = fmaxf(mx, v); }
;         mx = fmaxf(mx, __shfl_xor(mx, 16)); mx = fmaxf(mx, __shfl_xor(mx, 32)); mx = fmaxf(mx, sink);
;         float sum = 0.f;
; #pragma unroll
;         for (int t = 0; t < 10; ++t)
; #pragma unroll
;             for (int e = 0; e < 4; ++e) { const float p = __builtin_amdgcn_exp2f((sc_[t][e] - mx) * LOG2E); sc_[t][e] = p; sum += p; }
	v_mfma_f32_16x16x32_bf16 v[58:61], v[98:101], v[50:53], 0
	s_waitcnt lgkmcnt(12)
	v_mfma_f32_16x16x32_bf16 v[58:61], v[102:105], v[54:57], v[58:61]
	ds_read_b128 v[154:157], v45 offset:18432
	ds_read_b128 v[158:161], v45 offset:18496
	s_waitcnt lgkmcnt(13)
	v_mfma_f32_16x16x32_bf16 v[62:65], v[106:109], v[50:53], 0
	s_waitcnt lgkmcnt(12)
	v_mfma_f32_16x16x32_bf16 v[62:65], v[110:113], v[54:57], v[62:65]
	ds_read_b128 v[162:165], v45 offset:20736
	ds_read_b128 v[182:185], v45 offset:20800
	s_waitcnt lgkmcnt(13)
	v_mfma_f32_16x16x32_bf16 v[66:69], v[114:117], v[50:53], 0
	s_waitcnt lgkmcnt(12)
	v_mfma_f32_16x16x32_bf16 v[66:69], v[118:121], v[54:57], v[66:69]
	s_waitcnt lgkmcnt(11)
	v_mfma_f32_16x16x32_bf16 v[70:73], v[122:125], v[50:53], 0
	s_waitcnt lgkmcnt(10)
	v_mfma_f32_16x16x32_bf16 v[70:73], v[126:129], v[54:57], v[70:73]
	s_waitcnt lgkmcnt(9)
	v_mfma_f32_16x16x32_bf16 v[74:77], v[130:133], v[50:53], 0
	s_waitcnt lgkmcnt(8)
	v_mfma_f32_16x16x32_bf16 v[74:77], v[134:137], v[54:57], v[74:77]
	s_waitcnt lgkmcnt(7)
	v_mfma_f32_16x16x32_bf16 v[78:81], v[138:141], v[50:53], 0
	s_waitcnt lgkmcnt(6)
	v_mfma_f32_16x16x32_bf16 v[78:81], v[142:145], v[54:57], v[78:81]
	s_waitcnt lgkmcnt(5)
	v_mfma_f32_16x16x32_bf16 v[82:85], v[146:149], v[50:53], 0
	s_waitcnt lgkmcnt(4)
	v_mfma_f32_16x16x32_bf16 v[82:85], v[150:153], v[54:57], v[82:85]
	s_waitcnt lgkmcnt(3)
	v_mfma_f32_16x16x32_bf16 v[86:89], v[154:157], v[50:53], 0
	s_waitcnt lgkmcnt(2)
	v_mfma_f32_16x16x32_bf16 v[86:89], v[158:161], v[54:57], v[86:89]
	s_waitcnt lgkmcnt(1)
	v_mfma_f32_16x16x32_bf16 v[90:93], v[162:165], v[50:53], 0
	s_waitcnt lgkmcnt(0)
	v_mfma_f32_16x16x32_bf16 v[90:93], v[182:185], v[54:57], v[90:93]
	ds_read2_b64 v[98:101], v194 offset0:4 offset1:8
	ds_read2_b64 v[102:105], v195 offset0:4 offset1:8
	ds_read2_b64 v[106:109], v196 offset0:4 offset1:8
	ds_read2_b64 v[110:113], v197 offset0:4 offset1:8
	ds_read2_b64 v[114:117], v194 offset0:12 offset1:16
	ds_read2_b64 v[118:121], v195 offset0:12 offset1:16
	ds_read2_b64 v[122:125], v196 offset0:12 offset1:16
	ds_read2_b64 v[126:129], v197 offset0:12 offset1:16
	ds_read2_b64 v[130:133], v194 offset0:20 offset1:24
	ds_read2_b64 v[134:137], v195 offset0:20 offset1:24
	ds_read2_b64 v[138:141], v196 offset0:20 offset1:24
	ds_read2_b64 v[142:145], v197 offset0:20 offset1:24
	ds_read2_b64 v[146:149], v194 offset0:28 offset1:32
	ds_read2_b64 v[150:153], v195 offset0:28 offset1:32
	ds_read2_b64 v[154:157], v196 offset0:28 offset1:32
	s_nop 4
	v_cndmask_b32_e64 v58, v49, v58, s[48:49]
	v_cndmask_b32_e64 v59, v49, v59, s[50:51]
	v_cndmask_b32_e64 v60, v49, v60, s[52:53]
	v_cndmask_b32_e64 v61, v49, v61, s[26:27]
	v_cndmask_b32_e64 v62, v49, v62, s[28:29]
	v_cndmask_b32_e64 v63, v49, v63, s[28:29]
	v_cndmask_b32_e64 v64, v49, v64, s[28:29]
	v_cndmask_b32_e64 v65, v49, v65, s[28:29]
	v_cndmask_b32_e64 v66, v49, v66, s[28:29]
	v_cndmask_b32_e64 v67, v49, v67, s[28:29]
	v_cndmask_b32_e64 v68, v49, v68, s[28:29]
	v_cndmask_b32_e64 v69, v49, v69, s[28:29]
	v_cndmask_b32_e64 v70, v49, v70, s[28:29]
	v_cndmask_b32_e64 v71, v49, v71, s[28:29]
	v_cndmask_b32_e64 v72, v49, v72, s[28:29]
	v_cndmask_b32_e64 v73, v49, v73, s[28:29]
	v_cndmask_b32_e64 v74, v49, v74, s[28:29]
	v_cndmask_b32_e64 v75, v49, v75, s[28:29]
	v_cndmask_b32_e64 v76, v49, v76, s[28:29]
	v_cndmask_b32_e64 v77, v49, v77, s[28:29]
	v_cndmask_b32_e64 v78, v49, v78, s[28:29]
	v_cndmask_b32_e64 v79, v49, v79, s[28:29]
	v_cndmask_b32_e64 v80, v49, v80, s[28:29]
	v_cndmask_b32_e64 v81, v49, v81, s[28:29]
	v_cndmask_b32_e64 v82, v49, v82, s[28:29]
	v_cndmask_b32_e64 v83, v49, v83, s[28:29]
	v_cndmask_b32_e64 v84, v49, v84, s[28:29]
	v_cndmask_b32_e64 v85, v49, v85, s[28:29]
	v_cndmask_b32_e64 v90, v90, v49, s[40:41]
	v_cndmask_b32_e64 v91, v91, v49, s[42:43]
	v_cndmask_b32_e64 v92, v92, v49, s[44:45]
	v_cndmask_b32_e64 v93, v93, v49, s[46:47]
	v_max_f32_e32 v167, v58, v59
	v_max_f32_e32 v94, v60, v61
	v_max3_f32 v167, v167, v62, v63
	v_max3_f32 v94, v94, v64, v65
	v_max3_f32 v167, v167, v66, v67
	v_max3_f32 v94, v94, v68, v69
	v_max3_f32 v167, v167, v70, v71
	v_max3_f32 v94, v94, v72, v73
	v_max3_f32 v167, v167, v74, v75
	v_max3_f32 v94, v94, v76, v77
	v_max3_f32 v167, v167, v78, v79
	v_max3_f32 v94, v94, v80, v81
	v_max3_f32 v167, v167, v82, v83
	v_max3_f32 v94, v94, v84, v85
	v_max3_f32 v167, v167, v86, v87
	v_max3_f32 v94, v94, v88, v89
	v_max3_f32 v167, v167, v90, v91
	v_max3_f32 v94, v94, v92, v93
	v_max_f32_e32 v167, v167, v94
	v_mov_b32_e32 v166, v167
	s_nop 1
	v_permlane16_swap_b32_e32 v167, v166
	v_max_f32_e32 v167, v167, v166
	v_mov_b32_e32 v166, v167
	s_nop 1
	v_permlane32_swap_b32_e32 v167, v166
	v_max_f32_e32 v167, v167, v166
	v_max_f32_e32 v167, v167, v42
	v_mul_f32_e32 v94, 0xbfb8aa3b, v167
	v_fmamk_f32 v58, v58, 0x3fb8aa3b, v94
	v_fmamk_f32 v59, v59, 0x3fb8aa3b, v94
	v_fmamk_f32 v60, v60, 0x3fb8aa3b, v94
	v_fmamk_f32 v61, v61, 0x3fb8aa3b, v94
	v_fmamk_f32 v62, v62, 0x3fb8aa3b, v94
	v_fmamk_f32 v63, v63, 0x3fb8aa3b, v94
	v_fmamk_f32 v64, v64, 0x3fb8aa3b, v94
	v_fmamk_f32 v65, v65, 0x3fb8aa3b, v94
	v_fmamk_f32 v66, v66, 0x3fb8aa3b, v94
	v_fmamk_f32 v67, v67, 0x3fb8aa3b, v94
	v_fmamk_f32 v68, v68, 0x3fb8aa3b, v94
	v_fmamk_f32 v69, v69, 0x3fb8aa3b, v94
	v_fmamk_f32 v70, v70, 0x3fb8aa3b, v94
	v_fmamk_f32 v71, v71, 0x3fb8aa3b, v94
	v_fmamk_f32 v72, v72, 0x3fb8aa3b, v94
	v_fmamk_f32 v73, v73, 0x3fb8aa3b, v94
	v_fmamk_f32 v74, v74, 0x3fb8aa3b, v94
	v_fmamk_f32 v75, v75, 0x3fb8aa3b, v94
	v_fmamk_f32 v76, v76, 0x3fb8aa3b, v94
	v_fmamk_f32 v77, v77, 0x3fb8aa3b, v94
	v_fmamk_f32 v78, v78, 0x3fb8aa3b, v94
	v_fmamk_f32 v79, v79, 0x3fb8aa3b, v94
	v_fmamk_f32 v80, v80, 0x3fb8aa3b, v94
; __device__ __forceinline__ unsigned cvt_pk_bf16(float lo, float hi) { unsigned r; asm volatile("v_cvt_pk_bf16_f32 %0, %1, %2" : "=v"(r) : "v"(lo), "v"(hi)); return r; }
; #define LAS __attribute__((address_space(3)))
; #define MFMA16(a, b, c) __builtin_amdgcn_mfma_f32_16x16x32_bf16((a), (b), (c), 0, 0, 0)
; __device__ __forceinline__ void p2_block(LAS unsigned char* lds, const bf16_t* __restrict__ PROJ, bf16_t* __restrict__ ATT, bf16_t* __restrict__ SGU, const float* __restrict__ qn, const float* __restrict__ kn, ...
;     ...
;             for (int e = 0; e < 4; ++e) { const float p = __builtin_amdgcn_exp2f((sc_[t][e] - mx) * LOG2E); sc_[t][e] = p; sum += p; }
;         sum += __shfl_xor(sum, 16); sum += __shfl_xor(sum, 32);
;         const float inv = 1.0f / (sum + __builtin_amdgcn_exp2f((sink - mx) * LOG2E));
;         f32x4 o[4];
; #pragma unroll
;         for (int dt = 0; dt < 4; ++dt) o[dt] = (f32x4){0.f, 0.f, 0.f, 0.f};
; #pragma unroll
;         for (int j = 0; j < 5; ++j) {
;             u32x4 pw; pw.x = cvt_pk_bf16(sc_[2 * j][0], sc_[2 * j][1]); pw.y = cvt_pk_bf16(sc_[2 * j][2], sc_[2 * j][3]); pw.z = cvt_pk_bf16(sc_[2 * j + 1][0], sc_[2 * j + 1][1]); pw.w = cvt_pk_bf16(sc_[2 * j + 1][2], sc_[2 * j + 1][3]);
;             const bf16x8 pf = __builtin_bit_cast(bf16x8, pw);
; #pragma unroll
;             for (int dt = 0; dt < 4; ++dt) { const LAS unsigned char* vb = VT + (16 * dt + fr) * VT_STRIDE + (16 * (t0 + 2 * j) + 4 * fq) * 2;
;                 const u32x2 va = *(const LAS u32x2*)vb, vc = *(const LAS u32x2*)(vb + 32); u32x4 vw; vw.x = va.x; vw.y = va.y; vw.z = vc.x; vw.w = vc.y;
;                 o[dt] = MFMA16(__builtin_bit_cast(bf16x8, vw), pf, o[dt]); }
	v_fmamk_f32 v81, v81, 0x3fb8aa3b, v94
	v_fmamk_f32 v82, v82, 0x3fb8aa3b, v94
	v_fmamk_f32 v83, v83, 0x3fb8aa3b, v94
	v_fmamk_f32 v84, v84, 0x3fb8aa3b, v94
	v_fmamk_f32 v85, v85, 0x3fb8aa3b, v94
	v_fmamk_f32 v86, v86, 0x3fb8aa3b, v94
	v_fmamk_f32 v87, v87, 0x3fb8aa3b, v94
	v_fmamk_f32 v88, v88, 0x3fb8aa3b, v94
	v_fmamk_f32 v89, v89, 0x3fb8aa3b, v94
	v_fmamk_f32 v90, v90, 0x3fb8aa3b, v94
	v_fmamk_f32 v91, v91, 0x3fb8aa3b, v94
	v_fmamk_f32 v92, v92, 0x3fb8aa3b, v94
	v_fmamk_f32 v93, v93, 0x3fb8aa3b, v94
	v_exp_f32_e32 v58, v58
	v_exp_f32_e32 v59, v59
	v_exp_f32_e32 v60, v60
	v_exp_f32_e32 v61, v61
	v_exp_f32_e32 v62, v62
	v_exp_f32_e32 v63, v63
	v_exp_f32_e32 v64, v64
	v_exp_f32_e32 v65, v65
	v_exp_f32_e32 v66, v66
	v_exp_f32_e32 v67, v67
	v_exp_f32_e32 v68, v68
	v_exp_f32_e32 v69, v69
	v_exp_f32_e32 v70, v70
	v_exp_f32_e32 v71, v71
	v_exp_f32_e32 v72, v72
	v_exp_f32_e32 v73, v73
	v_exp_f32_e32 v74, v74
	v_exp_f32_e32 v75, v75
	v_exp_f32_e32 v76, v76
	v_exp_f32_e32 v77, v77
	v_exp_f32_e32 v78, v78
	v_exp_f32_e32 v79, v79
	v_exp_f32_e32 v80, v80
	v_exp_f32_e32 v81, v81
	v_exp_f32_e32 v82, v82
	v_exp_f32_e32 v83, v83
	v_exp_f32_e32 v84, v84
	v_exp_f32_e32 v85, v85
	v_exp_f32_e32 v86, v86
	v_exp_f32_e32 v87, v87
	v_exp_f32_e32 v88, v88
	v_exp_f32_e32 v89, v89
	v_exp_f32_e32 v90, v90
	v_exp_f32_e32 v91, v91
	v_exp_f32_e32 v92, v92
	v_exp_f32_e32 v93, v93
	v_fmamk_f32 v95, v42, 0x3fb8aa3b, v94
	v_exp_f32_e32 v95, v95
	v_add_f32_e32 v167, v58, v59
	v_add_f32_e32 v94, v60, v61
	v_add_f32_e32 v167, v167, v62
	v_add_f32_e32 v94, v94, v63
	v_add_f32_e32 v167, v167, v64
	v_add_f32_e32 v94, v94, v65
	v_add_f32_e32 v167, v167, v66
	v_add_f32_e32 v94, v94, v67
	v_add_f32_e32 v167, v167, v68
	v_add_f32_e32 v94, v94, v69
	v_add_f32_e32 v167, v167, v70
	v_add_f32_e32 v94, v94, v71
	v_add_f32_e32 v167, v167, v72
	v_add_f32_e32 v94, v94, v73
	v_add_f32_e32 v167, v167, v74
	v_add_f32_e32 v94, v94, v75
	v_add_f32_e32 v167, v167, v76
	v_add_f32_e32 v94, v94, v77
	v_add_f32_e32 v167, v167, v78
	v_add_f32_e32 v94, v94, v79
	v_add_f32_e32 v167, v167, v80
	v_add_f32_e32 v94, v94, v81
	v_add_f32_e32 v167, v167, v82
	v_add_f32_e32 v94, v94, v83
	v_add_f32_e32 v167, v167, v84
	v_add_f32_e32 v94, v94, v85
	v_add_f32_e32 v167, v167, v86
	v_add_f32_e32 v94, v94, v87
	v_add_f32_e32 v167, v167, v88
	v_add_f32_e32 v94, v94, v89
	v_add_f32_e32 v167, v167, v90
	v_add_f32_e32 v94, v94, v91
	v_add_f32_e32 v167, v167, v92
	v_add_f32_e32 v94, v94, v93
	v_add_f32_e32 v167, v167, v94
	v_mov_b32_e32 v166, v167
	s_nop 1
	v_permlane16_swap_b32_e32 v167, v166
	v_add_f32_e32 v167, v167, v166
	v_mov_b32_e32 v166, v167
	s_nop 1
	v_permlane32_swap_b32_e32 v167, v166
	v_add_f32_e32 v167, v167, v166
	v_add_f32_e32 v167, v167, v95
	v_rcp_f32_e32 v167, v167
	v_mov_b32_e32 v94, 0
	v_mov_b32_e32 v95, 0
	v_mov_b32_e32 v96, 0
	v_mov_b32_e32 v97, 0
	v_cvt_pk_bf16_f32 v58, v58, v59
	v_cvt_pk_bf16_f32 v59, v60, v61
	v_cvt_pk_bf16_f32 v60, v62, v63
	v_cvt_pk_bf16_f32 v61, v64, v65
	v_cvt_pk_bf16_f32 v66, v66, v67
	v_cvt_pk_bf16_f32 v67, v68, v69
	v_cvt_pk_bf16_f32 v68, v70, v71
	v_cvt_pk_bf16_f32 v69, v72, v73
	v_cvt_pk_bf16_f32 v74, v74, v75
	v_cvt_pk_bf16_f32 v75, v76, v77
	v_cvt_pk_bf16_f32 v76, v78, v79
	v_cvt_pk_bf16_f32 v77, v80, v81
	v_cvt_pk_bf16_f32 v82, v82, v83
	v_cvt_pk_bf16_f32 v83, v84, v85
	v_cvt_pk_bf16_f32 v84, v86, v87
	v_cvt_pk_bf16_f32 v85, v88, v89
	v_cvt_pk_bf16_f32 v90, v90, v91
	v_cvt_pk_bf16_f32 v91, v92, v93
	v_cvt_pk_bf16_f32 v92, v94, v95
	v_cvt_pk_bf16_f32 v93, v96, v97
	s_nop 1
	s_waitcnt lgkmcnt(14)
	v_mfma_f32_16x16x32_bf16 v[62:65], v[98:101], v[58:61], 0
	ds_read2_b64 v[158:161], v197 offset0:28 offset1:32
	s_waitcnt lgkmcnt(14)
	v_mfma_f32_16x16x32_bf16 v[70:73], v[102:105], v[58:61], 0
	ds_read2_b64 v[162:165], v194 offset0:36 offset1:40
	s_waitcnt lgkmcnt(14)
	v_mfma_f32_16x16x32_bf16 v[78:81], v[106:109], v[58:61], 0
	ds_read2_b64 v[182:185], v195 offset0:36 offset1:40
	s_waitcnt lgkmcnt(14)
	v_mfma_f32_16x16x32_bf16 v[86:89], v[110:113], v[58:61], 0
	ds_read2_b64 v[186:189], v196 offset0:36 offset1:40
	s_waitcnt lgkmcnt(14)
	v_mfma_f32_16x16x32_bf16 v[62:65], v[114:117], v[66:69], v[62:65]
	ds_read2_b64 v[190:193], v197 offset0:36 offset1:40
	s_waitcnt lgkmcnt(14)
	v_mfma_f32_16x16x32_bf16 v[70:73], v[118:121], v[66:69], v[70:73]
	s_waitcnt lgkmcnt(13)
	v_mfma_f32_16x16x32_bf16 v[78:81], v[122:125], v[66:69], v[78:81]
	s_waitcnt lgkmcnt(12)
	v_mfma_f32_16x16x32_bf16 v[86:89], v[126:129], v[66:69], v[86:89]
	s_waitcnt lgkmcnt(11)
	v_mfma_f32_16x16x32_bf16 v[62:65], v[130:133], v[74:77], v[62:65]
	s_waitcnt lgkmcnt(10)
	v_mfma_f32_16x16x32_bf16 v[70:73], v[134:137], v[74:77], v[70:73]
	s_waitcnt lgkmcnt(9)
	v_mfma_f32_16x16x32_bf16 v[78:81], v[138:141], v[74:77], v[78:81]
	s_waitcnt lgkmcnt(8)
	v_mfma_f32_16x16x32_bf16 v[86:89], v[142:145], v[74:77], v[86:89]
	s_waitcnt lgkmcnt(7)
	v_mfma_f32_16x16x32_bf16 v[62:65], v[146:149], v[82:85], v[62:65]
	s_waitcnt lgkmcnt(6)
	v_mfma_f32_16x16x32_bf16 v[70:73], v[150:153], v[82:85], v[70:73]
	s_waitcnt lgkmcnt(5)
	v_mfma_f32_16x16x32_bf16 v[78:81], v[154:157], v[82:85], v[78:81]
	s_waitcnt lgkmcnt(4)
	v_mfma_f32_16x16x32_bf16 v[86:89], v[158:161], v[82:85], v[86:89]
	s_waitcnt lgkmcnt(3)
	v_mfma_f32_16x16x32_bf16 v[62:65], v[162:165], v[90:93], v[62:65]
	s_waitcnt lgkmcnt(2)
	v_mfma_f32_16x16x32_bf16 v[70:73], v[182:185], v[90:93], v[70:73]
	s_waitcnt lgkmcnt(1)
	v_mfma_f32_16x16x32_bf16 v[78:81], v[186:189], v[90:93], v[78:81]
	s_waitcnt lgkmcnt(0)
; __device__ __forceinline__ unsigned cvt_pk_bf16(float lo, float hi) { unsigned r; asm volatile("v_cvt_pk_bf16_f32 %0, %1, %2" : "=v"(r) : "v"(lo), "v"(hi)); return r; }
; __device__ __forceinline__ void unpack8(const u32x4 w, float* f) { f[0] = bf_lo(w.x); f[1] = bf_hi(w.x); f[2] = bf_lo(w.y); f[3] = bf_hi(w.y); f[4] = bf_lo(w.z); f[5] = bf_hi(w.z); f[6] = bf_lo(w.w); f[7] = bf_hi(w.w); }
; __device__ __forceinline__ void p2_block(LAS unsigned char* lds, const bf16_t* __restrict__ PROJ, bf16_t* __restrict__ ATT, bf16_t* __restrict__ SGU, const float* __restrict__ qn, const float* __restrict__ kn, ...
;     ...
;             float x1[8], x2[8]; unpack8(qa[c], x1); unpack8(qb[c], x2);
;             float ss = 0.f;
; #pragma unroll
;             for (int j = 0; j < 8; ++j) ss += x1[j] * x1[j] + x2[j] * x2[j];
;             ss += __shfl_xor(ss, 16); ss += __shfl_xor(ss, 32);
;             const float rinv = rsqrtf(ss * (1.0f / 64.0f) + pg8::EPS) * 0.125f;
;             const float* cp = COS + pos * 32 + 8 * fq; const float* sp = SIN + pos * 32 + 8 * fq;
;             float o1[8], o2[8];
; #pragma unroll
;             for (int j = 0; j < 8; ++j) { const float a1 = x1[j] * rinv * qn[8 * fq + j], a2 = x2[j] * rinv * qn[32 + 8 * fq + j], cc = cp[j], sn = sp[j]; o1[j] = a1 * cc - a2 * sn; o2[j] = a2 * cc + a1 * sn; }
;             u32x4 w0, w1;
;             w0.x = cvt_pk_bf16(o1[0], o1[1]); w0.y = cvt_pk_bf16(o1[2], o1[3]); w0.z = cvt_pk_bf16(o1[4], o1[5]); w0.w = cvt_pk_bf16(o1[6], o1[7]);
;             w1.x = cvt_pk_bf16(o2[0], o2[1]); w1.y = cvt_pk_bf16(o2[2], o2[3]); w1.z = cvt_pk_bf16(o2[4], o2[5]); w1.w = cvt_pk_bf16(o2[6], o2[7]);
;             qf0 = __builtin_bit_cast(bf16x8, w0); qf1 = __builtin_bit_cast(bf16x8, w1);
;     ...
;         bf16_t* op = ATT + grow * 1024 + hq * 64 + 4 * fq;
; #pragma unroll
;         for (int dt = 0; dt < 4; ++dt) { u32x2 ow; ow.x = cvt_pk_bf16(o[dt][0] * inv, o[dt][1] * inv); ow.y = cvt_pk_bf16(o[dt][2] * inv, o[dt][3] * inv); *(u32x2*)(op + 16 * dt) = ow; }
	v_mfma_f32_16x16x32_bf16 v[86:89], v[190:193], v[90:93], v[86:89]
	ds_read_b128 v[98:101], v45 offset:4608
	ds_read_b128 v[102:105], v45 offset:4672
	ds_read_b128 v[106:109], v45 offset:6912
	ds_read_b128 v[110:113], v45 offset:6976
	ds_read_b128 v[114:117], v45 offset:9216
	ds_read_b128 v[118:121], v45 offset:9280
	ds_read_b128 v[122:125], v45 offset:11520
	ds_read_b128 v[126:129], v45 offset:11584
	ds_read_b128 v[130:133], v45 offset:13824
	ds_read_b128 v[134:137], v45 offset:13888
	ds_read_b128 v[138:141], v45 offset:16128
	ds_read_b128 v[142:145], v45 offset:16192
	ds_read_b128 v[146:149], v45 offset:18432
	ds_read_b128 v[150:153], v45 offset:18496
	s_nop 7
	v_mul_f32_e32 v62, v62, v167
	v_mul_f32_e32 v63, v63, v167
	v_mul_f32_e32 v64, v64, v167
	v_mul_f32_e32 v65, v65, v167
	v_mul_f32_e32 v70, v70, v167
	v_mul_f32_e32 v71, v71, v167
	v_mul_f32_e32 v72, v72, v167
	v_mul_f32_e32 v73, v73, v167
	v_mul_f32_e32 v78, v78, v167
	v_mul_f32_e32 v79, v79, v167
	v_mul_f32_e32 v80, v80, v167
	v_mul_f32_e32 v81, v81, v167
	v_mul_f32_e32 v86, v86, v167
	v_mul_f32_e32 v87, v87, v167
	v_mul_f32_e32 v88, v88, v167
	v_mul_f32_e32 v89, v89, v167
	v_cvt_pk_bf16_f32 v62, v62, v63
	v_cvt_pk_bf16_f32 v63, v64, v65
	global_store_dwordx2 v48, v[62:63], s[24:25] offset:0
	v_cvt_pk_bf16_f32 v70, v70, v71
	v_cvt_pk_bf16_f32 v71, v72, v73
	global_store_dwordx2 v48, v[70:71], s[24:25] offset:32
	v_cvt_pk_bf16_f32 v78, v78, v79
	v_cvt_pk_bf16_f32 v79, v80, v81
	global_store_dwordx2 v48, v[78:79], s[24:25] offset:64
	v_cvt_pk_bf16_f32 v86, v86, v87
	v_cvt_pk_bf16_f32 v87, v88, v89
	global_store_dwordx2 v48, v[86:87], s[24:25] offset:96
	v_add_u32_e32 v48, 0x8000, v48
	s_waitcnt vmcnt(14)
	v_lshlrev_b32_e32 v58, 16, v2
	v_and_b32_e32 v59, 0xffff0000, v2
	v_lshlrev_b32_e32 v66, 16, v6
	v_and_b32_e32 v67, 0xffff0000, v6
	v_lshlrev_b32_e32 v60, 16, v3
	v_and_b32_e32 v61, 0xffff0000, v3
	v_lshlrev_b32_e32 v68, 16, v7
	v_and_b32_e32 v69, 0xffff0000, v7
	v_lshlrev_b32_e32 v62, 16, v4
	v_and_b32_e32 v63, 0xffff0000, v4
	v_lshlrev_b32_e32 v70, 16, v8
	v_and_b32_e32 v71, 0xffff0000, v8
	v_lshlrev_b32_e32 v64, 16, v5
	v_and_b32_e32 v65, 0xffff0000, v5
	v_lshlrev_b32_e32 v72, 16, v9
	v_and_b32_e32 v73, 0xffff0000, v9
	v_mul_f32_e32 v74, v58, v58
	v_mul_f32_e32 v75, v59, v59
	v_fmac_f32_e32 v74, v60, v60
	v_fmac_f32_e32 v75, v61, v61
	v_fmac_f32_e32 v74, v62, v62
	v_fmac_f32_e32 v75, v63, v63
	v_fmac_f32_e32 v74, v64, v64
	v_fmac_f32_e32 v75, v65, v65
	v_fmac_f32_e32 v74, v66, v66
	v_fmac_f32_e32 v75, v67, v67
	v_fmac_f32_e32 v74, v68, v68
	v_fmac_f32_e32 v75, v69, v69
	v_fmac_f32_e32 v74, v70, v70
	v_fmac_f32_e32 v75, v71, v71
	v_fmac_f32_e32 v74, v72, v72
	v_fmac_f32_e32 v75, v73, v73
	v_add_f32_e32 v74, v74, v75
	v_mov_b32_e32 v166, v74
	s_nop 1
	v_permlane16_swap_b32_e32 v74, v166
	v_add_f32_e32 v74, v74, v166
	v_mov_b32_e32 v166, v74
	s_nop 1
	v_permlane32_swap_b32_e32 v74, v166
	v_add_f32_e32 v74, v74, v166
	v_fmamk_f32 v74, v74, 0x3c800000, v209
	v_rsq_f32_e32 v76, v74
	s_nop 0
	v_mul_f32_e32 v76, 0x3e000000, v76
	v_mul_f32_e32 v58, v58, v76
	v_mul_f32_e32 v66, v66, v76
	v_mul_f32_e32 v59, v59, v76
	v_mul_f32_e32 v67, v67, v76
	v_mul_f32_e32 v60, v60, v76
	v_mul_f32_e32 v68, v68, v76
	v_mul_f32_e32 v61, v61, v76
	v_mul_f32_e32 v69, v69, v76
	v_mul_f32_e32 v62, v62, v76
	v_mul_f32_e32 v70, v70, v76
	v_mul_f32_e32 v63, v63, v76
	v_mul_f32_e32 v71, v71, v76
	v_mul_f32_e32 v64, v64, v76
	v_mul_f32_e32 v72, v72, v76
	v_mul_f32_e32 v65, v65, v76
	v_mul_f32_e32 v73, v73, v76
	v_mul_f32_e32 v58, v58, v26
	v_mul_f32_e32 v66, v66, v34
	v_mul_f32_e32 v59, v59, v27
	v_mul_f32_e32 v67, v67, v35
	v_mul_f32_e32 v60, v60, v28
	v_mul_f32_e32 v68, v68, v36
	v_mul_f32_e32 v61, v61, v29
	v_mul_f32_e32 v69, v69, v37
	v_mul_f32_e32 v62, v62, v30
	v_mul_f32_e32 v70, v70, v38
	v_mul_f32_e32 v63, v63, v31
	v_mul_f32_e32 v71, v71, v39
	v_mul_f32_e32 v64, v64, v32
	v_mul_f32_e32 v72, v72, v40
	v_mul_f32_e32 v65, v65, v33
	v_mul_f32_e32 v73, v73, v41
	v_mul_f32_e32 v78, v66, v18
	v_mul_f32_e32 v86, v58, v18
	v_mul_f32_e32 v79, v67, v19
	v_mul_f32_e32 v87, v59, v19
	v_mul_f32_e32 v80, v68, v20
	v_mul_f32_e32 v88, v60, v20
	v_mul_f32_e32 v81, v69, v21
	v_mul_f32_e32 v89, v61, v21
	v_mul_f32_e32 v82, v70, v22
	v_mul_f32_e32 v90, v62, v22
	v_mul_f32_e32 v83, v71, v23
	v_mul_f32_e32 v91, v63, v23
	v_mul_f32_e32 v84, v72, v24
	v_mul_f32_e32 v92, v64, v24
	v_mul_f32_e32 v85, v73, v25
	v_mul_f32_e32 v93, v65, v25
	v_fma_f32 v78, v58, v10, -v78
	v_fmac_f32_e32 v86, v66, v10
	v_fma_f32 v79, v59, v11, -v79
	v_fmac_f32_e32 v87, v67, v11
	v_fma_f32 v80, v60, v12, -v80
	v_fmac_f32_e32 v88, v68, v12
	v_fma_f32 v81, v61, v13, -v81
	v_fmac_f32_e32 v89, v69, v13
	v_fma_f32 v82, v62, v14, -v82
	v_fmac_f32_e32 v90, v70, v14
	v_fma_f32 v83, v63, v15, -v83
	v_fmac_f32_e32 v91, v71, v15
	v_fma_f32 v84, v64, v16, -v84
	v_fmac_f32_e32 v92, v72, v16
	v_fma_f32 v85, v65, v17, -v85
	v_fmac_f32_e32 v93, v73, v17
	v_cvt_pk_bf16_f32 v50, v78, v79
	v_cvt_pk_bf16_f32 v54, v86, v87
	v_cvt_pk_bf16_f32 v51, v80, v81
	v_cvt_pk_bf16_f32 v55, v88, v89
	v_cvt_pk_bf16_f32 v52, v82, v83
	v_cvt_pk_bf16_f32 v56, v90, v91
	v_cvt_pk_bf16_f32 v53, v84, v85
	v_cvt_pk_bf16_f32 v57, v92, v93
	s_nop 1
	s_waitcnt lgkmcnt(13)
	v_mfma_f32_16x16x32_bf16 v[58:61], v[98:101], v[50:53], 0
	s_waitcnt lgkmcnt(12)
	v_mfma_f32_16x16x32_bf16 v[58:61], v[102:105], v[54:57], v[58:61]
	ds_read_b128 v[154:157], v45 offset:20736
	ds_read_b128 v[158:161], v45 offset:20800
	s_waitcnt lgkmcnt(13)
	v_mfma_f32_16x16x32_bf16 v[62:65], v[106:109], v[50:53], 0
	s_waitcnt lgkmcnt(12)
; #define LAS __attribute__((address_space(3)))
; #define MFMA16(a, b, c) __builtin_amdgcn_mfma_f32_16x16x32_bf16((a), (b), (c), 0, 0, 0)
; __device__ __forceinline__ void p2_block(LAS unsigned char* lds, const bf16_t* __restrict__ PROJ, bf16_t* __restrict__ ATT, bf16_t* __restrict__ SGU, const float* __restrict__ qn, const float* __restrict__ kn, ...
;     ...
;         for (int t = 0; t < 10; ++t) { const bf16x8 k0 = *(const LAS bf16x8*)(kbase + t * 16 * KS_STRIDE), k1 = *(const LAS bf16x8*)(kbase + t * 16 * KS_STRIDE + 64);
;             f32x4 z = (f32x4){0.f, 0.f, 0.f, 0.f}; z = MFMA16(k0, qf0, z); sc_[t] = MFMA16(k1, qf1, z); }
;         float mx = -1e30f;
; #pragma unroll
;         for (int t = 0; t < 10; ++t)
; #pragma unroll
;             for (int e = 0; e < 4; ++e) { const int kx = 16 * (t0 + t) + 4 * fq + e, d = kx - irow; const bool ok = (d >= 1) && (d <= 128) && (n > 0 || kx >= 128);
;                 const float v = ok ? sc_[t][e] : -1e30f; sc_[t][e] = v; mx = fmaxf(mx, v); }
;         mx = fmaxf(mx, __shfl_xor(mx, 16)); mx = fmaxf(mx, __shfl_xor(mx, 32)); mx = fmaxf(mx, sink);
;         float sum = 0.f;
; #pragma unroll
;         for (int t = 0; t < 10; ++t)
; #pragma unroll
;             for (int e = 0; e < 4; ++e) { const float p = __builtin_amdgcn_exp2f((sc_[t][e] - mx) * LOG2E); sc_[t][e] = p; sum += p; }
	v_mfma_f32_16x16x32_bf16 v[62:65], v[110:113], v[54:57], v[62:65]
	ds_read_b128 v[162:165], v45 offset:23040
	ds_read_b128 v[182:185], v45 offset:23104
	s_waitcnt lgkmcnt(13)
	v_mfma_f32_16x16x32_bf16 v[66:69], v[114:117], v[50:53], 0
	s_waitcnt lgkmcnt(12)
	v_mfma_f32_16x16x32_bf16 v[66:69], v[118:121], v[54:57], v[66:69]
	s_waitcnt lgkmcnt(11)
	v_mfma_f32_16x16x32_bf16 v[70:73], v[122:125], v[50:53], 0
	s_waitcnt lgkmcnt(10)
	v_mfma_f32_16x16x32_bf16 v[70:73], v[126:129], v[54:57], v[70:73]
	s_waitcnt lgkmcnt(9)
	v_mfma_f32_16x16x32_bf16 v[74:77], v[130:133], v[50:53], 0
	s_waitcnt lgkmcnt(8)
	v_mfma_f32_16x16x32_bf16 v[74:77], v[134:137], v[54:57], v[74:77]
	s_waitcnt lgkmcnt(7)
	v_mfma_f32_16x16x32_bf16 v[78:81], v[138:141], v[50:53], 0
	s_waitcnt lgkmcnt(6)
	v_mfma_f32_16x16x32_bf16 v[78:81], v[142:145], v[54:57], v[78:81]
	s_waitcnt lgkmcnt(5)
	v_mfma_f32_16x16x32_bf16 v[82:85], v[146:149], v[50:53], 0
	s_waitcnt lgkmcnt(4)
	v_mfma_f32_16x16x32_bf16 v[82:85], v[150:153], v[54:57], v[82:85]
	s_waitcnt lgkmcnt(3)
	v_mfma_f32_16x16x32_bf16 v[86:89], v[154:157], v[50:53], 0
	s_waitcnt lgkmcnt(2)
	v_mfma_f32_16x16x32_bf16 v[86:89], v[158:161], v[54:57], v[86:89]
	s_waitcnt lgkmcnt(1)
	v_mfma_f32_16x16x32_bf16 v[90:93], v[162:165], v[50:53], 0
	s_waitcnt lgkmcnt(0)
	v_mfma_f32_16x16x32_bf16 v[90:93], v[182:185], v[54:57], v[90:93]
	ds_read2_b64 v[98:101], v194 offset0:8 offset1:12
	ds_read2_b64 v[102:105], v195 offset0:8 offset1:12
	ds_read2_b64 v[106:109], v196 offset0:8 offset1:12
	ds_read2_b64 v[110:113], v197 offset0:8 offset1:12
	ds_read2_b64 v[114:117], v194 offset0:16 offset1:20
	ds_read2_b64 v[118:121], v195 offset0:16 offset1:20
	ds_read2_b64 v[122:125], v196 offset0:16 offset1:20
	ds_read2_b64 v[126:129], v197 offset0:16 offset1:20
	ds_read2_b64 v[130:133], v194 offset0:24 offset1:28
	ds_read2_b64 v[134:137], v195 offset0:24 offset1:28
	ds_read2_b64 v[138:141], v196 offset0:24 offset1:28
	ds_read2_b64 v[142:145], v197 offset0:24 offset1:28
	ds_read2_b64 v[146:149], v194 offset0:32 offset1:36
	ds_read2_b64 v[150:153], v195 offset0:32 offset1:36
	ds_read2_b64 v[154:157], v196 offset0:32 offset1:36
	s_nop 4
	v_cndmask_b32_e64 v58, v49, v58, s[48:49]
	v_cndmask_b32_e64 v59, v49, v59, s[50:51]
	v_cndmask_b32_e64 v60, v49, v60, s[52:53]
	v_cndmask_b32_e64 v61, v49, v61, s[26:27]
	v_cndmask_b32_e64 v62, v49, v62, s[28:29]
	v_cndmask_b32_e64 v63, v49, v63, s[28:29]
	v_cndmask_b32_e64 v64, v49, v64, s[28:29]
	v_cndmask_b32_e64 v65, v49, v65, s[28:29]
	v_cndmask_b32_e64 v66, v49, v66, s[28:29]
	v_cndmask_b32_e64 v67, v49, v67, s[28:29]
	v_cndmask_b32_e64 v68, v49, v68, s[28:29]
	v_cndmask_b32_e64 v69, v49, v69, s[28:29]
	v_cndmask_b32_e64 v70, v49, v70, s[28:29]
	v_cndmask_b32_e64 v71, v49, v71, s[28:29]
	v_cndmask_b32_e64 v72, v49, v72, s[28:29]
	v_cndmask_b32_e64 v73, v49, v73, s[28:29]
	v_cndmask_b32_e64 v74, v49, v74, s[28:29]
	v_cndmask_b32_e64 v75, v49, v75, s[28:29]
	v_cndmask_b32_e64 v76, v49, v76, s[28:29]
	v_cndmask_b32_e64 v77, v49, v77, s[28:29]
	v_cndmask_b32_e64 v78, v49, v78, s[28:29]
	v_cndmask_b32_e64 v79, v49, v79, s[28:29]
	v_cndmask_b32_e64 v80, v49, v80, s[28:29]
	v_cndmask_b32_e64 v81, v49, v81, s[28:29]
	v_cndmask_b32_e64 v90, v90, v49, s[40:41]
	v_cndmask_b32_e64 v91, v91, v49, s[42:43]
	v_cndmask_b32_e64 v92, v92, v49, s[44:45]
	v_cndmask_b32_e64 v93, v93, v49, s[46:47]
	v_max_f32_e32 v167, v58, v59
	v_max_f32_e32 v94, v60, v61
	v_max3_f32 v167, v167, v62, v63
	v_max3_f32 v94, v94, v64, v65
	v_max3_f32 v167, v167, v66, v67
	v_max3_f32 v94, v94, v68, v69
	v_max3_f32 v167, v167, v70, v71
	v_max3_f32 v94, v94, v72, v73
	v_max3_f32 v167, v167, v74, v75
	v_max3_f32 v94, v94, v76, v77
	v_max3_f32 v167, v167, v78, v79
	v_max3_f32 v94, v94, v80, v81
	v_max3_f32 v167, v167, v82, v83
	v_max3_f32 v94, v94, v84, v85
	v_max3_f32 v167, v167, v86, v87
	v_max3_f32 v94, v94, v88, v89
	v_max3_f32 v167, v167, v90, v91
	v_max3_f32 v94, v94, v92, v93
	v_max_f32_e32 v167, v167, v94
	v_mov_b32_e32 v166, v167
	s_nop 1
	v_permlane16_swap_b32_e32 v167, v166
	v_max_f32_e32 v167, v167, v166
	v_mov_b32_e32 v166, v167
	s_nop 1
	v_permlane32_swap_b32_e32 v167, v166
	v_max_f32_e32 v167, v167, v166
	v_max_f32_e32 v167, v167, v42
	v_mul_f32_e32 v94, 0xbfb8aa3b, v167
	v_fmamk_f32 v58, v58, 0x3fb8aa3b, v94
	v_fmamk_f32 v59, v59, 0x3fb8aa3b, v94
	v_fmamk_f32 v60, v60, 0x3fb8aa3b, v94
	v_fmamk_f32 v61, v61, 0x3fb8aa3b, v94
	v_fmamk_f32 v62, v62, 0x3fb8aa3b, v94
	v_fmamk_f32 v63, v63, 0x3fb8aa3b, v94
	v_fmamk_f32 v64, v64, 0x3fb8aa3b, v94
	v_fmamk_f32 v65, v65, 0x3fb8aa3b, v94
	v_fmamk_f32 v66, v66, 0x3fb8aa3b, v94
	v_fmamk_f32 v67, v67, 0x3fb8aa3b, v94
	v_fmamk_f32 v68, v68, 0x3fb8aa3b, v94
	v_fmamk_f32 v69, v69, 0x3fb8aa3b, v94
	v_fmamk_f32 v70, v70, 0x3fb8aa3b, v94
	v_fmamk_f32 v71, v71, 0x3fb8aa3b, v94
	v_fmamk_f32 v72, v72, 0x3fb8aa3b, v94
	v_fmamk_f32 v73, v73, 0x3fb8aa3b, v94
	v_fmamk_f32 v74, v74, 0x3fb8aa3b, v94
	v_fmamk_f32 v75, v75, 0x3fb8aa3b, v94
	v_fmamk_f32 v76, v76, 0x3fb8aa3b, v94
	v_fmamk_f32 v77, v77, 0x3fb8aa3b, v94
	v_fmamk_f32 v78, v78, 0x3fb8aa3b, v94
	v_fmamk_f32 v79, v79, 0x3fb8aa3b, v94
	v_fmamk_f32 v80, v80, 0x3fb8aa3b, v94
	v_fmamk_f32 v81, v81, 0x3fb8aa3b, v94
	v_fmamk_f32 v82, v82, 0x3fb8aa3b, v94
	v_fmamk_f32 v83, v83, 0x3fb8aa3b, v94
	v_fmamk_f32 v84, v84, 0x3fb8aa3b, v94
	v_fmamk_f32 v85, v85, 0x3fb8aa3b, v94
	v_fmamk_f32 v86, v86, 0x3fb8aa3b, v94
	v_fmamk_f32 v87, v87, 0x3fb8aa3b, v94
	v_fmamk_f32 v88, v88, 0x3fb8aa3b, v94
	v_fmamk_f32 v89, v89, 0x3fb8aa3b, v94
	v_fmamk_f32 v90, v90, 0x3fb8aa3b, v94
	v_fmamk_f32 v91, v91, 0x3fb8aa3b, v94
	v_fmamk_f32 v92, v92, 0x3fb8aa3b, v94
	v_fmamk_f32 v93, v93, 0x3fb8aa3b, v94
; __device__ __forceinline__ unsigned cvt_pk_bf16(float lo, float hi) { unsigned r; asm volatile("v_cvt_pk_bf16_f32 %0, %1, %2" : "=v"(r) : "v"(lo), "v"(hi)); return r; }
; #define LAS __attribute__((address_space(3)))
; #define MFMA16(a, b, c) __builtin_amdgcn_mfma_f32_16x16x32_bf16((a), (b), (c), 0, 0, 0)
; __device__ __forceinline__ void p2_block(LAS unsigned char* lds, const bf16_t* __restrict__ PROJ, bf16_t* __restrict__ ATT, bf16_t* __restrict__ SGU, const float* __restrict__ qn, const float* __restrict__ kn, ...
;     ...
;             for (int e = 0; e < 4; ++e) { const float p = __builtin_amdgcn_exp2f((sc_[t][e] - mx) * LOG2E); sc_[t][e] = p; sum += p; }
;         sum += __shfl_xor(sum, 16); sum += __shfl_xor(sum, 32);
;         const float inv = 1.0f / (sum + __builtin_amdgcn_exp2f((sink - mx) * LOG2E));
;         f32x4 o[4];
; #pragma unroll
;         for (int dt = 0; dt < 4; ++dt) o[dt] = (f32x4){0.f, 0.f, 0.f, 0.f};
; #pragma unroll
;         for (int j = 0; j < 5; ++j) {
;             u32x4 pw; pw.x = cvt_pk_bf16(sc_[2 * j][0], sc_[2 * j][1]); pw.y = cvt_pk_bf16(sc_[2 * j][2], sc_[2 * j][3]); pw.z = cvt_pk_bf16(sc_[2 * j + 1][0], sc_[2 * j + 1][1]); pw.w = cvt_pk_bf16(sc_[2 * j + 1][2], sc_[2 * j + 1][3]);
;             const bf16x8 pf = __builtin_bit_cast(bf16x8, pw);
; #pragma unroll
;             for (int dt = 0; dt < 4; ++dt) { const LAS unsigned char* vb = VT + (16 * dt + fr) * VT_STRIDE + (16 * (t0 + 2 * j) + 4 * fq) * 2;
;                 const u32x2 va = *(const LAS u32x2*)vb, vc = *(const LAS u32x2*)(vb + 32); u32x4 vw; vw.x = va.x; vw.y = va.y; vw.z = vc.x; vw.w = vc.y;
;                 o[dt] = MFMA16(__builtin_bit_cast(bf16x8, vw), pf, o[dt]); }
	v_exp_f32_e32 v58, v58
	v_exp_f32_e32 v59, v59
	v_exp_f32_e32 v60, v60
	v_exp_f32_e32 v61, v61
	v_exp_f32_e32 v62, v62
	v_exp_f32_e32 v63, v63
	v_exp_f32_e32 v64, v64
	v_exp_f32_e32 v65, v65
	v_exp_f32_e32 v66, v66
	v_exp_f32_e32 v67, v67
	v_exp_f32_e32 v68, v68
	v_exp_f32_e32 v69, v69
	v_exp_f32_e32 v70, v70
	v_exp_f32_e32 v71, v71
	v_exp_f32_e32 v72, v72
	v_exp_f32_e32 v73, v73
	v_exp_f32_e32 v74, v74
	v_exp_f32_e32 v75, v75
	v_exp_f32_e32 v76, v76
	v_exp_f32_e32 v77, v77
	v_exp_f32_e32 v78, v78
	v_exp_f32_e32 v79, v79
	v_exp_f32_e32 v80, v80
	v_exp_f32_e32 v81, v81
	v_exp_f32_e32 v82, v82
	v_exp_f32_e32 v83, v83
	v_exp_f32_e32 v84, v84
	v_exp_f32_e32 v85, v85
	v_exp_f32_e32 v86, v86
	v_exp_f32_e32 v87, v87
	v_exp_f32_e32 v88, v88
	v_exp_f32_e32 v89, v89
	v_exp_f32_e32 v90, v90
	v_exp_f32_e32 v91, v91
	v_exp_f32_e32 v92, v92
	v_exp_f32_e32 v93, v93
	v_fmamk_f32 v95, v42, 0x3fb8aa3b, v94
	v_exp_f32_e32 v95, v95
	v_add_f32_e32 v167, v58, v59
	v_add_f32_e32 v94, v60, v61
	v_add_f32_e32 v167, v167, v62
	v_add_f32_e32 v94, v94, v63
	v_add_f32_e32 v167, v167, v64
	v_add_f32_e32 v94, v94, v65
	v_add_f32_e32 v167, v167, v66
	v_add_f32_e32 v94, v94, v67
	v_add_f32_e32 v167, v167, v68
	v_add_f32_e32 v94, v94, v69
	v_add_f32_e32 v167, v167, v70
	v_add_f32_e32 v94, v94, v71
	v_add_f32_e32 v167, v167, v72
	v_add_f32_e32 v94, v94, v73
	v_add_f32_e32 v167, v167, v74
	v_add_f32_e32 v94, v94, v75
	v_add_f32_e32 v167, v167, v76
	v_add_f32_e32 v94, v94, v77
	v_add_f32_e32 v167, v167, v78
	v_add_f32_e32 v94, v94, v79
	v_add_f32_e32 v167, v167, v80
	v_add_f32_e32 v94, v94, v81
	v_add_f32_e32 v167, v167, v82
	v_add_f32_e32 v94, v94, v83
	v_add_f32_e32 v167, v167, v84
	v_add_f32_e32 v94, v94, v85
	v_add_f32_e32 v167, v167, v86
	v_add_f32_e32 v94, v94, v87
	v_add_f32_e32 v167, v167, v88
	v_add_f32_e32 v94, v94, v89
	v_add_f32_e32 v167, v167, v90
	v_add_f32_e32 v94, v94, v91
	v_add_f32_e32 v167, v167, v92
	v_add_f32_e32 v94, v94, v93
	v_add_f32_e32 v167, v167, v94
	v_mov_b32_e32 v166, v167
	s_nop 1
	v_permlane16_swap_b32_e32 v167, v166
	v_add_f32_e32 v167, v167, v166
	v_mov_b32_e32 v166, v167
	s_nop 1
	v_permlane32_swap_b32_e32 v167, v166
	v_add_f32_e32 v167, v167, v166
	v_add_f32_e32 v167, v167, v95
	v_rcp_f32_e32 v167, v167
	v_mov_b32_e32 v94, 0
	v_mov_b32_e32 v95, 0
	v_mov_b32_e32 v96, 0
	v_mov_b32_e32 v97, 0
	v_cvt_pk_bf16_f32 v58, v58, v59
	v_cvt_pk_bf16_f32 v59, v60, v61
	v_cvt_pk_bf16_f32 v60, v62, v63
	v_cvt_pk_bf16_f32 v61, v64, v65
	v_cvt_pk_bf16_f32 v66, v66, v67
	v_cvt_pk_bf16_f32 v67, v68, v69
	v_cvt_pk_bf16_f32 v68, v70, v71
	v_cvt_pk_bf16_f32 v69, v72, v73
	v_cvt_pk_bf16_f32 v74, v74, v75
	v_cvt_pk_bf16_f32 v75, v76, v77
	v_cvt_pk_bf16_f32 v76, v78, v79
	v_cvt_pk_bf16_f32 v77, v80, v81
	v_cvt_pk_bf16_f32 v82, v82, v83
	v_cvt_pk_bf16_f32 v83, v84, v85
	v_cvt_pk_bf16_f32 v84, v86, v87
	v_cvt_pk_bf16_f32 v85, v88, v89
	v_cvt_pk_bf16_f32 v90, v90, v91
	v_cvt_pk_bf16_f32 v91, v92, v93
	v_cvt_pk_bf16_f32 v92, v94, v95
	v_cvt_pk_bf16_f32 v93, v96, v97
	s_nop 1
	s_waitcnt lgkmcnt(14)
	v_mfma_f32_16x16x32_bf16 v[62:65], v[98:101], v[58:61], 0
	ds_read2_b64 v[158:161], v197 offset0:32 offset1:36
	s_waitcnt lgkmcnt(14)
	v_mfma_f32_16x16x32_bf16 v[70:73], v[102:105], v[58:61], 0
	ds_read2_b64 v[162:165], v194 offset0:40 offset1:44
	s_waitcnt lgkmcnt(14)
	v_mfma_f32_16x16x32_bf16 v[78:81], v[106:109], v[58:61], 0
	ds_read2_b64 v[182:185], v195 offset0:40 offset1:44
	s_waitcnt lgkmcnt(14)
	v_mfma_f32_16x16x32_bf16 v[86:89], v[110:113], v[58:61], 0
	ds_read2_b64 v[186:189], v196 offset0:40 offset1:44
	s_waitcnt lgkmcnt(14)
	v_mfma_f32_16x16x32_bf16 v[62:65], v[114:117], v[66:69], v[62:65]
	ds_read2_b64 v[190:193], v197 offset0:40 offset1:44
	s_waitcnt lgkmcnt(14)
	v_mfma_f32_16x16x32_bf16 v[70:73], v[118:121], v[66:69], v[70:73]
	s_waitcnt lgkmcnt(13)
	v_mfma_f32_16x16x32_bf16 v[78:81], v[122:125], v[66:69], v[78:81]
	s_waitcnt lgkmcnt(12)
	v_mfma_f32_16x16x32_bf16 v[86:89], v[126:129], v[66:69], v[86:89]
	s_waitcnt lgkmcnt(11)
	v_mfma_f32_16x16x32_bf16 v[62:65], v[130:133], v[74:77], v[62:65]
	s_waitcnt lgkmcnt(10)
	v_mfma_f32_16x16x32_bf16 v[70:73], v[134:137], v[74:77], v[70:73]
	s_waitcnt lgkmcnt(9)
	v_mfma_f32_16x16x32_bf16 v[78:81], v[138:141], v[74:77], v[78:81]
	s_waitcnt lgkmcnt(8)
	v_mfma_f32_16x16x32_bf16 v[86:89], v[142:145], v[74:77], v[86:89]
	s_waitcnt lgkmcnt(7)
	v_mfma_f32_16x16x32_bf16 v[62:65], v[146:149], v[82:85], v[62:65]
	s_waitcnt lgkmcnt(6)
	v_mfma_f32_16x16x32_bf16 v[70:73], v[150:153], v[82:85], v[70:73]
	s_waitcnt lgkmcnt(5)
	v_mfma_f32_16x16x32_bf16 v[78:81], v[154:157], v[82:85], v[78:81]
	s_waitcnt lgkmcnt(4)
	v_mfma_f32_16x16x32_bf16 v[86:89], v[158:161], v[82:85], v[86:89]
	s_waitcnt lgkmcnt(3)
	v_mfma_f32_16x16x32_bf16 v[62:65], v[162:165], v[90:93], v[62:65]
	s_waitcnt lgkmcnt(2)
	v_mfma_f32_16x16x32_bf16 v[70:73], v[182:185], v[90:93], v[70:73]
	s_waitcnt lgkmcnt(1)
	v_mfma_f32_16x16x32_bf16 v[78:81], v[186:189], v[90:93], v[78:81]
	s_waitcnt lgkmcnt(0)
; __device__ __forceinline__ unsigned cvt_pk_bf16(float lo, float hi) { unsigned r; asm volatile("v_cvt_pk_bf16_f32 %0, %1, %2" : "=v"(r) : "v"(lo), "v"(hi)); return r; }
; __device__ __forceinline__ void unpack8(const u32x4 w, float* f) { f[0] = bf_lo(w.x); f[1] = bf_hi(w.x); f[2] = bf_lo(w.y); f[3] = bf_hi(w.y); f[4] = bf_lo(w.z); f[5] = bf_hi(w.z); f[6] = bf_lo(w.w); f[7] = bf_hi(w.w); }
; __device__ __forceinline__ void p2_block(LAS unsigned char* lds, const bf16_t* __restrict__ PROJ, bf16_t* __restrict__ ATT, bf16_t* __restrict__ SGU, const float* __restrict__ qn, const float* __restrict__ kn, ...
;     ...
;             float x1[8], x2[8]; unpack8(qa[c], x1); unpack8(qb[c], x2);
;             float ss = 0.f;
; #pragma unroll
;             for (int j = 0; j < 8; ++j) ss += x1[j] * x1[j] + x2[j] * x2[j];
;             ss += __shfl_xor(ss, 16); ss += __shfl_xor(ss, 32);
;             const float rinv = rsqrtf(ss * (1.0f / 64.0f) + pg8::EPS) * 0.125f;
;             const float* cp = COS + pos * 32 + 8 * fq; const float* sp = SIN + pos * 32 + 8 * fq;
;             float o1[8], o2[8];
; #pragma unroll
;             for (int j = 0; j < 8; ++j) { const float a1 = x1[j] * rinv * qn[8 * fq + j], a2 = x2[j] * rinv * qn[32 + 8 * fq + j], cc = cp[j], sn = sp[j]; o1[j] = a1 * cc - a2 * sn; o2[j] = a2 * cc + a1 * sn; }
;             u32x4 w0, w1;
;             w0.x = cvt_pk_bf16(o1[0], o1[1]); w0.y = cvt_pk_bf16(o1[2], o1[3]); w0.z = cvt_pk_bf16(o1[4], o1[5]); w0.w = cvt_pk_bf16(o1[6], o1[7]);
;             w1.x = cvt_pk_bf16(o2[0], o2[1]); w1.y = cvt_pk_bf16(o2[2], o2[3]); w1.z = cvt_pk_bf16(o2[4], o2[5]); w1.w = cvt_pk_bf16(o2[6], o2[7]);
;             qf0 = __builtin_bit_cast(bf16x8, w0); qf1 = __builtin_bit_cast(bf16x8, w1);
;     ...
;         bf16_t* op = ATT + grow * 1024 + hq * 64 + 4 * fq;
; #pragma unroll
;         for (int dt = 0; dt < 4; ++dt) { u32x2 ow; ow.x = cvt_pk_bf16(o[dt][0] * inv, o[dt][1] * inv); ow.y = cvt_pk_bf16(o[dt][2] * inv, o[dt][3] * inv); *(u32x2*)(op + 16 * dt) = ow; }
	v_mfma_f32_16x16x32_bf16 v[86:89], v[190:193], v[90:93], v[86:89]
	ds_read_b128 v[98:101], v45 offset:6912
	ds_read_b128 v[102:105], v45 offset:6976
	ds_read_b128 v[106:109], v45 offset:9216
	ds_read_b128 v[110:113], v45 offset:9280
	ds_read_b128 v[114:117], v45 offset:11520
	ds_read_b128 v[118:121], v45 offset:11584
	ds_read_b128 v[122:125], v45 offset:13824
	ds_read_b128 v[126:129], v45 offset:13888
	ds_read_b128 v[130:133], v45 offset:16128
	ds_read_b128 v[134:137], v45 offset:16192
	ds_read_b128 v[138:141], v45 offset:18432
	ds_read_b128 v[142:145], v45 offset:18496
	ds_read_b128 v[146:149], v45 offset:20736
	ds_read_b128 v[150:153], v45 offset:20800
	s_nop 7
	v_mul_f32_e32 v62, v62, v167
	v_mul_f32_e32 v63, v63, v167
	v_mul_f32_e32 v64, v64, v167
	v_mul_f32_e32 v65, v65, v167
	v_mul_f32_e32 v70, v70, v167
	v_mul_f32_e32 v71, v71, v167
	v_mul_f32_e32 v72, v72, v167
	v_mul_f32_e32 v73, v73, v167
	v_mul_f32_e32 v78, v78, v167
	v_mul_f32_e32 v79, v79, v167
	v_mul_f32_e32 v80, v80, v167
	v_mul_f32_e32 v81, v81, v167
	v_mul_f32_e32 v86, v86, v167
	v_mul_f32_e32 v87, v87, v167
	v_mul_f32_e32 v88, v88, v167
	v_mul_f32_e32 v89, v89, v167
	v_cvt_pk_bf16_f32 v62, v62, v63
	v_cvt_pk_bf16_f32 v63, v64, v65
	global_store_dwordx2 v48, v[62:63], s[24:25] offset:0
	v_cvt_pk_bf16_f32 v70, v70, v71
	v_cvt_pk_bf16_f32 v71, v72, v73
	global_store_dwordx2 v48, v[70:71], s[24:25] offset:32
	v_cvt_pk_bf16_f32 v78, v78, v79
	v_cvt_pk_bf16_f32 v79, v80, v81
	global_store_dwordx2 v48, v[78:79], s[24:25] offset:64
	v_cvt_pk_bf16_f32 v86, v86, v87
	v_cvt_pk_bf16_f32 v87, v88, v89
	global_store_dwordx2 v48, v[86:87], s[24:25] offset:96
	v_add_u32_e32 v48, 0x8000, v48
	s_waitcnt vmcnt(8)
	v_lshlrev_b32_e32 v58, 16, v218
	v_and_b32_e32 v59, 0xffff0000, v218
	v_lshlrev_b32_e32 v66, 16, v222
	v_and_b32_e32 v67, 0xffff0000, v222
	v_lshlrev_b32_e32 v60, 16, v219
	v_and_b32_e32 v61, 0xffff0000, v219
	v_lshlrev_b32_e32 v68, 16, v223
	v_and_b32_e32 v69, 0xffff0000, v223
	v_lshlrev_b32_e32 v62, 16, v220
	v_and_b32_e32 v63, 0xffff0000, v220
	v_lshlrev_b32_e32 v70, 16, v224
	v_and_b32_e32 v71, 0xffff0000, v224
	v_lshlrev_b32_e32 v64, 16, v221
	v_and_b32_e32 v65, 0xffff0000, v221
	v_lshlrev_b32_e32 v72, 16, v225
	v_and_b32_e32 v73, 0xffff0000, v225
	v_mul_f32_e32 v74, v58, v58
	v_mul_f32_e32 v75, v59, v59
	v_fmac_f32_e32 v74, v60, v60
	v_fmac_f32_e32 v75, v61, v61
	v_fmac_f32_e32 v74, v62, v62
	v_fmac_f32_e32 v75, v63, v63
	v_fmac_f32_e32 v74, v64, v64
	v_fmac_f32_e32 v75, v65, v65
	v_fmac_f32_e32 v74, v66, v66
	v_fmac_f32_e32 v75, v67, v67
	v_fmac_f32_e32 v74, v68, v68
	v_fmac_f32_e32 v75, v69, v69
	v_fmac_f32_e32 v74, v70, v70
	v_fmac_f32_e32 v75, v71, v71
	v_fmac_f32_e32 v74, v72, v72
	v_fmac_f32_e32 v75, v73, v73
	v_add_f32_e32 v74, v74, v75
	v_mov_b32_e32 v166, v74
	s_nop 1
	v_permlane16_swap_b32_e32 v74, v166
	v_add_f32_e32 v74, v74, v166
	v_mov_b32_e32 v166, v74
	s_nop 1
	v_permlane32_swap_b32_e32 v74, v166
	v_add_f32_e32 v74, v74, v166
	v_fmamk_f32 v74, v74, 0x3c800000, v209
	v_rsq_f32_e32 v76, v74
	s_nop 0
	v_mul_f32_e32 v76, 0x3e000000, v76
	v_mul_f32_e32 v58, v58, v76
	v_mul_f32_e32 v66, v66, v76
	v_mul_f32_e32 v59, v59, v76
	v_mul_f32_e32 v67, v67, v76
	v_mul_f32_e32 v60, v60, v76
	v_mul_f32_e32 v68, v68, v76
	v_mul_f32_e32 v61, v61, v76
	v_mul_f32_e32 v69, v69, v76
	v_mul_f32_e32 v62, v62, v76
	v_mul_f32_e32 v70, v70, v76
	v_mul_f32_e32 v63, v63, v76
	v_mul_f32_e32 v71, v71, v76
	v_mul_f32_e32 v64, v64, v76
	v_mul_f32_e32 v72, v72, v76
	v_mul_f32_e32 v65, v65, v76
	v_mul_f32_e32 v73, v73, v76
	v_mul_f32_e32 v58, v58, v26
	v_mul_f32_e32 v66, v66, v34
	v_mul_f32_e32 v59, v59, v27
	v_mul_f32_e32 v67, v67, v35
	v_mul_f32_e32 v60, v60, v28
	v_mul_f32_e32 v68, v68, v36
	v_mul_f32_e32 v61, v61, v29
	v_mul_f32_e32 v69, v69, v37
	v_mul_f32_e32 v62, v62, v30
	v_mul_f32_e32 v70, v70, v38
	v_mul_f32_e32 v63, v63, v31
	v_mul_f32_e32 v71, v71, v39
	v_mul_f32_e32 v64, v64, v32
	v_mul_f32_e32 v72, v72, v40
	v_mul_f32_e32 v65, v65, v33
	v_mul_f32_e32 v73, v73, v41
	v_mul_f32_e32 v78, v66, v234
	v_mul_f32_e32 v86, v58, v234
	v_mul_f32_e32 v79, v67, v235
	v_mul_f32_e32 v87, v59, v235
	v_mul_f32_e32 v80, v68, v236
	v_mul_f32_e32 v88, v60, v236
	v_mul_f32_e32 v81, v69, v237
	v_mul_f32_e32 v89, v61, v237
	v_mul_f32_e32 v82, v70, v238
	v_mul_f32_e32 v90, v62, v238
	v_mul_f32_e32 v83, v71, v239
	v_mul_f32_e32 v91, v63, v239
	v_mul_f32_e32 v84, v72, v240
	v_mul_f32_e32 v92, v64, v240
	v_mul_f32_e32 v85, v73, v241
	v_mul_f32_e32 v93, v65, v241
	v_fma_f32 v78, v58, v226, -v78
	v_fmac_f32_e32 v86, v66, v226
	v_fma_f32 v79, v59, v227, -v79
	v_fmac_f32_e32 v87, v67, v227
	v_fma_f32 v80, v60, v228, -v80
	v_fmac_f32_e32 v88, v68, v228
	v_fma_f32 v81, v61, v229, -v81
	v_fmac_f32_e32 v89, v69, v229
	v_fma_f32 v82, v62, v230, -v82
	v_fmac_f32_e32 v90, v70, v230
	v_fma_f32 v83, v63, v231, -v83
	v_fmac_f32_e32 v91, v71, v231
	v_fma_f32 v84, v64, v232, -v84
	v_fmac_f32_e32 v92, v72, v232
	v_fma_f32 v85, v65, v233, -v85
	v_fmac_f32_e32 v93, v73, v233
	v_cvt_pk_bf16_f32 v50, v78, v79
	v_cvt_pk_bf16_f32 v54, v86, v87
	v_cvt_pk_bf16_f32 v51, v80, v81
	v_cvt_pk_bf16_f32 v55, v88, v89
	v_cvt_pk_bf16_f32 v52, v82, v83
	v_cvt_pk_bf16_f32 v56, v90, v91
	v_cvt_pk_bf16_f32 v53, v84, v85
	v_cvt_pk_bf16_f32 v57, v92, v93
	v_lshrrev_b32_e32 v242, 2, v204
	v_and_b32_e32 v242, 0x70, v242
	v_and_b32_e32 v243, 15, v204
	v_or_b32_e32 v242, v242, v243
	v_lshrrev_b32_e32 v243, 1, v204
	v_and_b32_e32 v243, 24, v243
	v_and_b32_e64 v244, s2, 3
	v_lshlrev_b32_e32 v244, 9, v244
	v_and_b32_e64 v245, s2, -4
	v_lshl_add_u32 v245, v245, 5, v242
	v_mul_u32_u24_e32 v245, 0x3c00, v245
	v_add3_u32 v245, v245, v244, v243
	v_lshlrev_b32_e32 v244, 1, v244
	v_lshl_add_u32 v244, v242, 2, v244
	global_load_dword v198, v244, s[22:23]
	global_load_dword v199, v244, s[22:23] offset:512
	global_load_dwordx2 v[218:219], v245, s[10:11] offset:3072
	global_load_dwordx2 v[220:221], v245, s[10:11] offset:3104
	global_load_dwordx2 v[222:223], v245, s[10:11] offset:3136
	global_load_dwordx2 v[224:225], v245, s[10:11] offset:3168
	global_load_dwordx2 v[226:227], v245, s[10:11] offset:3200
	global_load_dwordx2 v[228:229], v245, s[10:11] offset:3232
	global_load_dwordx2 v[230:231], v245, s[10:11] offset:3264
	global_load_dwordx2 v[232:233], v245, s[10:11] offset:3296
	global_load_dwordx2 v[234:235], v245, s[10:11] offset:3328
	global_load_dwordx2 v[236:237], v245, s[10:11] offset:3360
	global_load_dwordx2 v[238:239], v245, s[10:11] offset:3392
	global_load_dwordx2 v[240:241], v245, s[10:11] offset:3424
	global_load_dwordx2 v[242:243], v245, s[10:11] offset:3456
	global_load_dwordx2 v[200:201], v245, s[10:11] offset:3520
	global_load_dwordx2 v[202:203], v245, s[10:11] offset:3552
	global_load_dwordx2 v[244:245], v245, s[10:11] offset:3488
	s_nop 1
	s_waitcnt lgkmcnt(13)
; #define LAS __attribute__((address_space(3)))
; #define MFMA16(a, b, c) __builtin_amdgcn_mfma_f32_16x16x32_bf16((a), (b), (c), 0, 0, 0)
; __device__ __forceinline__ void p2_block(LAS unsigned char* lds, const bf16_t* __restrict__ PROJ, bf16_t* __restrict__ ATT, bf16_t* __restrict__ SGU, const float* __restrict__ qn, const float* __restrict__ kn, ...
;     ...
;         for (int t = 0; t < 10; ++t) { const bf16x8 k0 = *(const LAS bf16x8*)(kbase + t * 16 * KS_STRIDE), k1 = *(const LAS bf16x8*)(kbase + t * 16 * KS_STRIDE + 64);
;             f32x4 z = (f32x4){0.f, 0.f, 0.f, 0.f}; z = MFMA16(k0, qf0, z); sc_[t] = MFMA16(k1, qf1, z); }
;         float mx = -1e30f;
; #pragma unroll
;         for (int t = 0; t < 10; ++t)
; #pragma unroll
;             for (int e = 0; e < 4; ++e) { const int kx = 16 * (t0 + t) + 4 * fq + e, d = kx - irow; const bool ok = (d >= 1) && (d <= 128) && (n > 0 || kx >= 128);
;                 const float v = ok ? sc_[t][e] : -1e30f; sc_[t][e] = v; mx = fmaxf(mx, v); }
;         mx = fmaxf(mx, __shfl_xor(mx, 16)); mx = fmaxf(mx, __shfl_xor(mx, 32)); mx = fmaxf(mx, sink);
;         float sum = 0.f;
; #pragma unroll
;         for (int t = 0; t < 10; ++t)
; #pragma unroll
;             for (int e = 0; e < 4; ++e) { const float p = __builtin_amdgcn_exp2f((sc_[t][e] - mx) * LOG2E); sc_[t][e] = p; sum += p; }
	v_mfma_f32_16x16x32_bf16 v[58:61], v[98:101], v[50:53], 0
	s_waitcnt lgkmcnt(12)
	v_mfma_f32_16x16x32_bf16 v[58:61], v[102:105], v[54:57], v[58:61]
	ds_read_b128 v[154:157], v45 offset:23040
	ds_read_b128 v[158:161], v45 offset:23104
	s_waitcnt lgkmcnt(13)
	v_mfma_f32_16x16x32_bf16 v[62:65], v[106:109], v[50:53], 0
	s_waitcnt lgkmcnt(12)
	v_mfma_f32_16x16x32_bf16 v[62:65], v[110:113], v[54:57], v[62:65]
	ds_read_b128 v[162:165], v45 offset:25344
	ds_read_b128 v[182:185], v45 offset:25408
	s_waitcnt lgkmcnt(13)
	v_mfma_f32_16x16x32_bf16 v[66:69], v[114:117], v[50:53], 0
	s_waitcnt lgkmcnt(12)
	v_mfma_f32_16x16x32_bf16 v[66:69], v[118:121], v[54:57], v[66:69]
	s_waitcnt lgkmcnt(11)
	v_mfma_f32_16x16x32_bf16 v[70:73], v[122:125], v[50:53], 0
	s_waitcnt lgkmcnt(10)
	v_mfma_f32_16x16x32_bf16 v[70:73], v[126:129], v[54:57], v[70:73]
	s_waitcnt lgkmcnt(9)
	v_mfma_f32_16x16x32_bf16 v[74:77], v[130:133], v[50:53], 0
	s_waitcnt lgkmcnt(8)
	v_mfma_f32_16x16x32_bf16 v[74:77], v[134:137], v[54:57], v[74:77]
	s_waitcnt lgkmcnt(7)
	v_mfma_f32_16x16x32_bf16 v[78:81], v[138:141], v[50:53], 0
	s_waitcnt lgkmcnt(6)
	v_mfma_f32_16x16x32_bf16 v[78:81], v[142:145], v[54:57], v[78:81]
	s_waitcnt lgkmcnt(5)
	v_mfma_f32_16x16x32_bf16 v[82:85], v[146:149], v[50:53], 0
	s_waitcnt lgkmcnt(4)
	v_mfma_f32_16x16x32_bf16 v[82:85], v[150:153], v[54:57], v[82:85]
	s_waitcnt lgkmcnt(3)
	v_mfma_f32_16x16x32_bf16 v[86:89], v[154:157], v[50:53], 0
	s_waitcnt lgkmcnt(2)
	v_mfma_f32_16x16x32_bf16 v[86:89], v[158:161], v[54:57], v[86:89]
	s_waitcnt lgkmcnt(1)
	v_mfma_f32_16x16x32_bf16 v[90:93], v[162:165], v[50:53], 0
	s_waitcnt lgkmcnt(0)
	v_mfma_f32_16x16x32_bf16 v[90:93], v[182:185], v[54:57], v[90:93]
	ds_read2_b64 v[98:101], v194 offset0:12 offset1:16
	ds_read2_b64 v[102:105], v195 offset0:12 offset1:16
	ds_read2_b64 v[106:109], v196 offset0:12 offset1:16
	ds_read2_b64 v[110:113], v197 offset0:12 offset1:16
	ds_read2_b64 v[114:117], v194 offset0:20 offset1:24
	ds_read2_b64 v[118:121], v195 offset0:20 offset1:24
	ds_read2_b64 v[122:125], v196 offset0:20 offset1:24
	ds_read2_b64 v[126:129], v197 offset0:20 offset1:24
	ds_read2_b64 v[130:133], v194 offset0:28 offset1:32
	ds_read2_b64 v[134:137], v195 offset0:28 offset1:32
	ds_read2_b64 v[138:141], v196 offset0:28 offset1:32
	ds_read2_b64 v[142:145], v197 offset0:28 offset1:32
	ds_read2_b64 v[146:149], v194 offset0:36 offset1:40
	ds_read2_b64 v[150:153], v195 offset0:36 offset1:40
	ds_read2_b64 v[154:157], v196 offset0:36 offset1:40
	s_nop 4
	v_cndmask_b32_e64 v58, v49, v58, s[48:49]
	v_cndmask_b32_e64 v59, v49, v59, s[50:51]
	v_cndmask_b32_e64 v60, v49, v60, s[52:53]
	v_cndmask_b32_e64 v61, v49, v61, s[26:27]
	v_cndmask_b32_e64 v62, v49, v62, s[28:29]
	v_cndmask_b32_e64 v63, v49, v63, s[28:29]
	v_cndmask_b32_e64 v64, v49, v64, s[28:29]
	v_cndmask_b32_e64 v65, v49, v65, s[28:29]
	v_cndmask_b32_e64 v66, v49, v66, s[28:29]
	v_cndmask_b32_e64 v67, v49, v67, s[28:29]
	v_cndmask_b32_e64 v68, v49, v68, s[28:29]
	v_cndmask_b32_e64 v69, v49, v69, s[28:29]
	v_cndmask_b32_e64 v70, v49, v70, s[28:29]
	v_cndmask_b32_e64 v71, v49, v71, s[28:29]
	v_cndmask_b32_e64 v72, v49, v72, s[28:29]
	v_cndmask_b32_e64 v73, v49, v73, s[28:29]
	v_cndmask_b32_e64 v74, v49, v74, s[28:29]
	v_cndmask_b32_e64 v75, v49, v75, s[28:29]
	v_cndmask_b32_e64 v76, v49, v76, s[28:29]
	v_cndmask_b32_e64 v77, v49, v77, s[28:29]
	v_cndmask_b32_e64 v90, v90, v49, s[40:41]
	v_cndmask_b32_e64 v91, v91, v49, s[42:43]
	v_cndmask_b32_e64 v92, v92, v49, s[44:45]
	v_cndmask_b32_e64 v93, v93, v49, s[46:47]
	v_max_f32_e32 v167, v58, v59
	v_max_f32_e32 v94, v60, v61
	v_max3_f32 v167, v167, v62, v63
	v_max3_f32 v94, v94, v64, v65
	v_max3_f32 v167, v167, v66, v67
	v_max3_f32 v94, v94, v68, v69
	v_max3_f32 v167, v167, v70, v71
	v_max3_f32 v94, v94, v72, v73
	v_max3_f32 v167, v167, v74, v75
	v_max3_f32 v94, v94, v76, v77
	v_max3_f32 v167, v167, v78, v79
	v_max3_f32 v94, v94, v80, v81
	v_max3_f32 v167, v167, v82, v83
	v_max3_f32 v94, v94, v84, v85
	v_max3_f32 v167, v167, v86, v87
	v_max3_f32 v94, v94, v88, v89
	v_max3_f32 v167, v167, v90, v91
	v_max3_f32 v94, v94, v92, v93
	v_max_f32_e32 v167, v167, v94
	v_mov_b32_e32 v166, v167
	s_nop 1
	v_permlane16_swap_b32_e32 v167, v166
	v_max_f32_e32 v167, v167, v166
	v_mov_b32_e32 v166, v167
	s_nop 1
	v_permlane32_swap_b32_e32 v167, v166
	v_max_f32_e32 v167, v167, v166
	v_max_f32_e32 v167, v167, v42
	v_mul_f32_e32 v94, 0xbfb8aa3b, v167
	v_fmamk_f32 v58, v58, 0x3fb8aa3b, v94
	v_fmamk_f32 v59, v59, 0x3fb8aa3b, v94
	v_fmamk_f32 v60, v60, 0x3fb8aa3b, v94
	v_fmamk_f32 v61, v61, 0x3fb8aa3b, v94
	v_fmamk_f32 v62, v62, 0x3fb8aa3b, v94
	v_fmamk_f32 v63, v63, 0x3fb8aa3b, v94
	v_fmamk_f32 v64, v64, 0x3fb8aa3b, v94
	v_fmamk_f32 v65, v65, 0x3fb8aa3b, v94
	v_fmamk_f32 v66, v66, 0x3fb8aa3b, v94
	v_fmamk_f32 v67, v67, 0x3fb8aa3b, v94
	v_fmamk_f32 v68, v68, 0x3fb8aa3b, v94
	v_fmamk_f32 v69, v69, 0x3fb8aa3b, v94
	v_fmamk_f32 v70, v70, 0x3fb8aa3b, v94
	v_fmamk_f32 v71, v71, 0x3fb8aa3b, v94
	v_fmamk_f32 v72, v72, 0x3fb8aa3b, v94
	v_fmamk_f32 v73, v73, 0x3fb8aa3b, v94
	v_fmamk_f32 v74, v74, 0x3fb8aa3b, v94
	v_fmamk_f32 v75, v75, 0x3fb8aa3b, v94
	v_fmamk_f32 v76, v76, 0x3fb8aa3b, v94
	v_fmamk_f32 v77, v77, 0x3fb8aa3b, v94
	v_fmamk_f32 v78, v78, 0x3fb8aa3b, v94
	v_fmamk_f32 v79, v79, 0x3fb8aa3b, v94
	v_fmamk_f32 v80, v80, 0x3fb8aa3b, v94
	v_fmamk_f32 v81, v81, 0x3fb8aa3b, v94
	v_fmamk_f32 v82, v82, 0x3fb8aa3b, v94
	v_fmamk_f32 v83, v83, 0x3fb8aa3b, v94
	v_fmamk_f32 v84, v84, 0x3fb8aa3b, v94
	v_fmamk_f32 v85, v85, 0x3fb8aa3b, v94
	v_fmamk_f32 v86, v86, 0x3fb8aa3b, v94
	v_fmamk_f32 v87, v87, 0x3fb8aa3b, v94
	v_fmamk_f32 v88, v88, 0x3fb8aa3b, v94
	v_fmamk_f32 v89, v89, 0x3fb8aa3b, v94
; __device__ __forceinline__ unsigned cvt_pk_bf16(float lo, float hi) { unsigned r; asm volatile("v_cvt_pk_bf16_f32 %0, %1, %2" : "=v"(r) : "v"(lo), "v"(hi)); return r; }
; #define LAS __attribute__((address_space(3)))
; #define MFMA16(a, b, c) __builtin_amdgcn_mfma_f32_16x16x32_bf16((a), (b), (c), 0, 0, 0)
; __device__ __forceinline__ void p2_block(LAS unsigned char* lds, const bf16_t* __restrict__ PROJ, bf16_t* __restrict__ ATT, bf16_t* __restrict__ SGU, const float* __restrict__ qn, const float* __restrict__ kn, ...
;     ...
;             for (int e = 0; e < 4; ++e) { const float p = __builtin_amdgcn_exp2f((sc_[t][e] - mx) * LOG2E); sc_[t][e] = p; sum += p; }
;         sum += __shfl_xor(sum, 16); sum += __shfl_xor(sum, 32);
;         const float inv = 1.0f / (sum + __builtin_amdgcn_exp2f((sink - mx) * LOG2E));
;         f32x4 o[4];
; #pragma unroll
;         for (int dt = 0; dt < 4; ++dt) o[dt] = (f32x4){0.f, 0.f, 0.f, 0.f};
; #pragma unroll
;         for (int j = 0; j < 5; ++j) {
;             u32x4 pw; pw.x = cvt_pk_bf16(sc_[2 * j][0], sc_[2 * j][1]); pw.y = cvt_pk_bf16(sc_[2 * j][2], sc_[2 * j][3]); pw.z = cvt_pk_bf16(sc_[2 * j + 1][0], sc_[2 * j + 1][1]); pw.w = cvt_pk_bf16(sc_[2 * j + 1][2], sc_[2 * j + 1][3]);
;             const bf16x8 pf = __builtin_bit_cast(bf16x8, pw);
; #pragma unroll
;             for (int dt = 0; dt < 4; ++dt) { const LAS unsigned char* vb = VT + (16 * dt + fr) * VT_STRIDE + (16 * (t0 + 2 * j) + 4 * fq) * 2;
;                 const u32x2 va = *(const LAS u32x2*)vb, vc = *(const LAS u32x2*)(vb + 32); u32x4 vw; vw.x = va.x; vw.y = va.y; vw.z = vc.x; vw.w = vc.y;
;                 o[dt] = MFMA16(__builtin_bit_cast(bf16x8, vw), pf, o[dt]); }
;         }
;         bf16_t* op = ATT + grow * 1024 + hq * 64 + 4 * fq;
; #pragma unroll
;         for (int dt = 0; dt < 4; ++dt) { u32x2 ow; ow.x = cvt_pk_bf16(o[dt][0] * inv, o[dt][1] * inv); ow.y = cvt_pk_bf16(o[dt][2] * inv, o[dt][3] * inv); *(u32x2*)(op + 16 * dt) = ow; }
	v_fmamk_f32 v90, v90, 0x3fb8aa3b, v94
	v_fmamk_f32 v91, v91, 0x3fb8aa3b, v94
	v_fmamk_f32 v92, v92, 0x3fb8aa3b, v94
	v_fmamk_f32 v93, v93, 0x3fb8aa3b, v94
	v_exp_f32_e32 v58, v58
	v_exp_f32_e32 v59, v59
	v_exp_f32_e32 v60, v60
	v_exp_f32_e32 v61, v61
	v_exp_f32_e32 v62, v62
	v_exp_f32_e32 v63, v63
	v_exp_f32_e32 v64, v64
	v_exp_f32_e32 v65, v65
	v_exp_f32_e32 v66, v66
	v_exp_f32_e32 v67, v67
	v_exp_f32_e32 v68, v68
	v_exp_f32_e32 v69, v69
	v_exp_f32_e32 v70, v70
	v_exp_f32_e32 v71, v71
	v_exp_f32_e32 v72, v72
	v_exp_f32_e32 v73, v73
	v_exp_f32_e32 v74, v74
	v_exp_f32_e32 v75, v75
	v_exp_f32_e32 v76, v76
	v_exp_f32_e32 v77, v77
	v_exp_f32_e32 v78, v78
	v_exp_f32_e32 v79, v79
	v_exp_f32_e32 v80, v80
	v_exp_f32_e32 v81, v81
	v_exp_f32_e32 v82, v82
	v_exp_f32_e32 v83, v83
	v_exp_f32_e32 v84, v84
	v_exp_f32_e32 v85, v85
	v_exp_f32_e32 v86, v86
	v_exp_f32_e32 v87, v87
	v_exp_f32_e32 v88, v88
	v_exp_f32_e32 v89, v89
	v_exp_f32_e32 v90, v90
	v_exp_f32_e32 v91, v91
	v_exp_f32_e32 v92, v92
	v_exp_f32_e32 v93, v93
	v_fmamk_f32 v95, v42, 0x3fb8aa3b, v94
	v_exp_f32_e32 v95, v95
	v_add_f32_e32 v167, v58, v59
	v_add_f32_e32 v94, v60, v61
	v_add_f32_e32 v167, v167, v62
	v_add_f32_e32 v94, v94, v63
	v_add_f32_e32 v167, v167, v64
	v_add_f32_e32 v94, v94, v65
	v_add_f32_e32 v167, v167, v66
	v_add_f32_e32 v94, v94, v67
	v_add_f32_e32 v167, v167, v68
	v_add_f32_e32 v94, v94, v69
	v_add_f32_e32 v167, v167, v70
	v_add_f32_e32 v94, v94, v71
	v_add_f32_e32 v167, v167, v72
	v_add_f32_e32 v94, v94, v73
	v_add_f32_e32 v167, v167, v74
	v_add_f32_e32 v94, v94, v75
	v_add_f32_e32 v167, v167, v76
	v_add_f32_e32 v94, v94, v77
	v_add_f32_e32 v167, v167, v78
	v_add_f32_e32 v94, v94, v79
	v_add_f32_e32 v167, v167, v80
	v_add_f32_e32 v94, v94, v81
	v_add_f32_e32 v167, v167, v82
	v_add_f32_e32 v94, v94, v83
	v_add_f32_e32 v167, v167, v84
	v_add_f32_e32 v94, v94, v85
	v_add_f32_e32 v167, v167, v86
	v_add_f32_e32 v94, v94, v87
	v_add_f32_e32 v167, v167, v88
	v_add_f32_e32 v94, v94, v89
	v_add_f32_e32 v167, v167, v90
	v_add_f32_e32 v94, v94, v91
	v_add_f32_e32 v167, v167, v92
	v_add_f32_e32 v94, v94, v93
	v_add_f32_e32 v167, v167, v94
	v_mov_b32_e32 v166, v167
	s_nop 1
	v_permlane16_swap_b32_e32 v167, v166
	v_add_f32_e32 v167, v167, v166
	v_mov_b32_e32 v166, v167
	s_nop 1
	v_permlane32_swap_b32_e32 v167, v166
	v_add_f32_e32 v167, v167, v166
	v_add_f32_e32 v167, v167, v95
	v_rcp_f32_e32 v167, v167
	v_mov_b32_e32 v94, 0
	v_mov_b32_e32 v95, 0
	v_mov_b32_e32 v96, 0
	v_mov_b32_e32 v97, 0
	v_cvt_pk_bf16_f32 v58, v58, v59
	v_cvt_pk_bf16_f32 v59, v60, v61
	v_cvt_pk_bf16_f32 v60, v62, v63
	v_cvt_pk_bf16_f32 v61, v64, v65
	v_cvt_pk_bf16_f32 v66, v66, v67
	v_cvt_pk_bf16_f32 v67, v68, v69
	v_cvt_pk_bf16_f32 v68, v70, v71
	v_cvt_pk_bf16_f32 v69, v72, v73
	v_cvt_pk_bf16_f32 v74, v74, v75
	v_cvt_pk_bf16_f32 v75, v76, v77
	v_cvt_pk_bf16_f32 v76, v78, v79
	v_cvt_pk_bf16_f32 v77, v80, v81
	v_cvt_pk_bf16_f32 v82, v82, v83
	v_cvt_pk_bf16_f32 v83, v84, v85
	v_cvt_pk_bf16_f32 v84, v86, v87
	v_cvt_pk_bf16_f32 v85, v88, v89
	v_cvt_pk_bf16_f32 v90, v90, v91
	v_cvt_pk_bf16_f32 v91, v92, v93
	v_cvt_pk_bf16_f32 v92, v94, v95
	v_cvt_pk_bf16_f32 v93, v96, v97
	s_nop 1
	s_waitcnt lgkmcnt(14)
	v_mfma_f32_16x16x32_bf16 v[62:65], v[98:101], v[58:61], 0
	ds_read2_b64 v[158:161], v197 offset0:36 offset1:40
	s_waitcnt lgkmcnt(14)
	v_mfma_f32_16x16x32_bf16 v[70:73], v[102:105], v[58:61], 0
	ds_read2_b64 v[162:165], v194 offset0:44 offset1:48
	s_waitcnt lgkmcnt(14)
	v_mfma_f32_16x16x32_bf16 v[78:81], v[106:109], v[58:61], 0
	ds_read2_b64 v[182:185], v195 offset0:44 offset1:48
	s_waitcnt lgkmcnt(14)
	v_mfma_f32_16x16x32_bf16 v[86:89], v[110:113], v[58:61], 0
	ds_read2_b64 v[186:189], v196 offset0:44 offset1:48
	s_waitcnt lgkmcnt(14)
	v_mfma_f32_16x16x32_bf16 v[62:65], v[114:117], v[66:69], v[62:65]
	ds_read2_b64 v[190:193], v197 offset0:44 offset1:48
	s_waitcnt lgkmcnt(14)
	v_mfma_f32_16x16x32_bf16 v[70:73], v[118:121], v[66:69], v[70:73]
	s_waitcnt lgkmcnt(13)
	v_mfma_f32_16x16x32_bf16 v[78:81], v[122:125], v[66:69], v[78:81]
	s_waitcnt lgkmcnt(12)
	v_mfma_f32_16x16x32_bf16 v[86:89], v[126:129], v[66:69], v[86:89]
	s_waitcnt lgkmcnt(11)
	v_mfma_f32_16x16x32_bf16 v[62:65], v[130:133], v[74:77], v[62:65]
	s_waitcnt lgkmcnt(10)
	v_mfma_f32_16x16x32_bf16 v[70:73], v[134:137], v[74:77], v[70:73]
	s_waitcnt lgkmcnt(9)
	v_mfma_f32_16x16x32_bf16 v[78:81], v[138:141], v[74:77], v[78:81]
	s_waitcnt lgkmcnt(8)
	v_mfma_f32_16x16x32_bf16 v[86:89], v[142:145], v[74:77], v[86:89]
	s_waitcnt lgkmcnt(7)
	v_mfma_f32_16x16x32_bf16 v[62:65], v[146:149], v[82:85], v[62:65]
	s_waitcnt lgkmcnt(6)
	v_mfma_f32_16x16x32_bf16 v[70:73], v[150:153], v[82:85], v[70:73]
	s_waitcnt lgkmcnt(5)
	v_mfma_f32_16x16x32_bf16 v[78:81], v[154:157], v[82:85], v[78:81]
	s_waitcnt lgkmcnt(4)
	v_mfma_f32_16x16x32_bf16 v[86:89], v[158:161], v[82:85], v[86:89]
	s_waitcnt lgkmcnt(3)
	v_mfma_f32_16x16x32_bf16 v[62:65], v[162:165], v[90:93], v[62:65]
	s_waitcnt lgkmcnt(2)
	v_mfma_f32_16x16x32_bf16 v[70:73], v[182:185], v[90:93], v[70:73]
	s_waitcnt lgkmcnt(1)
	v_mfma_f32_16x16x32_bf16 v[78:81], v[186:189], v[90:93], v[78:81]
	s_waitcnt lgkmcnt(0)
	v_mfma_f32_16x16x32_bf16 v[86:89], v[190:193], v[90:93], v[86:89]
	s_nop 7
	v_mul_f32_e32 v62, v62, v167
	v_mul_f32_e32 v63, v63, v167
	v_mul_f32_e32 v64, v64, v167
	v_mul_f32_e32 v65, v65, v167
	v_mul_f32_e32 v70, v70, v167
	v_mul_f32_e32 v71, v71, v167
	v_mul_f32_e32 v72, v72, v167
	v_mul_f32_e32 v73, v73, v167
	v_mul_f32_e32 v78, v78, v167
	v_mul_f32_e32 v79, v79, v167
	v_mul_f32_e32 v80, v80, v167
	v_mul_f32_e32 v81, v81, v167
	v_mul_f32_e32 v86, v86, v167
	v_mul_f32_e32 v87, v87, v167
	v_mul_f32_e32 v88, v88, v167
	v_mul_f32_e32 v89, v89, v167
	v_cvt_pk_bf16_f32 v62, v62, v63
	v_cvt_pk_bf16_f32 v63, v64, v65
	global_store_dwordx2 v48, v[62:63], s[24:25] offset:0
	v_cvt_pk_bf16_f32 v70, v70, v71
	v_cvt_pk_bf16_f32 v71, v72, v73
	global_store_dwordx2 v48, v[70:71], s[24:25] offset:32
	v_cvt_pk_bf16_f32 v78, v78, v79
	v_cvt_pk_bf16_f32 v79, v80, v81
	global_store_dwordx2 v48, v[78:79], s[24:25] offset:64
	v_cvt_pk_bf16_f32 v86, v86, v87
	v_cvt_pk_bf16_f32 v87, v88, v89
	global_store_dwordx2 v48, v[86:87], s[24:25] offset:96
	v_add_u32_e32 v48, 0x8000, v48
	s_branch .Latt_done
; __device__ __forceinline__ unsigned cvt_pk_bf16(float lo, float hi) { unsigned r; asm volatile("v_cvt_pk_bf16_f32 %0, %1, %2" : "=v"(r) : "v"(lo), "v"(hi)); return r; }
; #define LAS __attribute__((address_space(3)))
; #define MFMA16(a, b, c) __builtin_amdgcn_mfma_f32_16x16x32_bf16((a), (b), (c), 0, 0, 0)
; __device__ __forceinline__ void p2_block(LAS unsigned char* lds, const bf16_t* __restrict__ PROJ, bf16_t* __restrict__ ATT, bf16_t* __restrict__ SGU, const float* __restrict__ qn, const float* __restrict__ kn, ...
;     ...
;         const int gg = 2 * kvh + gi, irow = 16 * w + fr, nks = (w >> 1) + 1;
;         const LAS unsigned char* VNT = lds + (gi ? VN_OFF1 : VN_OFF0);
;         f32x4 acc[8];
; #pragma unroll
;         for (int dt = 0; dt < 8; ++dt) acc[dt] = (f32x4){0.f, 0.f, 0.f, 0.f};
;         const float* wrow = wsp + (size_t)gg * 16384 + irow * 128 + 8 * fq;
; #pragma unroll
;         for (int ks = 0; ks < 4; ++ks) if (ks < nks) {
;             const f32x4 wa = *(const f32x4*)(wrow + 32 * ks), wb = *(const f32x4*)(wrow + 32 * ks + 4);
;             const int j0 = 32 * ks + 8 * fq; float wv[8];
; #pragma unroll
;             for (int e = 0; e < 4; ++e) { wv[e] = (j0 + e <= irow) ? wa[e] : 0.f; wv[4 + e] = (j0 + 4 + e <= irow) ? wb[e] : 0.f; }
;             u32x4 ww; ww.x = cvt_pk_bf16(wv[0], wv[1]); ww.y = cvt_pk_bf16(wv[2], wv[3]); ww.z = cvt_pk_bf16(wv[4], wv[5]); ww.w = cvt_pk_bf16(wv[6], wv[7]);
;             const bf16x8 wf = __builtin_bit_cast(bf16x8, ww);
; #pragma unroll
;             for (int dt = 0; dt < 8; ++dt) { const bf16x8 af = *(const LAS bf16x8*)(VNT + (16 * dt + fr) * VN_STRIDE + (32 * ks + 8 * fq) * 2); acc[dt] = MFMA16(af, wf, acc[dt]); }
;         }
.Latt_done:
	v_readfirstlane_b32 s16, v204
	v_and_b32_e32 v184, 15, v204
	v_bfe_u32 v185, v204, 4, 2
	s_and_b32 s24, s2, 3
	s_lshr_b32 s16, s16, 6
	s_lshl_b32 s4, s24, 17
	s_lshr_b32 s17, s16, 1
	v_lshl_add_u32 v191, s16, 4, v184
	v_lshlrev_b32_e32 v186, 9, v191
	v_lshl_add_u32 v186, v185, 5, v186
	v_add_u32_e32 v186, s4, v186
	v_add_u32_e32 v187, 0x10000, v186
	global_load_dwordx4 v[98:101], v186, s[20:21] offset:0
	global_load_dwordx4 v[102:105], v186, s[20:21] offset:16
	global_load_dwordx4 v[106:109], v186, s[20:21] offset:128
	global_load_dwordx4 v[110:113], v186, s[20:21] offset:144
	global_load_dwordx4 v[114:117], v186, s[20:21] offset:256
	global_load_dwordx4 v[118:121], v186, s[20:21] offset:272
	global_load_dwordx4 v[122:125], v186, s[20:21] offset:384
	global_load_dwordx4 v[126:129], v186, s[20:21] offset:400
	global_load_dwordx4 v[66:69], v187, s[20:21] offset:0
	global_load_dwordx4 v[70:73], v187, s[20:21] offset:16
	global_load_dwordx4 v[74:77], v187, s[20:21] offset:128
	global_load_dwordx4 v[78:81], v187, s[20:21] offset:144
	global_load_dwordx4 v[82:85], v187, s[20:21] offset:256
	global_load_dwordx4 v[86:89], v187, s[20:21] offset:272
	global_load_dwordx4 v[90:93], v187, s[20:21] offset:384
	global_load_dwordx4 v[94:97], v187, s[20:21] offset:400
	v_mul_u32_u24_e32 v194, 0x110, v184
	v_lshl_add_u32 v194, v185, 4, v194
	v_add_u32_e32 v194, 0x11800, v194
	v_lshlrev_b32_e32 v195, 3, v185
	v_sub_u32_e32 v195, v191, v195
	s_and_b32 s25, s2, -4
	s_lshl_b32 s25, s25, 5
	v_add_u32_e32 v192, s25, v191
	s_lshl_b32 s4, s24, 9
	v_lshl_add_u32 v193, v185, 3, s4
	v_lshl_add_u32 v182, v192, 11, v193
	s_cmp_eq_u32 s17, 0
	s_cbranch_scc1 .Lsgu_n1
	s_cmp_eq_u32 s17, 1
	s_cbranch_scc1 .Lsgu_n2
	s_cmp_eq_u32 s17, 2
	s_cbranch_scc1 .Lsgu_n3
	s_branch .Lsgu_n4
.Lsgu_n1:
	s_waitcnt vmcnt(8)
	v_mov_b32_e32 v164, v198
	v_mov_b32_e32 v165, v198
	v_mov_b32_e32 v166, v198
	v_mov_b32_e32 v167, v198
	v_mov_b32_e32 v186, v199
	v_mov_b32_e32 v187, v199
	v_mov_b32_e32 v188, v199
	v_mov_b32_e32 v189, v199
	v_mov_b32_e32 v196, v195
	v_cmp_le_i32_e64 s[40:41], 0, v196
	v_cmp_le_i32_e64 s[42:43], 1, v196
	v_cmp_le_i32_e64 s[44:45], 2, v196
	v_cmp_le_i32_e64 s[46:47], 3, v196
	v_cmp_le_i32_e64 s[48:49], 4, v196
	v_cmp_le_i32_e64 s[50:51], 5, v196
	v_cmp_le_i32_e64 s[52:53], 6, v196
	v_cmp_le_i32_e32 vcc, 7, v196
	v_cndmask_b32_e64 v98, 0, v98, s[40:41]
	v_cndmask_b32_e64 v99, 0, v99, s[42:43]
	v_cndmask_b32_e64 v100, 0, v100, s[44:45]
	v_cndmask_b32_e64 v101, 0, v101, s[46:47]
	v_cndmask_b32_e64 v102, 0, v102, s[48:49]
	v_cndmask_b32_e64 v103, 0, v103, s[50:51]
	v_cndmask_b32_e64 v104, 0, v104, s[52:53]
	v_cndmask_b32_e32 v105, 0, v105, vcc
	v_cvt_pk_bf16_f32 v144, v98, v99
	v_cvt_pk_bf16_f32 v145, v100, v101
	v_cvt_pk_bf16_f32 v146, v102, v103
	v_cvt_pk_bf16_f32 v147, v104, v105
	ds_read_b128 v[34:37], v194 offset:0
	ds_read_b128 v[38:41], v194 offset:4352
	ds_read_b128 v[42:45], v194 offset:8704
	ds_read_b128 v[46:49], v194 offset:13056
	ds_read_b128 v[50:53], v194 offset:17408
	ds_read_b128 v[54:57], v194 offset:21760
	ds_read_b128 v[58:61], v194 offset:26112
	ds_read_b128 v[62:65], v194 offset:30464
	s_waitcnt vmcnt(0)
	v_mov_b32_e32 v196, v195
	v_cmp_le_i32_e64 s[40:41], 0, v196
	v_cmp_le_i32_e64 s[42:43], 1, v196
	v_cmp_le_i32_e64 s[44:45], 2, v196
	v_cmp_le_i32_e64 s[46:47], 3, v196
	v_cmp_le_i32_e64 s[48:49], 4, v196
	v_cmp_le_i32_e64 s[50:51], 5, v196
	v_cmp_le_i32_e64 s[52:53], 6, v196
	v_cmp_le_i32_e32 vcc, 7, v196
	v_cndmask_b32_e64 v66, 0, v66, s[40:41]
	v_cndmask_b32_e64 v67, 0, v67, s[42:43]
	v_cndmask_b32_e64 v68, 0, v68, s[44:45]
	v_cndmask_b32_e64 v69, 0, v69, s[46:47]
	v_cndmask_b32_e64 v70, 0, v70, s[48:49]
	v_cndmask_b32_e64 v71, 0, v71, s[50:51]
	v_cndmask_b32_e64 v72, 0, v72, s[52:53]
	v_cndmask_b32_e32 v73, 0, v73, vcc
	v_cvt_pk_bf16_f32 v98, v66, v67
	v_cvt_pk_bf16_f32 v99, v68, v69
	v_cvt_pk_bf16_f32 v100, v70, v71
	v_cvt_pk_bf16_f32 v101, v72, v73
	ds_read_b128 v[66:69], v194 offset:34816
	ds_read_b128 v[70:73], v194 offset:39168
	ds_read_b128 v[74:77], v194 offset:43520
	ds_read_b128 v[78:81], v194 offset:47872
	ds_read_b128 v[82:85], v194 offset:52224
	ds_read_b128 v[86:89], v194 offset:56576
	ds_read_b128 v[90:93], v194 offset:60928
	ds_read_b128 v[94:97], v194 offset:65280
	s_waitcnt lgkmcnt(15)
	v_mfma_f32_16x16x32_bf16 v[2:5], v[34:37], v[144:147], v[164:167]
	s_waitcnt lgkmcnt(14)
	v_mfma_f32_16x16x32_bf16 v[6:9], v[38:41], v[144:147], v[164:167]
	s_waitcnt lgkmcnt(13)
	v_mfma_f32_16x16x32_bf16 v[10:13], v[42:45], v[144:147], v[164:167]
	s_waitcnt lgkmcnt(12)
	v_mfma_f32_16x16x32_bf16 v[14:17], v[46:49], v[144:147], v[164:167]
	s_waitcnt lgkmcnt(11)
	v_mfma_f32_16x16x32_bf16 v[18:21], v[50:53], v[144:147], v[164:167]
	s_waitcnt lgkmcnt(10)
	v_mfma_f32_16x16x32_bf16 v[22:25], v[54:57], v[144:147], v[164:167]
	s_waitcnt lgkmcnt(9)
	v_mfma_f32_16x16x32_bf16 v[26:29], v[58:61], v[144:147], v[164:167]
	s_waitcnt lgkmcnt(8)
	v_mfma_f32_16x16x32_bf16 v[30:33], v[62:65], v[144:147], v[164:167]
	s_waitcnt lgkmcnt(7)
	v_mfma_f32_16x16x32_bf16 v[114:117], v[66:69], v[98:101], v[186:189]
	s_waitcnt lgkmcnt(6)
	v_mfma_f32_16x16x32_bf16 v[118:121], v[70:73], v[98:101], v[186:189]
	s_waitcnt lgkmcnt(5)
	v_mfma_f32_16x16x32_bf16 v[122:125], v[74:77], v[98:101], v[186:189]
	s_waitcnt lgkmcnt(4)
	v_mfma_f32_16x16x32_bf16 v[126:129], v[78:81], v[98:101], v[186:189]
	s_waitcnt lgkmcnt(3)
	v_mfma_f32_16x16x32_bf16 v[130:133], v[82:85], v[98:101], v[186:189]
	s_waitcnt lgkmcnt(2)
	v_mfma_f32_16x16x32_bf16 v[134:137], v[86:89], v[98:101], v[186:189]
	s_waitcnt lgkmcnt(1)
	v_mfma_f32_16x16x32_bf16 v[138:141], v[90:93], v[98:101], v[186:189]
	s_waitcnt lgkmcnt(0)
	v_mfma_f32_16x16x32_bf16 v[160:163], v[94:97], v[98:101], v[186:189]
	s_branch .Lsgu_epi
; __device__ __forceinline__ unsigned cvt_pk_bf16(float lo, float hi) { unsigned r; asm volatile("v_cvt_pk_bf16_f32 %0, %1, %2" : "=v"(r) : "v"(lo), "v"(hi)); return r; }
; #define LAS __attribute__((address_space(3)))
; #define MFMA16(a, b, c) __builtin_amdgcn_mfma_f32_16x16x32_bf16((a), (b), (c), 0, 0, 0)
; __device__ __forceinline__ void p2_block(LAS unsigned char* lds, const bf16_t* __restrict__ PROJ, bf16_t* __restrict__ ATT, bf16_t* __restrict__ SGU, const float* __restrict__ qn, const float* __restrict__ kn, ...
;     ...
;         const float* wrow = wsp + (size_t)gg * 16384 + irow * 128 + 8 * fq;
; #pragma unroll
;         for (int ks = 0; ks < 4; ++ks) if (ks < nks) {
;             const f32x4 wa = *(const f32x4*)(wrow + 32 * ks), wb = *(const f32x4*)(wrow + 32 * ks + 4);
;             const int j0 = 32 * ks + 8 * fq; float wv[8];
; #pragma unroll
;             for (int e = 0; e < 4; ++e) { wv[e] = (j0 + e <= irow) ? wa[e] : 0.f; wv[4 + e] = (j0 + 4 + e <= irow) ? wb[e] : 0.f; }
;             u32x4 ww; ww.x = cvt_pk_bf16(wv[0], wv[1]); ww.y = cvt_pk_bf16(wv[2], wv[3]); ww.z = cvt_pk_bf16(wv[4], wv[5]); ww.w = cvt_pk_bf16(wv[6], wv[7]);
;             const bf16x8 wf = __builtin_bit_cast(bf16x8, ww);
; #pragma unroll
;             for (int dt = 0; dt < 8; ++dt) { const bf16x8 af = *(const LAS bf16x8*)(VNT + (16 * dt + fr) * VN_STRIDE + (32 * ks + 8 * fq) * 2); acc[dt] = MFMA16(af, wf, acc[dt]); }
.Lsgu_n2:
	s_waitcnt vmcnt(8)
	v_mov_b32_e32 v164, v198
	v_mov_b32_e32 v165, v198
	v_mov_b32_e32 v166, v198
	v_mov_b32_e32 v167, v198
	v_mov_b32_e32 v186, v199
	v_mov_b32_e32 v187, v199
	v_mov_b32_e32 v188, v199
	v_mov_b32_e32 v189, v199
	v_mov_b32_e32 v196, v195
	v_cmp_le_i32_e64 s[40:41], 0, v196
	v_cmp_le_i32_e64 s[42:43], 1, v196
	v_cmp_le_i32_e64 s[44:45], 2, v196
	v_cmp_le_i32_e64 s[46:47], 3, v196
	v_cmp_le_i32_e64 s[48:49], 4, v196
	v_cmp_le_i32_e64 s[50:51], 5, v196
	v_cmp_le_i32_e64 s[52:53], 6, v196
	v_cmp_le_i32_e32 vcc, 7, v196
	v_cndmask_b32_e64 v98, 0, v98, s[40:41]
	v_cndmask_b32_e64 v99, 0, v99, s[42:43]
	v_cndmask_b32_e64 v100, 0, v100, s[44:45]
	v_cndmask_b32_e64 v101, 0, v101, s[46:47]
	v_cndmask_b32_e64 v102, 0, v102, s[48:49]
	v_cndmask_b32_e64 v103, 0, v103, s[50:51]
	v_cndmask_b32_e64 v104, 0, v104, s[52:53]
	v_cndmask_b32_e32 v105, 0, v105, vcc
	v_cvt_pk_bf16_f32 v144, v98, v99
	v_cvt_pk_bf16_f32 v145, v100, v101
	v_cvt_pk_bf16_f32 v146, v102, v103
	v_cvt_pk_bf16_f32 v147, v104, v105
	v_add_u32_e32 v196, 4294967264, v195
	v_cmp_le_i32_e64 s[40:41], 0, v196
	v_cmp_le_i32_e64 s[42:43], 1, v196
	v_cmp_le_i32_e64 s[44:45], 2, v196
	v_cmp_le_i32_e64 s[46:47], 3, v196
	v_cmp_le_i32_e64 s[48:49], 4, v196
	v_cmp_le_i32_e64 s[50:51], 5, v196
	v_cmp_le_i32_e64 s[52:53], 6, v196
	v_cmp_le_i32_e32 vcc, 7, v196
	v_cndmask_b32_e64 v106, 0, v106, s[40:41]
	v_cndmask_b32_e64 v107, 0, v107, s[42:43]
	v_cndmask_b32_e64 v108, 0, v108, s[44:45]
	v_cndmask_b32_e64 v109, 0, v109, s[46:47]
	v_cndmask_b32_e64 v110, 0, v110, s[48:49]
	v_cndmask_b32_e64 v111, 0, v111, s[50:51]
	v_cndmask_b32_e64 v112, 0, v112, s[52:53]
	v_cndmask_b32_e32 v113, 0, v113, vcc
	v_cvt_pk_bf16_f32 v148, v106, v107
	v_cvt_pk_bf16_f32 v149, v108, v109
	v_cvt_pk_bf16_f32 v150, v110, v111
	v_cvt_pk_bf16_f32 v151, v112, v113
	ds_read_b128 v[34:37], v194 offset:0
	ds_read_b128 v[38:41], v194 offset:4352
	ds_read_b128 v[42:45], v194 offset:8704
	ds_read_b128 v[46:49], v194 offset:13056
	ds_read_b128 v[50:53], v194 offset:17408
	ds_read_b128 v[54:57], v194 offset:21760
	ds_read_b128 v[58:61], v194 offset:26112
	ds_read_b128 v[62:65], v194 offset:30464
	s_waitcnt vmcnt(0)
	v_mov_b32_e32 v196, v195
	v_cmp_le_i32_e64 s[40:41], 0, v196
	v_cmp_le_i32_e64 s[42:43], 1, v196
	v_cmp_le_i32_e64 s[44:45], 2, v196
	v_cmp_le_i32_e64 s[46:47], 3, v196
	v_cmp_le_i32_e64 s[48:49], 4, v196
	v_cmp_le_i32_e64 s[50:51], 5, v196
	v_cmp_le_i32_e64 s[52:53], 6, v196
	v_cmp_le_i32_e32 vcc, 7, v196
	v_cndmask_b32_e64 v66, 0, v66, s[40:41]
	v_cndmask_b32_e64 v67, 0, v67, s[42:43]
	v_cndmask_b32_e64 v68, 0, v68, s[44:45]
	v_cndmask_b32_e64 v69, 0, v69, s[46:47]
	v_cndmask_b32_e64 v70, 0, v70, s[48:49]
	v_cndmask_b32_e64 v71, 0, v71, s[50:51]
	v_cndmask_b32_e64 v72, 0, v72, s[52:53]
	v_cndmask_b32_e32 v73, 0, v73, vcc
	v_cvt_pk_bf16_f32 v98, v66, v67
	v_cvt_pk_bf16_f32 v99, v68, v69
	v_cvt_pk_bf16_f32 v100, v70, v71
	v_cvt_pk_bf16_f32 v101, v72, v73
	v_add_u32_e32 v196, 4294967264, v195
	v_cmp_le_i32_e64 s[40:41], 0, v196
	v_cmp_le_i32_e64 s[42:43], 1, v196
	v_cmp_le_i32_e64 s[44:45], 2, v196
	v_cmp_le_i32_e64 s[46:47], 3, v196
	v_cmp_le_i32_e64 s[48:49], 4, v196
	v_cmp_le_i32_e64 s[50:51], 5, v196
	v_cmp_le_i32_e64 s[52:53], 6, v196
	v_cmp_le_i32_e32 vcc, 7, v196
	v_cndmask_b32_e64 v74, 0, v74, s[40:41]
	v_cndmask_b32_e64 v75, 0, v75, s[42:43]
	v_cndmask_b32_e64 v76, 0, v76, s[44:45]
	v_cndmask_b32_e64 v77, 0, v77, s[46:47]
	v_cndmask_b32_e64 v78, 0, v78, s[48:49]
	v_cndmask_b32_e64 v79, 0, v79, s[50:51]
	v_cndmask_b32_e64 v80, 0, v80, s[52:53]
	v_cndmask_b32_e32 v81, 0, v81, vcc
	v_cvt_pk_bf16_f32 v102, v74, v75
	v_cvt_pk_bf16_f32 v103, v76, v77
	v_cvt_pk_bf16_f32 v104, v78, v79
	v_cvt_pk_bf16_f32 v105, v80, v81
	ds_read_b128 v[66:69], v194 offset:64
	ds_read_b128 v[70:73], v194 offset:4416
	ds_read_b128 v[74:77], v194 offset:8768
	ds_read_b128 v[78:81], v194 offset:13120
	ds_read_b128 v[82:85], v194 offset:17472
	ds_read_b128 v[86:89], v194 offset:21824
	ds_read_b128 v[90:93], v194 offset:26176
	ds_read_b128 v[94:97], v194 offset:30528
	s_waitcnt lgkmcnt(15)
	v_mfma_f32_16x16x32_bf16 v[2:5], v[34:37], v[144:147], v[164:167]
	s_waitcnt lgkmcnt(14)
	v_mfma_f32_16x16x32_bf16 v[6:9], v[38:41], v[144:147], v[164:167]
	s_waitcnt lgkmcnt(13)
	v_mfma_f32_16x16x32_bf16 v[10:13], v[42:45], v[144:147], v[164:167]
	s_waitcnt lgkmcnt(12)
	v_mfma_f32_16x16x32_bf16 v[14:17], v[46:49], v[144:147], v[164:167]
	s_waitcnt lgkmcnt(11)
	v_mfma_f32_16x16x32_bf16 v[18:21], v[50:53], v[144:147], v[164:167]
	s_waitcnt lgkmcnt(10)
	v_mfma_f32_16x16x32_bf16 v[22:25], v[54:57], v[144:147], v[164:167]
	s_waitcnt lgkmcnt(9)
	v_mfma_f32_16x16x32_bf16 v[26:29], v[58:61], v[144:147], v[164:167]
	s_waitcnt lgkmcnt(8)
	v_mfma_f32_16x16x32_bf16 v[30:33], v[62:65], v[144:147], v[164:167]
	ds_read_b128 v[34:37], v194 offset:34816
	ds_read_b128 v[38:41], v194 offset:39168
	ds_read_b128 v[42:45], v194 offset:43520
	ds_read_b128 v[46:49], v194 offset:47872
	ds_read_b128 v[50:53], v194 offset:52224
	ds_read_b128 v[54:57], v194 offset:56576
	ds_read_b128 v[58:61], v194 offset:60928
	ds_read_b128 v[62:65], v194 offset:65280
	s_waitcnt lgkmcnt(15)
	v_mfma_f32_16x16x32_bf16 v[2:5], v[66:69], v[148:151], v[2:5]
	s_waitcnt lgkmcnt(14)
	v_mfma_f32_16x16x32_bf16 v[6:9], v[70:73], v[148:151], v[6:9]
	s_waitcnt lgkmcnt(13)
	v_mfma_f32_16x16x32_bf16 v[10:13], v[74:77], v[148:151], v[10:13]
	s_waitcnt lgkmcnt(12)
	v_mfma_f32_16x16x32_bf16 v[14:17], v[78:81], v[148:151], v[14:17]
	s_waitcnt lgkmcnt(11)
	v_mfma_f32_16x16x32_bf16 v[18:21], v[82:85], v[148:151], v[18:21]
	s_waitcnt lgkmcnt(10)
	v_mfma_f32_16x16x32_bf16 v[22:25], v[86:89], v[148:151], v[22:25]
	s_waitcnt lgkmcnt(9)
; __device__ __forceinline__ unsigned cvt_pk_bf16(float lo, float hi) { unsigned r; asm volatile("v_cvt_pk_bf16_f32 %0, %1, %2" : "=v"(r) : "v"(lo), "v"(hi)); return r; }
; #define LAS __attribute__((address_space(3)))
; #define MFMA16(a, b, c) __builtin_amdgcn_mfma_f32_16x16x32_bf16((a), (b), (c), 0, 0, 0)
; __device__ __forceinline__ void p2_block(LAS unsigned char* lds, const bf16_t* __restrict__ PROJ, bf16_t* __restrict__ ATT, bf16_t* __restrict__ SGU, const float* __restrict__ qn, const float* __restrict__ kn, ...
;     ...
;         for (int ks = 0; ks < 4; ++ks) if (ks < nks) {
;             const f32x4 wa = *(const f32x4*)(wrow + 32 * ks), wb = *(const f32x4*)(wrow + 32 * ks + 4);
;             const int j0 = 32 * ks + 8 * fq; float wv[8];
; #pragma unroll
;             for (int e = 0; e < 4; ++e) { wv[e] = (j0 + e <= irow) ? wa[e] : 0.f; wv[4 + e] = (j0 + 4 + e <= irow) ? wb[e] : 0.f; }
;             u32x4 ww; ww.x = cvt_pk_bf16(wv[0], wv[1]); ww.y = cvt_pk_bf16(wv[2], wv[3]); ww.z = cvt_pk_bf16(wv[4], wv[5]); ww.w = cvt_pk_bf16(wv[6], wv[7]);
;             const bf16x8 wf = __builtin_bit_cast(bf16x8, ww);
; #pragma unroll
;             for (int dt = 0; dt < 8; ++dt) { const bf16x8 af = *(const LAS bf16x8*)(VNT + (16 * dt + fr) * VN_STRIDE + (32 * ks + 8 * fq) * 2); acc[dt] = MFMA16(af, wf, acc[dt]); }
	v_mfma_f32_16x16x32_bf16 v[26:29], v[90:93], v[148:151], v[26:29]
	s_waitcnt lgkmcnt(8)
	v_mfma_f32_16x16x32_bf16 v[30:33], v[94:97], v[148:151], v[30:33]
	ds_read_b128 v[66:69], v194 offset:34880
	ds_read_b128 v[70:73], v194 offset:39232
	ds_read_b128 v[74:77], v194 offset:43584
	ds_read_b128 v[78:81], v194 offset:47936
	ds_read_b128 v[82:85], v194 offset:52288
	ds_read_b128 v[86:89], v194 offset:56640
	ds_read_b128 v[90:93], v194 offset:60992
	ds_read_b128 v[94:97], v194 offset:65344
	s_waitcnt lgkmcnt(15)
	v_mfma_f32_16x16x32_bf16 v[114:117], v[34:37], v[98:101], v[186:189]
	s_waitcnt lgkmcnt(14)
	v_mfma_f32_16x16x32_bf16 v[118:121], v[38:41], v[98:101], v[186:189]
	s_waitcnt lgkmcnt(13)
	v_mfma_f32_16x16x32_bf16 v[122:125], v[42:45], v[98:101], v[186:189]
	s_waitcnt lgkmcnt(12)
	v_mfma_f32_16x16x32_bf16 v[126:129], v[46:49], v[98:101], v[186:189]
	s_waitcnt lgkmcnt(11)
	v_mfma_f32_16x16x32_bf16 v[130:133], v[50:53], v[98:101], v[186:189]
	s_waitcnt lgkmcnt(10)
	v_mfma_f32_16x16x32_bf16 v[134:137], v[54:57], v[98:101], v[186:189]
	s_waitcnt lgkmcnt(9)
	v_mfma_f32_16x16x32_bf16 v[138:141], v[58:61], v[98:101], v[186:189]
	s_waitcnt lgkmcnt(8)
	v_mfma_f32_16x16x32_bf16 v[160:163], v[62:65], v[98:101], v[186:189]
	s_waitcnt lgkmcnt(7)
	v_mfma_f32_16x16x32_bf16 v[114:117], v[66:69], v[102:105], v[114:117]
	s_waitcnt lgkmcnt(6)
	v_mfma_f32_16x16x32_bf16 v[118:121], v[70:73], v[102:105], v[118:121]
	s_waitcnt lgkmcnt(5)
	v_mfma_f32_16x16x32_bf16 v[122:125], v[74:77], v[102:105], v[122:125]
	s_waitcnt lgkmcnt(4)
	v_mfma_f32_16x16x32_bf16 v[126:129], v[78:81], v[102:105], v[126:129]
	s_waitcnt lgkmcnt(3)
	v_mfma_f32_16x16x32_bf16 v[130:133], v[82:85], v[102:105], v[130:133]
	s_waitcnt lgkmcnt(2)
	v_mfma_f32_16x16x32_bf16 v[134:137], v[86:89], v[102:105], v[134:137]
	s_waitcnt lgkmcnt(1)
	v_mfma_f32_16x16x32_bf16 v[138:141], v[90:93], v[102:105], v[138:141]
	s_waitcnt lgkmcnt(0)
	v_mfma_f32_16x16x32_bf16 v[160:163], v[94:97], v[102:105], v[160:163]
	s_branch .Lsgu_epi
.Lsgu_n3:
	s_waitcnt vmcnt(8)
	v_mov_b32_e32 v164, v198
	v_mov_b32_e32 v165, v198
	v_mov_b32_e32 v166, v198
	v_mov_b32_e32 v167, v198
	v_mov_b32_e32 v186, v199
	v_mov_b32_e32 v187, v199
	v_mov_b32_e32 v188, v199
	v_mov_b32_e32 v189, v199
	v_mov_b32_e32 v196, v195
	v_cmp_le_i32_e64 s[40:41], 0, v196
	v_cmp_le_i32_e64 s[42:43], 1, v196
	v_cmp_le_i32_e64 s[44:45], 2, v196
	v_cmp_le_i32_e64 s[46:47], 3, v196
	v_cmp_le_i32_e64 s[48:49], 4, v196
	v_cmp_le_i32_e64 s[50:51], 5, v196
	v_cmp_le_i32_e64 s[52:53], 6, v196
	v_cmp_le_i32_e32 vcc, 7, v196
	v_cndmask_b32_e64 v98, 0, v98, s[40:41]
	v_cndmask_b32_e64 v99, 0, v99, s[42:43]
	v_cndmask_b32_e64 v100, 0, v100, s[44:45]
	v_cndmask_b32_e64 v101, 0, v101, s[46:47]
	v_cndmask_b32_e64 v102, 0, v102, s[48:49]
	v_cndmask_b32_e64 v103, 0, v103, s[50:51]
	v_cndmask_b32_e64 v104, 0, v104, s[52:53]
	v_cndmask_b32_e32 v105, 0, v105, vcc
	v_cvt_pk_bf16_f32 v144, v98, v99
	v_cvt_pk_bf16_f32 v145, v100, v101
	v_cvt_pk_bf16_f32 v146, v102, v103
	v_cvt_pk_bf16_f32 v147, v104, v105
	v_add_u32_e32 v196, 4294967264, v195
	v_cmp_le_i32_e64 s[40:41], 0, v196
	v_cmp_le_i32_e64 s[42:43], 1, v196
	v_cmp_le_i32_e64 s[44:45], 2, v196
	v_cmp_le_i32_e64 s[46:47], 3, v196
	v_cmp_le_i32_e64 s[48:49], 4, v196
	v_cmp_le_i32_e64 s[50:51], 5, v196
	v_cmp_le_i32_e64 s[52:53], 6, v196
	v_cmp_le_i32_e32 vcc, 7, v196
	v_cndmask_b32_e64 v106, 0, v106, s[40:41]
	v_cndmask_b32_e64 v107, 0, v107, s[42:43]
	v_cndmask_b32_e64 v108, 0, v108, s[44:45]
	v_cndmask_b32_e64 v109, 0, v109, s[46:47]
	v_cndmask_b32_e64 v110, 0, v110, s[48:49]
	v_cndmask_b32_e64 v111, 0, v111, s[50:51]
	v_cndmask_b32_e64 v112, 0, v112, s[52:53]
	v_cndmask_b32_e32 v113, 0, v113, vcc
	v_cvt_pk_bf16_f32 v148, v106, v107
	v_cvt_pk_bf16_f32 v149, v108, v109
	v_cvt_pk_bf16_f32 v150, v110, v111
	v_cvt_pk_bf16_f32 v151, v112, v113
	v_add_u32_e32 v196, 4294967232, v195
	v_cmp_le_i32_e64 s[40:41], 0, v196
	v_cmp_le_i32_e64 s[42:43], 1, v196
	v_cmp_le_i32_e64 s[44:45], 2, v196
	v_cmp_le_i32_e64 s[46:47], 3, v196
	v_cmp_le_i32_e64 s[48:49], 4, v196
	v_cmp_le_i32_e64 s[50:51], 5, v196
	v_cmp_le_i32_e64 s[52:53], 6, v196
	v_cmp_le_i32_e32 vcc, 7, v196
	v_cndmask_b32_e64 v114, 0, v114, s[40:41]
	v_cndmask_b32_e64 v115, 0, v115, s[42:43]
	v_cndmask_b32_e64 v116, 0, v116, s[44:45]
	v_cndmask_b32_e64 v117, 0, v117, s[46:47]
	v_cndmask_b32_e64 v118, 0, v118, s[48:49]
	v_cndmask_b32_e64 v119, 0, v119, s[50:51]
	v_cndmask_b32_e64 v120, 0, v120, s[52:53]
	v_cndmask_b32_e32 v121, 0, v121, vcc
	v_cvt_pk_bf16_f32 v152, v114, v115
	v_cvt_pk_bf16_f32 v153, v116, v117
	v_cvt_pk_bf16_f32 v154, v118, v119
	v_cvt_pk_bf16_f32 v155, v120, v121
	ds_read_b128 v[34:37], v194 offset:0
	ds_read_b128 v[38:41], v194 offset:4352
	ds_read_b128 v[42:45], v194 offset:8704
	ds_read_b128 v[46:49], v194 offset:13056
	ds_read_b128 v[50:53], v194 offset:17408
	ds_read_b128 v[54:57], v194 offset:21760
	ds_read_b128 v[58:61], v194 offset:26112
	ds_read_b128 v[62:65], v194 offset:30464
	s_waitcnt vmcnt(0)
; __device__ __forceinline__ unsigned cvt_pk_bf16(float lo, float hi) { unsigned r; asm volatile("v_cvt_pk_bf16_f32 %0, %1, %2" : "=v"(r) : "v"(lo), "v"(hi)); return r; }
; #define LAS __attribute__((address_space(3)))
; #define MFMA16(a, b, c) __builtin_amdgcn_mfma_f32_16x16x32_bf16((a), (b), (c), 0, 0, 0)
; __device__ __forceinline__ void p2_block(LAS unsigned char* lds, const bf16_t* __restrict__ PROJ, bf16_t* __restrict__ ATT, bf16_t* __restrict__ SGU, const float* __restrict__ qn, const float* __restrict__ kn, ...
;     ...
;         for (int ks = 0; ks < 4; ++ks) if (ks < nks) {
;             const f32x4 wa = *(const f32x4*)(wrow + 32 * ks), wb = *(const f32x4*)(wrow + 32 * ks + 4);
;             const int j0 = 32 * ks + 8 * fq; float wv[8];
; #pragma unroll
;             for (int e = 0; e < 4; ++e) { wv[e] = (j0 + e <= irow) ? wa[e] : 0.f; wv[4 + e] = (j0 + 4 + e <= irow) ? wb[e] : 0.f; }
;             u32x4 ww; ww.x = cvt_pk_bf16(wv[0], wv[1]); ww.y = cvt_pk_bf16(wv[2], wv[3]); ww.z = cvt_pk_bf16(wv[4], wv[5]); ww.w = cvt_pk_bf16(wv[6], wv[7]);
;             const bf16x8 wf = __builtin_bit_cast(bf16x8, ww);
; #pragma unroll
;             for (int dt = 0; dt < 8; ++dt) { const bf16x8 af = *(const LAS bf16x8*)(VNT + (16 * dt + fr) * VN_STRIDE + (32 * ks + 8 * fq) * 2); acc[dt] = MFMA16(af, wf, acc[dt]); }
	v_mov_b32_e32 v196, v195
	v_cmp_le_i32_e64 s[40:41], 0, v196
	v_cmp_le_i32_e64 s[42:43], 1, v196
	v_cmp_le_i32_e64 s[44:45], 2, v196
	v_cmp_le_i32_e64 s[46:47], 3, v196
	v_cmp_le_i32_e64 s[48:49], 4, v196
	v_cmp_le_i32_e64 s[50:51], 5, v196
	v_cmp_le_i32_e64 s[52:53], 6, v196
	v_cmp_le_i32_e32 vcc, 7, v196
	v_cndmask_b32_e64 v66, 0, v66, s[40:41]
	v_cndmask_b32_e64 v67, 0, v67, s[42:43]
	v_cndmask_b32_e64 v68, 0, v68, s[44:45]
	v_cndmask_b32_e64 v69, 0, v69, s[46:47]
	v_cndmask_b32_e64 v70, 0, v70, s[48:49]
	v_cndmask_b32_e64 v71, 0, v71, s[50:51]
	v_cndmask_b32_e64 v72, 0, v72, s[52:53]
	v_cndmask_b32_e32 v73, 0, v73, vcc
	v_cvt_pk_bf16_f32 v98, v66, v67
	v_cvt_pk_bf16_f32 v99, v68, v69
	v_cvt_pk_bf16_f32 v100, v70, v71
	v_cvt_pk_bf16_f32 v101, v72, v73
	v_add_u32_e32 v196, 4294967264, v195
	v_cmp_le_i32_e64 s[40:41], 0, v196
	v_cmp_le_i32_e64 s[42:43], 1, v196
	v_cmp_le_i32_e64 s[44:45], 2, v196
	v_cmp_le_i32_e64 s[46:47], 3, v196
	v_cmp_le_i32_e64 s[48:49], 4, v196
	v_cmp_le_i32_e64 s[50:51], 5, v196
	v_cmp_le_i32_e64 s[52:53], 6, v196
	v_cmp_le_i32_e32 vcc, 7, v196
	v_cndmask_b32_e64 v74, 0, v74, s[40:41]
	v_cndmask_b32_e64 v75, 0, v75, s[42:43]
	v_cndmask_b32_e64 v76, 0, v76, s[44:45]
	v_cndmask_b32_e64 v77, 0, v77, s[46:47]
	v_cndmask_b32_e64 v78, 0, v78, s[48:49]
	v_cndmask_b32_e64 v79, 0, v79, s[50:51]
	v_cndmask_b32_e64 v80, 0, v80, s[52:53]
	v_cndmask_b32_e32 v81, 0, v81, vcc
	v_cvt_pk_bf16_f32 v102, v74, v75
	v_cvt_pk_bf16_f32 v103, v76, v77
	v_cvt_pk_bf16_f32 v104, v78, v79
	v_cvt_pk_bf16_f32 v105, v80, v81
	v_add_u32_e32 v196, 4294967232, v195
	v_cmp_le_i32_e64 s[40:41], 0, v196
	v_cmp_le_i32_e64 s[42:43], 1, v196
	v_cmp_le_i32_e64 s[44:45], 2, v196
	v_cmp_le_i32_e64 s[46:47], 3, v196
	v_cmp_le_i32_e64 s[48:49], 4, v196
	v_cmp_le_i32_e64 s[50:51], 5, v196
	v_cmp_le_i32_e64 s[52:53], 6, v196
	v_cmp_le_i32_e32 vcc, 7, v196
	v_cndmask_b32_e64 v82, 0, v82, s[40:41]
	v_cndmask_b32_e64 v83, 0, v83, s[42:43]
	v_cndmask_b32_e64 v84, 0, v84, s[44:45]
	v_cndmask_b32_e64 v85, 0, v85, s[46:47]
	v_cndmask_b32_e64 v86, 0, v86, s[48:49]
	v_cndmask_b32_e64 v87, 0, v87, s[50:51]
	v_cndmask_b32_e64 v88, 0, v88, s[52:53]
	v_cndmask_b32_e32 v89, 0, v89, vcc
	v_cvt_pk_bf16_f32 v106, v82, v83
	v_cvt_pk_bf16_f32 v107, v84, v85
	v_cvt_pk_bf16_f32 v108, v86, v87
	v_cvt_pk_bf16_f32 v109, v88, v89
	ds_read_b128 v[66:69], v194 offset:64
	ds_read_b128 v[70:73], v194 offset:4416
	ds_read_b128 v[74:77], v194 offset:8768
	ds_read_b128 v[78:81], v194 offset:13120
	ds_read_b128 v[82:85], v194 offset:17472
	ds_read_b128 v[86:89], v194 offset:21824
	ds_read_b128 v[90:93], v194 offset:26176
	ds_read_b128 v[94:97], v194 offset:30528
	s_waitcnt lgkmcnt(15)
	v_mfma_f32_16x16x32_bf16 v[2:5], v[34:37], v[144:147], v[164:167]
	s_waitcnt lgkmcnt(14)
	v_mfma_f32_16x16x32_bf16 v[6:9], v[38:41], v[144:147], v[164:167]
	s_waitcnt lgkmcnt(13)
	v_mfma_f32_16x16x32_bf16 v[10:13], v[42:45], v[144:147], v[164:167]
	s_waitcnt lgkmcnt(12)
	v_mfma_f32_16x16x32_bf16 v[14:17], v[46:49], v[144:147], v[164:167]
	s_waitcnt lgkmcnt(11)
	v_mfma_f32_16x16x32_bf16 v[18:21], v[50:53], v[144:147], v[164:167]
	s_waitcnt lgkmcnt(10)
	v_mfma_f32_16x16x32_bf16 v[22:25], v[54:57], v[144:147], v[164:167]
	s_waitcnt lgkmcnt(9)
	v_mfma_f32_16x16x32_bf16 v[26:29], v[58:61], v[144:147], v[164:167]
	s_waitcnt lgkmcnt(8)
	v_mfma_f32_16x16x32_bf16 v[30:33], v[62:65], v[144:147], v[164:167]
	ds_read_b128 v[34:37], v194 offset:128
	ds_read_b128 v[38:41], v194 offset:4480
	ds_read_b128 v[42:45], v194 offset:8832
	ds_read_b128 v[46:49], v194 offset:13184
	ds_read_b128 v[50:53], v194 offset:17536
	ds_read_b128 v[54:57], v194 offset:21888
	ds_read_b128 v[58:61], v194 offset:26240
	ds_read_b128 v[62:65], v194 offset:30592
	s_waitcnt lgkmcnt(15)
	v_mfma_f32_16x16x32_bf16 v[2:5], v[66:69], v[148:151], v[2:5]
	s_waitcnt lgkmcnt(14)
	v_mfma_f32_16x16x32_bf16 v[6:9], v[70:73], v[148:151], v[6:9]
	s_waitcnt lgkmcnt(13)
	v_mfma_f32_16x16x32_bf16 v[10:13], v[74:77], v[148:151], v[10:13]
	s_waitcnt lgkmcnt(12)
	v_mfma_f32_16x16x32_bf16 v[14:17], v[78:81], v[148:151], v[14:17]
	s_waitcnt lgkmcnt(11)
	v_mfma_f32_16x16x32_bf16 v[18:21], v[82:85], v[148:151], v[18:21]
	s_waitcnt lgkmcnt(10)
	v_mfma_f32_16x16x32_bf16 v[22:25], v[86:89], v[148:151], v[22:25]
	s_waitcnt lgkmcnt(9)
	v_mfma_f32_16x16x32_bf16 v[26:29], v[90:93], v[148:151], v[26:29]
	s_waitcnt lgkmcnt(8)
	v_mfma_f32_16x16x32_bf16 v[30:33], v[94:97], v[148:151], v[30:33]
	ds_read_b128 v[66:69], v194 offset:34816
	ds_read_b128 v[70:73], v194 offset:39168
	ds_read_b128 v[74:77], v194 offset:43520
	ds_read_b128 v[78:81], v194 offset:47872
	ds_read_b128 v[82:85], v194 offset:52224
	ds_read_b128 v[86:89], v194 offset:56576
	ds_read_b128 v[90:93], v194 offset:60928
	ds_read_b128 v[94:97], v194 offset:65280
	s_waitcnt lgkmcnt(15)
	v_mfma_f32_16x16x32_bf16 v[2:5], v[34:37], v[152:155], v[2:5]
	s_waitcnt lgkmcnt(14)
	v_mfma_f32_16x16x32_bf16 v[6:9], v[38:41], v[152:155], v[6:9]
	s_waitcnt lgkmcnt(13)
	v_mfma_f32_16x16x32_bf16 v[10:13], v[42:45], v[152:155], v[10:13]
	s_waitcnt lgkmcnt(12)
	v_mfma_f32_16x16x32_bf16 v[14:17], v[46:49], v[152:155], v[14:17]
	s_waitcnt lgkmcnt(11)
	v_mfma_f32_16x16x32_bf16 v[18:21], v[50:53], v[152:155], v[18:21]
	s_waitcnt lgkmcnt(10)
	v_mfma_f32_16x16x32_bf16 v[22:25], v[54:57], v[152:155], v[22:25]
	s_waitcnt lgkmcnt(9)
	v_mfma_f32_16x16x32_bf16 v[26:29], v[58:61], v[152:155], v[26:29]
	s_waitcnt lgkmcnt(8)
	v_mfma_f32_16x16x32_bf16 v[30:33], v[62:65], v[152:155], v[30:33]
	ds_read_b128 v[34:37], v194 offset:34880
	ds_read_b128 v[38:41], v194 offset:39232
	ds_read_b128 v[42:45], v194 offset:43584
	ds_read_b128 v[46:49], v194 offset:47936
	ds_read_b128 v[50:53], v194 offset:52288
	ds_read_b128 v[54:57], v194 offset:56640
	ds_read_b128 v[58:61], v194 offset:60992
	ds_read_b128 v[62:65], v194 offset:65344
	s_waitcnt lgkmcnt(15)
; __device__ __forceinline__ unsigned cvt_pk_bf16(float lo, float hi) { unsigned r; asm volatile("v_cvt_pk_bf16_f32 %0, %1, %2" : "=v"(r) : "v"(lo), "v"(hi)); return r; }
; #define LAS __attribute__((address_space(3)))
; #define MFMA16(a, b, c) __builtin_amdgcn_mfma_f32_16x16x32_bf16((a), (b), (c), 0, 0, 0)
; __device__ __forceinline__ void p2_block(LAS unsigned char* lds, const bf16_t* __restrict__ PROJ, bf16_t* __restrict__ ATT, bf16_t* __restrict__ SGU, const float* __restrict__ qn, const float* __restrict__ kn, ...
;     ...
;         for (int ks = 0; ks < 4; ++ks) if (ks < nks) {
;             const f32x4 wa = *(const f32x4*)(wrow + 32 * ks), wb = *(const f32x4*)(wrow + 32 * ks + 4);
;             const int j0 = 32 * ks + 8 * fq; float wv[8];
; #pragma unroll
;             for (int e = 0; e < 4; ++e) { wv[e] = (j0 + e <= irow) ? wa[e] : 0.f; wv[4 + e] = (j0 + 4 + e <= irow) ? wb[e] : 0.f; }
;             u32x4 ww; ww.x = cvt_pk_bf16(wv[0], wv[1]); ww.y = cvt_pk_bf16(wv[2], wv[3]); ww.z = cvt_pk_bf16(wv[4], wv[5]); ww.w = cvt_pk_bf16(wv[6], wv[7]);
;             const bf16x8 wf = __builtin_bit_cast(bf16x8, ww);
; #pragma unroll
;             for (int dt = 0; dt < 8; ++dt) { const bf16x8 af = *(const LAS bf16x8*)(VNT + (16 * dt + fr) * VN_STRIDE + (32 * ks + 8 * fq) * 2); acc[dt] = MFMA16(af, wf, acc[dt]); }
	v_mfma_f32_16x16x32_bf16 v[114:117], v[66:69], v[98:101], v[186:189]
	s_waitcnt lgkmcnt(14)
	v_mfma_f32_16x16x32_bf16 v[118:121], v[70:73], v[98:101], v[186:189]
	s_waitcnt lgkmcnt(13)
	v_mfma_f32_16x16x32_bf16 v[122:125], v[74:77], v[98:101], v[186:189]
	s_waitcnt lgkmcnt(12)
	v_mfma_f32_16x16x32_bf16 v[126:129], v[78:81], v[98:101], v[186:189]
	s_waitcnt lgkmcnt(11)
	v_mfma_f32_16x16x32_bf16 v[130:133], v[82:85], v[98:101], v[186:189]
	s_waitcnt lgkmcnt(10)
	v_mfma_f32_16x16x32_bf16 v[134:137], v[86:89], v[98:101], v[186:189]
	s_waitcnt lgkmcnt(9)
	v_mfma_f32_16x16x32_bf16 v[138:141], v[90:93], v[98:101], v[186:189]
	s_waitcnt lgkmcnt(8)
	v_mfma_f32_16x16x32_bf16 v[160:163], v[94:97], v[98:101], v[186:189]
	ds_read_b128 v[66:69], v194 offset:34944
	ds_read_b128 v[70:73], v194 offset:39296
	ds_read_b128 v[74:77], v194 offset:43648
	ds_read_b128 v[78:81], v194 offset:48000
	ds_read_b128 v[82:85], v194 offset:52352
	ds_read_b128 v[86:89], v194 offset:56704
	ds_read_b128 v[90:93], v194 offset:61056
	ds_read_b128 v[94:97], v194 offset:65408
	s_waitcnt lgkmcnt(15)
	v_mfma_f32_16x16x32_bf16 v[114:117], v[34:37], v[102:105], v[114:117]
	s_waitcnt lgkmcnt(14)
	v_mfma_f32_16x16x32_bf16 v[118:121], v[38:41], v[102:105], v[118:121]
	s_waitcnt lgkmcnt(13)
	v_mfma_f32_16x16x32_bf16 v[122:125], v[42:45], v[102:105], v[122:125]
	s_waitcnt lgkmcnt(12)
	v_mfma_f32_16x16x32_bf16 v[126:129], v[46:49], v[102:105], v[126:129]
	s_waitcnt lgkmcnt(11)
	v_mfma_f32_16x16x32_bf16 v[130:133], v[50:53], v[102:105], v[130:133]
	s_waitcnt lgkmcnt(10)
	v_mfma_f32_16x16x32_bf16 v[134:137], v[54:57], v[102:105], v[134:137]
	s_waitcnt lgkmcnt(9)
	v_mfma_f32_16x16x32_bf16 v[138:141], v[58:61], v[102:105], v[138:141]
	s_waitcnt lgkmcnt(8)
	v_mfma_f32_16x16x32_bf16 v[160:163], v[62:65], v[102:105], v[160:163]
	s_waitcnt lgkmcnt(7)
	v_mfma_f32_16x16x32_bf16 v[114:117], v[66:69], v[106:109], v[114:117]
	s_waitcnt lgkmcnt(6)
	v_mfma_f32_16x16x32_bf16 v[118:121], v[70:73], v[106:109], v[118:121]
	s_waitcnt lgkmcnt(5)
	v_mfma_f32_16x16x32_bf16 v[122:125], v[74:77], v[106:109], v[122:125]
	s_waitcnt lgkmcnt(4)
	v_mfma_f32_16x16x32_bf16 v[126:129], v[78:81], v[106:109], v[126:129]
	s_waitcnt lgkmcnt(3)
	v_mfma_f32_16x16x32_bf16 v[130:133], v[82:85], v[106:109], v[130:133]
	s_waitcnt lgkmcnt(2)
	v_mfma_f32_16x16x32_bf16 v[134:137], v[86:89], v[106:109], v[134:137]
	s_waitcnt lgkmcnt(1)
	v_mfma_f32_16x16x32_bf16 v[138:141], v[90:93], v[106:109], v[138:141]
	s_waitcnt lgkmcnt(0)
	v_mfma_f32_16x16x32_bf16 v[160:163], v[94:97], v[106:109], v[160:163]
	s_branch .Lsgu_epi
.Lsgu_n4:
	s_waitcnt vmcnt(8)
	v_mov_b32_e32 v164, v198
	v_mov_b32_e32 v165, v198
	v_mov_b32_e32 v166, v198
	v_mov_b32_e32 v167, v198
	v_mov_b32_e32 v186, v199
	v_mov_b32_e32 v187, v199
	v_mov_b32_e32 v188, v199
	v_mov_b32_e32 v189, v199
	v_mov_b32_e32 v196, v195
	v_cmp_le_i32_e64 s[40:41], 0, v196
	v_cmp_le_i32_e64 s[42:43], 1, v196
	v_cmp_le_i32_e64 s[44:45], 2, v196
	v_cmp_le_i32_e64 s[46:47], 3, v196
	v_cmp_le_i32_e64 s[48:49], 4, v196
	v_cmp_le_i32_e64 s[50:51], 5, v196
	v_cmp_le_i32_e64 s[52:53], 6, v196
	v_cmp_le_i32_e32 vcc, 7, v196
	v_cndmask_b32_e64 v98, 0, v98, s[40:41]
	v_cndmask_b32_e64 v99, 0, v99, s[42:43]
	v_cndmask_b32_e64 v100, 0, v100, s[44:45]
	v_cndmask_b32_e64 v101, 0, v101, s[46:47]
	v_cndmask_b32_e64 v102, 0, v102, s[48:49]
	v_cndmask_b32_e64 v103, 0, v103, s[50:51]
	v_cndmask_b32_e64 v104, 0, v104, s[52:53]
	v_cndmask_b32_e32 v105, 0, v105, vcc
	v_cvt_pk_bf16_f32 v144, v98, v99
	v_cvt_pk_bf16_f32 v145, v100, v101
	v_cvt_pk_bf16_f32 v146, v102, v103
	v_cvt_pk_bf16_f32 v147, v104, v105
	v_add_u32_e32 v196, 4294967264, v195
	v_cmp_le_i32_e64 s[40:41], 0, v196
	v_cmp_le_i32_e64 s[42:43], 1, v196
	v_cmp_le_i32_e64 s[44:45], 2, v196
	v_cmp_le_i32_e64 s[46:47], 3, v196
	v_cmp_le_i32_e64 s[48:49], 4, v196
	v_cmp_le_i32_e64 s[50:51], 5, v196
	v_cmp_le_i32_e64 s[52:53], 6, v196
	v_cmp_le_i32_e32 vcc, 7, v196
	v_cndmask_b32_e64 v106, 0, v106, s[40:41]
	v_cndmask_b32_e64 v107, 0, v107, s[42:43]
	v_cndmask_b32_e64 v108, 0, v108, s[44:45]
	v_cndmask_b32_e64 v109, 0, v109, s[46:47]
	v_cndmask_b32_e64 v110, 0, v110, s[48:49]
	v_cndmask_b32_e64 v111, 0, v111, s[50:51]
	v_cndmask_b32_e64 v112, 0, v112, s[52:53]
	v_cndmask_b32_e32 v113, 0, v113, vcc
	v_cvt_pk_bf16_f32 v148, v106, v107
	v_cvt_pk_bf16_f32 v149, v108, v109
	v_cvt_pk_bf16_f32 v150, v110, v111
	v_cvt_pk_bf16_f32 v151, v112, v113
	v_add_u32_e32 v196, 4294967232, v195
	v_cmp_le_i32_e64 s[40:41], 0, v196
	v_cmp_le_i32_e64 s[42:43], 1, v196
	v_cmp_le_i32_e64 s[44:45], 2, v196
	v_cmp_le_i32_e64 s[46:47], 3, v196
	v_cmp_le_i32_e64 s[48:49], 4, v196
	v_cmp_le_i32_e64 s[50:51], 5, v196
	v_cmp_le_i32_e64 s[52:53], 6, v196
	v_cmp_le_i32_e32 vcc, 7, v196
	v_cndmask_b32_e64 v114, 0, v114, s[40:41]
	v_cndmask_b32_e64 v115, 0, v115, s[42:43]
	v_cndmask_b32_e64 v116, 0, v116, s[44:45]
	v_cndmask_b32_e64 v117, 0, v117, s[46:47]
	v_cndmask_b32_e64 v118, 0, v118, s[48:49]
	v_cndmask_b32_e64 v119, 0, v119, s[50:51]
	v_cndmask_b32_e64 v120, 0, v120, s[52:53]
	v_cndmask_b32_e32 v121, 0, v121, vcc
	v_cvt_pk_bf16_f32 v152, v114, v115
	v_cvt_pk_bf16_f32 v153, v116, v117
	v_cvt_pk_bf16_f32 v154, v118, v119
	v_cvt_pk_bf16_f32 v155, v120, v121
	v_add_u32_e32 v196, 4294967200, v195
	v_cmp_le_i32_e64 s[40:41], 0, v196
	v_cmp_le_i32_e64 s[42:43], 1, v196
	v_cmp_le_i32_e64 s[44:45], 2, v196
	v_cmp_le_i32_e64 s[46:47], 3, v196
	v_cmp_le_i32_e64 s[48:49], 4, v196
	v_cmp_le_i32_e64 s[50:51], 5, v196
	v_cmp_le_i32_e64 s[52:53], 6, v196
	v_cmp_le_i32_e32 vcc, 7, v196
	v_cndmask_b32_e64 v122, 0, v122, s[40:41]
	v_cndmask_b32_e64 v123, 0, v123, s[42:43]
	v_cndmask_b32_e64 v124, 0, v124, s[44:45]
	v_cndmask_b32_e64 v125, 0, v125, s[46:47]
	v_cndmask_b32_e64 v126, 0, v126, s[48:49]
	v_cndmask_b32_e64 v127, 0, v127, s[50:51]
	v_cndmask_b32_e64 v128, 0, v128, s[52:53]
	v_cndmask_b32_e32 v129, 0, v129, vcc
	v_cvt_pk_bf16_f32 v156, v122, v123
	v_cvt_pk_bf16_f32 v157, v124, v125
	v_cvt_pk_bf16_f32 v158, v126, v127
	v_cvt_pk_bf16_f32 v159, v128, v129
	ds_read_b128 v[34:37], v194 offset:0
	ds_read_b128 v[38:41], v194 offset:4352
	ds_read_b128 v[42:45], v194 offset:8704
	ds_read_b128 v[46:49], v194 offset:13056
	ds_read_b128 v[50:53], v194 offset:17408
	ds_read_b128 v[54:57], v194 offset:21760
	ds_read_b128 v[58:61], v194 offset:26112
	ds_read_b128 v[62:65], v194 offset:30464
	s_waitcnt vmcnt(0)
; __device__ __forceinline__ unsigned cvt_pk_bf16(float lo, float hi) { unsigned r; asm volatile("v_cvt_pk_bf16_f32 %0, %1, %2" : "=v"(r) : "v"(lo), "v"(hi)); return r; }
; #define LAS __attribute__((address_space(3)))
; #define MFMA16(a, b, c) __builtin_amdgcn_mfma_f32_16x16x32_bf16((a), (b), (c), 0, 0, 0)
; __device__ __forceinline__ void p2_block(LAS unsigned char* lds, const bf16_t* __restrict__ PROJ, bf16_t* __restrict__ ATT, bf16_t* __restrict__ SGU, const float* __restrict__ qn, const float* __restrict__ kn, ...
;     ...
;         for (int ks = 0; ks < 4; ++ks) if (ks < nks) {
;             const f32x4 wa = *(const f32x4*)(wrow + 32 * ks), wb = *(const f32x4*)(wrow + 32 * ks + 4);
;             const int j0 = 32 * ks + 8 * fq; float wv[8];
; #pragma unroll
;             for (int e = 0; e < 4; ++e) { wv[e] = (j0 + e <= irow) ? wa[e] : 0.f; wv[4 + e] = (j0 + 4 + e <= irow) ? wb[e] : 0.f; }
;             u32x4 ww; ww.x = cvt_pk_bf16(wv[0], wv[1]); ww.y = cvt_pk_bf16(wv[2], wv[3]); ww.z = cvt_pk_bf16(wv[4], wv[5]); ww.w = cvt_pk_bf16(wv[6], wv[7]);
;             const bf16x8 wf = __builtin_bit_cast(bf16x8, ww);
; #pragma unroll
;             for (int dt = 0; dt < 8; ++dt) { const bf16x8 af = *(const LAS bf16x8*)(VNT + (16 * dt + fr) * VN_STRIDE + (32 * ks + 8 * fq) * 2); acc[dt] = MFMA16(af, wf, acc[dt]); }
	v_mov_b32_e32 v196, v195
	v_cmp_le_i32_e64 s[40:41], 0, v196
	v_cmp_le_i32_e64 s[42:43], 1, v196
	v_cmp_le_i32_e64 s[44:45], 2, v196
	v_cmp_le_i32_e64 s[46:47], 3, v196
	v_cmp_le_i32_e64 s[48:49], 4, v196
	v_cmp_le_i32_e64 s[50:51], 5, v196
	v_cmp_le_i32_e64 s[52:53], 6, v196
	v_cmp_le_i32_e32 vcc, 7, v196
	v_cndmask_b32_e64 v66, 0, v66, s[40:41]
	v_cndmask_b32_e64 v67, 0, v67, s[42:43]
	v_cndmask_b32_e64 v68, 0, v68, s[44:45]
	v_cndmask_b32_e64 v69, 0, v69, s[46:47]
	v_cndmask_b32_e64 v70, 0, v70, s[48:49]
	v_cndmask_b32_e64 v71, 0, v71, s[50:51]
	v_cndmask_b32_e64 v72, 0, v72, s[52:53]
	v_cndmask_b32_e32 v73, 0, v73, vcc
	v_cvt_pk_bf16_f32 v98, v66, v67
	v_cvt_pk_bf16_f32 v99, v68, v69
	v_cvt_pk_bf16_f32 v100, v70, v71
	v_cvt_pk_bf16_f32 v101, v72, v73
	v_add_u32_e32 v196, 4294967264, v195
	v_cmp_le_i32_e64 s[40:41], 0, v196
	v_cmp_le_i32_e64 s[42:43], 1, v196
	v_cmp_le_i32_e64 s[44:45], 2, v196
	v_cmp_le_i32_e64 s[46:47], 3, v196
	v_cmp_le_i32_e64 s[48:49], 4, v196
	v_cmp_le_i32_e64 s[50:51], 5, v196
	v_cmp_le_i32_e64 s[52:53], 6, v196
	v_cmp_le_i32_e32 vcc, 7, v196
	v_cndmask_b32_e64 v74, 0, v74, s[40:41]
	v_cndmask_b32_e64 v75, 0, v75, s[42:43]
	v_cndmask_b32_e64 v76, 0, v76, s[44:45]
	v_cndmask_b32_e64 v77, 0, v77, s[46:47]
	v_cndmask_b32_e64 v78, 0, v78, s[48:49]
	v_cndmask_b32_e64 v79, 0, v79, s[50:51]
	v_cndmask_b32_e64 v80, 0, v80, s[52:53]
	v_cndmask_b32_e32 v81, 0, v81, vcc
	v_cvt_pk_bf16_f32 v102, v74, v75
	v_cvt_pk_bf16_f32 v103, v76, v77
	v_cvt_pk_bf16_f32 v104, v78, v79
	v_cvt_pk_bf16_f32 v105, v80, v81
	v_add_u32_e32 v196, 4294967232, v195
	v_cmp_le_i32_e64 s[40:41], 0, v196
	v_cmp_le_i32_e64 s[42:43], 1, v196
	v_cmp_le_i32_e64 s[44:45], 2, v196
	v_cmp_le_i32_e64 s[46:47], 3, v196
	v_cmp_le_i32_e64 s[48:49], 4, v196
	v_cmp_le_i32_e64 s[50:51], 5, v196
	v_cmp_le_i32_e64 s[52:53], 6, v196
	v_cmp_le_i32_e32 vcc, 7, v196
	v_cndmask_b32_e64 v82, 0, v82, s[40:41]
	v_cndmask_b32_e64 v83, 0, v83, s[42:43]
	v_cndmask_b32_e64 v84, 0, v84, s[44:45]
	v_cndmask_b32_e64 v85, 0, v85, s[46:47]
	v_cndmask_b32_e64 v86, 0, v86, s[48:49]
	v_cndmask_b32_e64 v87, 0, v87, s[50:51]
	v_cndmask_b32_e64 v88, 0, v88, s[52:53]
	v_cndmask_b32_e32 v89, 0, v89, vcc
	v_cvt_pk_bf16_f32 v106, v82, v83
	v_cvt_pk_bf16_f32 v107, v84, v85
	v_cvt_pk_bf16_f32 v108, v86, v87
	v_cvt_pk_bf16_f32 v109, v88, v89
	v_add_u32_e32 v196, 4294967200, v195
	v_cmp_le_i32_e64 s[40:41], 0, v196
	v_cmp_le_i32_e64 s[42:43], 1, v196
	v_cmp_le_i32_e64 s[44:45], 2, v196
	v_cmp_le_i32_e64 s[46:47], 3, v196
	v_cmp_le_i32_e64 s[48:49], 4, v196
	v_cmp_le_i32_e64 s[50:51], 5, v196
	v_cmp_le_i32_e64 s[52:53], 6, v196
	v_cmp_le_i32_e32 vcc, 7, v196
	v_cndmask_b32_e64 v90, 0, v90, s[40:41]
	v_cndmask_b32_e64 v91, 0, v91, s[42:43]
	v_cndmask_b32_e64 v92, 0, v92, s[44:45]
	v_cndmask_b32_e64 v93, 0, v93, s[46:47]
	v_cndmask_b32_e64 v94, 0, v94, s[48:49]
	v_cndmask_b32_e64 v95, 0, v95, s[50:51]
	v_cndmask_b32_e64 v96, 0, v96, s[52:53]
	v_cndmask_b32_e32 v97, 0, v97, vcc
	v_cvt_pk_bf16_f32 v110, v90, v91
	v_cvt_pk_bf16_f32 v111, v92, v93
	v_cvt_pk_bf16_f32 v112, v94, v95
	v_cvt_pk_bf16_f32 v113, v96, v97
	ds_read_b128 v[66:69], v194 offset:64
	ds_read_b128 v[70:73], v194 offset:4416
	ds_read_b128 v[74:77], v194 offset:8768
	ds_read_b128 v[78:81], v194 offset:13120
	ds_read_b128 v[82:85], v194 offset:17472
	ds_read_b128 v[86:89], v194 offset:21824
	ds_read_b128 v[90:93], v194 offset:26176
	ds_read_b128 v[94:97], v194 offset:30528
	s_waitcnt lgkmcnt(15)
	v_mfma_f32_16x16x32_bf16 v[2:5], v[34:37], v[144:147], v[164:167]
	s_waitcnt lgkmcnt(14)
	v_mfma_f32_16x16x32_bf16 v[6:9], v[38:41], v[144:147], v[164:167]
	s_waitcnt lgkmcnt(13)
	v_mfma_f32_16x16x32_bf16 v[10:13], v[42:45], v[144:147], v[164:167]
	s_waitcnt lgkmcnt(12)
	v_mfma_f32_16x16x32_bf16 v[14:17], v[46:49], v[144:147], v[164:167]
	s_waitcnt lgkmcnt(11)
	v_mfma_f32_16x16x32_bf16 v[18:21], v[50:53], v[144:147], v[164:167]
	s_waitcnt lgkmcnt(10)
	v_mfma_f32_16x16x32_bf16 v[22:25], v[54:57], v[144:147], v[164:167]
	s_waitcnt lgkmcnt(9)
	v_mfma_f32_16x16x32_bf16 v[26:29], v[58:61], v[144:147], v[164:167]
	s_waitcnt lgkmcnt(8)
	v_mfma_f32_16x16x32_bf16 v[30:33], v[62:65], v[144:147], v[164:167]
	ds_read_b128 v[34:37], v194 offset:128
	ds_read_b128 v[38:41], v194 offset:4480
	ds_read_b128 v[42:45], v194 offset:8832
	ds_read_b128 v[46:49], v194 offset:13184
	ds_read_b128 v[50:53], v194 offset:17536
	ds_read_b128 v[54:57], v194 offset:21888
	ds_read_b128 v[58:61], v194 offset:26240
	ds_read_b128 v[62:65], v194 offset:30592
	s_waitcnt lgkmcnt(15)
	v_mfma_f32_16x16x32_bf16 v[2:5], v[66:69], v[148:151], v[2:5]
	s_waitcnt lgkmcnt(14)
	v_mfma_f32_16x16x32_bf16 v[6:9], v[70:73], v[148:151], v[6:9]
	s_waitcnt lgkmcnt(13)
	v_mfma_f32_16x16x32_bf16 v[10:13], v[74:77], v[148:151], v[10:13]
	s_waitcnt lgkmcnt(12)
	v_mfma_f32_16x16x32_bf16 v[14:17], v[78:81], v[148:151], v[14:17]
	s_waitcnt lgkmcnt(11)
	v_mfma_f32_16x16x32_bf16 v[18:21], v[82:85], v[148:151], v[18:21]
	s_waitcnt lgkmcnt(10)
	v_mfma_f32_16x16x32_bf16 v[22:25], v[86:89], v[148:151], v[22:25]
	s_waitcnt lgkmcnt(9)
	v_mfma_f32_16x16x32_bf16 v[26:29], v[90:93], v[148:151], v[26:29]
	s_waitcnt lgkmcnt(8)
	v_mfma_f32_16x16x32_bf16 v[30:33], v[94:97], v[148:151], v[30:33]
	ds_read_b128 v[66:69], v194 offset:192
	ds_read_b128 v[70:73], v194 offset:4544
	ds_read_b128 v[74:77], v194 offset:8896
	ds_read_b128 v[78:81], v194 offset:13248
	ds_read_b128 v[82:85], v194 offset:17600
	ds_read_b128 v[86:89], v194 offset:21952
	ds_read_b128 v[90:93], v194 offset:26304
	ds_read_b128 v[94:97], v194 offset:30656
	s_waitcnt lgkmcnt(15)
	v_mfma_f32_16x16x32_bf16 v[2:5], v[34:37], v[152:155], v[2:5]
	s_waitcnt lgkmcnt(14)
; __device__ __forceinline__ unsigned cvt_pk_bf16(float lo, float hi) { unsigned r; asm volatile("v_cvt_pk_bf16_f32 %0, %1, %2" : "=v"(r) : "v"(lo), "v"(hi)); return r; }
; #define LAS __attribute__((address_space(3)))
; #define MFMA16(a, b, c) __builtin_amdgcn_mfma_f32_16x16x32_bf16((a), (b), (c), 0, 0, 0)
; __device__ __forceinline__ void p2_block(LAS unsigned char* lds, const bf16_t* __restrict__ PROJ, bf16_t* __restrict__ ATT, bf16_t* __restrict__ SGU, const float* __restrict__ qn, const float* __restrict__ kn, ...
;     ...
;         for (int ks = 0; ks < 4; ++ks) if (ks < nks) {
;             const f32x4 wa = *(const f32x4*)(wrow + 32 * ks), wb = *(const f32x4*)(wrow + 32 * ks + 4);
;             const int j0 = 32 * ks + 8 * fq; float wv[8];
; #pragma unroll
;             for (int e = 0; e < 4; ++e) { wv[e] = (j0 + e <= irow) ? wa[e] : 0.f; wv[4 + e] = (j0 + 4 + e <= irow) ? wb[e] : 0.f; }
;             u32x4 ww; ww.x = cvt_pk_bf16(wv[0], wv[1]); ww.y = cvt_pk_bf16(wv[2], wv[3]); ww.z = cvt_pk_bf16(wv[4], wv[5]); ww.w = cvt_pk_bf16(wv[6], wv[7]);
;             const bf16x8 wf = __builtin_bit_cast(bf16x8, ww);
; #pragma unroll
;             for (int dt = 0; dt < 8; ++dt) { const bf16x8 af = *(const LAS bf16x8*)(VNT + (16 * dt + fr) * VN_STRIDE + (32 * ks + 8 * fq) * 2); acc[dt] = MFMA16(af, wf, acc[dt]); }
	v_mfma_f32_16x16x32_bf16 v[6:9], v[38:41], v[152:155], v[6:9]
	s_waitcnt lgkmcnt(13)
	v_mfma_f32_16x16x32_bf16 v[10:13], v[42:45], v[152:155], v[10:13]
	s_waitcnt lgkmcnt(12)
	v_mfma_f32_16x16x32_bf16 v[14:17], v[46:49], v[152:155], v[14:17]
	s_waitcnt lgkmcnt(11)
	v_mfma_f32_16x16x32_bf16 v[18:21], v[50:53], v[152:155], v[18:21]
	s_waitcnt lgkmcnt(10)
	v_mfma_f32_16x16x32_bf16 v[22:25], v[54:57], v[152:155], v[22:25]
	s_waitcnt lgkmcnt(9)
	v_mfma_f32_16x16x32_bf16 v[26:29], v[58:61], v[152:155], v[26:29]
	s_waitcnt lgkmcnt(8)
	v_mfma_f32_16x16x32_bf16 v[30:33], v[62:65], v[152:155], v[30:33]
	ds_read_b128 v[34:37], v194 offset:34816
	ds_read_b128 v[38:41], v194 offset:39168
	ds_read_b128 v[42:45], v194 offset:43520
	ds_read_b128 v[46:49], v194 offset:47872
	ds_read_b128 v[50:53], v194 offset:52224
	ds_read_b128 v[54:57], v194 offset:56576
	ds_read_b128 v[58:61], v194 offset:60928
	ds_read_b128 v[62:65], v194 offset:65280
	s_waitcnt lgkmcnt(15)
	v_mfma_f32_16x16x32_bf16 v[2:5], v[66:69], v[156:159], v[2:5]
	s_waitcnt lgkmcnt(14)
	v_mfma_f32_16x16x32_bf16 v[6:9], v[70:73], v[156:159], v[6:9]
	s_waitcnt lgkmcnt(13)
	v_mfma_f32_16x16x32_bf16 v[10:13], v[74:77], v[156:159], v[10:13]
	s_waitcnt lgkmcnt(12)
	v_mfma_f32_16x16x32_bf16 v[14:17], v[78:81], v[156:159], v[14:17]
	s_waitcnt lgkmcnt(11)
	v_mfma_f32_16x16x32_bf16 v[18:21], v[82:85], v[156:159], v[18:21]
	s_waitcnt lgkmcnt(10)
	v_mfma_f32_16x16x32_bf16 v[22:25], v[86:89], v[156:159], v[22:25]
	s_waitcnt lgkmcnt(9)
	v_mfma_f32_16x16x32_bf16 v[26:29], v[90:93], v[156:159], v[26:29]
	s_waitcnt lgkmcnt(8)
	v_mfma_f32_16x16x32_bf16 v[30:33], v[94:97], v[156:159], v[30:33]
	ds_read_b128 v[66:69], v194 offset:34880
	ds_read_b128 v[70:73], v194 offset:39232
	ds_read_b128 v[74:77], v194 offset:43584
	ds_read_b128 v[78:81], v194 offset:47936
	ds_read_b128 v[82:85], v194 offset:52288
	ds_read_b128 v[86:89], v194 offset:56640
	ds_read_b128 v[90:93], v194 offset:60992
	ds_read_b128 v[94:97], v194 offset:65344
	s_waitcnt lgkmcnt(15)
	v_mfma_f32_16x16x32_bf16 v[114:117], v[34:37], v[98:101], v[186:189]
	s_waitcnt lgkmcnt(14)
	v_mfma_f32_16x16x32_bf16 v[118:121], v[38:41], v[98:101], v[186:189]
	s_waitcnt lgkmcnt(13)
	v_mfma_f32_16x16x32_bf16 v[122:125], v[42:45], v[98:101], v[186:189]
	s_waitcnt lgkmcnt(12)
	v_mfma_f32_16x16x32_bf16 v[126:129], v[46:49], v[98:101], v[186:189]
	s_waitcnt lgkmcnt(11)
	v_mfma_f32_16x16x32_bf16 v[130:133], v[50:53], v[98:101], v[186:189]
	s_waitcnt lgkmcnt(10)
	v_mfma_f32_16x16x32_bf16 v[134:137], v[54:57], v[98:101], v[186:189]
	s_waitcnt lgkmcnt(9)
	v_mfma_f32_16x16x32_bf16 v[138:141], v[58:61], v[98:101], v[186:189]
	s_waitcnt lgkmcnt(8)
	v_mfma_f32_16x16x32_bf16 v[160:163], v[62:65], v[98:101], v[186:189]
	ds_read_b128 v[34:37], v194 offset:34944
	ds_read_b128 v[38:41], v194 offset:39296
	ds_read_b128 v[42:45], v194 offset:43648
	ds_read_b128 v[46:49], v194 offset:48000
	ds_read_b128 v[50:53], v194 offset:52352
	ds_read_b128 v[54:57], v194 offset:56704
	ds_read_b128 v[58:61], v194 offset:61056
	ds_read_b128 v[62:65], v194 offset:65408
	s_waitcnt lgkmcnt(15)
	v_mfma_f32_16x16x32_bf16 v[114:117], v[66:69], v[102:105], v[114:117]
	s_waitcnt lgkmcnt(14)
	v_mfma_f32_16x16x32_bf16 v[118:121], v[70:73], v[102:105], v[118:121]
	s_waitcnt lgkmcnt(13)
	v_mfma_f32_16x16x32_bf16 v[122:125], v[74:77], v[102:105], v[122:125]
	s_waitcnt lgkmcnt(12)
	v_mfma_f32_16x16x32_bf16 v[126:129], v[78:81], v[102:105], v[126:129]
	s_waitcnt lgkmcnt(11)
	v_mfma_f32_16x16x32_bf16 v[130:133], v[82:85], v[102:105], v[130:133]
	s_waitcnt lgkmcnt(10)
	v_mfma_f32_16x16x32_bf16 v[134:137], v[86:89], v[102:105], v[134:137]
	s_waitcnt lgkmcnt(9)
	v_mfma_f32_16x16x32_bf16 v[138:141], v[90:93], v[102:105], v[138:141]
	s_waitcnt lgkmcnt(8)
	v_mfma_f32_16x16x32_bf16 v[160:163], v[94:97], v[102:105], v[160:163]
	ds_read_b128 v[66:69], v194 offset:35008
	ds_read_b128 v[70:73], v194 offset:39360
	ds_read_b128 v[74:77], v194 offset:43712
	ds_read_b128 v[78:81], v194 offset:48064
	ds_read_b128 v[82:85], v194 offset:52416
	ds_read_b128 v[86:89], v194 offset:56768
	ds_read_b128 v[90:93], v194 offset:61120
	ds_read_b128 v[94:97], v194 offset:65472
	s_waitcnt lgkmcnt(15)
	v_mfma_f32_16x16x32_bf16 v[114:117], v[34:37], v[106:109], v[114:117]
	s_waitcnt lgkmcnt(14)
	v_mfma_f32_16x16x32_bf16 v[118:121], v[38:41], v[106:109], v[118:121]
	s_waitcnt lgkmcnt(13)
	v_mfma_f32_16x16x32_bf16 v[122:125], v[42:45], v[106:109], v[122:125]
	s_waitcnt lgkmcnt(12)
	v_mfma_f32_16x16x32_bf16 v[126:129], v[46:49], v[106:109], v[126:129]
	s_waitcnt lgkmcnt(11)
	v_mfma_f32_16x16x32_bf16 v[130:133], v[50:53], v[106:109], v[130:133]
	s_waitcnt lgkmcnt(10)
	v_mfma_f32_16x16x32_bf16 v[134:137], v[54:57], v[106:109], v[134:137]
	s_waitcnt lgkmcnt(9)
	v_mfma_f32_16x16x32_bf16 v[138:141], v[58:61], v[106:109], v[138:141]
	s_waitcnt lgkmcnt(8)
	v_mfma_f32_16x16x32_bf16 v[160:163], v[62:65], v[106:109], v[160:163]
	s_waitcnt lgkmcnt(7)
	v_mfma_f32_16x16x32_bf16 v[114:117], v[66:69], v[110:113], v[114:117]
	s_waitcnt lgkmcnt(6)
	v_mfma_f32_16x16x32_bf16 v[118:121], v[70:73], v[110:113], v[118:121]
	s_waitcnt lgkmcnt(5)
	v_mfma_f32_16x16x32_bf16 v[122:125], v[74:77], v[110:113], v[122:125]
	s_waitcnt lgkmcnt(4)
	v_mfma_f32_16x16x32_bf16 v[126:129], v[78:81], v[110:113], v[126:129]
	s_waitcnt lgkmcnt(3)
	v_mfma_f32_16x16x32_bf16 v[130:133], v[82:85], v[110:113], v[130:133]
	s_waitcnt lgkmcnt(2)
	v_mfma_f32_16x16x32_bf16 v[134:137], v[86:89], v[110:113], v[134:137]
	s_waitcnt lgkmcnt(1)
	v_mfma_f32_16x16x32_bf16 v[138:141], v[90:93], v[110:113], v[138:141]
	s_waitcnt lgkmcnt(0)
	v_mfma_f32_16x16x32_bf16 v[160:163], v[94:97], v[110:113], v[160:163]
	s_branch .Lsgu_epi
; __device__ __forceinline__ unsigned cvt_pk_bf16(float lo, float hi) { unsigned r; asm volatile("v_cvt_pk_bf16_f32 %0, %1, %2" : "=v"(r) : "v"(lo), "v"(hi)); return r; }
; __device__ __forceinline__ float bf_lo(unsigned w) { return __uint_as_float(w << 16); }
; __device__ __forceinline__ float bf_hi(unsigned w) { return __uint_as_float(w & 0xffff0000u); }
; __device__ __forceinline__ float gelu_f(float x) { const float y2 = 1.5957691216057308f * x * (1.0f + 0.044715f * x * x); return x * sigmoid_f(y2); }
; __device__ __forceinline__ float sigmoid_f(float v) { return __builtin_amdgcn_rcpf(1.0f + __expf(-v)); }
; __device__ __forceinline__ void p2_block(LAS unsigned char* lds, const bf16_t* __restrict__ PROJ, bf16_t* __restrict__ ATT, bf16_t* __restrict__ SGU, const float* __restrict__ qn, const float* __restrict__ kn, ...
;     ...
;         for (int dt = 0; dt < 8; ++dt) { const u32x2 uw = *(const u32x2*)(up + 16 * dt);
;             const float u0 = gelu_f(bf_lo(uw.x)), u1 = gelu_f(bf_hi(uw.x)), u2 = gelu_f(bf_lo(uw.y)), u3 = gelu_f(bf_hi(uw.y));
;             u32x2 ow; ow.x = cvt_pk_bf16(u0 * (acc[dt][0] + bias), u1 * (acc[dt][1] + bias)); ow.y = cvt_pk_bf16(u2 * (acc[dt][2] + bias), u3 * (acc[dt][3] + bias)); *(u32x2*)(op + 16 * dt) = ow; }
.Lsgu_epi:
	v_mov_b32_e32 v197, 0xbdd2d3e7
	s_waitcnt vmcnt(0)
	v_lshlrev_b32_e32 v34, 16, v218
	v_and_b32_e32 v35, 0xffff0000, v218
	v_lshlrev_b32_e32 v36, 16, v219
	v_and_b32_e32 v37, 0xffff0000, v219
	v_mul_f32_e32 v38, v34, v34
	v_mul_f32_e32 v39, v35, v35
	v_mul_f32_e32 v40, v36, v36
	v_mul_f32_e32 v41, v37, v37
	v_fmaak_f32 v38, v38, v197, 0xc0135761
	v_fmaak_f32 v39, v39, v197, 0xc0135761
	v_fmaak_f32 v40, v40, v197, 0xc0135761
	v_fmaak_f32 v41, v41, v197, 0xc0135761
	v_mul_f32_e32 v38, v38, v34
	v_mul_f32_e32 v39, v39, v35
	v_mul_f32_e32 v40, v40, v36
	v_mul_f32_e32 v41, v41, v37
	v_exp_f32_e32 v38, v38
	v_exp_f32_e32 v39, v39
	v_exp_f32_e32 v40, v40
	v_exp_f32_e32 v41, v41
	v_add_f32_e32 v38, 1.0, v38
	v_add_f32_e32 v39, 1.0, v39
	v_add_f32_e32 v40, 1.0, v40
	v_add_f32_e32 v41, 1.0, v41
	v_rcp_f32_e32 v38, v38
	v_rcp_f32_e32 v39, v39
	v_rcp_f32_e32 v40, v40
	v_rcp_f32_e32 v41, v41
	v_mul_f32_e32 v34, v38, v34
	v_mul_f32_e32 v35, v39, v35
	v_mul_f32_e32 v36, v40, v36
	v_mul_f32_e32 v37, v41, v37
	v_mul_f32_e32 v46, v2, v34
	v_mul_f32_e32 v47, v3, v35
	v_mul_f32_e32 v48, v4, v36
	v_mul_f32_e32 v49, v5, v37
	v_cvt_pk_bf16_f32 v50, v46, v47
	v_cvt_pk_bf16_f32 v51, v48, v49
	global_store_dwordx2 v182, v[50:51], s[12:13] offset:0
	v_lshlrev_b32_e32 v34, 16, v220
	v_and_b32_e32 v35, 0xffff0000, v220
	v_lshlrev_b32_e32 v36, 16, v221
	v_and_b32_e32 v37, 0xffff0000, v221
	v_mul_f32_e32 v38, v34, v34
	v_mul_f32_e32 v39, v35, v35
	v_mul_f32_e32 v40, v36, v36
	v_mul_f32_e32 v41, v37, v37
	v_fmaak_f32 v38, v38, v197, 0xc0135761
	v_fmaak_f32 v39, v39, v197, 0xc0135761
	v_fmaak_f32 v40, v40, v197, 0xc0135761
	v_fmaak_f32 v41, v41, v197, 0xc0135761
	v_mul_f32_e32 v38, v38, v34
	v_mul_f32_e32 v39, v39, v35
	v_mul_f32_e32 v40, v40, v36
	v_mul_f32_e32 v41, v41, v37
	v_exp_f32_e32 v38, v38
	v_exp_f32_e32 v39, v39
	v_exp_f32_e32 v40, v40
	v_exp_f32_e32 v41, v41
	v_add_f32_e32 v38, 1.0, v38
	v_add_f32_e32 v39, 1.0, v39
	v_add_f32_e32 v40, 1.0, v40
	v_add_f32_e32 v41, 1.0, v41
	v_rcp_f32_e32 v38, v38
	v_rcp_f32_e32 v39, v39
	v_rcp_f32_e32 v40, v40
	v_rcp_f32_e32 v41, v41
	v_mul_f32_e32 v34, v38, v34
	v_mul_f32_e32 v35, v39, v35
	v_mul_f32_e32 v36, v40, v36
	v_mul_f32_e32 v37, v41, v37
	v_mul_f32_e32 v46, v6, v34
	v_mul_f32_e32 v47, v7, v35
	v_mul_f32_e32 v48, v8, v36
	v_mul_f32_e32 v49, v9, v37
	v_cvt_pk_bf16_f32 v50, v46, v47
	v_cvt_pk_bf16_f32 v51, v48, v49
	global_store_dwordx2 v182, v[50:51], s[12:13] offset:32
	v_lshlrev_b32_e32 v34, 16, v222
	v_and_b32_e32 v35, 0xffff0000, v222
	v_lshlrev_b32_e32 v36, 16, v223
	v_and_b32_e32 v37, 0xffff0000, v223
	v_mul_f32_e32 v38, v34, v34
	v_mul_f32_e32 v39, v35, v35
	v_mul_f32_e32 v40, v36, v36
	v_mul_f32_e32 v41, v37, v37
	v_fmaak_f32 v38, v38, v197, 0xc0135761
	v_fmaak_f32 v39, v39, v197, 0xc0135761
	v_fmaak_f32 v40, v40, v197, 0xc0135761
	v_fmaak_f32 v41, v41, v197, 0xc0135761
	v_mul_f32_e32 v38, v38, v34
	v_mul_f32_e32 v39, v39, v35
	v_mul_f32_e32 v40, v40, v36
	v_mul_f32_e32 v41, v41, v37
	v_exp_f32_e32 v38, v38
	v_exp_f32_e32 v39, v39
	v_exp_f32_e32 v40, v40
	v_exp_f32_e32 v41, v41
	v_add_f32_e32 v38, 1.0, v38
	v_add_f32_e32 v39, 1.0, v39
	v_add_f32_e32 v40, 1.0, v40
	v_add_f32_e32 v41, 1.0, v41
	v_rcp_f32_e32 v38, v38
	v_rcp_f32_e32 v39, v39
	v_rcp_f32_e32 v40, v40
	v_rcp_f32_e32 v41, v41
	v_mul_f32_e32 v34, v38, v34
	v_mul_f32_e32 v35, v39, v35
	v_mul_f32_e32 v36, v40, v36
	v_mul_f32_e32 v37, v41, v37
	v_mul_f32_e32 v46, v10, v34
	v_mul_f32_e32 v47, v11, v35
	v_mul_f32_e32 v48, v12, v36
	v_mul_f32_e32 v49, v13, v37
	v_cvt_pk_bf16_f32 v50, v46, v47
	v_cvt_pk_bf16_f32 v51, v48, v49
	global_store_dwordx2 v182, v[50:51], s[12:13] offset:64
	v_lshlrev_b32_e32 v34, 16, v224
	v_and_b32_e32 v35, 0xffff0000, v224
	v_lshlrev_b32_e32 v36, 16, v225
	v_and_b32_e32 v37, 0xffff0000, v225
	v_mul_f32_e32 v38, v34, v34
	v_mul_f32_e32 v39, v35, v35
	v_mul_f32_e32 v40, v36, v36
	v_mul_f32_e32 v41, v37, v37
	v_fmaak_f32 v38, v38, v197, 0xc0135761
	v_fmaak_f32 v39, v39, v197, 0xc0135761
	v_fmaak_f32 v40, v40, v197, 0xc0135761
	v_fmaak_f32 v41, v41, v197, 0xc0135761
	v_mul_f32_e32 v38, v38, v34
	v_mul_f32_e32 v39, v39, v35
	v_mul_f32_e32 v40, v40, v36
	v_mul_f32_e32 v41, v41, v37
	v_exp_f32_e32 v38, v38
	v_exp_f32_e32 v39, v39
	v_exp_f32_e32 v40, v40
	v_exp_f32_e32 v41, v41
	v_add_f32_e32 v38, 1.0, v38
	v_add_f32_e32 v39, 1.0, v39
	v_add_f32_e32 v40, 1.0, v40
	v_add_f32_e32 v41, 1.0, v41
	v_rcp_f32_e32 v38, v38
	v_rcp_f32_e32 v39, v39
	v_rcp_f32_e32 v40, v40
	v_rcp_f32_e32 v41, v41
	v_mul_f32_e32 v34, v38, v34
	v_mul_f32_e32 v35, v39, v35
	v_mul_f32_e32 v36, v40, v36
	v_mul_f32_e32 v37, v41, v37
	v_mul_f32_e32 v46, v14, v34
	v_mul_f32_e32 v47, v15, v35
	v_mul_f32_e32 v48, v16, v36
	v_mul_f32_e32 v49, v17, v37
	v_cvt_pk_bf16_f32 v50, v46, v47
	v_cvt_pk_bf16_f32 v51, v48, v49
	global_store_dwordx2 v182, v[50:51], s[12:13] offset:96
	v_lshlrev_b32_e32 v34, 16, v226
	v_and_b32_e32 v35, 0xffff0000, v226
	v_lshlrev_b32_e32 v36, 16, v227
	v_and_b32_e32 v37, 0xffff0000, v227
	v_mul_f32_e32 v38, v34, v34
	v_mul_f32_e32 v39, v35, v35
	v_mul_f32_e32 v40, v36, v36
	v_mul_f32_e32 v41, v37, v37
	v_fmaak_f32 v38, v38, v197, 0xc0135761
	v_fmaak_f32 v39, v39, v197, 0xc0135761
	v_fmaak_f32 v40, v40, v197, 0xc0135761
	v_fmaak_f32 v41, v41, v197, 0xc0135761
	v_mul_f32_e32 v38, v38, v34
	v_mul_f32_e32 v39, v39, v35
	v_mul_f32_e32 v40, v40, v36
	v_mul_f32_e32 v41, v41, v37
	v_exp_f32_e32 v38, v38
	v_exp_f32_e32 v39, v39
	v_exp_f32_e32 v40, v40
	v_exp_f32_e32 v41, v41
	v_add_f32_e32 v38, 1.0, v38
	v_add_f32_e32 v39, 1.0, v39
	v_add_f32_e32 v40, 1.0, v40
	v_add_f32_e32 v41, 1.0, v41
	v_rcp_f32_e32 v38, v38
	v_rcp_f32_e32 v39, v39
	v_rcp_f32_e32 v40, v40
; __device__ __forceinline__ unsigned cvt_pk_bf16(float lo, float hi) { unsigned r; asm volatile("v_cvt_pk_bf16_f32 %0, %1, %2" : "=v"(r) : "v"(lo), "v"(hi)); return r; }
; __device__ __forceinline__ float bf_lo(unsigned w) { return __uint_as_float(w << 16); }
; __device__ __forceinline__ float bf_hi(unsigned w) { return __uint_as_float(w & 0xffff0000u); }
; __device__ __forceinline__ float gelu_f(float x) { const float y2 = 1.5957691216057308f * x * (1.0f + 0.044715f * x * x); return x * sigmoid_f(y2); }
; __device__ __forceinline__ float sigmoid_f(float v) { return __builtin_amdgcn_rcpf(1.0f + __expf(-v)); }
; __device__ __forceinline__ void p2_block(LAS unsigned char* lds, const bf16_t* __restrict__ PROJ, bf16_t* __restrict__ ATT, bf16_t* __restrict__ SGU, const float* __restrict__ qn, const float* __restrict__ kn, ...
;     ...
;         for (int dt = 0; dt < 8; ++dt) { const u32x2 uw = *(const u32x2*)(up + 16 * dt);
;             const float u0 = gelu_f(bf_lo(uw.x)), u1 = gelu_f(bf_hi(uw.x)), u2 = gelu_f(bf_lo(uw.y)), u3 = gelu_f(bf_hi(uw.y));
;             u32x2 ow; ow.x = cvt_pk_bf16(u0 * (acc[dt][0] + bias), u1 * (acc[dt][1] + bias)); ow.y = cvt_pk_bf16(u2 * (acc[dt][2] + bias), u3 * (acc[dt][3] + bias)); *(u32x2*)(op + 16 * dt) = ow; }
	v_rcp_f32_e32 v41, v41
	v_mul_f32_e32 v34, v38, v34
	v_mul_f32_e32 v35, v39, v35
	v_mul_f32_e32 v36, v40, v36
	v_mul_f32_e32 v37, v41, v37
	v_mul_f32_e32 v46, v18, v34
	v_mul_f32_e32 v47, v19, v35
	v_mul_f32_e32 v48, v20, v36
	v_mul_f32_e32 v49, v21, v37
	v_cvt_pk_bf16_f32 v50, v46, v47
	v_cvt_pk_bf16_f32 v51, v48, v49
	global_store_dwordx2 v182, v[50:51], s[12:13] offset:128
	v_lshlrev_b32_e32 v34, 16, v228
	v_and_b32_e32 v35, 0xffff0000, v228
	v_lshlrev_b32_e32 v36, 16, v229
	v_and_b32_e32 v37, 0xffff0000, v229
	v_mul_f32_e32 v38, v34, v34
	v_mul_f32_e32 v39, v35, v35
	v_mul_f32_e32 v40, v36, v36
	v_mul_f32_e32 v41, v37, v37
	v_fmaak_f32 v38, v38, v197, 0xc0135761
	v_fmaak_f32 v39, v39, v197, 0xc0135761
	v_fmaak_f32 v40, v40, v197, 0xc0135761
	v_fmaak_f32 v41, v41, v197, 0xc0135761
	v_mul_f32_e32 v38, v38, v34
	v_mul_f32_e32 v39, v39, v35
	v_mul_f32_e32 v40, v40, v36
	v_mul_f32_e32 v41, v41, v37
	v_exp_f32_e32 v38, v38
	v_exp_f32_e32 v39, v39
	v_exp_f32_e32 v40, v40
	v_exp_f32_e32 v41, v41
	v_add_f32_e32 v38, 1.0, v38
	v_add_f32_e32 v39, 1.0, v39
	v_add_f32_e32 v40, 1.0, v40
	v_add_f32_e32 v41, 1.0, v41
	v_rcp_f32_e32 v38, v38
	v_rcp_f32_e32 v39, v39
	v_rcp_f32_e32 v40, v40
	v_rcp_f32_e32 v41, v41
	v_mul_f32_e32 v34, v38, v34
	v_mul_f32_e32 v35, v39, v35
	v_mul_f32_e32 v36, v40, v36
	v_mul_f32_e32 v37, v41, v37
	v_mul_f32_e32 v46, v22, v34
	v_mul_f32_e32 v47, v23, v35
	v_mul_f32_e32 v48, v24, v36
	v_mul_f32_e32 v49, v25, v37
	v_cvt_pk_bf16_f32 v50, v46, v47
	v_cvt_pk_bf16_f32 v51, v48, v49
	global_store_dwordx2 v182, v[50:51], s[12:13] offset:160
	v_lshlrev_b32_e32 v34, 16, v230
	v_and_b32_e32 v35, 0xffff0000, v230
	v_lshlrev_b32_e32 v36, 16, v231
	v_and_b32_e32 v37, 0xffff0000, v231
	v_mul_f32_e32 v38, v34, v34
	v_mul_f32_e32 v39, v35, v35
	v_mul_f32_e32 v40, v36, v36
	v_mul_f32_e32 v41, v37, v37
	v_fmaak_f32 v38, v38, v197, 0xc0135761
	v_fmaak_f32 v39, v39, v197, 0xc0135761
	v_fmaak_f32 v40, v40, v197, 0xc0135761
	v_fmaak_f32 v41, v41, v197, 0xc0135761
	v_mul_f32_e32 v38, v38, v34
	v_mul_f32_e32 v39, v39, v35
	v_mul_f32_e32 v40, v40, v36
	v_mul_f32_e32 v41, v41, v37
	v_exp_f32_e32 v38, v38
	v_exp_f32_e32 v39, v39
	v_exp_f32_e32 v40, v40
	v_exp_f32_e32 v41, v41
	v_add_f32_e32 v38, 1.0, v38
	v_add_f32_e32 v39, 1.0, v39
	v_add_f32_e32 v40, 1.0, v40
	v_add_f32_e32 v41, 1.0, v41
	v_rcp_f32_e32 v38, v38
	v_rcp_f32_e32 v39, v39
	v_rcp_f32_e32 v40, v40
	v_rcp_f32_e32 v41, v41
	v_mul_f32_e32 v34, v38, v34
	v_mul_f32_e32 v35, v39, v35
	v_mul_f32_e32 v36, v40, v36
	v_mul_f32_e32 v37, v41, v37
	v_mul_f32_e32 v46, v26, v34
	v_mul_f32_e32 v47, v27, v35
	v_mul_f32_e32 v48, v28, v36
	v_mul_f32_e32 v49, v29, v37
	v_cvt_pk_bf16_f32 v50, v46, v47
	v_cvt_pk_bf16_f32 v51, v48, v49
	global_store_dwordx2 v182, v[50:51], s[12:13] offset:192
	v_lshlrev_b32_e32 v34, 16, v232
	v_and_b32_e32 v35, 0xffff0000, v232
	v_lshlrev_b32_e32 v36, 16, v233
	v_and_b32_e32 v37, 0xffff0000, v233
	v_mul_f32_e32 v38, v34, v34
	v_mul_f32_e32 v39, v35, v35
	v_mul_f32_e32 v40, v36, v36
	v_mul_f32_e32 v41, v37, v37
	v_fmaak_f32 v38, v38, v197, 0xc0135761
	v_fmaak_f32 v39, v39, v197, 0xc0135761
	v_fmaak_f32 v40, v40, v197, 0xc0135761
	v_fmaak_f32 v41, v41, v197, 0xc0135761
	v_mul_f32_e32 v38, v38, v34
	v_mul_f32_e32 v39, v39, v35
	v_mul_f32_e32 v40, v40, v36
	v_mul_f32_e32 v41, v41, v37
	v_exp_f32_e32 v38, v38
	v_exp_f32_e32 v39, v39
	v_exp_f32_e32 v40, v40
	v_exp_f32_e32 v41, v41
	v_add_f32_e32 v38, 1.0, v38
	v_add_f32_e32 v39, 1.0, v39
	v_add_f32_e32 v40, 1.0, v40
	v_add_f32_e32 v41, 1.0, v41
	v_rcp_f32_e32 v38, v38
	v_rcp_f32_e32 v39, v39
	v_rcp_f32_e32 v40, v40
	v_rcp_f32_e32 v41, v41
	v_mul_f32_e32 v34, v38, v34
	v_mul_f32_e32 v35, v39, v35
	v_mul_f32_e32 v36, v40, v36
	v_mul_f32_e32 v37, v41, v37
	v_mul_f32_e32 v46, v30, v34
	v_mul_f32_e32 v47, v31, v35
	v_mul_f32_e32 v48, v32, v36
	v_mul_f32_e32 v49, v33, v37
	v_cvt_pk_bf16_f32 v50, v46, v47
	v_cvt_pk_bf16_f32 v51, v48, v49
	global_store_dwordx2 v182, v[50:51], s[12:13] offset:224
	v_lshlrev_b32_e32 v34, 16, v234
	v_and_b32_e32 v35, 0xffff0000, v234
	v_lshlrev_b32_e32 v36, 16, v235
	v_and_b32_e32 v37, 0xffff0000, v235
	v_mul_f32_e32 v38, v34, v34
	v_mul_f32_e32 v39, v35, v35
	v_mul_f32_e32 v40, v36, v36
	v_mul_f32_e32 v41, v37, v37
	v_fmaak_f32 v38, v38, v197, 0xc0135761
	v_fmaak_f32 v39, v39, v197, 0xc0135761
	v_fmaak_f32 v40, v40, v197, 0xc0135761
	v_fmaak_f32 v41, v41, v197, 0xc0135761
	v_mul_f32_e32 v38, v38, v34
	v_mul_f32_e32 v39, v39, v35
	v_mul_f32_e32 v40, v40, v36
	v_mul_f32_e32 v41, v41, v37
	v_exp_f32_e32 v38, v38
	v_exp_f32_e32 v39, v39
	v_exp_f32_e32 v40, v40
	v_exp_f32_e32 v41, v41
	v_add_f32_e32 v38, 1.0, v38
	v_add_f32_e32 v39, 1.0, v39
	v_add_f32_e32 v40, 1.0, v40
	v_add_f32_e32 v41, 1.0, v41
	v_rcp_f32_e32 v38, v38
	v_rcp_f32_e32 v39, v39
	v_rcp_f32_e32 v40, v40
	v_rcp_f32_e32 v41, v41
	v_mul_f32_e32 v34, v38, v34
	v_mul_f32_e32 v35, v39, v35
	v_mul_f32_e32 v36, v40, v36
	v_mul_f32_e32 v37, v41, v37
	v_mul_f32_e32 v46, v114, v34
	v_mul_f32_e32 v47, v115, v35
	v_mul_f32_e32 v48, v116, v36
	v_mul_f32_e32 v49, v117, v37
	v_cvt_pk_bf16_f32 v50, v46, v47
	v_cvt_pk_bf16_f32 v51, v48, v49
	global_store_dwordx2 v182, v[50:51], s[12:13] offset:256
	v_lshlrev_b32_e32 v34, 16, v236
	v_and_b32_e32 v35, 0xffff0000, v236
	v_lshlrev_b32_e32 v36, 16, v237
	v_and_b32_e32 v37, 0xffff0000, v237
	v_mul_f32_e32 v38, v34, v34
	v_mul_f32_e32 v39, v35, v35
	v_mul_f32_e32 v40, v36, v36
	v_mul_f32_e32 v41, v37, v37
	v_fmaak_f32 v38, v38, v197, 0xc0135761
	v_fmaak_f32 v39, v39, v197, 0xc0135761
	v_fmaak_f32 v40, v40, v197, 0xc0135761
	v_fmaak_f32 v41, v41, v197, 0xc0135761
	v_mul_f32_e32 v38, v38, v34
	v_mul_f32_e32 v39, v39, v35
; __device__ __forceinline__ unsigned cvt_pk_bf16(float lo, float hi) { unsigned r; asm volatile("v_cvt_pk_bf16_f32 %0, %1, %2" : "=v"(r) : "v"(lo), "v"(hi)); return r; }
; __device__ __forceinline__ float bf_lo(unsigned w) { return __uint_as_float(w << 16); }
; __device__ __forceinline__ float bf_hi(unsigned w) { return __uint_as_float(w & 0xffff0000u); }
; __device__ __forceinline__ float gelu_f(float x) { const float y2 = 1.5957691216057308f * x * (1.0f + 0.044715f * x * x); return x * sigmoid_f(y2); }
; __device__ __forceinline__ float sigmoid_f(float v) { return __builtin_amdgcn_rcpf(1.0f + __expf(-v)); }
; __device__ __forceinline__ void p2_block(LAS unsigned char* lds, const bf16_t* __restrict__ PROJ, bf16_t* __restrict__ ATT, bf16_t* __restrict__ SGU, const float* __restrict__ qn, const float* __restrict__ kn, ...
;     ...
;         for (int dt = 0; dt < 8; ++dt) { const u32x2 uw = *(const u32x2*)(up + 16 * dt);
;             const float u0 = gelu_f(bf_lo(uw.x)), u1 = gelu_f(bf_hi(uw.x)), u2 = gelu_f(bf_lo(uw.y)), u3 = gelu_f(bf_hi(uw.y));
;             u32x2 ow; ow.x = cvt_pk_bf16(u0 * (acc[dt][0] + bias), u1 * (acc[dt][1] + bias)); ow.y = cvt_pk_bf16(u2 * (acc[dt][2] + bias), u3 * (acc[dt][3] + bias)); *(u32x2*)(op + 16 * dt) = ow; }
	v_mul_f32_e32 v40, v40, v36
	v_mul_f32_e32 v41, v41, v37
	v_exp_f32_e32 v38, v38
	v_exp_f32_e32 v39, v39
	v_exp_f32_e32 v40, v40
	v_exp_f32_e32 v41, v41
	v_add_f32_e32 v38, 1.0, v38
	v_add_f32_e32 v39, 1.0, v39
	v_add_f32_e32 v40, 1.0, v40
	v_add_f32_e32 v41, 1.0, v41
	v_rcp_f32_e32 v38, v38
	v_rcp_f32_e32 v39, v39
	v_rcp_f32_e32 v40, v40
	v_rcp_f32_e32 v41, v41
	v_mul_f32_e32 v34, v38, v34
	v_mul_f32_e32 v35, v39, v35
	v_mul_f32_e32 v36, v40, v36
	v_mul_f32_e32 v37, v41, v37
	v_mul_f32_e32 v46, v118, v34
	v_mul_f32_e32 v47, v119, v35
	v_mul_f32_e32 v48, v120, v36
	v_mul_f32_e32 v49, v121, v37
	v_cvt_pk_bf16_f32 v50, v46, v47
	v_cvt_pk_bf16_f32 v51, v48, v49
	global_store_dwordx2 v182, v[50:51], s[12:13] offset:288
	v_lshlrev_b32_e32 v34, 16, v238
	v_and_b32_e32 v35, 0xffff0000, v238
	v_lshlrev_b32_e32 v36, 16, v239
	v_and_b32_e32 v37, 0xffff0000, v239
	v_mul_f32_e32 v38, v34, v34
	v_mul_f32_e32 v39, v35, v35
	v_mul_f32_e32 v40, v36, v36
	v_mul_f32_e32 v41, v37, v37
	v_fmaak_f32 v38, v38, v197, 0xc0135761
	v_fmaak_f32 v39, v39, v197, 0xc0135761
	v_fmaak_f32 v40, v40, v197, 0xc0135761
	v_fmaak_f32 v41, v41, v197, 0xc0135761
	v_mul_f32_e32 v38, v38, v34
	v_mul_f32_e32 v39, v39, v35
	v_mul_f32_e32 v40, v40, v36
	v_mul_f32_e32 v41, v41, v37
	v_exp_f32_e32 v38, v38
	v_exp_f32_e32 v39, v39
	v_exp_f32_e32 v40, v40
	v_exp_f32_e32 v41, v41
	v_add_f32_e32 v38, 1.0, v38
	v_add_f32_e32 v39, 1.0, v39
	v_add_f32_e32 v40, 1.0, v40
	v_add_f32_e32 v41, 1.0, v41
	v_rcp_f32_e32 v38, v38
	v_rcp_f32_e32 v39, v39
	v_rcp_f32_e32 v40, v40
	v_rcp_f32_e32 v41, v41
	v_mul_f32_e32 v34, v38, v34
	v_mul_f32_e32 v35, v39, v35
	v_mul_f32_e32 v36, v40, v36
	v_mul_f32_e32 v37, v41, v37
	v_mul_f32_e32 v46, v122, v34
	v_mul_f32_e32 v47, v123, v35
	v_mul_f32_e32 v48, v124, v36
	v_mul_f32_e32 v49, v125, v37
	v_cvt_pk_bf16_f32 v50, v46, v47
	v_cvt_pk_bf16_f32 v51, v48, v49
	global_store_dwordx2 v182, v[50:51], s[12:13] offset:320
	v_lshlrev_b32_e32 v34, 16, v240
	v_and_b32_e32 v35, 0xffff0000, v240
	v_lshlrev_b32_e32 v36, 16, v241
	v_and_b32_e32 v37, 0xffff0000, v241
	v_mul_f32_e32 v38, v34, v34
	v_mul_f32_e32 v39, v35, v35
	v_mul_f32_e32 v40, v36, v36
	v_mul_f32_e32 v41, v37, v37
	v_fmaak_f32 v38, v38, v197, 0xc0135761
	v_fmaak_f32 v39, v39, v197, 0xc0135761
	v_fmaak_f32 v40, v40, v197, 0xc0135761
	v_fmaak_f32 v41, v41, v197, 0xc0135761
	v_mul_f32_e32 v38, v38, v34
	v_mul_f32_e32 v39, v39, v35
	v_mul_f32_e32 v40, v40, v36
	v_mul_f32_e32 v41, v41, v37
	v_exp_f32_e32 v38, v38
	v_exp_f32_e32 v39, v39
	v_exp_f32_e32 v40, v40
	v_exp_f32_e32 v41, v41
	v_add_f32_e32 v38, 1.0, v38
	v_add_f32_e32 v39, 1.0, v39
	v_add_f32_e32 v40, 1.0, v40
	v_add_f32_e32 v41, 1.0, v41
	v_rcp_f32_e32 v38, v38
	v_rcp_f32_e32 v39, v39
	v_rcp_f32_e32 v40, v40
	v_rcp_f32_e32 v41, v41
	v_mul_f32_e32 v34, v38, v34
	v_mul_f32_e32 v35, v39, v35
	v_mul_f32_e32 v36, v40, v36
	v_mul_f32_e32 v37, v41, v37
	v_mul_f32_e32 v46, v126, v34
	v_mul_f32_e32 v47, v127, v35
	v_mul_f32_e32 v48, v128, v36
	v_mul_f32_e32 v49, v129, v37
	v_cvt_pk_bf16_f32 v50, v46, v47
	v_cvt_pk_bf16_f32 v51, v48, v49
	global_store_dwordx2 v182, v[50:51], s[12:13] offset:352
	v_lshlrev_b32_e32 v34, 16, v242
	v_and_b32_e32 v35, 0xffff0000, v242
	v_lshlrev_b32_e32 v36, 16, v243
	v_and_b32_e32 v37, 0xffff0000, v243
	v_mul_f32_e32 v38, v34, v34
	v_mul_f32_e32 v39, v35, v35
	v_mul_f32_e32 v40, v36, v36
	v_mul_f32_e32 v41, v37, v37
	v_fmaak_f32 v38, v38, v197, 0xc0135761
	v_fmaak_f32 v39, v39, v197, 0xc0135761
	v_fmaak_f32 v40, v40, v197, 0xc0135761
	v_fmaak_f32 v41, v41, v197, 0xc0135761
	v_mul_f32_e32 v38, v38, v34
	v_mul_f32_e32 v39, v39, v35
	v_mul_f32_e32 v40, v40, v36
	v_mul_f32_e32 v41, v41, v37
	v_exp_f32_e32 v38, v38
	v_exp_f32_e32 v39, v39
	v_exp_f32_e32 v40, v40
	v_exp_f32_e32 v41, v41
	v_add_f32_e32 v38, 1.0, v38
	v_add_f32_e32 v39, 1.0, v39
	v_add_f32_e32 v40, 1.0, v40
	v_add_f32_e32 v41, 1.0, v41
	v_rcp_f32_e32 v38, v38
	v_rcp_f32_e32 v39, v39
	v_rcp_f32_e32 v40, v40
	v_rcp_f32_e32 v41, v41
	v_mul_f32_e32 v34, v38, v34
	v_mul_f32_e32 v35, v39, v35
; __device__ __forceinline__ unsigned cvt_pk_bf16(float lo, float hi) { unsigned r; asm volatile("v_cvt_pk_bf16_f32 %0, %1, %2" : "=v"(r) : "v"(lo), "v"(hi)); return r; }
; __device__ __forceinline__ float bf_lo(unsigned w) { return __uint_as_float(w << 16); }
; __device__ __forceinline__ float bf_hi(unsigned w) { return __uint_as_float(w & 0xffff0000u); }
; __device__ __forceinline__ float gelu_f(float x) { const float y2 = 1.5957691216057308f * x * (1.0f + 0.044715f * x * x); return x * sigmoid_f(y2); }
; __device__ __forceinline__ void p2_block(LAS unsigned char* lds, const bf16_t* __restrict__ PROJ, bf16_t* __restrict__ ATT, bf16_t* __restrict__ SGU, const float* __restrict__ qn, const float* __restrict__ kn, ...
;     ...
;         for (int dt = 0; dt < 8; ++dt) { const u32x2 uw = *(const u32x2*)(up + 16 * dt);
;             const float u0 = gelu_f(bf_lo(uw.x)), u1 = gelu_f(bf_hi(uw.x)), u2 = gelu_f(bf_lo(uw.y)), u3 = gelu_f(bf_hi(uw.y));
;             u32x2 ow; ow.x = cvt_pk_bf16(u0 * (acc[dt][0] + bias), u1 * (acc[dt][1] + bias)); ow.y = cvt_pk_bf16(u2 * (acc[dt][2] + bias), u3 * (acc[dt][3] + bias)); *(u32x2*)(op + 16 * dt) = ow; }
;     }
;     __syncthreads();
; __global__ void __launch_bounds__(NTHREADS, 2) mk_fwd(Args args) {
;     ...
;             for (int it = blk; it < 256; it += G) p2_block(lds, PROJ, ATT, SGU, args.in[3] + l * 64, args.in[4] + l * 64, args.in[5] + l * 16, COS, SIN, args.in[6] + l * 1024, args.in[7] + l * 1024,
;                                                            args.in[8] + (size_t)l * 8 * 16384, args.in[9] + l * 1024, it, tid);
	v_mul_f32_e32 v36, v40, v36
	v_mul_f32_e32 v37, v41, v37
	v_mul_f32_e32 v46, v130, v34
	v_mul_f32_e32 v47, v131, v35
	v_mul_f32_e32 v48, v132, v36
	v_mul_f32_e32 v49, v133, v37
	v_cvt_pk_bf16_f32 v50, v46, v47
	v_cvt_pk_bf16_f32 v51, v48, v49
	global_store_dwordx2 v182, v[50:51], s[12:13] offset:384
	v_lshlrev_b32_e32 v34, 16, v244
	v_and_b32_e32 v35, 0xffff0000, v244
	v_lshlrev_b32_e32 v36, 16, v245
	v_and_b32_e32 v37, 0xffff0000, v245
	v_mul_f32_e32 v38, v34, v34
	v_mul_f32_e32 v39, v35, v35
	v_mul_f32_e32 v40, v36, v36
	v_mul_f32_e32 v41, v37, v37
	v_fmaak_f32 v38, v38, v197, 0xc0135761
	v_fmaak_f32 v39, v39, v197, 0xc0135761
	v_fmaak_f32 v40, v40, v197, 0xc0135761
	v_fmaak_f32 v41, v41, v197, 0xc0135761
	v_mul_f32_e32 v38, v38, v34
	v_mul_f32_e32 v39, v39, v35
	v_mul_f32_e32 v40, v40, v36
	v_mul_f32_e32 v41, v41, v37
	v_exp_f32_e32 v38, v38
	v_exp_f32_e32 v39, v39
	v_exp_f32_e32 v40, v40
	v_exp_f32_e32 v41, v41
	v_add_f32_e32 v38, 1.0, v38
	v_add_f32_e32 v39, 1.0, v39
	v_add_f32_e32 v40, 1.0, v40
	v_add_f32_e32 v41, 1.0, v41
	v_rcp_f32_e32 v38, v38
	v_rcp_f32_e32 v39, v39
	v_rcp_f32_e32 v40, v40
	v_rcp_f32_e32 v41, v41
	v_mul_f32_e32 v34, v38, v34
	v_mul_f32_e32 v35, v39, v35
	v_mul_f32_e32 v36, v40, v36
	v_mul_f32_e32 v37, v41, v37
	v_mul_f32_e32 v46, v134, v34
	v_mul_f32_e32 v47, v135, v35
	v_mul_f32_e32 v48, v136, v36
	v_mul_f32_e32 v49, v137, v37
	v_cvt_pk_bf16_f32 v50, v46, v47
	v_cvt_pk_bf16_f32 v51, v48, v49
	global_store_dwordx2 v182, v[50:51], s[12:13] offset:416
	v_lshlrev_b32_e32 v34, 16, v200
	v_and_b32_e32 v35, 0xffff0000, v200
	v_lshlrev_b32_e32 v36, 16, v201
	v_and_b32_e32 v37, 0xffff0000, v201
	v_mul_f32_e32 v38, v34, v34
	v_mul_f32_e32 v39, v35, v35
	v_mul_f32_e32 v40, v36, v36
	v_mul_f32_e32 v41, v37, v37
	v_fmaak_f32 v38, v38, v197, 0xc0135761
	v_fmaak_f32 v39, v39, v197, 0xc0135761
	v_fmaak_f32 v40, v40, v197, 0xc0135761
	v_fmaak_f32 v41, v41, v197, 0xc0135761
	v_mul_f32_e32 v38, v38, v34
	v_mul_f32_e32 v39, v39, v35
	v_mul_f32_e32 v40, v40, v36
	v_mul_f32_e32 v41, v41, v37
	v_exp_f32_e32 v38, v38
	v_exp_f32_e32 v39, v39
	v_exp_f32_e32 v40, v40
	v_exp_f32_e32 v41, v41
	v_add_f32_e32 v38, 1.0, v38
	v_add_f32_e32 v39, 1.0, v39
	v_add_f32_e32 v40, 1.0, v40
	v_add_f32_e32 v41, 1.0, v41
	v_rcp_f32_e32 v38, v38
	v_rcp_f32_e32 v39, v39
	v_rcp_f32_e32 v40, v40
	v_rcp_f32_e32 v41, v41
	v_mul_f32_e32 v34, v38, v34
	v_mul_f32_e32 v35, v39, v35
	v_mul_f32_e32 v36, v40, v36
	v_mul_f32_e32 v37, v41, v37
	v_mul_f32_e32 v46, v138, v34
	v_mul_f32_e32 v47, v139, v35
	v_mul_f32_e32 v48, v140, v36
	v_mul_f32_e32 v49, v141, v37
	v_cvt_pk_bf16_f32 v50, v46, v47
	v_cvt_pk_bf16_f32 v51, v48, v49
	global_store_dwordx2 v182, v[50:51], s[12:13] offset:448
	v_lshlrev_b32_e32 v34, 16, v202
	v_and_b32_e32 v35, 0xffff0000, v202
	v_lshlrev_b32_e32 v36, 16, v203
	v_and_b32_e32 v37, 0xffff0000, v203
	v_mul_f32_e32 v38, v34, v34
	v_mul_f32_e32 v39, v35, v35
	v_mul_f32_e32 v40, v36, v36
	v_mul_f32_e32 v41, v37, v37
	v_fmaak_f32 v38, v38, v197, 0xc0135761
	v_fmaak_f32 v39, v39, v197, 0xc0135761
	v_fmaak_f32 v40, v40, v197, 0xc0135761
	v_fmaak_f32 v41, v41, v197, 0xc0135761
	v_mul_f32_e32 v38, v38, v34
	v_mul_f32_e32 v39, v39, v35
	v_mul_f32_e32 v40, v40, v36
	v_mul_f32_e32 v41, v41, v37
	v_exp_f32_e32 v38, v38
	v_exp_f32_e32 v39, v39
	v_exp_f32_e32 v40, v40
	v_exp_f32_e32 v41, v41
	v_add_f32_e32 v38, 1.0, v38
	v_add_f32_e32 v39, 1.0, v39
	v_add_f32_e32 v40, 1.0, v40
	v_add_f32_e32 v41, 1.0, v41
	v_rcp_f32_e32 v38, v38
	v_rcp_f32_e32 v39, v39
	v_rcp_f32_e32 v40, v40
	v_rcp_f32_e32 v41, v41
	v_mul_f32_e32 v34, v38, v34
	v_mul_f32_e32 v35, v39, v35
	v_mul_f32_e32 v36, v40, v36
	v_mul_f32_e32 v37, v41, v37
	v_mul_f32_e32 v46, v160, v34
	v_mul_f32_e32 v47, v161, v35
	v_mul_f32_e32 v48, v162, v36
	v_mul_f32_e32 v49, v163, v37
	v_cvt_pk_bf16_f32 v50, v46, v47
	v_cvt_pk_bf16_f32 v51, v48, v49
	global_store_dwordx2 v182, v[50:51], s[12:13] offset:480
	s_add_i32 s2, s2, s3
	s_cmpk_lt_i32 s2, 0x100
	s_waitcnt lgkmcnt(0)
	s_barrier
	s_cbranch_scc1 .LBB0_330
